# mixers: LDS reads hoisted and renamed to free VGPRs in all retention/attention MFMA sections (bit-identical math)
# baseline (speedup 1.0000x reference)
; __device__ __forceinline__ void attention_item(LAS unsigned char* lds, const bf16* ZH, bf16* OP, float* LP, bf16* MIX, const float* qg, const float* kg, int item, int tid0) {
;     ...
;         float lsum = 0.f;
;         {
;           const int i = 16 * w + lr, rb = 16 * jt0 + 4 * lg - 64 - i, lo_i = -(i + B.qi0), hi_i = B.m - 1 - i - B.qi0;
;           const float rbf = (float)rb, LO = (float)(lo_i > -64 ? lo_i : -64), HI = (float)(hi_i < 64 ? hi_i : 64);
;           const float L2E = 1.4426950408889634f, sdl = sd * L2E, sml = smax * L2E;
; #pragma unroll
;           for (int t = 0; t < 10; ++t)
; #pragma unroll
;             for (int rr = 0; rr < 4; ++rr) { const float relf = rbf + (float)(16 * t + rr);
;                 const float x = __builtin_fmaf(sT[t][rr], L2E, __builtin_fmaf(-sdl, __builtin_fabsf(relf), -sml));
;                 const bool ok = __builtin_amdgcn_fmed3f(relf, LO, HI) == relf;
;                 const float p = ok ? __builtin_amdgcn_exp2f(x) : 0.f; sT[t][rr] = p; lsum += p; } }
.LBB0_438:
	s_waitcnt lgkmcnt(0)
	s_lshl_b32 s34, 1, s42
	v_cvt_f32_ubyte0_e32 v160, s34
	v_mul_f32_e32 v165, v229, v160
	s_lshr_b32 s34, s47, s42
	v_lshlrev_b32_e32 v160, 2, v4
	s_lshr_b32 s35, s64, s42
	s_add_i32 s34, s55, s34
	v_or_b32_e32 v163, v5, v2
	v_add_u32_e32 v162, v162, v160
	v_sub_u32_e32 v162, v162, v163
	v_add_u32_e32 v164, s34, v163
	s_sub_i32 s35, s35, s34
	v_subrev_u32_e32 v162, 64, v162
	v_sub_u32_e32 v164, 0, v164
	v_xad_u32 v166, v163, -1, s35
	v_cvt_f32_i32_e32 v163, v162
	v_max_i32_e32 v162, 0xffffffc0, v164
	v_min_i32_e32 v164, 64, v166
	v_cvt_f32_i32_e32 v162, v162
	v_cvt_f32_i32_e32 v164, v164
	v_mul_f32_e32 v165, 0xbfb8aa3b, v165
	v_fma_f32 v166, v165, |v163|, v239
	v_fmac_f32_e32 v166, 0x3fb8aa3b, v154
	v_med3_f32 v154, v163, v162, v164
	v_cmp_eq_f32_e32 vcc, v154, v163
	v_exp_f32_e32 v154, v166
	v_add_f32_e32 v167, 1.0, v163
	v_fma_f32 v168, v165, |v167|, v239
	v_fmac_f32_e32 v168, 0x3fb8aa3b, v155
	v_med3_f32 v155, v167, v162, v164
	v_cndmask_b32_e32 v154, 0, v154, vcc
	v_cmp_eq_f32_e32 vcc, v155, v167
	v_exp_f32_e32 v155, v168
	v_add_f32_e32 v167, 2.0, v163
	v_fma_f32 v168, v165, |v167|, v239
	v_fmac_f32_e32 v168, 0x3fb8aa3b, v156
	v_med3_f32 v156, v167, v162, v164
	v_cndmask_b32_e32 v155, 0, v155, vcc
	v_cmp_eq_f32_e32 vcc, v156, v167
	v_exp_f32_e32 v156, v168
	v_add_f32_e32 v167, 0x40400000, v163
	v_fma_f32 v168, v165, |v167|, v239
	v_fmac_f32_e32 v168, 0x3fb8aa3b, v157
	v_med3_f32 v157, v167, v162, v164
	v_cndmask_b32_e32 v156, 0, v156, vcc
	v_cmp_eq_f32_e32 vcc, v157, v167
	v_exp_f32_e32 v157, v168
	v_add_f32_e32 v167, 0x41800000, v163
	v_fma_f32 v168, v165, |v167|, v239
	v_fmac_f32_e32 v168, 0x3fb8aa3b, v150
	v_med3_f32 v150, v167, v162, v164
	v_cndmask_b32_e32 v157, 0, v157, vcc
	v_cmp_eq_f32_e32 vcc, v150, v167
	v_exp_f32_e32 v150, v168
	v_add_f32_e32 v167, 0x41880000, v163
	v_fma_f32 v168, v165, |v167|, v239
	v_fmac_f32_e32 v168, 0x3fb8aa3b, v151
	v_med3_f32 v151, v167, v162, v164
	v_cndmask_b32_e32 v150, 0, v150, vcc
	v_cmp_eq_f32_e32 vcc, v151, v167
	v_exp_f32_e32 v151, v168
	v_add_f32_e32 v167, 0x41900000, v163
	v_fma_f32 v168, v165, |v167|, v239
	v_fmac_f32_e32 v168, 0x3fb8aa3b, v152
	v_med3_f32 v152, v167, v162, v164
	v_cndmask_b32_e32 v151, 0, v151, vcc
	v_cmp_eq_f32_e32 vcc, v152, v167
	v_exp_f32_e32 v152, v168
	v_add_f32_e32 v167, 0x41980000, v163
	v_fma_f32 v168, v165, |v167|, v239
	v_fmac_f32_e32 v168, 0x3fb8aa3b, v153
	v_med3_f32 v153, v167, v162, v164
	v_cndmask_b32_e32 v152, 0, v152, vcc
	v_cmp_eq_f32_e32 vcc, v153, v167
	v_exp_f32_e32 v153, v168
	v_add_f32_e32 v167, 0x42000000, v163
	v_fma_f32 v168, v165, |v167|, v239
	v_fmac_f32_e32 v168, 0x3fb8aa3b, v146
	v_med3_f32 v146, v167, v162, v164
	v_cndmask_b32_e32 v153, 0, v153, vcc
	v_cmp_eq_f32_e32 vcc, v146, v167
	v_exp_f32_e32 v146, v168
	v_add_f32_e32 v167, 0x42040000, v163
	v_fma_f32 v168, v165, |v167|, v239
	v_fmac_f32_e32 v168, 0x3fb8aa3b, v147
	v_med3_f32 v147, v167, v162, v164
	v_cndmask_b32_e32 v146, 0, v146, vcc
	v_cmp_eq_f32_e32 vcc, v147, v167
	v_exp_f32_e32 v147, v168
	v_add_f32_e32 v167, 0x42080000, v163
	v_fma_f32 v168, v165, |v167|, v239
	v_fmac_f32_e32 v168, 0x3fb8aa3b, v148
	v_med3_f32 v148, v167, v162, v164
	v_cndmask_b32_e32 v147, 0, v147, vcc
	v_cmp_eq_f32_e32 vcc, v148, v167
	v_exp_f32_e32 v148, v168
	v_add_f32_e32 v167, 0x420c0000, v163
	v_fma_f32 v168, v165, |v167|, v239
	v_fmac_f32_e32 v168, 0x3fb8aa3b, v149
	v_med3_f32 v149, v167, v162, v164
	v_cndmask_b32_e32 v148, 0, v148, vcc
	v_cmp_eq_f32_e32 vcc, v149, v167
	v_exp_f32_e32 v149, v168
	v_add_f32_e32 v167, 0x42400000, v163
	v_fma_f32 v168, v165, |v167|, v239
	v_fmac_f32_e32 v168, 0x3fb8aa3b, v142
	v_med3_f32 v142, v167, v162, v164
	v_cndmask_b32_e32 v149, 0, v149, vcc
	v_cmp_eq_f32_e32 vcc, v142, v167
	v_exp_f32_e32 v142, v168
	v_add_f32_e32 v167, 0x42440000, v163
	v_fma_f32 v168, v165, |v167|, v239
	v_fmac_f32_e32 v168, 0x3fb8aa3b, v143
	v_med3_f32 v143, v167, v162, v164
	v_cndmask_b32_e32 v142, 0, v142, vcc
	v_cmp_eq_f32_e32 vcc, v143, v167
	v_exp_f32_e32 v143, v168
	v_add_f32_e32 v167, 0x42480000, v163
	v_fma_f32 v168, v165, |v167|, v239
	v_fmac_f32_e32 v168, 0x3fb8aa3b, v144
	v_med3_f32 v144, v167, v162, v164
	v_cndmask_b32_e32 v143, 0, v143, vcc
	v_cmp_eq_f32_e32 vcc, v144, v167
	v_exp_f32_e32 v144, v168
	v_add_f32_e32 v167, 0x424c0000, v163
	v_fma_f32 v168, v165, |v167|, v239
	v_fmac_f32_e32 v168, 0x3fb8aa3b, v145
	v_med3_f32 v145, v167, v162, v164
	v_cndmask_b32_e32 v144, 0, v144, vcc
	v_cmp_eq_f32_e32 vcc, v145, v167
	v_exp_f32_e32 v145, v168
	v_add_f32_e32 v167, 0x42800000, v163
	v_fma_f32 v168, v165, |v167|, v239
	v_fmac_f32_e32 v168, 0x3fb8aa3b, v138
	v_med3_f32 v138, v167, v162, v164
	v_cndmask_b32_e32 v145, 0, v145, vcc
	v_cmp_eq_f32_e32 vcc, v138, v167
	v_exp_f32_e32 v138, v168
	v_add_f32_e32 v167, 0x42820000, v163
	v_fma_f32 v168, v165, |v167|, v239
	v_fmac_f32_e32 v168, 0x3fb8aa3b, v139
	v_med3_f32 v139, v167, v162, v164
	v_cndmask_b32_e32 v138, 0, v138, vcc
	v_cmp_eq_f32_e32 vcc, v139, v167
	v_exp_f32_e32 v139, v168
	v_add_f32_e32 v167, 0x42840000, v163
	v_fma_f32 v168, v165, |v167|, v239
	v_fmac_f32_e32 v168, 0x3fb8aa3b, v140
	v_med3_f32 v140, v167, v162, v164
	v_cndmask_b32_e32 v139, 0, v139, vcc
	v_cmp_eq_f32_e32 vcc, v140, v167
	v_exp_f32_e32 v140, v168
	v_add_f32_e32 v167, 0x42860000, v163
	v_fma_f32 v168, v165, |v167|, v239
	v_fmac_f32_e32 v168, 0x3fb8aa3b, v141
	v_med3_f32 v141, v167, v162, v164
	v_cndmask_b32_e32 v140, 0, v140, vcc
	v_cmp_eq_f32_e32 vcc, v141, v167
	v_exp_f32_e32 v141, v168
	v_add_f32_e32 v166, 0, v154
	v_add_f32_e32 v167, 0x42a00000, v163
	v_add_f32_e32 v166, v155, v166
	v_fma_f32 v168, v165, |v167|, v239
; __device__ __forceinline__ unsigned pk2(float lo, float hi) { return pg8::cvt_pk_bf16(lo, hi); }
; __device__ __forceinline__ void attention_item(LAS unsigned char* lds, const bf16* ZH, bf16* OP, float* LP, bf16* MIX, const float* qg, const float* kg, int item, int tid0) {
;     ...
;           const int i = 16 * w + lr, rb = 16 * jt0 + 4 * lg - 64 - i, lo_i = -(i + B.qi0), hi_i = B.m - 1 - i - B.qi0;
;           const float rbf = (float)rb, LO = (float)(lo_i > -64 ? lo_i : -64), HI = (float)(hi_i < 64 ? hi_i : 64);
;           const float L2E = 1.4426950408889634f, sdl = sd * L2E, sml = smax * L2E;
; #pragma unroll
;           for (int t = 0; t < 10; ++t)
; #pragma unroll
;             for (int rr = 0; rr < 4; ++rr) { const float relf = rbf + (float)(16 * t + rr);
;                 const float x = __builtin_fmaf(sT[t][rr], L2E, __builtin_fmaf(-sdl, __builtin_fabsf(relf), -sml));
;                 const bool ok = __builtin_amdgcn_fmed3f(relf, LO, HI) == relf;
;                 const float p = ok ? __builtin_amdgcn_exp2f(x) : 0.f; sT[t][rr] = p; lsum += p; } }
;         bf16x8 pt[5];
; #pragma unroll
;         for (int k = 0; k < 5; ++k) { v4u o; o.x = pk2(sT[2 * k][0], sT[2 * k][1]); o.y = pk2(sT[2 * k][2], sT[2 * k][3]); o.z = pk2(sT[2 * k + 1][0], sT[2 * k + 1][1]); o.w = pk2(sT[2 * k + 1][2], sT[2 * k + 1][3]); pt[k] = __builtin_bit_cast(bf16x8, o); }
	v_add_f32_e32 v166, v156, v166
	v_fmac_f32_e32 v168, 0x3fb8aa3b, v134
	v_med3_f32 v134, v167, v162, v164
	v_add_f32_e32 v166, v157, v166
	v_cndmask_b32_e32 v141, 0, v141, vcc
	v_cmp_eq_f32_e32 vcc, v134, v167
	v_exp_f32_e32 v134, v168
	v_add_f32_e32 v166, v150, v166
	v_add_f32_e32 v167, 0x42a20000, v163
	v_add_f32_e32 v166, v151, v166
	v_fma_f32 v168, v165, |v167|, v239
	v_add_f32_e32 v166, v152, v166
	v_fmac_f32_e32 v168, 0x3fb8aa3b, v135
	v_med3_f32 v135, v167, v162, v164
	v_add_f32_e32 v166, v153, v166
	v_cndmask_b32_e32 v134, 0, v134, vcc
	v_cmp_eq_f32_e32 vcc, v135, v167
	v_exp_f32_e32 v135, v168
	v_add_f32_e32 v166, v146, v166
	v_add_f32_e32 v167, 0x42a40000, v163
	v_add_f32_e32 v166, v147, v166
	v_fma_f32 v168, v165, |v167|, v239
	v_add_f32_e32 v166, v148, v166
	v_fmac_f32_e32 v168, 0x3fb8aa3b, v136
	v_med3_f32 v136, v167, v162, v164
	v_add_f32_e32 v166, v149, v166
	v_cndmask_b32_e32 v135, 0, v135, vcc
	v_cmp_eq_f32_e32 vcc, v136, v167
	v_exp_f32_e32 v136, v168
	v_add_f32_e32 v166, v142, v166
	v_add_f32_e32 v167, 0x42a60000, v163
	v_add_f32_e32 v166, v143, v166
	v_fma_f32 v168, v165, |v167|, v239
	v_add_f32_e32 v166, v144, v166
	v_fmac_f32_e32 v168, 0x3fb8aa3b, v137
	v_med3_f32 v137, v167, v162, v164
	v_add_f32_e32 v166, v145, v166
	v_cndmask_b32_e32 v136, 0, v136, vcc
	v_cmp_eq_f32_e32 vcc, v137, v167
	v_exp_f32_e32 v137, v168
	v_add_f32_e32 v166, v138, v166
	v_add_f32_e32 v167, 0x42c00000, v163
	v_add_f32_e32 v166, v139, v166
	v_fma_f32 v168, v165, |v167|, v239
	v_add_f32_e32 v166, v140, v166
	v_fmac_f32_e32 v168, 0x3fb8aa3b, v130
	v_med3_f32 v130, v167, v162, v164
	v_add_f32_e32 v166, v141, v166
	v_cndmask_b32_e32 v137, 0, v137, vcc
	v_cmp_eq_f32_e32 vcc, v130, v167
	v_exp_f32_e32 v130, v168
	v_add_f32_e32 v166, v134, v166
	v_add_f32_e32 v166, v135, v166
	v_add_f32_e32 v166, v136, v166
	v_add_f32_e32 v166, v137, v166
	v_cndmask_b32_e32 v167, 0, v130, vcc
	v_add_f32_e32 v130, v167, v166
	v_add_f32_e32 v166, 0x42c20000, v163
	v_fma_f32 v168, v165, |v166|, v239
	v_fmac_f32_e32 v168, 0x3fb8aa3b, v131
	v_med3_f32 v131, v166, v162, v164
	v_cmp_eq_f32_e32 vcc, v131, v166
	v_exp_f32_e32 v131, v168
	v_cvt_pk_bf16_f32 v154, v154, v155
	v_cvt_pk_bf16_f32 v155, v156, v157
	v_cvt_pk_bf16_f32 v156, v150, v151
	v_cvt_pk_bf16_f32 v157, v152, v153
	s_xor_b64 s[6:7], s[6:7], -1
	v_cndmask_b32_e32 v166, 0, v131, vcc
	v_add_f32_e32 v131, 0x42c40000, v163
	v_fma_f32 v168, v165, |v131|, v239
	v_fmac_f32_e32 v168, 0x3fb8aa3b, v132
	v_med3_f32 v132, v131, v162, v164
	v_cmp_eq_f32_e32 vcc, v132, v131
	v_exp_f32_e32 v131, v168
	v_add_f32_e32 v130, v166, v130
	v_cndmask_b32_e32 v168, 0, v131, vcc
	v_add_f32_e32 v131, 0x42c60000, v163
	v_fma_f32 v132, v165, |v131|, v239
	v_fmac_f32_e32 v132, 0x3fb8aa3b, v133
	v_med3_f32 v133, v131, v162, v164
	v_cmp_eq_f32_e32 vcc, v133, v131
	v_exp_f32_e32 v131, v132
	v_add_f32_e32 v130, v168, v130
	v_cndmask_b32_e32 v169, 0, v131, vcc
	v_add_f32_e32 v131, 0x42e00000, v163
	v_fma_f32 v132, v165, |v131|, v239
	v_fmac_f32_e32 v132, 0x3fb8aa3b, v126
	v_med3_f32 v126, v131, v162, v164
	v_cmp_eq_f32_e32 vcc, v126, v131
	v_exp_f32_e32 v126, v132
	v_add_f32_e32 v130, v169, v130
	v_cndmask_b32_e32 v170, 0, v126, vcc
	v_add_f32_e32 v126, v170, v130
	v_add_f32_e32 v130, 0x42e20000, v163
	v_fma_f32 v131, v165, |v130|, v239
	v_fmac_f32_e32 v131, 0x3fb8aa3b, v127
	v_med3_f32 v127, v130, v162, v164
	v_cmp_eq_f32_e32 vcc, v127, v130
	v_exp_f32_e32 v127, v131
	s_nop 0
	v_cndmask_b32_e32 v171, 0, v127, vcc
	v_add_f32_e32 v127, 0x42e40000, v163
	v_fma_f32 v130, v165, |v127|, v239
	v_fmac_f32_e32 v130, 0x3fb8aa3b, v128
	v_med3_f32 v128, v127, v162, v164
	v_cmp_eq_f32_e32 vcc, v128, v127
	v_exp_f32_e32 v127, v130
	v_add_f32_e32 v126, v171, v126
	v_cvt_pk_bf16_f32 v130, v146, v147
	v_cvt_pk_bf16_f32 v131, v148, v149
	v_cndmask_b32_e32 v172, 0, v127, vcc
	v_add_f32_e32 v127, 0x42e60000, v163
	v_fma_f32 v128, v165, |v127|, v239
	v_fmac_f32_e32 v128, 0x3fb8aa3b, v129
	v_med3_f32 v129, v127, v162, v164
	v_cmp_eq_f32_e32 vcc, v129, v127
	v_exp_f32_e32 v127, v128
	v_add_f32_e32 v126, v172, v126
	v_cvt_pk_bf16_f32 v132, v142, v143
	v_cvt_pk_bf16_f32 v133, v144, v145
	v_cndmask_b32_e32 v173, 0, v127, vcc
	v_add_f32_e32 v127, 0x43000000, v163
	v_fma_f32 v128, v165, |v127|, v239
	v_fmac_f32_e32 v128, 0x3fb8aa3b, v122
	v_med3_f32 v122, v127, v162, v164
	v_cmp_eq_f32_e32 vcc, v122, v127
	v_exp_f32_e32 v122, v128
	v_add_f32_e32 v127, 0x43010000, v163
	v_fma_f32 v128, v165, |v127|, v239
	v_fmac_f32_e32 v128, 0x3fb8aa3b, v123
	v_med3_f32 v123, v127, v162, v164
	v_cndmask_b32_e32 v122, 0, v122, vcc
	v_cmp_eq_f32_e32 vcc, v123, v127
	v_exp_f32_e32 v123, v128
	v_add_f32_e32 v127, 0x43020000, v163
	v_fma_f32 v128, v165, |v127|, v239
	v_fmac_f32_e32 v128, 0x3fb8aa3b, v124
	v_med3_f32 v124, v127, v162, v164
	v_cndmask_b32_e32 v123, 0, v123, vcc
	v_cmp_eq_f32_e32 vcc, v124, v127
	v_exp_f32_e32 v124, v128
	v_add_f32_e32 v127, 0x43030000, v163
	v_fma_f32 v128, v165, |v127|, v239
	v_fmac_f32_e32 v128, 0x3fb8aa3b, v125
	v_med3_f32 v125, v127, v162, v164
	v_cndmask_b32_e32 v124, 0, v124, vcc
	v_cmp_eq_f32_e32 vcc, v125, v127
	v_exp_f32_e32 v125, v128
	v_add_f32_e32 v126, v173, v126
	v_add_f32_e32 v126, v122, v126
	v_add_f32_e32 v126, v123, v126
	v_add_f32_e32 v126, v124, v126
	v_cndmask_b32_e32 v125, 0, v125, vcc
	v_add_f32_e32 v174, v125, v126
	v_add_f32_e32 v126, 0x43100000, v163
	v_fma_f32 v127, v165, |v126|, v239
	v_fmac_f32_e32 v127, 0x3fb8aa3b, v118
	v_med3_f32 v118, v126, v162, v164
	v_cmp_eq_f32_e32 vcc, v118, v126
	v_exp_f32_e32 v118, v127
	s_nop 0
	v_cndmask_b32_e32 v175, 0, v118, vcc
	v_add_f32_e32 v118, 0x43110000, v163
	v_fma_f32 v126, v165, |v118|, v239
; #define LAS __attribute__((address_space(3)))
; __device__ __forceinline__ unsigned pk2(float lo, float hi) { return pg8::cvt_pk_bf16(lo, hi); }
; #define MFMA16(a, b, c) __builtin_amdgcn_mfma_f32_16x16x32_bf16((a), (b), (c), 0, 0, 0)
; __device__ __forceinline__ bf16x8 ds_tr2(LAS unsigned char* p, int rstride) { const s16x4 a = ds_tr(p), b = ds_tr(p + 16 * rstride); bf16x8 r; r[0] = a[0]; r[1] = a[1]; r[2] = a[2]; r[3] = a[3]; r[4] = b[0]; r[5] = b[1]; r[6] = b[2]; r[7] = b[3]; return r; }
; __device__ __forceinline__ void attention_item(LAS unsigned char* lds, const bf16* ZH, bf16* OP, float* LP, bf16* MIX, const float* qg, const float* kg, int item, int tid0) {
;     ...
;                 const float p = ok ? __builtin_amdgcn_exp2f(x) : 0.f; sT[t][rr] = p; lsum += p; } }
;         bf16x8 pt[5];
; #pragma unroll
;         for (int k = 0; k < 5; ++k) { v4u o; o.x = pk2(sT[2 * k][0], sT[2 * k][1]); o.y = pk2(sT[2 * k][2], sT[2 * k][3]); o.z = pk2(sT[2 * k + 1][0], sT[2 * k + 1][1]); o.w = pk2(sT[2 * k + 1][2], sT[2 * k + 1][3]); pt[k] = __builtin_bit_cast(bf16x8, o); }
;         f32x4 o[8];
;         { LAS unsigned char* trp = lds + A_V + (4 * lg + ((l & 15) >> 2)) * RSB + (l & 3) * 8;
; #pragma unroll
;           for (int e = 0; e < 8; ++e) o[e] = (f32x4){0.f, 0.f, 0.f, 0.f};
; #pragma unroll
;           for (int k = 0; k < 5; ++k) { const int rowb = (16 * jt0 + 32 * k + off) & 255;
; #pragma unroll
;             for (int e = 0; e < 8; ++e) { const bf16x8 vf = ds_tr2(trp + rowb * RSB + (16 * e) * 2, RSB); o[e] = MFMA16(vf, pt[k], o[e]);
;                 if (e == 3) __builtin_amdgcn_sched_barrier(0); }
;             __builtin_amdgcn_sched_barrier(0); } }
	v_fmac_f32_e32 v126, 0x3fb8aa3b, v119
	v_med3_f32 v119, v118, v162, v164
	v_cmp_eq_f32_e32 vcc, v119, v118
	v_exp_f32_e32 v118, v126
	v_cvt_pk_bf16_f32 v126, v138, v139
	v_cvt_pk_bf16_f32 v127, v140, v141
	v_cvt_pk_bf16_f32 v128, v134, v135
	v_add_f32_e32 v134, v175, v174
	v_cndmask_b32_e32 v176, 0, v118, vcc
	v_add_f32_e32 v118, 0x43120000, v163
	v_fma_f32 v119, v165, |v118|, v239
	v_fmac_f32_e32 v119, 0x3fb8aa3b, v120
	v_med3_f32 v120, v118, v162, v164
	v_cmp_eq_f32_e32 vcc, v120, v118
	v_exp_f32_e32 v118, v119
	v_add_f32_e32 v134, v176, v134
	v_lshlrev_b32_e32 v135, 3, v161
	v_and_b32_e32 v135, 24, v135
	v_cndmask_b32_e32 v177, 0, v118, vcc
	v_add_f32_e32 v118, 0x43130000, v163
	v_fma_f32 v119, v165, |v118|, v239
	v_fmac_f32_e32 v119, 0x3fb8aa3b, v121
	v_med3_f32 v120, v118, v162, v164
	v_add_f32_e32 v150, v177, v134
	v_lshrrev_b32_e32 v134, 2, v2
	v_cmp_eq_f32_e32 vcc, v120, v118
	v_exp_f32_e32 v118, v119
	v_or_b32_e32 v134, v160, v134
	v_mul_u32_u24_e32 v134, 0x120, v134
	v_add3_u32 v134, s92, v134, v135
	v_mad_u32_u24 v135, v158, s74, v134
	ds_read_b64_tr_b16 v[208:209], v135 offset:4608
	ds_read_b64_tr_b16 v[206:207], v135
	ds_read_b64_tr_b16 v[210:211], v135 offset:32
	ds_read_b64_tr_b16 v[212:213], v135 offset:4640
	ds_read_b64_tr_b16 v[214:215], v135 offset:64
	ds_read_b64_tr_b16 v[216:217], v135 offset:4672
	ds_read_b64_tr_b16 v[218:219], v135 offset:96
	ds_read_b64_tr_b16 v[220:221], v135 offset:4704
	ds_read_b64_tr_b16 v[222:223], v135 offset:128
	ds_read_b64_tr_b16 v[224:225], v135 offset:4736
	ds_read_b64_tr_b16 v[242:243], v135 offset:4768
	ds_read_b64_tr_b16 v[240:241], v135 offset:160
	ds_read_b64_tr_b16 v[244:245], v135 offset:192
	ds_read_b64_tr_b16 v[248:249], v135 offset:224
	ds_read_b64_tr_b16 v[246:247], v135 offset:4800
	ds_read_b64_tr_b16 v[250:251], v135 offset:4832
	v_cndmask_b32_e32 v162, 0, v118, vcc
	v_cvt_pk_bf16_f32 v129, v136, v137
	v_cvt_pk_bf16_f32 v118, v167, v166
	v_cvt_pk_bf16_f32 v119, v168, v169
	v_cvt_pk_bf16_f32 v120, v170, v171
	v_cvt_pk_bf16_f32 v121, v172, v173
	v_cvt_pk_bf16_f32 v122, v122, v123
	v_cvt_pk_bf16_f32 v123, v124, v125
	v_cvt_pk_bf16_f32 v124, v175, v176
	v_cvt_pk_bf16_f32 v125, v177, v162
	s_waitcnt lgkmcnt(14)
	v_mfma_f32_16x16x32_bf16 v[136:139], v[206:209], v[154:157], 0
	s_waitcnt lgkmcnt(12)
	v_mfma_f32_16x16x32_bf16 v[140:143], v[210:213], v[154:157], 0
	s_waitcnt lgkmcnt(10)
	v_mfma_f32_16x16x32_bf16 v[144:147], v[214:217], v[154:157], 0
	s_waitcnt lgkmcnt(8)
	v_mfma_f32_16x16x32_bf16 v[164:167], v[218:221], v[154:157], 0
	s_waitcnt lgkmcnt(4)
	v_mfma_f32_16x16x32_bf16 v[172:175], v[240:243], v[154:157], 0
	s_waitcnt lgkmcnt(1)
	v_mfma_f32_16x16x32_bf16 v[176:179], v[244:247], v[154:157], 0
	v_mfma_f32_16x16x32_bf16 v[168:171], v[222:225], v[154:157], 0
	s_waitcnt lgkmcnt(0)
	v_mfma_f32_16x16x32_bf16 v[152:155], v[248:251], v[154:157], 0
	v_add_u32_e32 v135, 32, v159
	v_and_b32_e32 v135, 0xe0, v135
	v_mad_u32_u24 v135, v135, s74, v134
	ds_read_b64_tr_b16 v[208:209], v135 offset:4608
	ds_read_b64_tr_b16 v[206:207], v135
	ds_read_b64_tr_b16 v[210:211], v135 offset:32
	ds_read_b64_tr_b16 v[212:213], v135 offset:4640
	ds_read_b64_tr_b16 v[214:215], v135 offset:64
	ds_read_b64_tr_b16 v[216:217], v135 offset:4672
	ds_read_b64_tr_b16 v[218:219], v135 offset:96
	ds_read_b64_tr_b16 v[220:221], v135 offset:4704
	ds_read_b64_tr_b16 v[242:243], v135 offset:4736
	ds_read_b64_tr_b16 v[240:241], v135 offset:128
	ds_read_b64_tr_b16 v[244:245], v135 offset:192
	ds_read_b64_tr_b16 v[246:247], v135 offset:4800
	ds_read_b64_tr_b16 v[222:223], v135 offset:224
	ds_read_b64_tr_b16 v[224:225], v135 offset:4832
	s_waitcnt lgkmcnt(12)
	v_mfma_f32_16x16x32_bf16 v[136:139], v[206:209], v[130:133], v[136:139]
	s_waitcnt lgkmcnt(8)
	v_mfma_f32_16x16x32_bf16 v[144:147], v[214:217], v[130:133], v[144:147]
	v_mfma_f32_16x16x32_bf16 v[140:143], v[210:213], v[130:133], v[140:143]
	s_waitcnt lgkmcnt(6)
	v_mfma_f32_16x16x32_bf16 v[164:167], v[218:221], v[130:133], v[164:167]
	ds_read_b64_tr_b16 v[184:185], v135 offset:160
	ds_read_b64_tr_b16 v[186:187], v135 offset:4768
	s_waitcnt lgkmcnt(6)
	v_mfma_f32_16x16x32_bf16 v[168:171], v[240:243], v[130:133], v[168:171]
	s_waitcnt lgkmcnt(4)
	v_mfma_f32_16x16x32_bf16 v[176:179], v[244:247], v[130:133], v[176:179]
	s_waitcnt lgkmcnt(0)
	v_mfma_f32_16x16x32_bf16 v[172:175], v[184:187], v[130:133], v[172:175]
	v_mfma_f32_16x16x32_bf16 v[130:133], v[222:225], v[130:133], v[152:155]
	v_add_u32_e32 v135, 64, v159
	v_and_b32_e32 v135, 0xe0, v135
	v_mad_u32_u24 v135, v135, s74, v134
	ds_read_b64_tr_b16 v[250:251], v135 offset:4608
	ds_read_b64_tr_b16 v[248:249], v135
	ds_read_b64_tr_b16 v[206:207], v135 offset:32
	ds_read_b64_tr_b16 v[208:209], v135 offset:4640
	ds_read_b64_tr_b16 v[214:215], v135 offset:64
	ds_read_b64_tr_b16 v[216:217], v135 offset:4672
	ds_read_b64_tr_b16 v[210:211], v135 offset:96
	ds_read_b64_tr_b16 v[212:213], v135 offset:4704
	ds_read_b64_tr_b16 v[220:221], v135 offset:4736
	ds_read_b64_tr_b16 v[218:219], v135 offset:128
	ds_read_b64_tr_b16 v[240:241], v135 offset:160
	ds_read_b64_tr_b16 v[242:243], v135 offset:4768
	ds_read_b64_tr_b16 v[244:245], v135 offset:192
	ds_read_b64_tr_b16 v[246:247], v135 offset:4800
	s_waitcnt lgkmcnt(12)
	v_mfma_f32_16x16x32_bf16 v[136:139], v[248:251], v[126:129], v[136:139]
	ds_read_b64_tr_b16 v[222:223], v135 offset:224
	ds_read_b64_tr_b16 v[224:225], v135 offset:4832
	s_waitcnt lgkmcnt(10)
	v_mfma_f32_16x16x32_bf16 v[144:147], v[214:217], v[126:129], v[144:147]
	v_mfma_f32_16x16x32_bf16 v[140:143], v[206:209], v[126:129], v[140:143]
	s_waitcnt lgkmcnt(8)
	v_mfma_f32_16x16x32_bf16 v[152:155], v[210:213], v[126:129], v[164:167]
	s_nop 2
	s_waitcnt lgkmcnt(6)
; #define GAS __attribute__((address_space(1)))
; #define LAS __attribute__((address_space(3)))
; __device__ __forceinline__ unsigned pk2(float lo, float hi) { return pg8::cvt_pk_bf16(lo, hi); }
; #define MFMA16(a, b, c) __builtin_amdgcn_mfma_f32_16x16x32_bf16((a), (b), (c), 0, 0, 0)
; __device__ __forceinline__ bf16x8 ds_tr2(LAS unsigned char* p, int rstride) { const s16x4 a = ds_tr(p), b = ds_tr(p + 16 * rstride); bf16x8 r; r[0] = a[0]; r[1] = a[1]; r[2] = a[2]; r[3] = a[3]; r[4] = b[0]; r[5] = b[1]; r[6] = b[2]; r[7] = b[3]; return r; }
; __device__ __forceinline__ void attention_item(LAS unsigned char* lds, const bf16* ZH, bf16* OP, float* LP, bf16* MIX, const float* qg, const float* kg, int item, int tid0) {
;     ...
;         { LAS unsigned char* trp = lds + A_V + (4 * lg + ((l & 15) >> 2)) * RSB + (l & 3) * 8;
; #pragma unroll
;           for (int e = 0; e < 8; ++e) o[e] = (f32x4){0.f, 0.f, 0.f, 0.f};
; #pragma unroll
;           for (int k = 0; k < 5; ++k) { const int rowb = (16 * jt0 + 32 * k + off) & 255;
; #pragma unroll
;             for (int e = 0; e < 8; ++e) { const bf16x8 vf = ds_tr2(trp + rowb * RSB + (16 * e) * 2, RSB); o[e] = MFMA16(vf, pt[k], o[e]);
;                 if (e == 3) __builtin_amdgcn_sched_barrier(0); }
;             __builtin_amdgcn_sched_barrier(0); } }
;         lsum += __shfl_xor(lsum, 16); lsum += __shfl_xor(lsum, 32);
;         const int row = rowbase + B.r + B.d * (B.qi0 + 16 * w + lr);
;         if (B.dsh != 0) {
;             const int pb = B.dsh == 4 ? 0 : 1;
;             bf16* op = OP + ((size_t)pb * M + row) * 2048 + h * HD + 4 * lg;
; #pragma unroll
;             for (int e = 0; e < 8; ++e) { v2u ov; ov.x = pk2(o[e][0], o[e][1]); ov.y = pk2(o[e][2], o[e][3]); *(GAS v2u*)(op + 16 * e) = ov; }
;             if (lg == 0) LP[((size_t)pb * NH + h) * M + row] = lsum;
	v_mfma_f32_16x16x32_bf16 v[164:167], v[218:221], v[126:129], v[168:171]
	s_waitcnt lgkmcnt(4)
	v_mfma_f32_16x16x32_bf16 v[168:171], v[240:243], v[126:129], v[172:175]
	s_nop 2
	s_waitcnt lgkmcnt(2)
	v_mfma_f32_16x16x32_bf16 v[172:175], v[244:247], v[126:129], v[176:179]
	s_nop 2
	s_waitcnt lgkmcnt(0)
	v_mfma_f32_16x16x32_bf16 v[126:129], v[222:225], v[126:129], v[130:133]
	s_nop 2
	v_add_u32_e32 v130, 0x60, v159
	v_and_b32_e32 v130, 0xe0, v130
	v_mad_u32_u24 v135, v130, s74, v134
	ds_read_b64_tr_b16 v[250:251], v135 offset:4608
	ds_read_b64_tr_b16 v[248:249], v135
	ds_read_b64_tr_b16 v[214:215], v135 offset:32
	ds_read_b64_tr_b16 v[216:217], v135 offset:4640
	ds_read_b64_tr_b16 v[206:207], v135 offset:64
	ds_read_b64_tr_b16 v[208:209], v135 offset:4672
	ds_read_b64_tr_b16 v[210:211], v135 offset:96
	ds_read_b64_tr_b16 v[212:213], v135 offset:4704
	ds_read_b64_tr_b16 v[220:221], v135 offset:4736
	ds_read_b64_tr_b16 v[218:219], v135 offset:128
	ds_read_b64_tr_b16 v[240:241], v135 offset:160
	ds_read_b64_tr_b16 v[242:243], v135 offset:4768
	ds_read_b64_tr_b16 v[244:245], v135 offset:192
	ds_read_b64_tr_b16 v[246:247], v135 offset:4800
	s_waitcnt lgkmcnt(12)
	v_mfma_f32_16x16x32_bf16 v[130:133], v[248:251], v[118:121], v[136:139]
	ds_read_b64_tr_b16 v[222:223], v135 offset:224
	ds_read_b64_tr_b16 v[224:225], v135 offset:4832
	s_waitcnt lgkmcnt(12)
	v_mfma_f32_16x16x32_bf16 v[136:139], v[214:217], v[118:121], v[140:143]
	s_nop 2
	s_waitcnt lgkmcnt(10)
	v_mfma_f32_16x16x32_bf16 v[176:179], v[206:209], v[118:121], v[144:147]
	s_waitcnt lgkmcnt(8)
	v_mfma_f32_16x16x32_bf16 v[152:155], v[210:213], v[118:121], v[152:155]
	s_waitcnt lgkmcnt(6)
	v_mfma_f32_16x16x32_bf16 v[164:167], v[218:221], v[118:121], v[164:167]
	s_waitcnt lgkmcnt(2)
	v_mfma_f32_16x16x32_bf16 v[172:175], v[244:247], v[118:121], v[172:175]
	v_mfma_f32_16x16x32_bf16 v[168:171], v[240:243], v[118:121], v[168:171]
	s_waitcnt lgkmcnt(0)
	v_mfma_f32_16x16x32_bf16 v[180:183], v[222:225], v[118:121], v[126:129]
	v_xor_b32_e32 v118, 0x80, v158
	v_mad_u32_u24 v151, v118, s74, v134
	ds_read_b64_tr_b16 v[250:251], v151 offset:4608
	ds_read_b64_tr_b16 v[248:249], v151
	ds_read_b64_tr_b16 v[214:215], v151 offset:32
	ds_read_b64_tr_b16 v[216:217], v151 offset:4640
	ds_read_b64_tr_b16 v[206:207], v151 offset:64
	ds_read_b64_tr_b16 v[208:209], v151 offset:4672
	ds_read_b64_tr_b16 v[210:211], v151 offset:96
	ds_read_b64_tr_b16 v[212:213], v151 offset:4704
	ds_read_b64_tr_b16 v[220:221], v151 offset:4736
	ds_read_b64_tr_b16 v[218:219], v151 offset:128
	ds_read_b64_tr_b16 v[244:245], v151 offset:160
	ds_read_b64_tr_b16 v[246:247], v151 offset:4768
	ds_read_b64_tr_b16 v[240:241], v151 offset:192
	ds_read_b64_tr_b16 v[242:243], v151 offset:4800
	s_waitcnt lgkmcnt(12)
	v_mfma_f32_16x16x32_bf16 v[146:149], v[248:251], v[122:125], v[130:133]
	s_waitcnt lgkmcnt(10)
	v_mfma_f32_16x16x32_bf16 v[142:145], v[214:217], v[122:125], v[136:139]
	s_waitcnt lgkmcnt(8)
	v_mfma_f32_16x16x32_bf16 v[134:137], v[206:209], v[122:125], v[176:179]
	s_waitcnt lgkmcnt(6)
	v_mfma_f32_16x16x32_bf16 v[138:141], v[210:213], v[122:125], v[152:155]
	s_waitcnt lgkmcnt(4)
	v_mfma_f32_16x16x32_bf16 v[130:133], v[218:221], v[122:125], v[164:167]
	ds_read_b64_tr_b16 v[152:153], v151 offset:224
	ds_read_b64_tr_b16 v[154:155], v151 offset:4832
	s_waitcnt lgkmcnt(4)
	v_mfma_f32_16x16x32_bf16 v[126:129], v[244:247], v[122:125], v[168:171]
	s_waitcnt lgkmcnt(2)
	v_mfma_f32_16x16x32_bf16 v[118:121], v[240:243], v[122:125], v[172:175]
	s_waitcnt lgkmcnt(0)
	v_mfma_f32_16x16x32_bf16 v[122:125], v[152:155], v[122:125], v[180:183]
	v_add_f32_e32 v150, v162, v150
	ds_bpermute_b32 v151, v205, v150
	v_or_b32_e32 v2, s34, v2
	v_add_lshl_u32 v2, v2, v5, s42
	s_add_i32 s28, s28, s20
	v_add_u32_e32 v172, s28, v2
	s_waitcnt lgkmcnt(0)
	v_add_f32_e32 v150, v150, v151
	ds_bpermute_b32 v151, v226, v150
	s_mov_b64 s[34:35], -1
	s_andn2_b64 vcc, exec, s[6:7]
	v_ashrrev_i32_e32 v173, 31, v172
	v_lshlrev_b32_e32 v2, 1, v160
	s_waitcnt lgkmcnt(0)
	v_add_f32_e32 v178, v150, v151
	s_cbranch_vccnz .LBB0_442
	s_and_b64 s[6:7], exec, s[40:41]
	s_cselect_b32 s28, 0, 0x4000
	v_lshl_add_u64 v[150:151], s[28:29], 0, v[172:173]
	v_lshlrev_b64 v[150:151], 12, v[150:151]
	v_lshl_add_u64 v[150:151], s[72:73], 0, v[150:151]
	v_lshl_add_u64 v[150:151], v[150:151], 0, v[2:3]
	v_cvt_pk_bf16_f32 v152, v146, v147
	v_cvt_pk_bf16_f32 v153, v148, v149
	global_store_dwordx2 v[150:151], v[152:153], off
	v_cvt_pk_bf16_f32 v152, v142, v143
	v_cvt_pk_bf16_f32 v153, v144, v145
	global_store_dwordx2 v[150:151], v[152:153], off offset:32
	v_cvt_pk_bf16_f32 v152, v134, v135
	v_cvt_pk_bf16_f32 v153, v136, v137
	global_store_dwordx2 v[150:151], v[152:153], off offset:64
	v_cvt_pk_bf16_f32 v152, v138, v139
	v_cvt_pk_bf16_f32 v153, v140, v141
	global_store_dwordx2 v[150:151], v[152:153], off offset:96
	v_cvt_pk_bf16_f32 v152, v130, v131
	v_cvt_pk_bf16_f32 v153, v132, v133
	global_store_dwordx2 v[150:151], v[152:153], off offset:128
	v_cvt_pk_bf16_f32 v152, v126, v127
	v_cvt_pk_bf16_f32 v153, v128, v129
	global_store_dwordx2 v[150:151], v[152:153], off offset:160
	v_cvt_pk_bf16_f32 v152, v118, v119
	v_cvt_pk_bf16_f32 v153, v120, v121
	v_cmp_eq_u32_e32 vcc, 0, v4
	global_store_dwordx2 v[150:151], v[152:153], off offset:192
	v_cvt_pk_bf16_f32 v152, v122, v123
	v_cvt_pk_bf16_f32 v153, v124, v125
	global_store_dwordx2 v[150:151], v[152:153], off offset:224
	s_and_saveexec_b64 s[6:7], vcc
	s_cbranch_execz .LBB0_441
	s_and_b64 s[34:35], exec, s[40:41]
	s_cselect_b32 s28, 0, 16
	s_or_b32 s28, s28, s46
	s_lshl_b32 s28, s28, 16
	s_add_u32 s34, s21, s28
	s_addc_u32 s35, s65, 0
	v_lshl_add_u64 v[4:5], v[172:173], 2, s[34:35]
	global_store_dword v[4:5], v178, off

; #define GAS __attribute__((address_space(1)))
; #define LAS __attribute__((address_space(3)))
; __device__ __forceinline__ unsigned pk2(float lo, float hi) { return pg8::cvt_pk_bf16(lo, hi); }
; #define MFMA16(a, b, c) __builtin_amdgcn_mfma_f32_16x16x32_bf16((a), (b), (c), 0, 0, 0)
; template <int DIR, bool INTRA, bool FINAL> __device__ __forceinline__ void retention_pass(LAS unsigned char* lds, const bf16* ZH, bf16* YF, bf16* MIX, const float* ld, const float* gn, int seq, int h, int n0, int ncnt, ...
;     ...
;             for (int e = 0; e < 8; ++e) {
; #pragma unroll
;                 for (int ks = 0; ks < 4; ++ks) { const bf16x8 sf = *(const LAS bf16x8*)(lds + R_ST + (16 * e + lr) * RS + (8 * lg + 32 * ks) * 2); y[e] = MFMA16(sf, qx[ks], y[e]); }
;                 __builtin_amdgcn_sched_barrier(0); }
;             const int row = r0 + 16 * w + lr;
;             bf16* yp = YF + (size_t)row * 2048 + h * HD + 4 * lg;
;             if constexpr (!FINAL) {
; #pragma unroll
;                 for (int e = 0; e < 8; ++e) { v2u o; o.x = pk2(y[e][0], y[e][1]); o.y = pk2(y[e][2], y[e][3]); *(GAS v2u*)(yp + 16 * e) = o; }
.LBB0_448:
	s_waitcnt lgkmcnt(0)
	v_add3_u32 v2, s95, v216, v214
	ds_read_b128 v[218:221], v2
	ds_read_b128 v[222:225], v2 offset:64
	ds_read_b128 v[226:229], v2 offset:128
	ds_read_b128 v[240:243], v2 offset:192
	ds_read_b128 v[244:247], v2 offset:4352
	ds_read_b128 v[248:251], v2 offset:4416
	s_waitcnt lgkmcnt(5)
	v_mfma_f32_16x16x32_bf16 v[36:39], v[218:221], v[84:87], v[120:123]
	ds_read_b128 v[218:221], v2 offset:4480
	s_waitcnt lgkmcnt(5)
	v_mfma_f32_16x16x32_bf16 v[36:39], v[222:225], v[88:91], v[36:39]
	ds_read_b128 v[222:225], v2 offset:4544
	s_waitcnt lgkmcnt(5)
	v_mfma_f32_16x16x32_bf16 v[36:39], v[226:229], v[92:95], v[36:39]
	ds_read_b128 v[226:229], v2 offset:8704
	s_waitcnt lgkmcnt(5)
	v_mfma_f32_16x16x32_bf16 v[36:39], v[240:243], v[96:99], v[36:39]
	ds_read_b128 v[240:243], v2 offset:8768
	s_waitcnt lgkmcnt(5)
	v_mfma_f32_16x16x32_bf16 v[40:43], v[244:247], v[84:87], v[136:139]
	ds_read_b128 v[244:247], v2 offset:8832
	s_waitcnt lgkmcnt(5)
	v_mfma_f32_16x16x32_bf16 v[40:43], v[248:251], v[88:91], v[40:43]
	ds_read_b128 v[248:251], v2 offset:8896
	s_waitcnt lgkmcnt(5)
	v_mfma_f32_16x16x32_bf16 v[40:43], v[218:221], v[92:95], v[40:43]
	ds_read_b128 v[218:221], v2 offset:13056
	s_waitcnt lgkmcnt(5)
	v_mfma_f32_16x16x32_bf16 v[40:43], v[222:225], v[96:99], v[40:43]
	ds_read_b128 v[222:225], v2 offset:13120
	s_waitcnt lgkmcnt(5)
	v_mfma_f32_16x16x32_bf16 v[44:47], v[226:229], v[84:87], v[140:143]
	ds_read_b128 v[226:229], v2 offset:13184
	s_waitcnt lgkmcnt(5)
	v_mfma_f32_16x16x32_bf16 v[44:47], v[240:243], v[88:91], v[44:47]
	ds_read_b128 v[240:243], v2 offset:13248
	s_waitcnt lgkmcnt(5)
	v_mfma_f32_16x16x32_bf16 v[44:47], v[244:247], v[92:95], v[44:47]
	ds_read_b128 v[244:247], v2 offset:17408
	s_waitcnt lgkmcnt(5)
	v_mfma_f32_16x16x32_bf16 v[44:47], v[248:251], v[96:99], v[44:47]
	ds_read_b128 v[248:251], v2 offset:17472
	s_waitcnt lgkmcnt(5)
	v_mfma_f32_16x16x32_bf16 v[48:51], v[218:221], v[84:87], v[144:147]
	ds_read_b128 v[218:221], v2 offset:17536
	s_waitcnt lgkmcnt(5)
	v_mfma_f32_16x16x32_bf16 v[48:51], v[222:225], v[88:91], v[48:51]
	ds_read_b128 v[222:225], v2 offset:17600
	s_waitcnt lgkmcnt(5)
	v_mfma_f32_16x16x32_bf16 v[48:51], v[226:229], v[92:95], v[48:51]
	ds_read_b128 v[226:229], v2 offset:21760
	s_waitcnt lgkmcnt(5)
	v_mfma_f32_16x16x32_bf16 v[48:51], v[240:243], v[96:99], v[48:51]
	ds_read_b128 v[240:243], v2 offset:21824
	s_waitcnt lgkmcnt(5)
	v_mfma_f32_16x16x32_bf16 v[52:55], v[244:247], v[84:87], v[148:151]
	ds_read_b128 v[244:247], v2 offset:21888
	s_waitcnt lgkmcnt(5)
	v_mfma_f32_16x16x32_bf16 v[52:55], v[248:251], v[88:91], v[52:55]
	ds_read_b128 v[248:251], v2 offset:21952
	s_waitcnt lgkmcnt(5)
	v_mfma_f32_16x16x32_bf16 v[52:55], v[218:221], v[92:95], v[52:55]
	ds_read_b128 v[218:221], v2 offset:26112
	s_waitcnt lgkmcnt(5)
	v_mfma_f32_16x16x32_bf16 v[52:55], v[222:225], v[96:99], v[52:55]
	ds_read_b128 v[222:225], v2 offset:26176
	s_waitcnt lgkmcnt(5)
	v_mfma_f32_16x16x32_bf16 v[56:59], v[226:229], v[84:87], v[152:155]
	ds_read_b128 v[226:229], v2 offset:26240
	s_waitcnt lgkmcnt(5)
	v_mfma_f32_16x16x32_bf16 v[56:59], v[240:243], v[88:91], v[56:59]
	ds_read_b128 v[240:243], v2 offset:26304
	s_waitcnt lgkmcnt(5)
	v_mfma_f32_16x16x32_bf16 v[56:59], v[244:247], v[92:95], v[56:59]
	ds_read_b128 v[244:247], v2 offset:30464
	s_waitcnt lgkmcnt(5)
	v_mfma_f32_16x16x32_bf16 v[56:59], v[248:251], v[96:99], v[56:59]
	ds_read_b128 v[248:251], v2 offset:30528
	s_waitcnt lgkmcnt(5)
	v_mfma_f32_16x16x32_bf16 v[60:63], v[218:221], v[84:87], v[156:159]
	ds_read_b128 v[218:221], v2 offset:30592
	s_waitcnt lgkmcnt(5)
	v_mfma_f32_16x16x32_bf16 v[60:63], v[222:225], v[88:91], v[60:63]
	ds_read_b128 v[222:225], v2 offset:30656
	s_waitcnt lgkmcnt(5)
	v_mfma_f32_16x16x32_bf16 v[60:63], v[226:229], v[92:95], v[60:63]
	s_waitcnt lgkmcnt(4)
	v_mfma_f32_16x16x32_bf16 v[60:63], v[240:243], v[96:99], v[60:63]
	s_waitcnt lgkmcnt(3)
	v_mfma_f32_16x16x32_bf16 v[64:67], v[244:247], v[84:87], v[176:179]
	s_waitcnt lgkmcnt(2)
	v_mfma_f32_16x16x32_bf16 v[64:67], v[248:251], v[88:91], v[64:67]
	s_waitcnt lgkmcnt(1)
	v_mfma_f32_16x16x32_bf16 v[64:67], v[218:221], v[92:95], v[64:67]
	s_waitcnt lgkmcnt(0)
	v_mfma_f32_16x16x32_bf16 v[64:67], v[222:225], v[96:99], v[64:67]
	s_add_i32 s6, s54, s60
	v_add_u32_e32 v2, s6, v207
	v_add_u32_e32 v68, 0xffffff20, v2
	v_ashrrev_i32_e32 v69, 31, v68
	v_lshlrev_b64 v[68:69], 12, v[68:69]
	v_lshl_add_u64 v[68:69], s[36:37], 0, v[68:69]
	v_lshlrev_b32_e32 v2, 1, v181
	v_lshl_add_u64 v[68:69], v[68:69], 0, v[2:3]
	v_cvt_pk_bf16_f32 v36, v36, v37
	v_cvt_pk_bf16_f32 v37, v38, v39
	global_store_dwordx2 v[68:69], v[36:37], off
	v_cvt_pk_bf16_f32 v36, v40, v41
	v_cvt_pk_bf16_f32 v37, v42, v43
	global_store_dwordx2 v[68:69], v[36:37], off offset:32
	v_cvt_pk_bf16_f32 v36, v44, v45
	v_cvt_pk_bf16_f32 v37, v46, v47
	global_store_dwordx2 v[68:69], v[36:37], off offset:64
	v_cvt_pk_bf16_f32 v36, v48, v49
	v_cvt_pk_bf16_f32 v37, v50, v51
	global_store_dwordx2 v[68:69], v[36:37], off offset:96
	v_cvt_pk_bf16_f32 v36, v52, v53
	v_cvt_pk_bf16_f32 v37, v54, v55
	global_store_dwordx2 v[68:69], v[36:37], off offset:128
	v_cvt_pk_bf16_f32 v36, v56, v57
	v_cvt_pk_bf16_f32 v37, v58, v59
	global_store_dwordx2 v[68:69], v[36:37], off offset:160
	v_cvt_pk_bf16_f32 v36, v60, v61
	v_cvt_pk_bf16_f32 v37, v62, v63
	global_store_dwordx2 v[68:69], v[36:37], off offset:192
	v_cvt_pk_bf16_f32 v36, v64, v65
	v_cvt_pk_bf16_f32 v37, v66, v67
	global_store_dwordx2 v[68:69], v[36:37], off offset:224
	s_addk_i32 s60, 0x80
	s_waitcnt vmcnt(11)
	v_mov_b64_e32 v[60:61], v[160:161]
	s_waitcnt vmcnt(10)
	v_mov_b64_e32 v[64:65], v[164:165]
	s_waitcnt vmcnt(9)
	v_mov_b64_e32 v[68:69], v[168:169]
	s_waitcnt vmcnt(8)
	v_mov_b64_e32 v[72:73], v[172:173]
	v_mov_b64_e32 v[40:41], v[104:105]
	v_mov_b64_e32 v[48:49], v[112:113]
	v_mov_b64_e32 v[56:57], v[124:125]
	v_mov_b64_e32 v[76:77], v[132:133]
	v_mov_b64_e32 v[36:37], v[100:101]
	v_mov_b64_e32 v[44:45], v[108:109]
	v_mov_b64_e32 v[52:53], v[116:117]
	v_mov_b64_e32 v[80:81], v[128:129]
	s_cmpk_lg_i32 s60, 0x8e0
	v_mov_b64_e32 v[62:63], v[162:163]
	v_mov_b64_e32 v[66:67], v[166:167]
	v_mov_b64_e32 v[70:71], v[170:171]
	v_mov_b64_e32 v[74:75], v[174:175]
	v_mov_b64_e32 v[42:43], v[106:107]
	v_mov_b64_e32 v[50:51], v[114:115]
	v_mov_b64_e32 v[58:59], v[126:127]
	v_mov_b64_e32 v[78:79], v[134:135]
	v_mov_b64_e32 v[38:39], v[102:103]
	v_mov_b64_e32 v[46:47], v[110:111]
	v_mov_b64_e32 v[54:55], v[118:119]
	v_mov_b64_e32 v[82:83], v[130:131]
	s_cbranch_scc0 .LBB0_709
; #define LAS __attribute__((address_space(3)))
; #define WG_BARRIER() do { asm volatile("s_waitcnt lgkmcnt(0)" ::: "memory"); __builtin_amdgcn_s_barrier(); asm volatile("" ::: "memory"); } while (0)
; __device__ __forceinline__ unsigned pk2(float lo, float hi) { return pg8::cvt_pk_bf16(lo, hi); }
; __device__ __forceinline__ v4u scale8(v4u x, float sc) { v4u o; o.x = pk2(bf_lo(x.x) * sc, bf_hi(x.x) * sc); o.y = pk2(bf_lo(x.y) * sc, bf_hi(x.y) * sc); o.z = pk2(bf_lo(x.z) * sc, bf_hi(x.z) * sc); o.w = pk2(bf_lo(x.w) * sc, bf_hi(x.w) * sc); return o; }
; template <int DIR, bool INTRA, bool FINAL> __device__ __forceinline__ void retention_pass(LAS unsigned char* lds, const bf16* ZH, bf16* YF, bf16* MIX, const float* ld, const float* gn, int seq, int h, int n0, int ncnt, ...
;     ...
;             WG_BARRIER();
; #pragma unroll
;             for (int cc = 0; cc < 4; ++cc) { const int row = srow + 32 * cc;
;                 if constexpr (INTRA) *(LAS v4u*)(lds + R_K + row * RS + 16 * sch) = kreg[cc];
;                 const float wj = DIR == 0 ? __expf(lf * (float)(127 - row)) : __expf(lb * (float)row);
;                 *(LAS v4u*)(lds + R_KW + row * RSB + 16 * sch) = scale8(kreg[cc], wj);
;                 *(LAS v4u*)(lds + R_V + row * RSB + 16 * sch) = vreg[cc]; }
; #pragma unroll
;             for (int e = 0; e < 8; ++e) { v2u o; o.x = pk2(st[e][0], st[e][1]); o.y = pk2(st[e][2], st[e][3]); *(LAS v2u*)(lds + R_ST + (16 * e + lr) * RS + (16 * w + 4 * lg) * 2) = o; }
;             WG_BARRIER();
.LBB0_449:
	v_mov_b32_e32 v138, v191
	v_mov_b32_e32 v132, v190
	s_waitcnt vmcnt(12)
	v_mov_b32_e32 v136, v212
	s_waitcnt vmcnt(11)
	v_and_b32_e32 v87, 0xffff0000, v36
	v_ashrrev_i32_e32 v213, 4, v132
	v_sub_u32_e32 v86, 0x7f, v213
	v_cvt_f32_i32_e32 v86, v86
	v_and_b32_e32 v183, 15, v132
	v_lshlrev_b32_e32 v2, 4, v183
	v_add_u32_e32 v84, 0, v2
	v_mul_f32_e32 v86, v138, v86
	v_mul_f32_e32 v86, 0x3fb8aa3b, v86
	v_exp_f32_e32 v89, v86
	v_add_u32_e32 v85, s93, v2
	v_lshlrev_b32_e32 v86, 16, v36
	v_mad_u64_u32 v[90:91], s[6:7], v213, s33, v[84:85]
	v_mul_f32_e32 v86, v89, v86
	v_mul_f32_e32 v87, v89, v87
	s_waitcnt lgkmcnt(0)
	s_barrier
	ds_write_b128 v90, v[36:39]
	v_cvt_pk_bf16_f32 v86, v86, v87
	v_lshlrev_b32_e32 v87, 16, v37
	v_and_b32_e32 v88, 0xffff0000, v37
	v_mul_f32_e32 v87, v89, v87
	v_mul_f32_e32 v88, v89, v88
	v_cvt_pk_bf16_f32 v87, v87, v88
	v_lshlrev_b32_e32 v88, 16, v38
	v_and_b32_e32 v91, 0xffff0000, v38
	v_mul_f32_e32 v88, v89, v88
	v_mul_f32_e32 v91, v89, v91
	v_cvt_pk_bf16_f32 v88, v88, v91
	v_lshlrev_b32_e32 v91, 16, v39
	v_and_b32_e32 v92, 0xffff0000, v39
	v_mul_f32_e32 v91, v89, v91
	v_mul_f32_e32 v89, v89, v92
	v_cvt_pk_bf16_f32 v89, v91, v89
	v_mul_lo_u32 v91, v213, s74
	v_add_u32_e32 v92, v84, v91
	ds_write_b128 v92, v[86:89] offset:34816
	v_add_u32_e32 v86, v85, v91
	s_waitcnt vmcnt(10)
	ds_write_b128 v86, v[40:43]
	s_waitcnt vmcnt(9)
	ds_write_b128 v90, v[44:47] offset:8704
	v_sub_u32_e32 v86, 0x5f, v213
	v_cvt_f32_i32_e32 v86, v86
	v_and_b32_e32 v87, 0xffff0000, v44
	v_and_b32_e32 v88, 0xffff0000, v45
	v_and_b32_e32 v92, 0xffff0000, v46
	v_mul_f32_e32 v86, v138, v86
	v_mul_f32_e32 v86, 0x3fb8aa3b, v86
	v_exp_f32_e32 v89, v86
	v_lshlrev_b32_e32 v86, 16, v44
	v_and_b32_e32 v93, 0xffff0000, v47
	v_ashrrev_i32_e32 v134, 6, v132
	v_mul_f32_e32 v86, v89, v86
	v_mul_f32_e32 v87, v89, v87
	v_cvt_pk_bf16_f32 v86, v86, v87
	v_lshlrev_b32_e32 v87, 16, v45
	v_mul_f32_e32 v87, v89, v87
	v_mul_f32_e32 v88, v89, v88
	v_cvt_pk_bf16_f32 v87, v87, v88
	v_lshlrev_b32_e32 v88, 16, v46
	v_mul_f32_e32 v88, v89, v88
	v_mul_f32_e32 v92, v89, v92
	v_cvt_pk_bf16_f32 v88, v88, v92
	v_lshlrev_b32_e32 v92, 16, v47
	v_mul_f32_e32 v92, v89, v92
	v_mul_f32_e32 v89, v89, v93
	v_cvt_pk_bf16_f32 v89, v92, v89
	v_add_u32_e32 v92, 0x2400, v91
	v_add_u32_e32 v93, v84, v92
	ds_write_b128 v93, v[86:89] offset:34816
	v_add_u32_e32 v86, v85, v92
	s_waitcnt vmcnt(8)
	ds_write_b128 v86, v[48:51]
	s_waitcnt vmcnt(7)
	ds_write_b128 v90, v[52:55] offset:17408
	v_sub_u32_e32 v86, 63, v213
	v_cvt_f32_i32_e32 v86, v86
	v_and_b32_e32 v87, 0xffff0000, v52
	v_and_b32_e32 v88, 0xffff0000, v53
	v_and_b32_e32 v92, 0xffff0000, v54
	v_mul_f32_e32 v86, v138, v86
	v_mul_f32_e32 v86, 0x3fb8aa3b, v86
	v_exp_f32_e32 v89, v86
	v_lshlrev_b32_e32 v86, 16, v52
	v_and_b32_e32 v93, 0xffff0000, v55
	v_bfe_u32 v100, v132, 4, 2
	v_mul_f32_e32 v86, v89, v86
	v_mul_f32_e32 v87, v89, v87
	v_cvt_pk_bf16_f32 v86, v86, v87
	v_lshlrev_b32_e32 v87, 16, v53
	v_mul_f32_e32 v87, v89, v87
	v_mul_f32_e32 v88, v89, v88
	v_cvt_pk_bf16_f32 v87, v87, v88
	v_lshlrev_b32_e32 v88, 16, v54
	v_mul_f32_e32 v88, v89, v88
	v_mul_f32_e32 v92, v89, v92
	v_cvt_pk_bf16_f32 v88, v88, v92
	v_lshlrev_b32_e32 v92, 16, v55
	v_mul_f32_e32 v92, v89, v92
	v_mul_f32_e32 v89, v89, v93
	v_cvt_pk_bf16_f32 v89, v92, v89
	v_add_u32_e32 v92, 0x4800, v91
	v_add_u32_e32 v93, v84, v92
	ds_write_b128 v93, v[86:89] offset:34816
	v_add_u32_e32 v86, v85, v92
	s_waitcnt vmcnt(6)
	ds_write_b128 v86, v[56:59]
	s_waitcnt vmcnt(1)
	ds_write_b128 v90, v[80:83] offset:26112
	v_sub_u32_e32 v86, 31, v213
	v_cvt_f32_i32_e32 v86, v86
	v_and_b32_e32 v87, 0xffff0000, v80
	v_and_b32_e32 v88, 0xffff0000, v81
	v_and_b32_e32 v90, 0xffff0000, v82
	v_mul_f32_e32 v86, v138, v86
	v_mul_f32_e32 v86, 0x3fb8aa3b, v86
	v_exp_f32_e32 v89, v86
	v_lshlrev_b32_e32 v86, 16, v80
	v_and_b32_e32 v92, 0xffff0000, v83
	v_lshlrev_b32_e32 v133, 5, v134
	v_mul_f32_e32 v86, v89, v86
	v_mul_f32_e32 v87, v89, v87
	v_cvt_pk_bf16_f32 v86, v86, v87
	v_lshlrev_b32_e32 v87, 16, v81
	v_mul_f32_e32 v87, v89, v87
	v_mul_f32_e32 v88, v89, v88
	v_cvt_pk_bf16_f32 v87, v87, v88
	v_lshlrev_b32_e32 v88, 16, v82
	v_mul_f32_e32 v88, v89, v88
	v_mul_f32_e32 v90, v89, v90
	v_cvt_pk_bf16_f32 v88, v88, v90
	v_lshlrev_b32_e32 v90, 16, v83
	v_mul_f32_e32 v90, v89, v90
	v_mul_f32_e32 v89, v89, v92
	v_cvt_pk_bf16_f32 v89, v90, v89
	v_add_u32_e32 v90, 0x6c00, v91
	v_add_u32_e32 v84, v84, v90
	ds_write_b128 v84, v[86:89] offset:34816
	v_add_u32_e32 v84, v85, v90
	v_lshlrev_b32_e32 v215, 3, v100
	v_add_u32_e32 v86, s95, v133
	v_mul_u32_u24_e32 v214, 0x110, v183
	s_waitcnt vmcnt(0)
	ds_write_b128 v84, v[76:79]
	v_cvt_pk_bf16_f32 v84, v20, v21
	v_add3_u32 v86, v86, v215, v214
	v_cvt_pk_bf16_f32 v85, v22, v23
	ds_write_b64 v86, v[84:85]
	v_cvt_pk_bf16_f32 v84, v4, v5
	v_cvt_pk_bf16_f32 v85, v6, v7
	ds_write_b64 v86, v[84:85] offset:4352
	v_cvt_pk_bf16_f32 v84, v8, v9
	v_cvt_pk_bf16_f32 v85, v10, v11
	ds_write_b64 v86, v[84:85] offset:8704
	v_cvt_pk_bf16_f32 v84, v12, v13
	v_cvt_pk_bf16_f32 v85, v14, v15
	ds_write_b64 v86, v[84:85] offset:13056
	v_cvt_pk_bf16_f32 v84, v16, v17
	v_cvt_pk_bf16_f32 v85, v18, v19
	ds_write_b64 v86, v[84:85] offset:17408
	v_cvt_pk_bf16_f32 v84, v24, v25
	v_cvt_pk_bf16_f32 v85, v26, v27
	ds_write_b64 v86, v[84:85] offset:21760
	v_cvt_pk_bf16_f32 v84, v28, v29
	v_cvt_pk_bf16_f32 v85, v30, v31
	ds_write_b64 v86, v[84:85] offset:26112
	v_cvt_pk_bf16_f32 v84, v32, v33
	v_lshlrev_b32_e32 v217, 4, v134
	v_cvt_pk_bf16_f32 v85, v34, v35
	ds_write_b64 v86, v[84:85] offset:30464
	v_or_b32_e32 v84, v183, v217
	v_add_u32_e32 v84, 1, v84
	v_cvt_f32_i32_e32 v84, v84
	v_and_b32_e32 v85, 0xffff0000, v60
	s_waitcnt lgkmcnt(0)
	s_barrier
; #define LAS __attribute__((address_space(3)))
; #define MFMA16(a, b, c) __builtin_amdgcn_mfma_f32_16x16x32_bf16((a), (b), (c), 0, 0, 0)
; __device__ __forceinline__ v4u scale8(v4u x, float sc) { v4u o; o.x = pk2(bf_lo(x.x) * sc, bf_hi(x.x) * sc); o.y = pk2(bf_lo(x.y) * sc, bf_hi(x.y) * sc); o.z = pk2(bf_lo(x.z) * sc, bf_hi(x.z) * sc); o.w = pk2(bf_lo(x.w) * sc, bf_hi(x.w) * sc); return o; }
; template <int DIR, bool INTRA, bool FINAL> __device__ __forceinline__ void retention_pass(LAS unsigned char* lds, const bf16* ZH, bf16* YF, bf16* MIX, const float* ld, const float* gn, int seq, int h, int n0, int ncnt, ...
;     ...
;             { const float xi = DIR == 0 ? __expf(lf * (float)(16 * w + lr + 1)) : __expf(lb * (float)(128 - 16 * w - lr));
; #pragma unroll
;               for (int ks = 0; ks < 4; ++ks) qx[ks] = __builtin_bit_cast(bf16x8, scale8(__builtin_bit_cast(v4u, qf[ks]), xi)); }
;             bf16x8 pt[4];
;             if constexpr (INTRA) {
;                 f32x4 s[8];
; #pragma unroll
;                 for (int jt = 0; jt < 8; ++jt) { s[jt] = (f32x4){0.f, 0.f, 0.f, 0.f};
; #pragma unroll
;                     for (int ks = 0; ks < 4; ++ks) { const bf16x8 a = *(const LAS bf16x8*)(lds + R_K + (16 * jt + lr) * RS + (8 * lg + 32 * ks) * 2); s[jt] = MFMA16(a, qf[ks], s[jt]); }
;                     __builtin_amdgcn_sched_barrier(0); }
	s_waitcnt lgkmcnt(0)
	v_mul_f32_e32 v84, v138, v84
	v_mul_f32_e32 v84, 0x3fb8aa3b, v84
	v_exp_f32_e32 v99, v84
	v_lshlrev_b32_e32 v84, 16, v60
	v_and_b32_e32 v86, 0xffff0000, v61
	v_mul_f32_e32 v84, v99, v84
	v_mul_f32_e32 v85, v99, v85
	v_cvt_pk_bf16_f32 v84, v84, v85
	v_lshlrev_b32_e32 v85, 16, v61
	v_mul_f32_e32 v85, v99, v85
	v_mul_f32_e32 v86, v99, v86
	v_cvt_pk_bf16_f32 v85, v85, v86
	v_lshlrev_b32_e32 v86, 16, v62
	v_and_b32_e32 v87, 0xffff0000, v62
	v_mul_f32_e32 v86, v99, v86
	v_mul_f32_e32 v87, v99, v87
	v_cvt_pk_bf16_f32 v86, v86, v87
	v_lshlrev_b32_e32 v87, 16, v63
	v_and_b32_e32 v88, 0xffff0000, v63
	v_mul_f32_e32 v87, v99, v87
	v_mul_f32_e32 v88, v99, v88
	v_cvt_pk_bf16_f32 v87, v87, v88
	v_lshlrev_b32_e32 v88, 16, v64
	v_and_b32_e32 v89, 0xffff0000, v64
	v_mul_f32_e32 v88, v99, v88
	v_mul_f32_e32 v89, v99, v89
	v_cvt_pk_bf16_f32 v88, v88, v89
	v_lshlrev_b32_e32 v89, 16, v65
	v_and_b32_e32 v90, 0xffff0000, v65
	v_mul_f32_e32 v89, v99, v89
	v_mul_f32_e32 v90, v99, v90
	v_cvt_pk_bf16_f32 v89, v89, v90
	v_lshlrev_b32_e32 v90, 16, v66
	v_and_b32_e32 v91, 0xffff0000, v66
	v_mul_f32_e32 v90, v99, v90
	v_mul_f32_e32 v91, v99, v91
	v_cvt_pk_bf16_f32 v90, v90, v91
	v_lshlrev_b32_e32 v91, 16, v67
	v_and_b32_e32 v92, 0xffff0000, v67
	v_mul_f32_e32 v91, v99, v91
	v_mul_f32_e32 v92, v99, v92
	v_cvt_pk_bf16_f32 v91, v91, v92
	v_lshlrev_b32_e32 v92, 16, v68
	v_and_b32_e32 v93, 0xffff0000, v68
	v_mul_f32_e32 v92, v99, v92
	v_mul_f32_e32 v93, v99, v93
	v_cvt_pk_bf16_f32 v92, v92, v93
	v_lshlrev_b32_e32 v93, 16, v69
	v_and_b32_e32 v94, 0xffff0000, v69
	v_mul_f32_e32 v93, v99, v93
	v_mul_f32_e32 v94, v99, v94
	v_cvt_pk_bf16_f32 v93, v93, v94
	v_lshlrev_b32_e32 v94, 16, v70
	v_and_b32_e32 v95, 0xffff0000, v70
	v_mul_f32_e32 v94, v99, v94
	v_mul_f32_e32 v95, v99, v95
	v_cvt_pk_bf16_f32 v94, v94, v95
	v_lshlrev_b32_e32 v95, 16, v71
	v_and_b32_e32 v96, 0xffff0000, v71
	v_mul_f32_e32 v95, v99, v95
	v_mul_f32_e32 v96, v99, v96
	v_cvt_pk_bf16_f32 v95, v95, v96
	v_lshlrev_b32_e32 v96, 16, v72
	v_and_b32_e32 v97, 0xffff0000, v72
	v_mul_f32_e32 v96, v99, v96
	v_mul_f32_e32 v97, v99, v97
	v_cvt_pk_bf16_f32 v96, v96, v97
	v_lshlrev_b32_e32 v97, 16, v73
	v_and_b32_e32 v98, 0xffff0000, v73
	v_mul_f32_e32 v97, v99, v97
	v_mul_f32_e32 v98, v99, v98
	v_cvt_pk_bf16_f32 v97, v97, v98
	v_lshlrev_b32_e32 v98, 16, v74
	v_and_b32_e32 v101, 0xffff0000, v74
	v_mul_f32_e32 v98, v99, v98
	v_mul_f32_e32 v101, v99, v101
	v_cvt_pk_bf16_f32 v98, v98, v101
	v_lshlrev_b32_e32 v101, 16, v75
	v_and_b32_e32 v102, 0xffff0000, v75
	v_lshlrev_b32_e32 v216, 4, v100
	v_mul_f32_e32 v101, v99, v101
	v_mul_f32_e32 v99, v99, v102
	v_add3_u32 v135, 0, v216, v214
	ds_read_b128 v[144:147], v135
	ds_read_b128 v[152:155], v135 offset:64
	ds_read_b128 v[156:159], v135 offset:128
	ds_read_b128 v[160:163], v135 offset:192
	ds_read_b128 v[164:167], v135 offset:4352
	ds_read_b128 v[168:171], v135 offset:4416
	ds_read_b128 v[172:175], v135 offset:4480
	ds_read_b128 v[176:179], v135 offset:4544
	v_lshlrev_b32_e32 v181, 2, v100
	v_cvt_pk_bf16_f32 v99, v101, v99
	s_waitcnt lgkmcnt(7)
	v_mfma_f32_16x16x32_bf16 v[100:103], v[144:147], v[60:63], 0
	ds_read_b128 v[144:147], v135 offset:8704
	s_waitcnt lgkmcnt(7)
	v_mfma_f32_16x16x32_bf16 v[100:103], v[152:155], v[64:67], v[100:103]
	ds_read_b128 v[152:155], v135 offset:8768
	s_waitcnt lgkmcnt(7)
	v_mfma_f32_16x16x32_bf16 v[100:103], v[156:159], v[68:71], v[100:103]
	ds_read_b128 v[156:159], v135 offset:8832
	s_waitcnt lgkmcnt(7)
	v_mfma_f32_16x16x32_bf16 v[100:103], v[160:163], v[72:75], v[100:103]
	ds_read_b128 v[160:163], v135 offset:8896
	s_waitcnt lgkmcnt(7)
	v_mfma_f32_16x16x32_bf16 v[104:107], v[164:167], v[60:63], 0
	ds_read_b128 v[164:167], v135 offset:13056
	s_waitcnt lgkmcnt(7)
	v_mfma_f32_16x16x32_bf16 v[104:107], v[168:171], v[64:67], v[104:107]
	ds_read_b128 v[168:171], v135 offset:13120
	s_waitcnt lgkmcnt(7)
; #define LAS __attribute__((address_space(3)))
; #define MFMA16(a, b, c) __builtin_amdgcn_mfma_f32_16x16x32_bf16((a), (b), (c), 0, 0, 0)
; template <int DIR, bool INTRA, bool FINAL> __device__ __forceinline__ void retention_pass(LAS unsigned char* lds, const bf16* ZH, bf16* YF, bf16* MIX, const float* ld, const float* gn, int seq, int h, int n0, int ncnt, ...
;     ...
;                     for (int ks = 0; ks < 4; ++ks) { const bf16x8 a = *(const LAS bf16x8*)(lds + R_K + (16 * jt + lr) * RS + (8 * lg + 32 * ks) * 2); s[jt] = MFMA16(a, qf[ks], s[jt]); }
;                     __builtin_amdgcn_sched_barrier(0); }
;                 float Fr[4], Br[4];
; #pragma unroll
;                 for (int r = 0; r < 4; ++r) { const float br = (float)(lr - 4 * lg - r); Fr[r] = __expf(lf * br); Br[r] = __expf(-lb * br); }
; #pragma unroll
;                 for (int jt = 0; jt < 8; ++jt) { const int dt = w - jt; const float cf = __expf(lf * 16.f * (float)dt), cb = __expf(-lb * 16.f * (float)dt);
; #pragma unroll
;                     for (int r = 0; r < 4; ++r) { const float dec = dt > 0 ? Fr[r] * cf : (dt < 0 ? Br[r] * cb : ((lr - 4 * lg - r) >= 0 ? Fr[r] : Br[r])); s[jt][r] *= dec; } }
	v_mfma_f32_16x16x32_bf16 v[104:107], v[172:175], v[68:71], v[104:107]
	ds_read_b128 v[172:175], v135 offset:13184
	s_waitcnt lgkmcnt(7)
	v_mfma_f32_16x16x32_bf16 v[104:107], v[176:179], v[72:75], v[104:107]
	ds_read_b128 v[176:179], v135 offset:13248
	s_waitcnt lgkmcnt(7)
	v_mfma_f32_16x16x32_bf16 v[108:111], v[144:147], v[60:63], 0
	ds_read_b128 v[144:147], v135 offset:17408
	s_waitcnt lgkmcnt(7)
	v_mfma_f32_16x16x32_bf16 v[108:111], v[152:155], v[64:67], v[108:111]
	ds_read_b128 v[152:155], v135 offset:17472
	s_waitcnt lgkmcnt(7)
	v_mfma_f32_16x16x32_bf16 v[108:111], v[156:159], v[68:71], v[108:111]
	ds_read_b128 v[156:159], v135 offset:17536
	s_waitcnt lgkmcnt(7)
	v_mfma_f32_16x16x32_bf16 v[108:111], v[160:163], v[72:75], v[108:111]
	ds_read_b128 v[160:163], v135 offset:17600
	s_waitcnt lgkmcnt(7)
	v_mfma_f32_16x16x32_bf16 v[112:115], v[164:167], v[60:63], 0
	ds_read_b128 v[164:167], v135 offset:21760
	s_waitcnt lgkmcnt(7)
	v_mfma_f32_16x16x32_bf16 v[112:115], v[168:171], v[64:67], v[112:115]
	ds_read_b128 v[168:171], v135 offset:21824
	s_waitcnt lgkmcnt(7)
	v_mfma_f32_16x16x32_bf16 v[112:115], v[172:175], v[68:71], v[112:115]
	ds_read_b128 v[172:175], v135 offset:21888
	s_waitcnt lgkmcnt(7)
	v_mfma_f32_16x16x32_bf16 v[112:115], v[176:179], v[72:75], v[112:115]
	ds_read_b128 v[176:179], v135 offset:21952
	s_waitcnt lgkmcnt(7)
	v_mfma_f32_16x16x32_bf16 v[116:119], v[144:147], v[60:63], 0
	ds_read_b128 v[144:147], v135 offset:26112
	s_waitcnt lgkmcnt(7)
	v_mfma_f32_16x16x32_bf16 v[116:119], v[152:155], v[64:67], v[116:119]
	ds_read_b128 v[152:155], v135 offset:26176
	s_waitcnt lgkmcnt(7)
	v_mfma_f32_16x16x32_bf16 v[116:119], v[156:159], v[68:71], v[116:119]
	ds_read_b128 v[156:159], v135 offset:26240
	s_waitcnt lgkmcnt(7)
	v_mfma_f32_16x16x32_bf16 v[116:119], v[160:163], v[72:75], v[116:119]
	ds_read_b128 v[160:163], v135 offset:26304
	s_waitcnt lgkmcnt(7)
	v_mfma_f32_16x16x32_bf16 v[120:123], v[164:167], v[60:63], 0
	ds_read_b128 v[164:167], v135 offset:30464
	s_waitcnt lgkmcnt(7)
	v_mfma_f32_16x16x32_bf16 v[120:123], v[168:171], v[64:67], v[120:123]
	ds_read_b128 v[168:171], v135 offset:30528
	s_waitcnt lgkmcnt(7)
	v_mfma_f32_16x16x32_bf16 v[120:123], v[172:175], v[68:71], v[120:123]
	ds_read_b128 v[172:175], v135 offset:30592
	s_waitcnt lgkmcnt(7)
	v_mfma_f32_16x16x32_bf16 v[120:123], v[176:179], v[72:75], v[120:123]
	s_waitcnt lgkmcnt(6)
	v_mfma_f32_16x16x32_bf16 v[124:127], v[144:147], v[60:63], 0
	s_waitcnt lgkmcnt(5)
	v_mfma_f32_16x16x32_bf16 v[124:127], v[152:155], v[64:67], v[124:127]
	s_waitcnt lgkmcnt(4)
	v_mfma_f32_16x16x32_bf16 v[124:127], v[156:159], v[68:71], v[124:127]
	s_waitcnt lgkmcnt(3)
	v_mfma_f32_16x16x32_bf16 v[128:131], v[160:163], v[72:75], v[124:127]
	s_nop 4
	s_waitcnt lgkmcnt(2)
	v_mfma_f32_16x16x32_bf16 v[124:127], v[164:167], v[60:63], 0
	s_waitcnt lgkmcnt(1)
	v_mfma_f32_16x16x32_bf16 v[124:127], v[168:171], v[64:67], v[124:127]
	s_waitcnt lgkmcnt(0)
	v_mfma_f32_16x16x32_bf16 v[124:127], v[172:175], v[68:71], v[124:127]
	ds_read_b128 v[140:143], v135 offset:30656
	s_waitcnt lgkmcnt(0)
	v_mfma_f32_16x16x32_bf16 v[124:127], v[140:143], v[72:75], v[124:127]
	v_sub_u32_e32 v135, v183, v181
	v_cvt_f32_i32_e32 v135, v135
	v_cvt_f32_i32_e32 v137, v134
	v_mul_f32_e32 v151, 0xc1800000, v136
	v_cmp_gt_i32_e64 s[6:7], 1, v134
	v_mul_f32_e32 v139, v138, v135
	v_mul_f32_e64 v135, -v136, v135
	v_mul_f32_e32 v135, 0x3fb8aa3b, v135
	v_exp_f32_e32 v140, v135
	v_mul_f32_e32 v135, v151, v137
	v_mul_f32_e32 v139, 0x3fb8aa3b, v139
	v_mul_f32_e32 v135, 0x3fb8aa3b, v135
	v_exp_f32_e32 v139, v139
	v_exp_f32_e32 v150, v135
	v_cmp_lt_i32_e32 vcc, -1, v134
	s_and_saveexec_b64 s[8:9], s[6:7]
	s_xor_b64 s[34:35], exec, s[8:9]
	s_cbranch_execz .LBB0_455
	s_and_saveexec_b64 s[8:9], vcc
	s_xor_b64 s[46:47], exec, s[8:9]
	v_cmp_lt_u32_e64 s[8:9], v183, v181
	s_nop 1
	v_cndmask_b32_e64 v135, v139, v140, s[8:9]
	s_andn2_saveexec_b64 s[8:9], s[46:47]
	v_mul_f32_e32 v135, v150, v140
	s_or_b64 exec, exec, s[8:9]

; __device__ __forceinline__ unsigned pk2(float lo, float hi) { return pg8::cvt_pk_bf16(lo, hi); }
; #define MFMA16(a, b, c) __builtin_amdgcn_mfma_f32_16x16x32_bf16((a), (b), (c), 0, 0, 0)
; __device__ __forceinline__ bf16x8 ds_tr2(LAS unsigned char* p, int rstride) { const s16x4 a = ds_tr(p), b = ds_tr(p + 16 * rstride); bf16x8 r; r[0] = a[0]; r[1] = a[1]; r[2] = a[2]; r[3] = a[3]; r[4] = b[0]; r[5] = b[1]; r[6] = b[2]; r[7] = b[3]; return r; }
; template <int DIR, bool INTRA, bool FINAL> __device__ __forceinline__ void retention_pass(LAS unsigned char* lds, const bf16* ZH, bf16* YF, bf16* MIX, const float* ld, const float* gn, int seq, int h, int n0, int ncnt, ...
;     ...
; #pragma unroll
;                 for (int ks = 0; ks < 4; ++ks) { v4u o; o.x = pk2(s[2 * ks][0], s[2 * ks][1]); o.y = pk2(s[2 * ks][2], s[2 * ks][3]); o.z = pk2(s[2 * ks + 1][0], s[2 * ks + 1][1]); o.w = pk2(s[2 * ks + 1][2], s[2 * ks + 1][3]); pt[ks] = __builtin_bit_cast(bf16x8, o); }
;             }
;             f32x4 y[8];
; #pragma unroll
;             for (int e = 0; e < 8; ++e) y[e] = (f32x4){0.f, 0.f, 0.f, 0.f};
;             { bf16x8 kwf[4];
; #pragma unroll
;               for (int ks = 0; ks < 4; ++ks) kwf[ks] = ds_tr2(trp + R_KW + (32 * ks) * RSB + (16 * w) * 2, RSB);
; #pragma unroll
;               for (int e = 0; e < 8; ++e) { st[e] = st[e] * gC;
; #pragma unroll
;                 for (int ks = 0; ks < 4; ++ks) { const bf16x8 vf = ds_tr2(trp + R_V + (32 * ks) * RSB + (16 * e) * 2, RSB);
;                     if constexpr (INTRA) y[e] = MFMA16(vf, pt[ks], y[e]);
;                     st[e] = MFMA16(kwf[ks], vf, st[e]); }
;                 __builtin_amdgcn_sched_barrier(0); } }
.LBB0_705:
	s_waitcnt lgkmcnt(0)
	s_or_b64 exec, exec, s[6:7]
	v_mul_f32_e32 v145, v116, v163
	v_lshrrev_b32_e32 v116, 2, v183
	v_or_b32_e32 v116, v181, v116
	v_mul_f32_e32 v100, v100, v135
	v_mul_u32_u24_e32 v135, 0x120, v116
	v_lshlrev_b32_e32 v116, 3, v132
	v_and_b32_e32 v132, 24, v116
	v_mul_f32_e32 v113, v113, v160
	v_mul_f32_e32 v104, v104, v150
	v_add3_u32 v160, 0, v135, v132
	v_mul_f32_e32 v140, v126, v141
	v_mul_f32_e32 v139, v125, v139
	v_mul_f32_e32 v134, v124, v134
	v_mul_f32_e32 v122, v122, v169
	v_mul_f32_e32 v120, v120, v167
	v_mul_f32_e32 v111, v111, v158
	v_mul_f32_e32 v110, v110, v157
	v_mul_f32_e32 v109, v109, v156
	v_mul_f32_e32 v108, v108, v155
	v_mul_f32_e32 v106, v106, v153
	v_mul_f32_e32 v105, v105, v152
	v_mul_f32_e32 v103, v103, v138
	v_mul_f32_e32 v102, v102, v137
	v_mul_f32_e32 v101, v101, v136
	v_cvt_pk_bf16_f32 v124, v100, v101
	v_cvt_pk_bf16_f32 v125, v102, v103
	v_cvt_pk_bf16_f32 v126, v104, v105
	v_add_u32_e32 v104, v160, v133
	ds_read_b64_tr_b16 v[220:221], v104 offset:34816
	ds_read_b64_tr_b16 v[222:223], v104 offset:39424
	ds_read_b64_tr_b16 v[224:225], v104 offset:53248
	ds_read_b64_tr_b16 v[226:227], v104 offset:57856
	v_mul_f32_e32 v131, v131, v174
	v_mul_f32_e32 v130, v130, v173
	v_mul_f32_e32 v129, v129, v172
	v_mul_f32_e32 v128, v128, v171
	v_mul_f32_e32 v123, v123, v170
	v_mul_f32_e32 v121, v121, v168
	v_mul_f32_e32 v141, v119, v166
	v_mul_f32_e32 v143, v118, v165
	v_mul_f32_e32 v144, v117, v164
	v_mul_f32_e32 v115, v115, v162
	v_mul_f32_e32 v114, v114, v161
	v_mul_f32_e32 v112, v112, v159
	v_mul_f32_e32 v107, v107, v154
	v_mul_f32_e32 v136, v127, v142
	v_cvt_pk_bf16_f32 v127, v106, v107
	v_cvt_pk_bf16_f32 v116, v108, v109
	v_cvt_pk_bf16_f32 v117, v110, v111
	v_cvt_pk_bf16_f32 v118, v112, v113
	v_cvt_pk_bf16_f32 v119, v114, v115
	v_cvt_pk_bf16_f32 v108, v145, v144
	v_cvt_pk_bf16_f32 v109, v143, v141
	v_cvt_pk_bf16_f32 v110, v120, v121
	v_cvt_pk_bf16_f32 v111, v122, v123
	v_add_u32_e32 v106, 0x8800, v104
	v_add_u32_e32 v120, 0x11800, v160
	ds_read_b64_tr_b16 v[240:241], v120
	v_add_u32_e32 v122, 0x12a00, v160
	ds_read_b64_tr_b16 v[242:243], v122
	v_cvt_pk_bf16_f32 v100, v128, v129
	v_cvt_pk_bf16_f32 v101, v130, v131
	v_cvt_pk_bf16_f32 v102, v134, v139
	v_cvt_pk_bf16_f32 v103, v140, v136
	ds_read_b64_tr_b16 v[128:129], v104 offset:44032
	ds_read_b64_tr_b16 v[130:131], v104 offset:48640
	ds_read_b64_tr_b16 v[104:105], v104 offset:62464
	ds_read_b64_tr_b16 v[106:107], v106 offset:32256
	v_mov_b32_e32 v207, v206
	v_pk_mul_f32 v[22:23], v[206:207], v[22:23]
	v_pk_mul_f32 v[20:21], v[208:209], v[20:21]
	s_waitcnt lgkmcnt(4)
	v_mfma_f32_16x16x32_bf16 v[136:139], v[240:243], v[124:127], 0
	v_mfma_f32_16x16x32_bf16 v[20:23], v[220:223], v[240:243], v[20:23]
	v_add_u32_e32 v120, 0x13c00, v160
	ds_read_b64_tr_b16 v[244:245], v120
	v_add_u32_e32 v122, 0x14e00, v160
	ds_read_b64_tr_b16 v[246:247], v122
	s_waitcnt lgkmcnt(0)
	v_mfma_f32_16x16x32_bf16 v[136:139], v[244:247], v[116:119], v[136:139]
	v_mfma_f32_16x16x32_bf16 v[20:23], v[128:131], v[244:247], v[20:23]
	v_add_u32_e32 v120, 0x16000, v160
	ds_read_b64_tr_b16 v[248:249], v120
	v_add_u32_e32 v122, 0x17200, v160
	ds_read_b64_tr_b16 v[250:251], v122
	s_waitcnt lgkmcnt(0)
	v_mfma_f32_16x16x32_bf16 v[136:139], v[248:251], v[108:111], v[136:139]
	v_mfma_f32_16x16x32_bf16 v[20:23], v[224:227], v[248:251], v[20:23]
	v_add_u32_e32 v120, 0x18400, v160
	ds_read_b64_tr_b16 v[240:241], v120
	v_add_u32_e32 v120, 0x19600, v160
	ds_read_b64_tr_b16 v[242:243], v120
	s_waitcnt lgkmcnt(0)
	v_mfma_f32_16x16x32_bf16 v[120:123], v[240:243], v[100:103], v[136:139]
	v_mfma_f32_16x16x32_bf16 v[20:23], v[104:107], v[240:243], v[20:23]
	s_nop 1
	v_add_u32_e32 v136, 0x11820, v160
	ds_read_b64_tr_b16 v[244:245], v136
	v_add_u32_e32 v138, 0x12a20, v160
	ds_read_b64_tr_b16 v[246:247], v138
	v_pk_mul_f32 v[6:7], v[206:207], v[6:7]
	v_pk_mul_f32 v[4:5], v[208:209], v[4:5]
	s_waitcnt lgkmcnt(0)
	v_mfma_f32_16x16x32_bf16 v[140:143], v[244:247], v[124:127], 0
	v_mfma_f32_16x16x32_bf16 v[4:7], v[220:223], v[244:247], v[4:7]
	v_add_u32_e32 v136, 0x13c20, v160
	ds_read_b64_tr_b16 v[248:249], v136
	v_add_u32_e32 v138, 0x14e20, v160
	ds_read_b64_tr_b16 v[250:251], v138
	s_waitcnt lgkmcnt(0)
	v_mfma_f32_16x16x32_bf16 v[140:143], v[248:251], v[116:119], v[140:143]
	v_mfma_f32_16x16x32_bf16 v[4:7], v[128:131], v[248:251], v[4:7]
	v_add_u32_e32 v136, 0x16020, v160
	ds_read_b64_tr_b16 v[240:241], v136
	v_add_u32_e32 v138, 0x17220, v160
	ds_read_b64_tr_b16 v[242:243], v138
	s_waitcnt lgkmcnt(0)
	v_mfma_f32_16x16x32_bf16 v[140:143], v[240:243], v[108:111], v[140:143]
	v_mfma_f32_16x16x32_bf16 v[4:7], v[224:227], v[240:243], v[4:7]
	v_add_u32_e32 v136, 0x18420, v160
	ds_read_b64_tr_b16 v[244:245], v136
	v_add_u32_e32 v136, 0x19620, v160
	ds_read_b64_tr_b16 v[246:247], v136
	s_waitcnt lgkmcnt(0)
	v_mfma_f32_16x16x32_bf16 v[136:139], v[244:247], v[100:103], v[140:143]
	v_mfma_f32_16x16x32_bf16 v[4:7], v[104:107], v[244:247], v[4:7]
	s_nop 1
	v_add_u32_e32 v140, 0x11840, v160
	ds_read_b64_tr_b16 v[248:249], v140
	v_add_u32_e32 v142, 0x12a40, v160
	ds_read_b64_tr_b16 v[250:251], v142
	v_pk_mul_f32 v[10:11], v[206:207], v[10:11]
	v_pk_mul_f32 v[8:9], v[208:209], v[8:9]
	s_waitcnt lgkmcnt(0)
	v_mfma_f32_16x16x32_bf16 v[144:147], v[248:251], v[124:127], 0
	v_mfma_f32_16x16x32_bf16 v[8:11], v[220:223], v[248:251], v[8:11]
	v_add_u32_e32 v140, 0x13c40, v160
	ds_read_b64_tr_b16 v[240:241], v140
	v_add_u32_e32 v142, 0x14e40, v160
	ds_read_b64_tr_b16 v[242:243], v142
	s_waitcnt lgkmcnt(0)
; #define MFMA16(a, b, c) __builtin_amdgcn_mfma_f32_16x16x32_bf16((a), (b), (c), 0, 0, 0)
; __device__ __forceinline__ bf16x8 ds_tr2(LAS unsigned char* p, int rstride) { const s16x4 a = ds_tr(p), b = ds_tr(p + 16 * rstride); bf16x8 r; r[0] = a[0]; r[1] = a[1]; r[2] = a[2]; r[3] = a[3]; r[4] = b[0]; r[5] = b[1]; r[6] = b[2]; r[7] = b[3]; return r; }
; template <int DIR, bool INTRA, bool FINAL> __device__ __forceinline__ void retention_pass(LAS unsigned char* lds, const bf16* ZH, bf16* YF, bf16* MIX, const float* ld, const float* gn, int seq, int h, int n0, int ncnt, ...
;     ...
;               for (int e = 0; e < 8; ++e) { st[e] = st[e] * gC;
; #pragma unroll
;                 for (int ks = 0; ks < 4; ++ks) { const bf16x8 vf = ds_tr2(trp + R_V + (32 * ks) * RSB + (16 * e) * 2, RSB);
;                     if constexpr (INTRA) y[e] = MFMA16(vf, pt[ks], y[e]);
;                     st[e] = MFMA16(kwf[ks], vf, st[e]); }
;                 __builtin_amdgcn_sched_barrier(0); } }
	v_mfma_f32_16x16x32_bf16 v[144:147], v[240:243], v[116:119], v[144:147]
	v_mfma_f32_16x16x32_bf16 v[8:11], v[128:131], v[240:243], v[8:11]
	v_add_u32_e32 v140, 0x16040, v160
	ds_read_b64_tr_b16 v[244:245], v140
	v_add_u32_e32 v142, 0x17240, v160
	ds_read_b64_tr_b16 v[246:247], v142
	s_waitcnt lgkmcnt(0)
	v_mfma_f32_16x16x32_bf16 v[144:147], v[244:247], v[108:111], v[144:147]
	v_mfma_f32_16x16x32_bf16 v[8:11], v[224:227], v[244:247], v[8:11]
	v_add_u32_e32 v140, 0x18440, v160
	ds_read_b64_tr_b16 v[248:249], v140
	v_add_u32_e32 v140, 0x19640, v160
	ds_read_b64_tr_b16 v[250:251], v140
	s_waitcnt lgkmcnt(0)
	v_mfma_f32_16x16x32_bf16 v[140:143], v[248:251], v[100:103], v[144:147]
	v_mfma_f32_16x16x32_bf16 v[8:11], v[104:107], v[248:251], v[8:11]
	s_nop 1
	v_add_u32_e32 v144, 0x11860, v160
	ds_read_b64_tr_b16 v[240:241], v144
	v_add_u32_e32 v146, 0x12a60, v160
	ds_read_b64_tr_b16 v[242:243], v146
	v_pk_mul_f32 v[14:15], v[206:207], v[14:15]
	v_pk_mul_f32 v[12:13], v[208:209], v[12:13]
	s_waitcnt lgkmcnt(0)
	v_mfma_f32_16x16x32_bf16 v[148:151], v[240:243], v[124:127], 0
	v_mfma_f32_16x16x32_bf16 v[12:15], v[220:223], v[240:243], v[12:15]
	v_add_u32_e32 v144, 0x13c60, v160
	ds_read_b64_tr_b16 v[244:245], v144
	v_add_u32_e32 v146, 0x14e60, v160
	ds_read_b64_tr_b16 v[246:247], v146
	s_waitcnt lgkmcnt(0)
	v_mfma_f32_16x16x32_bf16 v[148:151], v[244:247], v[116:119], v[148:151]
	v_mfma_f32_16x16x32_bf16 v[12:15], v[128:131], v[244:247], v[12:15]
	v_add_u32_e32 v144, 0x16060, v160
	ds_read_b64_tr_b16 v[248:249], v144
	v_add_u32_e32 v146, 0x17260, v160
	ds_read_b64_tr_b16 v[250:251], v146
	s_waitcnt lgkmcnt(0)
	v_mfma_f32_16x16x32_bf16 v[148:151], v[248:251], v[108:111], v[148:151]
	v_mfma_f32_16x16x32_bf16 v[12:15], v[224:227], v[248:251], v[12:15]
	v_add_u32_e32 v144, 0x18460, v160
	ds_read_b64_tr_b16 v[240:241], v144
	v_add_u32_e32 v144, 0x19660, v160
	ds_read_b64_tr_b16 v[242:243], v144
	s_waitcnt lgkmcnt(0)
	v_mfma_f32_16x16x32_bf16 v[144:147], v[240:243], v[100:103], v[148:151]
	v_mfma_f32_16x16x32_bf16 v[12:15], v[104:107], v[240:243], v[12:15]
	s_nop 1
	v_add_u32_e32 v148, 0x11880, v160
	ds_read_b64_tr_b16 v[244:245], v148
	v_add_u32_e32 v150, 0x12a80, v160
	ds_read_b64_tr_b16 v[246:247], v150
	v_pk_mul_f32 v[18:19], v[206:207], v[18:19]
	v_pk_mul_f32 v[16:17], v[208:209], v[16:17]
	s_waitcnt lgkmcnt(0)
	v_mfma_f32_16x16x32_bf16 v[152:155], v[244:247], v[124:127], 0
	v_mfma_f32_16x16x32_bf16 v[16:19], v[220:223], v[244:247], v[16:19]
	v_add_u32_e32 v148, 0x13c80, v160
	ds_read_b64_tr_b16 v[248:249], v148
	v_add_u32_e32 v150, 0x14e80, v160
	ds_read_b64_tr_b16 v[250:251], v150
	s_waitcnt lgkmcnt(0)
	v_mfma_f32_16x16x32_bf16 v[152:155], v[248:251], v[116:119], v[152:155]
	v_mfma_f32_16x16x32_bf16 v[16:19], v[128:131], v[248:251], v[16:19]
	v_add_u32_e32 v148, 0x16080, v160
	ds_read_b64_tr_b16 v[240:241], v148
	v_add_u32_e32 v150, 0x17280, v160
	ds_read_b64_tr_b16 v[242:243], v150
	s_waitcnt lgkmcnt(0)
	v_mfma_f32_16x16x32_bf16 v[152:155], v[240:243], v[108:111], v[152:155]
	v_mfma_f32_16x16x32_bf16 v[16:19], v[224:227], v[240:243], v[16:19]
	v_add_u32_e32 v148, 0x18480, v160
	ds_read_b64_tr_b16 v[244:245], v148
	v_add_u32_e32 v148, 0x19680, v160
	ds_read_b64_tr_b16 v[246:247], v148
	s_waitcnt lgkmcnt(0)
	v_mfma_f32_16x16x32_bf16 v[148:151], v[244:247], v[100:103], v[152:155]
	v_mfma_f32_16x16x32_bf16 v[16:19], v[104:107], v[244:247], v[16:19]
	s_nop 1
	v_add_u32_e32 v152, 0x118a0, v160
	ds_read_b64_tr_b16 v[248:249], v152
	v_add_u32_e32 v154, 0x12aa0, v160
	ds_read_b64_tr_b16 v[250:251], v154
	v_pk_mul_f32 v[26:27], v[206:207], v[26:27]
	v_pk_mul_f32 v[24:25], v[208:209], v[24:25]
	s_waitcnt lgkmcnt(0)
	v_mfma_f32_16x16x32_bf16 v[156:159], v[248:251], v[124:127], 0
	v_mfma_f32_16x16x32_bf16 v[24:27], v[220:223], v[248:251], v[24:27]
	v_add_u32_e32 v152, 0x13ca0, v160
	ds_read_b64_tr_b16 v[240:241], v152
	v_add_u32_e32 v154, 0x14ea0, v160
	ds_read_b64_tr_b16 v[242:243], v154
	s_waitcnt lgkmcnt(0)
	v_mfma_f32_16x16x32_bf16 v[156:159], v[240:243], v[116:119], v[156:159]
	v_mfma_f32_16x16x32_bf16 v[24:27], v[128:131], v[240:243], v[24:27]
	v_add_u32_e32 v152, 0x160a0, v160
	ds_read_b64_tr_b16 v[244:245], v152
	v_add_u32_e32 v154, 0x172a0, v160
	ds_read_b64_tr_b16 v[246:247], v154
	s_waitcnt lgkmcnt(0)
	v_mfma_f32_16x16x32_bf16 v[156:159], v[244:247], v[108:111], v[156:159]
	v_mfma_f32_16x16x32_bf16 v[24:27], v[224:227], v[244:247], v[24:27]
	v_add_u32_e32 v152, 0x184a0, v160
	ds_read_b64_tr_b16 v[248:249], v152
	v_add_u32_e32 v152, 0x196a0, v160
	ds_read_b64_tr_b16 v[250:251], v152
	s_waitcnt lgkmcnt(0)
; #define GAS __attribute__((address_space(1)))
; #define MFMA16(a, b, c) __builtin_amdgcn_mfma_f32_16x16x32_bf16((a), (b), (c), 0, 0, 0)
; __device__ __forceinline__ bf16x8 ds_tr2(LAS unsigned char* p, int rstride) { const s16x4 a = ds_tr(p), b = ds_tr(p + 16 * rstride); bf16x8 r; r[0] = a[0]; r[1] = a[1]; r[2] = a[2]; r[3] = a[3]; r[4] = b[0]; r[5] = b[1]; r[6] = b[2]; r[7] = b[3]; return r; }
; template <int DIR, bool INTRA, bool FINAL> __device__ __forceinline__ void retention_pass(LAS unsigned char* lds, const bf16* ZH, bf16* YF, bf16* MIX, const float* ld, const float* gn, int seq, int h, int n0, int ncnt, ...
;     ...
;               for (int e = 0; e < 8; ++e) { st[e] = st[e] * gC;
; #pragma unroll
;                 for (int ks = 0; ks < 4; ++ks) { const bf16x8 vf = ds_tr2(trp + R_V + (32 * ks) * RSB + (16 * e) * 2, RSB);
;                     if constexpr (INTRA) y[e] = MFMA16(vf, pt[ks], y[e]);
;                     st[e] = MFMA16(kwf[ks], vf, st[e]); }
;                 __builtin_amdgcn_sched_barrier(0); } }
;             v2u ywv[8], gwv[8];
;             if constexpr (FINAL) { const int row_ = r0 + 16 * w + lr; const bf16* yp_ = YF + (size_t)row_ * 2048 + h * HD + 4 * lg; const bf16* gp_ = Gp + (size_t)(n * 128 + 16 * w + lr) * HD + 4 * lg;
; #pragma unroll
;                 for (int e = 0; e < 8; ++e) { ywv[e] = *(const GAS v2u*)(yp_ + 16 * e); gwv[e] = *(const GAS v2u*)(gp_ + 16 * e); } }
;             if (cn + 1 < ncnt) {
; #pragma unroll
;               for (int cc = 0; cc < 4; ++cc) { kreg[cc] = *(const GAS v4u*)(Kp + (size_t)(nn * 128 + srow + 32 * cc) * HD + 8 * sch); vreg[cc] = *(const GAS v4u*)(Vp + (size_t)(nn * 128 + srow + 32 * cc) * HD + 8 * sch); }
; #pragma unroll
;               for (int ks = 0; ks < 4; ++ks) qf[ks] = *(const GAS bf16x8*)(Qp + (size_t)(nn * 128 + 16 * w + lr) * HD + 8 * lg + 32 * ks); }
	v_mfma_f32_16x16x32_bf16 v[152:155], v[248:251], v[100:103], v[156:159]
	v_mfma_f32_16x16x32_bf16 v[24:27], v[104:107], v[248:251], v[24:27]
	s_nop 1
	v_add_u32_e32 v156, 0x118c0, v160
	ds_read_b64_tr_b16 v[240:241], v156
	v_add_u32_e32 v158, 0x12ac0, v160
	ds_read_b64_tr_b16 v[242:243], v158
	v_pk_mul_f32 v[30:31], v[206:207], v[30:31]
	v_pk_mul_f32 v[28:29], v[208:209], v[28:29]
	s_waitcnt lgkmcnt(0)
	v_mfma_f32_16x16x32_bf16 v[162:165], v[240:243], v[124:127], 0
	v_mfma_f32_16x16x32_bf16 v[28:31], v[220:223], v[240:243], v[28:31]
	v_add_u32_e32 v156, 0x13cc0, v160
	ds_read_b64_tr_b16 v[244:245], v156
	v_add_u32_e32 v158, 0x14ec0, v160
	ds_read_b64_tr_b16 v[246:247], v158
	s_waitcnt lgkmcnt(0)
	v_mfma_f32_16x16x32_bf16 v[162:165], v[244:247], v[116:119], v[162:165]
	v_mfma_f32_16x16x32_bf16 v[28:31], v[128:131], v[244:247], v[28:31]
	v_add_u32_e32 v156, 0x160c0, v160
	ds_read_b64_tr_b16 v[248:249], v156
	v_add_u32_e32 v158, 0x172c0, v160
	ds_read_b64_tr_b16 v[250:251], v158
	s_waitcnt lgkmcnt(0)
	v_mfma_f32_16x16x32_bf16 v[162:165], v[248:251], v[108:111], v[162:165]
	v_mfma_f32_16x16x32_bf16 v[28:31], v[224:227], v[248:251], v[28:31]
	v_add_u32_e32 v156, 0x184c0, v160
	ds_read_b64_tr_b16 v[166:167], v156
	v_add_u32_e32 v156, 0x196c0, v160
	ds_read_b64_tr_b16 v[168:169], v156
	s_waitcnt lgkmcnt(0)
	v_mfma_f32_16x16x32_bf16 v[156:159], v[166:169], v[100:103], v[162:165]
	v_mfma_f32_16x16x32_bf16 v[28:31], v[104:107], v[166:169], v[28:31]
	v_add_u32_e32 v161, 0x118e0, v160
	s_nop 0
	ds_read_b64_tr_b16 v[162:163], v161
	v_add_u32_e32 v161, 0x12ae0, v160
	ds_read_b64_tr_b16 v[164:165], v161
	v_pk_mul_f32 v[34:35], v[206:207], v[34:35]
	v_pk_mul_f32 v[32:33], v[208:209], v[32:33]
	s_waitcnt lgkmcnt(0)
	v_mfma_f32_16x16x32_bf16 v[124:127], v[162:165], v[124:127], 0
	v_mfma_f32_16x16x32_bf16 v[32:35], v[220:223], v[162:165], v[32:35]
	v_add_u32_e32 v132, 0x13ce0, v160
	v_add_u32_e32 v134, 0x14ee0, v160
	ds_read_b64_tr_b16 v[132:133], v132
	ds_read_b64_tr_b16 v[134:135], v134
	s_waitcnt lgkmcnt(0)
	v_mfma_f32_16x16x32_bf16 v[116:119], v[132:135], v[116:119], v[124:127]
	s_nop 2
	v_add_u32_e32 v124, 0x160e0, v160
	v_add_u32_e32 v126, 0x172e0, v160
	ds_read_b64_tr_b16 v[124:125], v124
	ds_read_b64_tr_b16 v[126:127], v126
	v_mfma_f32_16x16x32_bf16 v[32:35], v[128:131], v[132:135], v[32:35]
	s_waitcnt lgkmcnt(0)
	v_mfma_f32_16x16x32_bf16 v[32:35], v[224:227], v[124:127], v[32:35]
	v_add_u32_e32 v112, 0x184e0, v160
	v_add_u32_e32 v114, 0x196e0, v160
	ds_read_b64_tr_b16 v[112:113], v112
	ds_read_b64_tr_b16 v[114:115], v114
	v_mfma_f32_16x16x32_bf16 v[108:111], v[124:127], v[108:111], v[116:119]
	s_waitcnt lgkmcnt(0)
	v_mfma_f32_16x16x32_bf16 v[176:179], v[112:115], v[100:103], v[108:111]
	v_mfma_f32_16x16x32_bf16 v[32:35], v[104:107], v[112:115], v[32:35]
	s_mov_b64 s[6:7], -1
	s_cmpk_lg_i32 s60, 0x860
	v_add_u32_e32 v218, v217, v183
	s_cbranch_scc0 .LBB0_707
	v_add_u32_e32 v207, v217, v183
	v_lshl_add_u64 v[130:131], s[24:25], 0, v[2:3]
	v_lshl_add_u64 v[132:133], s[26:27], 0, v[2:3]
	v_add_u32_e32 v2, s60, v207
	v_add_u32_e32 v128, s60, v213
	v_add_u32_e32 v160, 0xffffffa0, v2
	v_add_u32_e32 v100, 0xffffffa0, v128
	v_subrev_u32_e32 v108, 64, v128
	v_subrev_u32_e32 v116, 32, v128
	v_ashrrev_i32_e32 v161, 31, v160
	v_ashrrev_i32_e32 v101, 31, v100
	v_ashrrev_i32_e32 v109, 31, v108
	v_ashrrev_i32_e32 v117, 31, v116
	v_ashrrev_i32_e32 v129, 31, v128
	v_lshlrev_b64 v[160:161], 8, v[160:161]
	v_lshlrev_b64 v[100:101], 8, v[100:101]
	v_lshlrev_b64 v[108:109], 8, v[108:109]
	v_lshlrev_b64 v[116:117], 8, v[116:117]
	v_lshlrev_b64 v[128:129], 8, v[128:129]
	v_lshl_add_u64 v[160:161], s[22:23], 0, v[160:161]
	v_lshlrev_b32_e32 v2, 1, v215
	v_lshl_add_u64 v[102:103], v[130:131], 0, v[100:101]
	v_lshl_add_u64 v[104:105], v[132:133], 0, v[100:101]
	v_lshl_add_u64 v[110:111], v[130:131], 0, v[108:109]
	v_lshl_add_u64 v[112:113], v[132:133], 0, v[108:109]
	v_lshl_add_u64 v[118:119], v[130:131], 0, v[116:117]
	v_lshl_add_u64 v[124:125], v[132:133], 0, v[116:117]
	v_lshl_add_u64 v[130:131], v[130:131], 0, v[128:129]
	v_lshl_add_u64 v[132:133], v[132:133], 0, v[128:129]
	v_lshl_add_u64 v[172:173], v[160:161], 0, v[2:3]
	global_load_dwordx4 v[100:103], v[102:103], off
	s_nop 0
	global_load_dwordx4 v[104:107], v[104:105], off
	s_nop 0
	global_load_dwordx4 v[108:111], v[110:111], off
	s_nop 0
	global_load_dwordx4 v[112:115], v[112:113], off
	s_nop 0
	global_load_dwordx4 v[116:119], v[118:119], off
	s_nop 0
	global_load_dwordx4 v[124:127], v[124:125], off
	s_nop 0
	global_load_dwordx4 v[128:131], v[130:131], off
	s_nop 0
	global_load_dwordx4 v[132:135], v[132:133], off
	s_nop 0
	global_load_dwordx4 v[160:163], v[172:173], off
	global_load_dwordx4 v[164:167], v[172:173], off offset:64
	global_load_dwordx4 v[168:171], v[172:173], off offset:128
	s_nop 0
	global_load_dwordx4 v[172:175], v[172:173], off offset:192
	s_mov_b64 s[6:7], 0

; #define GAS __attribute__((address_space(1)))
; #define LAS __attribute__((address_space(3)))
; __device__ __forceinline__ unsigned pk2(float lo, float hi) { return pg8::cvt_pk_bf16(lo, hi); }
; __device__ __forceinline__ float bf_lo(unsigned w) { return __uint_as_float(w << 16); }
; __device__ __forceinline__ float bf_hi(unsigned w) { return __uint_as_float(w & 0xffff0000u); }
; #define MFMA16(a, b, c) __builtin_amdgcn_mfma_f32_16x16x32_bf16((a), (b), (c), 0, 0, 0)
; template <int DIR, bool INTRA, bool FINAL> __device__ __forceinline__ void retention_pass(LAS unsigned char* lds, const bf16* ZH, bf16* YF, bf16* MIX, const float* ld, const float* gn, int seq, int h, int n0, int ncnt, ...
;     ...
;             for (int e = 0; e < 8; ++e) {
; #pragma unroll
;                 for (int ks = 0; ks < 4; ++ks) { const bf16x8 sf = *(const LAS bf16x8*)(lds + R_ST + (16 * e + lr) * RS + (8 * lg + 32 * ks) * 2); y[e] = MFMA16(sf, qx[ks], y[e]); }
;                 __builtin_amdgcn_sched_barrier(0); }
;             const int row = r0 + 16 * w + lr;
;             bf16* yp = YF + (size_t)row * 2048 + h * HD + 4 * lg;
;             if constexpr (!FINAL) {
; #pragma unroll
;                 for (int e = 0; e < 8; ++e) { v2u o; o.x = pk2(y[e][0], y[e][1]); o.y = pk2(y[e][2], y[e][3]); *(GAS v2u*)(yp + 16 * e) = o; }
;             } else {
;                 float sum = 0.f;
; #pragma unroll
;                 for (int e = 0; e < 8; ++e) { const v2u yw = ywv[e]; y[e][0] += bf_lo(yw.x); y[e][1] += bf_hi(yw.x); y[e][2] += bf_lo(yw.y); y[e][3] += bf_hi(yw.y); sum += (y[e][0] + y[e][1]) + (y[e][2] + y[e][3]); }
.LBB0_712:
	s_waitcnt lgkmcnt(0)
	v_lshlrev_b32_e32 v117, 4, v142
	v_add3_u32 v2, s95, v117, v143
	ds_read_b128 v[184:187], v2
	ds_read_b128 v[206:209], v2 offset:64
	ds_read_b128 v[212:215], v2 offset:128
	ds_read_b128 v[216:219], v2 offset:192
	ds_read_b128 v[220:223], v2 offset:4352
	ds_read_b128 v[224:227], v2 offset:4416
	ds_read_b128 v[240:243], v2 offset:4480
	ds_read_b128 v[244:247], v2 offset:4544
	s_waitcnt lgkmcnt(7)
	v_mfma_f32_16x16x32_bf16 v[142:145], v[184:187], v[84:87], 0
	ds_read_b128 v[184:187], v2 offset:8704
	s_waitcnt lgkmcnt(7)
	v_mfma_f32_16x16x32_bf16 v[142:145], v[206:209], v[88:91], v[142:145]
	ds_read_b128 v[206:209], v2 offset:8768
	s_waitcnt lgkmcnt(7)
	v_mfma_f32_16x16x32_bf16 v[142:145], v[212:215], v[92:95], v[142:145]
	ds_read_b128 v[212:215], v2 offset:8832
	s_waitcnt lgkmcnt(7)
	v_mfma_f32_16x16x32_bf16 v[142:145], v[216:219], v[96:99], v[142:145]
	ds_read_b128 v[216:219], v2 offset:8896
	s_waitcnt lgkmcnt(7)
	v_mfma_f32_16x16x32_bf16 v[152:155], v[220:223], v[84:87], 0
	ds_read_b128 v[220:223], v2 offset:13056
	s_waitcnt lgkmcnt(7)
	v_mfma_f32_16x16x32_bf16 v[152:155], v[224:227], v[88:91], v[152:155]
	ds_read_b128 v[224:227], v2 offset:13120
	s_waitcnt lgkmcnt(7)
	v_mfma_f32_16x16x32_bf16 v[152:155], v[240:243], v[92:95], v[152:155]
	ds_read_b128 v[240:243], v2 offset:13184
	s_waitcnt lgkmcnt(7)
	v_mfma_f32_16x16x32_bf16 v[152:155], v[244:247], v[96:99], v[152:155]
	ds_read_b128 v[244:247], v2 offset:13248
	s_waitcnt lgkmcnt(7)
	v_mfma_f32_16x16x32_bf16 v[156:159], v[184:187], v[84:87], 0
	ds_read_b128 v[184:187], v2 offset:17408
	s_waitcnt lgkmcnt(7)
	v_mfma_f32_16x16x32_bf16 v[156:159], v[206:209], v[88:91], v[156:159]
	ds_read_b128 v[206:209], v2 offset:17472
	s_waitcnt lgkmcnt(7)
	v_mfma_f32_16x16x32_bf16 v[156:159], v[212:215], v[92:95], v[156:159]
	ds_read_b128 v[212:215], v2 offset:17536
	s_waitcnt lgkmcnt(7)
	v_mfma_f32_16x16x32_bf16 v[156:159], v[216:219], v[96:99], v[156:159]
	ds_read_b128 v[216:219], v2 offset:17600
	s_waitcnt lgkmcnt(7)
	v_mfma_f32_16x16x32_bf16 v[160:163], v[220:223], v[84:87], 0
	ds_read_b128 v[220:223], v2 offset:21760
	s_waitcnt lgkmcnt(7)
	v_mfma_f32_16x16x32_bf16 v[160:163], v[224:227], v[88:91], v[160:163]
	ds_read_b128 v[224:227], v2 offset:21824
	s_waitcnt lgkmcnt(7)
	v_mfma_f32_16x16x32_bf16 v[160:163], v[240:243], v[92:95], v[160:163]
	ds_read_b128 v[240:243], v2 offset:21888
	s_waitcnt lgkmcnt(7)
	v_mfma_f32_16x16x32_bf16 v[160:163], v[244:247], v[96:99], v[160:163]
	ds_read_b128 v[244:247], v2 offset:21952
	s_waitcnt lgkmcnt(7)
	v_mfma_f32_16x16x32_bf16 v[164:167], v[184:187], v[84:87], 0
	ds_read_b128 v[184:187], v2 offset:26112
	s_waitcnt lgkmcnt(7)
	v_mfma_f32_16x16x32_bf16 v[164:167], v[206:209], v[88:91], v[164:167]
	ds_read_b128 v[206:209], v2 offset:26176
	s_waitcnt lgkmcnt(7)
	v_mfma_f32_16x16x32_bf16 v[164:167], v[212:215], v[92:95], v[164:167]
	ds_read_b128 v[212:215], v2 offset:26240
	s_waitcnt lgkmcnt(7)
	v_mfma_f32_16x16x32_bf16 v[164:167], v[216:219], v[96:99], v[164:167]
	ds_read_b128 v[216:219], v2 offset:26304
	s_waitcnt lgkmcnt(7)
	v_mfma_f32_16x16x32_bf16 v[168:171], v[220:223], v[84:87], 0
	ds_read_b128 v[220:223], v2 offset:30464
	s_waitcnt lgkmcnt(7)
	v_mfma_f32_16x16x32_bf16 v[168:171], v[224:227], v[88:91], v[168:171]
	ds_read_b128 v[224:227], v2 offset:30528
	s_waitcnt lgkmcnt(7)
	v_mfma_f32_16x16x32_bf16 v[168:171], v[240:243], v[92:95], v[168:171]
	ds_read_b128 v[240:243], v2 offset:30592
	s_waitcnt lgkmcnt(7)
	v_mfma_f32_16x16x32_bf16 v[168:171], v[244:247], v[96:99], v[168:171]
	ds_read_b128 v[244:247], v2 offset:30656
	s_waitcnt lgkmcnt(7)
	v_mfma_f32_16x16x32_bf16 v[172:175], v[184:187], v[84:87], 0
	s_waitcnt lgkmcnt(6)
	v_mfma_f32_16x16x32_bf16 v[172:175], v[206:209], v[88:91], v[172:175]
	s_waitcnt lgkmcnt(5)
	v_mfma_f32_16x16x32_bf16 v[172:175], v[212:215], v[92:95], v[172:175]
	s_waitcnt lgkmcnt(4)
	v_mfma_f32_16x16x32_bf16 v[172:175], v[216:219], v[96:99], v[172:175]
	s_waitcnt lgkmcnt(3)
	v_mfma_f32_16x16x32_bf16 v[84:87], v[220:223], v[84:87], 0
	s_waitcnt lgkmcnt(2)
	v_mfma_f32_16x16x32_bf16 v[84:87], v[224:227], v[88:91], v[84:87]
	s_waitcnt lgkmcnt(1)
	v_mfma_f32_16x16x32_bf16 v[84:87], v[240:243], v[92:95], v[84:87]
	s_waitcnt lgkmcnt(0)
	v_mfma_f32_16x16x32_bf16 v[176:179], v[244:247], v[96:99], v[84:87]
	s_waitcnt vmcnt(15)
	s_nop 3
	v_lshlrev_b32_e32 v84, 16, v134
	v_and_b32_e32 v85, 0xffff0000, v134
	v_pk_add_f32 v[146:147], v[142:143], v[84:85]
	v_lshlrev_b32_e32 v84, 16, v135
	v_and_b32_e32 v85, 0xffff0000, v135
	v_pk_add_f32 v[144:145], v[144:145], v[84:85]
	s_waitcnt vmcnt(14)
	v_lshlrev_b32_e32 v84, 16, v130
	v_and_b32_e32 v85, 0xffff0000, v130
	v_pk_add_f32 v[142:143], v[152:153], v[84:85]
	v_lshlrev_b32_e32 v84, 16, v131
	v_and_b32_e32 v85, 0xffff0000, v131
	v_pk_add_f32 v[138:139], v[154:155], v[84:85]
	v_mov_b32_e32 v84, v146
	v_mov_b32_e32 v85, v142
	v_mov_b32_e32 v86, v147
	v_mov_b32_e32 v87, v143
	v_pk_add_f32 v[84:85], v[84:85], v[86:87]
	v_mov_b32_e32 v86, v144
	v_mov_b32_e32 v87, v138
	v_mov_b32_e32 v88, v145
	v_mov_b32_e32 v89, v139
	v_pk_add_f32 v[86:87], v[86:87], v[88:89]
	s_waitcnt vmcnt(7)
; __device__ __forceinline__ float bf_lo(unsigned w) { return __uint_as_float(w << 16); }
; __device__ __forceinline__ float bf_hi(unsigned w) { return __uint_as_float(w & 0xffff0000u); }
; __device__ __forceinline__ float fast_rsqrt(float x) { return __builtin_amdgcn_rsqf(x); }
; template <int DIR, bool INTRA, bool FINAL> __device__ __forceinline__ void retention_pass(LAS unsigned char* lds, const bf16* ZH, bf16* YF, bf16* MIX, const float* ld, const float* gn, int seq, int h, int n0, int ncnt, ...
;     ...
;                 float sum = 0.f;
; #pragma unroll
;                 for (int e = 0; e < 8; ++e) { const v2u yw = ywv[e]; y[e][0] += bf_lo(yw.x); y[e][1] += bf_hi(yw.x); y[e][2] += bf_lo(yw.y); y[e][3] += bf_hi(yw.y); sum += (y[e][0] + y[e][1]) + (y[e][2] + y[e][3]); }
;                 sum += __shfl_xor(sum, 16); sum += __shfl_xor(sum, 32);
;                 const float mu = sum * (1.f / 128.f); float q = 0.f;
; #pragma unroll
;                 for (int e = 0; e < 8; ++e) { y[e] = y[e] - mu; q += (y[e][0] * y[e][0] + y[e][1] * y[e][1]) + (y[e][2] * y[e][2] + y[e][3] * y[e][3]); }
;                 q += __shfl_xor(q, 16); q += __shfl_xor(q, 32);
;                 const float rstd = fast_rsqrt(q * (1.f / 128.f) + GN_EPS);
	v_lshlrev_b32_e32 v92, 16, v140
	v_pk_add_f32 v[84:85], v[84:85], v[86:87]
	v_lshlrev_b32_e32 v86, 16, v126
	v_and_b32_e32 v87, 0xffff0000, v126
	v_pk_add_f32 v[134:135], v[156:157], v[86:87]
	v_lshlrev_b32_e32 v86, 16, v127
	v_and_b32_e32 v87, 0xffff0000, v127
	v_pk_add_f32 v[130:131], v[158:159], v[86:87]
	v_mov_b32_e32 v86, v134
	v_mov_b32_e32 v87, v130
	v_mov_b32_e32 v88, v135
	v_mov_b32_e32 v89, v131
	v_pk_add_f32 v[86:87], v[86:87], v[88:89]
	v_lshlrev_b32_e32 v88, 16, v124
	v_and_b32_e32 v89, 0xffff0000, v124
	v_pk_add_f32 v[126:127], v[160:161], v[88:89]
	v_lshlrev_b32_e32 v88, 16, v125
	v_and_b32_e32 v89, 0xffff0000, v125
	v_and_b32_e32 v93, 0xffff0000, v140
	v_pk_add_f32 v[124:125], v[162:163], v[88:89]
	v_pk_add_f32 v[120:121], v[164:165], v[92:93]
	v_lshlrev_b32_e32 v92, 16, v141
	v_and_b32_e32 v93, 0xffff0000, v141
	v_add_f32_e32 v2, 0, v84
	v_pk_add_f32 v[86:87], v[86:87], v[86:87] op_sel:[0,1] op_sel_hi:[1,0]
	v_pk_add_f32 v[88:89], v[126:127], v[126:127] op_sel:[0,1] op_sel_hi:[1,0]
	v_pk_add_f32 v[90:91], v[124:125], v[124:125] op_sel:[0,1] op_sel_hi:[1,0]
	v_pk_add_f32 v[98:99], v[166:167], v[92:93]
	v_add_f32_e32 v84, v2, v85
	v_mov_b32_e32 v85, v120
	v_mov_b32_e32 v87, v121
	v_mov_b32_e32 v89, v98
	v_mov_b32_e32 v91, v99
	v_pk_add_f32 v[84:85], v[84:85], v[86:87]
	v_pk_add_f32 v[86:87], v[88:89], v[90:91]
	s_addk_i32 s35, 0xff80
	v_pk_add_f32 v[84:85], v[84:85], v[86:87]
	s_cmpk_lg_i32 s35, 0xff00
	v_pk_add_f32 v[96:97], v[84:85], v[84:85] op_sel:[0,1] op_sel_hi:[1,0]
	s_waitcnt vmcnt(6)
	v_lshlrev_b32_e32 v84, 16, v136
	v_and_b32_e32 v85, 0xffff0000, v136
	v_pk_add_f32 v[94:95], v[168:169], v[84:85]
	v_lshlrev_b32_e32 v84, 16, v137
	v_and_b32_e32 v85, 0xffff0000, v137
	v_pk_add_f32 v[92:93], v[170:171], v[84:85]
	v_mov_b32_e32 v84, v94
	v_mov_b32_e32 v85, v92
	v_mov_b32_e32 v86, v95
	v_mov_b32_e32 v87, v93
	v_pk_add_f32 v[84:85], v[84:85], v[86:87]
	s_nop 0
	v_pk_add_f32 v[136:137], v[84:85], v[84:85] op_sel:[0,1] op_sel_hi:[1,0]
	s_waitcnt vmcnt(5)
	v_lshlrev_b32_e32 v84, 16, v132
	v_and_b32_e32 v85, 0xffff0000, v132
	v_pk_add_f32 v[90:91], v[172:173], v[84:85]
	v_lshlrev_b32_e32 v84, 16, v133
	v_and_b32_e32 v85, 0xffff0000, v133
	v_pk_add_f32 v[88:89], v[174:175], v[84:85]
	s_waitcnt vmcnt(4)
	v_lshlrev_b32_e32 v84, 16, v128
	v_and_b32_e32 v85, 0xffff0000, v128
	v_pk_add_f32 v[86:87], v[176:177], v[84:85]
	v_lshlrev_b32_e32 v84, 16, v129
	v_and_b32_e32 v85, 0xffff0000, v129
	v_pk_add_f32 v[132:133], v[90:91], v[90:91] op_sel:[0,1] op_sel_hi:[1,0]
	v_pk_add_f32 v[140:141], v[88:89], v[88:89] op_sel:[0,1] op_sel_hi:[1,0]
	v_pk_add_f32 v[84:85], v[178:179], v[84:85]
	v_mov_b32_e32 v97, v86
	v_mov_b32_e32 v137, v87
	v_mov_b32_e32 v133, v84
	v_mov_b32_e32 v141, v85
	v_pk_add_f32 v[96:97], v[96:97], v[136:137]
	v_pk_add_f32 v[128:129], v[132:133], v[140:141]
	s_nop 0
	v_pk_add_f32 v[96:97], v[96:97], v[128:129]
	s_nop 0
	v_add_f32_e32 v2, v96, v97
	v_and_b32_e32 v97, 64, v235
	v_xor_b32_e32 v96, 16, v235
	v_add_u32_e32 v97, 64, v97
	v_cmp_lt_i32_e32 vcc, v96, v97
	s_nop 1
	v_cndmask_b32_e32 v96, v235, v96, vcc
	v_lshlrev_b32_e32 v151, 2, v96
	ds_bpermute_b32 v96, v151, v2
	s_waitcnt lgkmcnt(0)
	v_add_f32_e32 v2, v2, v96
	v_xor_b32_e32 v96, 32, v235
	v_cmp_lt_i32_e32 vcc, v96, v97
	s_nop 1
	v_cndmask_b32_e32 v96, v235, v96, vcc
	v_lshlrev_b32_e32 v154, 2, v96
	ds_bpermute_b32 v96, v154, v2
	s_waitcnt lgkmcnt(0)
	v_add_f32_e32 v155, v2, v96
	v_fmamk_f32 v128, v155, 0xbc000000, v145
	v_fmamk_f32 v132, v155, 0xbc000000, v147
	v_fmamk_f32 v129, v155, 0xbc000000, v139
	v_fmac_f32_e32 v138, 0xbc000000, v155
	v_fmamk_f32 v133, v155, 0xbc000000, v143
	v_fmac_f32_e32 v142, 0xbc000000, v155
	v_fmac_f32_e32 v144, 0xbc000000, v155
	v_fmac_f32_e32 v146, 0xbc000000, v155
	v_mov_b32_e32 v147, v142
	v_pk_mul_f32 v[96:97], v[132:133], v[132:133]
	v_mov_b32_e32 v145, v138
	v_pk_mul_f32 v[136:137], v[128:129], v[128:129]
	v_pk_fma_f32 v[96:97], v[146:147], v[146:147], v[96:97]
	v_pk_fma_f32 v[136:137], v[144:145], v[144:145], v[136:137]
	v_fmamk_f32 v135, v155, 0xbc000000, v135
	v_fmac_f32_e32 v134, 0xbc000000, v155
	v_fmamk_f32 v131, v155, 0xbc000000, v131
	v_fmac_f32_e32 v130, 0xbc000000, v155
	v_pk_add_f32 v[96:97], v[96:97], v[136:137]
	v_pk_mul_f32 v[136:137], v[130:131], v[130:131]
	v_pk_mul_f32 v[140:141], v[134:135], v[134:135]
	v_fmac_f32_e32 v126, 0xbc000000, v155
	v_pk_mov_b32 v[152:153], v[140:141], v[136:137] op_sel:[1,0]
	v_mov_b32_e32 v141, v137
	v_fmamk_f32 v127, v155, 0xbc000000, v127
	v_fmac_f32_e32 v124, 0xbc000000, v155
	v_mul_f32_e32 v2, v126, v126
	v_pk_add_f32 v[136:137], v[152:153], v[140:141]
	v_fmamk_f32 v125, v155, 0xbc000000, v125
	v_pk_fma_f32 v[140:141], v[126:127], v[126:127], v[2:3] op_sel_hi:[1,1,0]
	v_mul_f32_e32 v2, v124, v124
	v_pk_add_f32 v[96:97], v[96:97], v[96:97] op_sel_hi:[0,1]
	v_pk_add_f32 v[136:137], v[136:137], v[136:137] op_sel_hi:[0,1]
	v_pk_fma_f32 v[152:153], v[124:125], v[124:125], v[2:3] op_sel_hi:[1,1,0]
	v_fmamk_f32 v139, v155, 0xbc000000, v99
	v_fmac_f32_e32 v98, 0xbc000000, v155
	v_fmamk_f32 v121, v155, 0xbc000000, v121
	v_fmac_f32_e32 v120, 0xbc000000, v155
	v_mul_f32_e32 v140, v120, v120
	v_mul_f32_e32 v152, v121, v121
	v_mul_f32_e32 v136, v98, v98
	v_mul_f32_e32 v96, v139, v139
	v_pk_add_f32 v[140:141], v[140:141], v[152:153]
	v_pk_add_f32 v[96:97], v[136:137], v[96:97]
	v_fmamk_f32 v95, v155, 0xbc000000, v95
	v_fmac_f32_e32 v94, 0xbc000000, v155
	v_fmamk_f32 v93, v155, 0xbc000000, v93
	v_fmac_f32_e32 v92, 0xbc000000, v155
	v_pk_add_f32 v[96:97], v[140:141], v[96:97]
	v_pk_mul_f32 v[136:137], v[92:93], v[92:93]
	v_pk_mul_f32 v[140:141], v[94:95], v[94:95]
	v_fmac_f32_e32 v90, 0xbc000000, v155
	v_pk_mov_b32 v[152:153], v[140:141], v[136:137] op_sel:[1,0]
	v_mov_b32_e32 v141, v137
	v_fmamk_f32 v91, v155, 0xbc000000, v91
	v_fmac_f32_e32 v88, 0xbc000000, v155
	v_mul_f32_e32 v2, v90, v90
	v_pk_add_f32 v[136:137], v[152:153], v[140:141]
	v_fmamk_f32 v89, v155, 0xbc000000, v89
	v_pk_fma_f32 v[140:141], v[90:91], v[90:91], v[2:3] op_sel_hi:[1,1,0]
	v_mul_f32_e32 v2, v88, v88
	v_pk_add_f32 v[96:97], v[96:97], v[96:97] op_sel_hi:[0,1]
	v_pk_add_f32 v[136:137], v[136:137], v[136:137] op_sel_hi:[0,1]
	v_pk_fma_f32 v[152:153], v[88:89], v[88:89], v[2:3] op_sel_hi:[1,1,0]
	v_fmamk_f32 v85, v155, 0xbc000000, v85
	v_fmac_f32_e32 v84, 0xbc000000, v155
	v_fmamk_f32 v99, v155, 0xbc000000, v87
	v_fmac_f32_e32 v86, 0xbc000000, v155
	v_mul_f32_e32 v140, v86, v86
	v_mul_f32_e32 v152, v99, v99
	v_mul_f32_e32 v136, v84, v84
	v_mul_f32_e32 v96, v85, v85
	v_pk_add_f32 v[140:141], v[140:141], v[152:153]
	v_pk_add_f32 v[96:97], v[136:137], v[96:97]
	v_lshlrev_b32_e32 v136, 16, v123
	v_pk_add_f32 v[96:97], v[140:141], v[96:97]
	v_and_b32_e32 v140, 0xffff0000, v123
	v_add_f32_e32 v2, v96, v97
	ds_bpermute_b32 v87, v151, v2
	v_lshlrev_b64 v[96:97], 13, v[114:115]
	v_lshlrev_b32_e32 v114, 16, v122
	v_mul_f32_e32 v115, 0xbfb8aa3b, v114
	v_lshl_add_u64 v[96:97], s[8:9], 0, v[96:97]
	s_waitcnt lgkmcnt(0)
; __device__ __forceinline__ float fast_sigmoid(float x) { return __builtin_amdgcn_rcpf(1.0f + __expf(-x)); }
; #define GAS __attribute__((address_space(1)))
; #define LAS __attribute__((address_space(3)))
; __device__ __forceinline__ unsigned pk2(float lo, float hi) { return pg8::cvt_pk_bf16(lo, hi); }
; __device__ __forceinline__ float bf_lo(unsigned w) { return __uint_as_float(w << 16); }
; __device__ __forceinline__ float bf_hi(unsigned w) { return __uint_as_float(w & 0xffff0000u); }
; __device__ __forceinline__ float fast_rsqrt(float x) { return __builtin_amdgcn_rsqf(x); }
; template <int DIR, bool INTRA, bool FINAL> __device__ __forceinline__ void retention_pass(LAS unsigned char* lds, const bf16* ZH, bf16* YF, bf16* MIX, const float* ld, const float* gn, int seq, int h, int n0, int ncnt, ...
;     ...
;                 const float rstd = fast_rsqrt(q * (1.f / 128.f) + GN_EPS);
;                 bf16* mp = MIX + (size_t)row * D + h * HD + 4 * lg;
; #pragma unroll
;                 for (int e = 0; e < 8; ++e) { const v2u gw2 = gwv[e]; const f32x4 gg = *(const LAS f32x4*)(lds + R_GN + (16 * e + 4 * lg) * 4);
;                     const float g0 = bf_lo(gw2.x), g1 = bf_hi(gw2.x), g2 = bf_lo(gw2.y), g3 = bf_hi(gw2.y);
;                     v2u o; o.x = pk2(g0 * pg8::fast_sigmoid(g0) * (y[e][0] * rstd * gg.x), g1 * pg8::fast_sigmoid(g1) * (y[e][1] * rstd * gg.y));
;                     o.y = pk2(g2 * pg8::fast_sigmoid(g2) * (y[e][2] * rstd * gg.z), g3 * pg8::fast_sigmoid(g3) * (y[e][3] * rstd * gg.w));
;                     *(GAS v2u*)(mp + 16 * e) = o; }
	v_add_f32_e32 v2, v2, v87
	ds_bpermute_b32 v87, v154, v2
	v_exp_f32_e32 v115, v115
	v_and_b32_e32 v122, 0xffff0000, v122
	s_waitcnt lgkmcnt(0)
	v_add_f32_e32 v2, v2, v87
	v_fmamk_f32 v2, v2, 0x3c000000, v234
	v_rsq_f32_e32 v87, v2
	v_lshlrev_b32_e32 v2, 1, v150
	v_lshl_add_u64 v[96:97], v[96:97], 0, v[2:3]
	v_add_u32_e32 v2, 0, v117
	v_add_u32_e32 v2, 0x23000, v2
	ds_read_b128 v[150:153], v2
	v_add_f32_e32 v115, 1.0, v115
	v_rcp_f32_e32 v154, v115
	v_mul_f32_e32 v117, 0xbfb8aa3b, v122
	v_exp_f32_e32 v117, v117
	v_mul_f32_e32 v115, v146, v87
	s_waitcnt lgkmcnt(0)
	v_mov_b32_e32 v155, v150
	v_pk_mul_f32 v[114:115], v[154:155], v[114:115]
	v_mul_f32_e32 v123, v132, v87
	v_mul_f32_e32 v137, v114, v115
	v_add_f32_e32 v114, 1.0, v117
	v_rcp_f32_e32 v150, v114
	v_mul_f32_e32 v114, 0xbfb8aa3b, v136
	v_exp_f32_e32 v117, v114
	v_mul_f32_e32 v141, v128, v87
	v_pk_mul_f32 v[114:115], v[150:151], v[122:123]
	v_mov_b32_e32 v123, v152
	v_mul_f32_e32 v114, v114, v115
	v_add_f32_e32 v115, 1.0, v117
	v_mul_f32_e32 v117, 0xbfb8aa3b, v140
	v_exp_f32_e32 v117, v117
	v_rcp_f32_e32 v122, v115
	v_cvt_pk_bf16_f32 v114, v137, v114
	v_mul_f32_e32 v137, v144, v87
	v_add_f32_e32 v115, 1.0, v117
	v_rcp_f32_e32 v152, v115
	v_pk_mul_f32 v[122:123], v[122:123], v[136:137]
	v_and_b32_e32 v128, 0xffff0000, v113
	v_mul_f32_e32 v115, v122, v123
	v_pk_mul_f32 v[122:123], v[152:153], v[140:141]
	v_mul_f32_e32 v129, v129, v87
	v_mul_f32_e32 v117, v122, v123
	v_cvt_pk_bf16_f32 v115, v115, v117
	global_store_dwordx2 v[96:97], v[114:115], off
	v_lshlrev_b32_e32 v114, 16, v112
	v_mul_f32_e32 v115, 0xbfb8aa3b, v114
	v_exp_f32_e32 v115, v115
	v_and_b32_e32 v112, 0xffff0000, v112
	v_lshlrev_b32_e32 v122, 16, v113
	ds_read_b128 v[144:147], v2 offset:64
	v_add_f32_e32 v113, 1.0, v115
	v_rcp_f32_e32 v136, v113
	v_mul_f32_e32 v113, 0xbfb8aa3b, v112
	v_exp_f32_e32 v113, v113
	v_mul_f32_e32 v115, v142, v87
	s_waitcnt lgkmcnt(0)
	v_mov_b32_e32 v137, v144
	v_pk_mul_f32 v[114:115], v[136:137], v[114:115]
	v_add_f32_e32 v113, 1.0, v113
	v_rcp_f32_e32 v144, v113
	v_mul_f32_e32 v114, v114, v115
	v_mul_f32_e32 v115, 0xbfb8aa3b, v122
	v_exp_f32_e32 v115, v115
	v_mul_f32_e32 v113, v133, v87
	v_pk_mul_f32 v[112:113], v[144:145], v[112:113]
	v_mul_f32_e32 v123, v138, v87
	v_mul_f32_e32 v112, v112, v113
	v_cvt_pk_bf16_f32 v112, v114, v112
	v_add_f32_e32 v113, 1.0, v115
	v_mul_f32_e32 v114, 0xbfb8aa3b, v128
	v_exp_f32_e32 v117, v114
	v_rcp_f32_e32 v114, v113
	v_mov_b32_e32 v115, v146
	v_and_b32_e32 v132, 0xffff0000, v111
	v_add_f32_e32 v113, 1.0, v117
	v_pk_mul_f32 v[114:115], v[114:115], v[122:123]
	v_lshlrev_b32_e32 v122, 16, v110
	v_mul_f32_e32 v117, 0xbfb8aa3b, v122
	v_rcp_f32_e32 v146, v113
	v_exp_f32_e32 v117, v117
	v_mul_f32_e32 v113, v114, v115
	v_and_b32_e32 v110, 0xffff0000, v110
	v_pk_mul_f32 v[114:115], v[146:147], v[128:129]
	v_lshlrev_b32_e32 v128, 16, v111
	v_add_f32_e32 v111, 1.0, v117
	v_mul_f32_e32 v114, v114, v115
	v_cvt_pk_bf16_f32 v113, v113, v114
	v_rcp_f32_e32 v136, v111
	v_mul_f32_e32 v111, 0xbfb8aa3b, v110
	global_store_dwordx2 v[96:97], v[112:113], off offset:32
	ds_read_b128 v[112:115], v2 offset:128
	v_exp_f32_e32 v111, v111
	v_mul_f32_e32 v123, v134, v87
	v_mul_f32_e32 v129, v130, v87
	v_mul_f32_e32 v133, v131, v87
	v_add_f32_e32 v111, 1.0, v111
	s_waitcnt lgkmcnt(0)
	v_mov_b32_e32 v137, v112
	v_rcp_f32_e32 v112, v111
	v_pk_mul_f32 v[122:123], v[136:137], v[122:123]
	v_mul_f32_e32 v111, v135, v87
	v_mul_f32_e32 v117, v122, v123
	v_mul_f32_e32 v122, 0xbfb8aa3b, v128
	v_pk_mul_f32 v[110:111], v[112:113], v[110:111]
	v_exp_f32_e32 v122, v122
	v_mul_f32_e32 v110, v110, v111
	v_mul_f32_e32 v112, 0xbfb8aa3b, v132
	v_cvt_pk_bf16_f32 v110, v117, v110
	v_exp_f32_e32 v117, v112
	v_add_f32_e32 v111, 1.0, v122
	v_rcp_f32_e32 v112, v111
	v_mov_b32_e32 v113, v114
	v_add_f32_e32 v111, 1.0, v117
	v_rcp_f32_e32 v114, v111
	v_pk_mul_f32 v[112:113], v[112:113], v[128:129]
	v_lshlrev_b32_e32 v122, 16, v109
	v_mul_f32_e32 v111, v112, v113
	v_pk_mul_f32 v[112:113], v[114:115], v[132:133]
	v_lshlrev_b32_e32 v114, 16, v108
	v_mul_f32_e32 v115, 0xbfb8aa3b, v114
	v_exp_f32_e32 v115, v115
	v_and_b32_e32 v108, 0xffff0000, v108
	v_and_b32_e32 v128, 0xffff0000, v109
	v_mul_f32_e32 v112, v112, v113
	v_add_f32_e32 v109, 1.0, v115
	v_cvt_pk_bf16_f32 v111, v111, v112
	v_rcp_f32_e32 v130, v109
	v_mul_f32_e32 v109, 0xbfb8aa3b, v108
	global_store_dwordx2 v[96:97], v[110:111], off offset:64
	ds_read_b128 v[110:113], v2 offset:192
	v_exp_f32_e32 v109, v109
	v_mul_f32_e32 v115, v126, v87
	v_mul_f32_e32 v123, v124, v87
	v_mul_f32_e32 v129, v125, v87
	v_add_f32_e32 v109, 1.0, v109
	s_waitcnt lgkmcnt(0)
	v_mov_b32_e32 v131, v110
	v_rcp_f32_e32 v110, v109
	v_pk_mul_f32 v[114:115], v[130:131], v[114:115]
	v_mul_f32_e32 v109, v127, v87
	v_mul_f32_e32 v114, v114, v115
	v_mul_f32_e32 v115, 0xbfb8aa3b, v122
	v_pk_mul_f32 v[108:109], v[110:111], v[108:109]
	v_exp_f32_e32 v115, v115
	v_mul_f32_e32 v108, v108, v109
	v_mul_f32_e32 v110, 0xbfb8aa3b, v128
	v_cvt_pk_bf16_f32 v108, v114, v108
	v_exp_f32_e32 v114, v110
	v_add_f32_e32 v109, 1.0, v115
	v_rcp_f32_e32 v110, v109
	v_mov_b32_e32 v111, v112
	v_add_f32_e32 v109, 1.0, v114
	v_rcp_f32_e32 v112, v109
	v_pk_mul_f32 v[110:111], v[110:111], v[122:123]
	s_waitcnt vmcnt(6)
	v_lshlrev_b32_e32 v114, 16, v107
	v_mul_f32_e32 v109, v110, v111
	v_pk_mul_f32 v[110:111], v[112:113], v[128:129]
	v_lshlrev_b32_e32 v112, 16, v106
	v_mul_f32_e32 v113, 0xbfb8aa3b, v112
	v_exp_f32_e32 v113, v113
	v_and_b32_e32 v106, 0xffff0000, v106
	v_and_b32_e32 v122, 0xffff0000, v107
	v_mul_f32_e32 v110, v110, v111
	v_add_f32_e32 v107, 1.0, v113
	v_cvt_pk_bf16_f32 v109, v109, v110
	v_rcp_f32_e32 v124, v107
	v_mul_f32_e32 v107, 0xbfb8aa3b, v106
	global_store_dwordx2 v[96:97], v[108:109], off offset:96
	ds_read_b128 v[108:111], v2 offset:256
	v_exp_f32_e32 v107, v107
	v_mul_f32_e32 v113, v120, v87
	v_mul_f32_e32 v115, v98, v87
	v_mul_f32_e32 v123, v139, v87
	v_add_f32_e32 v107, 1.0, v107
	s_waitcnt lgkmcnt(0)
; __device__ __forceinline__ float fast_sigmoid(float x) { return __builtin_amdgcn_rcpf(1.0f + __expf(-x)); }
; #define GAS __attribute__((address_space(1)))
; #define LAS __attribute__((address_space(3)))
; __device__ __forceinline__ unsigned pk2(float lo, float hi) { return pg8::cvt_pk_bf16(lo, hi); }
; __device__ __forceinline__ float bf_lo(unsigned w) { return __uint_as_float(w << 16); }
; __device__ __forceinline__ float bf_hi(unsigned w) { return __uint_as_float(w & 0xffff0000u); }
; template <int DIR, bool INTRA, bool FINAL> __device__ __forceinline__ void retention_pass(LAS unsigned char* lds, const bf16* ZH, bf16* YF, bf16* MIX, const float* ld, const float* gn, int seq, int h, int n0, int ncnt, ...
;     ...
; #pragma unroll
;                 for (int e = 0; e < 8; ++e) { const v2u gw2 = gwv[e]; const f32x4 gg = *(const LAS f32x4*)(lds + R_GN + (16 * e + 4 * lg) * 4);
;                     const float g0 = bf_lo(gw2.x), g1 = bf_hi(gw2.x), g2 = bf_lo(gw2.y), g3 = bf_hi(gw2.y);
;                     v2u o; o.x = pk2(g0 * pg8::fast_sigmoid(g0) * (y[e][0] * rstd * gg.x), g1 * pg8::fast_sigmoid(g1) * (y[e][1] * rstd * gg.y));
;                     o.y = pk2(g2 * pg8::fast_sigmoid(g2) * (y[e][2] * rstd * gg.z), g3 * pg8::fast_sigmoid(g3) * (y[e][3] * rstd * gg.w));
;                     *(GAS v2u*)(mp + 16 * e) = o; }
	v_mov_b32_e32 v125, v108
	v_rcp_f32_e32 v108, v107
	v_pk_mul_f32 v[112:113], v[124:125], v[112:113]
	v_mul_f32_e32 v107, v121, v87
	v_mul_f32_e32 v112, v112, v113
	v_mul_f32_e32 v113, 0xbfb8aa3b, v114
	v_pk_mul_f32 v[106:107], v[108:109], v[106:107]
	v_exp_f32_e32 v113, v113
	v_mul_f32_e32 v106, v106, v107
	v_mul_f32_e32 v108, 0xbfb8aa3b, v122
	v_cvt_pk_bf16_f32 v106, v112, v106
	v_exp_f32_e32 v112, v108
	v_add_f32_e32 v107, 1.0, v113
	v_rcp_f32_e32 v108, v107
	v_mov_b32_e32 v109, v110
	v_add_f32_e32 v98, 1.0, v112
	v_rcp_f32_e32 v110, v98
	v_pk_mul_f32 v[108:109], v[108:109], v[114:115]
	v_mul_f32_e32 v121, v94, v87
	v_mul_f32_e32 v98, v108, v109
	v_pk_mul_f32 v[108:109], v[110:111], v[122:123]
	s_waitcnt vmcnt(6)
	v_lshlrev_b32_e32 v110, 16, v104
	v_mul_f32_e32 v107, v108, v109
	v_and_b32_e32 v104, 0xffff0000, v104
	v_cvt_pk_bf16_f32 v107, v98, v107
	v_mul_f32_e32 v94, 0xbfb8aa3b, v104
	global_store_dwordx2 v[96:97], v[106:107], off offset:128
	ds_read_b128 v[106:109], v2 offset:320
	v_exp_f32_e32 v94, v94
	v_lshlrev_b32_e32 v112, 16, v105
	v_and_b32_e32 v114, 0xffff0000, v105
	v_mul_f32_e32 v95, v95, v87
	v_add_f32_e32 v94, 1.0, v94
	s_waitcnt lgkmcnt(0)
	v_mov_b32_e32 v111, v106
	v_rcp_f32_e32 v94, v94
	v_mul_f32_e32 v106, 0xbfb8aa3b, v112
	v_exp_f32_e32 v106, v106
	v_mov_b32_e32 v105, v107
	v_pk_mul_f32 v[94:95], v[94:95], v[104:105]
	v_mul_f32_e32 v98, 0xbfb8aa3b, v110
	v_mul_f32_e32 v94, v94, v95
	v_add_f32_e32 v95, 1.0, v106
	v_exp_f32_e32 v98, v98
	v_rcp_f32_e32 v104, v95
	v_mul_f32_e32 v95, 0xbfb8aa3b, v114
	v_exp_f32_e32 v95, v95
	v_add_f32_e32 v98, 1.0, v98
	v_rcp_f32_e32 v120, v98
	v_mul_f32_e32 v105, v92, v87
	v_add_f32_e32 v92, 1.0, v95
	v_rcp_f32_e32 v92, v92
	v_mov_b32_e32 v113, v108
	v_pk_mul_f32 v[110:111], v[120:121], v[110:111]
	v_pk_mul_f32 v[104:105], v[104:105], v[112:113]
	v_mul_f32_e32 v93, v93, v87
	v_mov_b32_e32 v115, v109
	v_mul_f32_e32 v98, v110, v111
	v_mul_f32_e32 v95, v104, v105
	v_pk_mul_f32 v[92:93], v[92:93], v[114:115]
	s_waitcnt vmcnt(6)
	v_lshlrev_b32_e32 v104, 16, v102
	v_and_b32_e32 v102, 0xffff0000, v102
	v_cvt_pk_bf16_f32 v94, v98, v94
	v_mul_f32_e32 v92, v92, v93
	v_cvt_pk_bf16_f32 v95, v95, v92
	v_mul_f32_e32 v98, 0xbfb8aa3b, v104
	v_mul_f32_e32 v111, v90, v87
	v_mul_f32_e32 v90, 0xbfb8aa3b, v102
	global_store_dwordx2 v[96:97], v[94:95], off offset:160
	ds_read_b128 v[92:95], v2 offset:384
	v_exp_f32_e32 v98, v98
	v_exp_f32_e32 v90, v90
	v_lshlrev_b32_e32 v106, 16, v103
	v_and_b32_e32 v108, 0xffff0000, v103
	v_add_f32_e32 v98, 1.0, v98
	v_add_f32_e32 v90, 1.0, v90
	v_rcp_f32_e32 v110, v98
	v_rcp_f32_e32 v90, v90
	s_waitcnt lgkmcnt(0)
	v_mov_b32_e32 v103, v93
	v_mul_f32_e32 v93, 0xbfb8aa3b, v106
	v_exp_f32_e32 v93, v93
	v_mov_b32_e32 v105, v92
	v_mul_f32_e32 v91, v91, v87
	v_pk_mul_f32 v[104:105], v[110:111], v[104:105]
	v_pk_mul_f32 v[90:91], v[90:91], v[102:103]
	v_mul_f32_e32 v92, v104, v105
	v_mul_f32_e32 v90, v90, v91
	v_add_f32_e32 v91, 1.0, v93
	v_cvt_pk_bf16_f32 v90, v92, v90
	v_rcp_f32_e32 v92, v91
	v_mul_f32_e32 v91, 0xbfb8aa3b, v108
	v_exp_f32_e32 v91, v91
	v_mul_f32_e32 v93, v88, v87
	v_mov_b32_e32 v107, v94
	v_pk_mul_f32 v[92:93], v[92:93], v[106:107]
	v_add_f32_e32 v88, 1.0, v91
	v_rcp_f32_e32 v88, v88
	v_mul_f32_e32 v89, v89, v87
	v_mov_b32_e32 v109, v95
	v_mul_f32_e32 v91, v92, v93
	v_pk_mul_f32 v[88:89], v[88:89], v[108:109]
	s_waitcnt vmcnt(6)
	v_lshlrev_b32_e32 v92, 16, v100
	v_mul_f32_e32 v88, v88, v89
	v_cvt_pk_bf16_f32 v91, v91, v88
	global_store_dwordx2 v[96:97], v[90:91], off offset:192
	ds_read_b128 v[88:91], v2 offset:448
	v_mul_f32_e32 v2, 0xbfb8aa3b, v92
	v_exp_f32_e32 v2, v2
	v_and_b32_e32 v94, 0xffff0000, v100
	v_mul_f32_e32 v103, v86, v87
	s_waitcnt lgkmcnt(0)
	v_mov_b32_e32 v93, v88
	v_add_f32_e32 v2, 1.0, v2
	v_rcp_f32_e32 v102, v2
	v_mul_f32_e32 v2, 0xbfb8aa3b, v94
	v_exp_f32_e32 v2, v2
	v_lshlrev_b32_e32 v98, 16, v101
	v_pk_mul_f32 v[92:93], v[102:103], v[92:93]
	v_mov_b32_e32 v95, v89
	v_add_f32_e32 v2, 1.0, v2
	v_mul_f32_e32 v86, v92, v93
	v_rcp_f32_e32 v92, v2
	v_mul_f32_e32 v2, 0xbfb8aa3b, v98
	v_exp_f32_e32 v2, v2
	v_mul_f32_e32 v93, v99, v87
	v_pk_mul_f32 v[88:89], v[92:93], v[94:95]
	v_and_b32_e32 v100, 0xffff0000, v101
	v_mul_f32_e32 v88, v88, v89
	v_add_f32_e32 v2, 1.0, v2
	v_cvt_pk_bf16_f32 v86, v86, v88
	v_rcp_f32_e32 v88, v2
	v_mul_f32_e32 v2, 0xbfb8aa3b, v100
	v_exp_f32_e32 v2, v2
	v_mul_f32_e32 v89, v84, v87
	v_mov_b32_e32 v99, v90
	v_mul_f32_e32 v85, v85, v87
	v_add_f32_e32 v2, 1.0, v2
	v_rcp_f32_e32 v84, v2
	v_mov_b32_e32 v101, v91
	v_pk_mul_f32 v[88:89], v[88:89], v[98:99]
	v_pk_mul_f32 v[84:85], v[84:85], v[100:101]
	v_mul_f32_e32 v2, v88, v89
	v_mul_f32_e32 v84, v84, v85
	v_cvt_pk_bf16_f32 v87, v2, v84
	global_store_dwordx2 v[96:97], v[86:87], off offset:224
	s_cbranch_scc0 .LBB0_715
; #define LAS __attribute__((address_space(3)))
; #define WG_BARRIER() do { asm volatile("s_waitcnt lgkmcnt(0)" ::: "memory"); __builtin_amdgcn_s_barrier(); asm volatile("" ::: "memory"); } while (0)
; __device__ __forceinline__ unsigned pk2(float lo, float hi) { return pg8::cvt_pk_bf16(lo, hi); }
; __device__ __forceinline__ v4u scale8(v4u x, float sc) { v4u o; o.x = pk2(bf_lo(x.x) * sc, bf_hi(x.x) * sc); o.y = pk2(bf_lo(x.y) * sc, bf_hi(x.y) * sc); o.z = pk2(bf_lo(x.z) * sc, bf_hi(x.z) * sc); o.w = pk2(bf_lo(x.w) * sc, bf_hi(x.w) * sc); return o; }
; template <int DIR, bool INTRA, bool FINAL> __device__ __forceinline__ void retention_pass(LAS unsigned char* lds, const bf16* ZH, bf16* YF, bf16* MIX, const float* ld, const float* gn, int seq, int h, int n0, int ncnt, ...
;     ...
;             const int n = DIR == 0 ? n0 + cn : n0 + ncnt - 1 - cn, nn = DIR == 0 ? n + 1 : n - 1;
;             const int r0 = rowbase + n * 128;
;             int tid = tid0; float lf = lf0, lb = lb0; asm volatile("" : "+v"(tid), "+v"(lf), "+v"(lb));
;             const int w = tid >> 6, l = tid & 63, lr = l & 15, lg = l >> 4, srow = tid >> 4, sch = tid & 15;
;             LAS unsigned char* trp = lds + (4 * lg + ((l & 15) >> 2)) * RSB + (l & 3) * 8;
;             WG_BARRIER();
; #pragma unroll
;             for (int cc = 0; cc < 4; ++cc) { const int row = srow + 32 * cc;
;                 if constexpr (INTRA) *(LAS v4u*)(lds + R_K + row * RS + 16 * sch) = kreg[cc];
;                 const float wj = DIR == 0 ? __expf(lf * (float)(127 - row)) : __expf(lb * (float)row);
;                 *(LAS v4u*)(lds + R_KW + row * RSB + 16 * sch) = scale8(kreg[cc], wj);
;                 *(LAS v4u*)(lds + R_V + row * RSB + 16 * sch) = vreg[cc]; }
; #pragma unroll
;             for (int e = 0; e < 8; ++e) { v2u o; o.x = pk2(st[e][0], st[e][1]); o.y = pk2(st[e][2], st[e][3]); *(LAS v2u*)(lds + R_ST + (16 * e + lr) * RS + (16 * w + 4 * lg) * 2) = o; }
;             WG_BARRIER();
;             bf16x8 qx[4];
;             { const float xi = DIR == 0 ? __expf(lf * (float)(16 * w + lr + 1)) : __expf(lb * (float)(128 - 16 * w - lr));
.LBB0_713:
	v_mov_b32_e32 v2, v148
	v_mov_b32_e32 v88, v190
	v_mov_b32_e32 v89, v149
	s_waitcnt vmcnt(11)
	v_and_b32_e32 v85, 0xffff0000, v4
	v_ashrrev_i32_e32 v121, 4, v88
	v_cvt_f32_i32_e32 v84, v121
	s_waitcnt lgkmcnt(0)
	s_barrier
	v_mul_f32_e32 v84, v89, v84
	v_mul_f32_e32 v84, 0x3fb8aa3b, v84
	v_exp_f32_e32 v87, v84
	v_lshlrev_b32_e32 v84, 16, v4
	v_and_b32_e32 v86, 0xffff0000, v5
	v_bfe_u32 v142, v88, 4, 2
	v_mul_f32_e32 v84, v87, v84
	v_mul_f32_e32 v85, v87, v85
	v_cvt_pk_bf16_f32 v84, v84, v85
	v_lshlrev_b32_e32 v85, 16, v5
	v_mul_f32_e32 v85, v87, v85
	v_mul_f32_e32 v86, v87, v86
	v_cvt_pk_bf16_f32 v85, v85, v86
	v_lshlrev_b32_e32 v86, 16, v6
	v_and_b32_e32 v92, 0xffff0000, v6
	v_lshlrev_b32_e32 v150, 2, v142
	v_bfe_u32 v2, v88, 2, 2
	v_mul_f32_e32 v86, v87, v86
	v_mul_f32_e32 v92, v87, v92
	v_and_b32_e32 v90, 15, v88
	v_or_b32_e32 v2, v150, v2
	v_cvt_pk_bf16_f32 v86, v86, v92
	v_lshlrev_b32_e32 v92, 16, v7
	v_and_b32_e32 v93, 0xffff0000, v7
	v_mul_u32_u24_e32 v100, 0x120, v2
	v_lshlrev_b32_e32 v2, 3, v88
	v_lshlrev_b32_e32 v120, 4, v90
	v_mul_f32_e32 v92, v87, v92
	v_mul_f32_e32 v87, v87, v93
	v_and_b32_e32 v101, 24, v2
	v_add_u32_e32 v2, 0, v120
	v_cvt_pk_bf16_f32 v87, v92, v87
	v_mul_lo_u32 v92, v121, s74
	v_add_u32_e32 v91, s93, v120
	v_add_u32_e32 v93, v2, v92
	ds_write_b128 v93, v[84:87] offset:34816
	v_add_u32_e32 v84, v91, v92
	s_waitcnt vmcnt(10)
	ds_write_b128 v84, v[8:11]
	v_add_u32_e32 v84, 32, v121
	v_cvt_f32_i32_e32 v84, v84
	s_waitcnt vmcnt(9)
	v_and_b32_e32 v85, 0xffff0000, v12
	v_and_b32_e32 v86, 0xffff0000, v13
	v_and_b32_e32 v93, 0xffff0000, v14
	v_mul_f32_e32 v84, v89, v84
	v_mul_f32_e32 v84, 0x3fb8aa3b, v84
	v_exp_f32_e32 v87, v84
	v_lshlrev_b32_e32 v84, 16, v12
	v_and_b32_e32 v94, 0xffff0000, v15
	v_mul_u32_u24_e32 v143, 0x110, v90
	v_mul_f32_e32 v84, v87, v84
	v_mul_f32_e32 v85, v87, v85
	v_cvt_pk_bf16_f32 v84, v84, v85
	v_lshlrev_b32_e32 v85, 16, v13
	v_mul_f32_e32 v85, v87, v85
	v_mul_f32_e32 v86, v87, v86
	v_cvt_pk_bf16_f32 v85, v85, v86
	v_lshlrev_b32_e32 v86, 16, v14
	v_mul_f32_e32 v86, v87, v86
	v_mul_f32_e32 v93, v87, v93
	v_cvt_pk_bf16_f32 v86, v86, v93
	v_lshlrev_b32_e32 v93, 16, v15
	v_mul_f32_e32 v93, v87, v93
	v_mul_f32_e32 v87, v87, v94
	v_cvt_pk_bf16_f32 v87, v93, v87
	v_add_u32_e32 v93, 0x2400, v92
	v_add_u32_e32 v94, v2, v93
	ds_write_b128 v94, v[84:87] offset:34816
	v_add_u32_e32 v84, v91, v93
	s_waitcnt vmcnt(8)
	ds_write_b128 v84, v[16:19]
	v_add_u32_e32 v84, 64, v121
	v_cvt_f32_i32_e32 v84, v84
	s_waitcnt vmcnt(7)
	v_and_b32_e32 v85, 0xffff0000, v20
	v_and_b32_e32 v86, 0xffff0000, v21
	v_and_b32_e32 v93, 0xffff0000, v22
	v_mul_f32_e32 v84, v89, v84
	v_mul_f32_e32 v84, 0x3fb8aa3b, v84
	v_exp_f32_e32 v87, v84
	v_lshlrev_b32_e32 v84, 16, v20
	v_and_b32_e32 v94, 0xffff0000, v23
	s_waitcnt vmcnt(1)
	v_and_b32_e32 v95, 0xffff0000, v46
	v_mul_f32_e32 v84, v87, v84
	v_mul_f32_e32 v85, v87, v85
	v_cvt_pk_bf16_f32 v84, v84, v85
	v_lshlrev_b32_e32 v85, 16, v21
	v_mul_f32_e32 v85, v87, v85
	v_mul_f32_e32 v86, v87, v86
	v_cvt_pk_bf16_f32 v85, v85, v86
	v_lshlrev_b32_e32 v86, 16, v22
	v_mul_f32_e32 v86, v87, v86
	v_mul_f32_e32 v93, v87, v93
	v_cvt_pk_bf16_f32 v86, v86, v93
	v_lshlrev_b32_e32 v93, 16, v23
	v_mul_f32_e32 v93, v87, v93
	v_mul_f32_e32 v87, v87, v94
	v_cvt_pk_bf16_f32 v87, v93, v87
	v_add_u32_e32 v93, 0x4800, v92
	v_add_u32_e32 v94, v2, v93
	ds_write_b128 v94, v[84:87] offset:34816
	v_add_u32_e32 v84, v91, v93
	ds_write_b128 v84, v[24:27]
	v_add_u32_e32 v84, 0x60, v121
	v_cvt_f32_i32_e32 v84, v84
	v_and_b32_e32 v85, 0xffff0000, v28
	v_and_b32_e32 v86, 0xffff0000, v29
	v_and_b32_e32 v93, 0xffff0000, v30
	v_mul_f32_e32 v84, v89, v84
	v_mul_f32_e32 v84, 0x3fb8aa3b, v84
	v_exp_f32_e32 v87, v84
	v_lshlrev_b32_e32 v84, 16, v28
	v_and_b32_e32 v94, 0xffff0000, v31
	v_add_u32_e32 v92, 0x6c00, v92
	v_mul_f32_e32 v84, v87, v84
	v_mul_f32_e32 v85, v87, v85
	v_cvt_pk_bf16_f32 v84, v84, v85
	v_lshlrev_b32_e32 v85, 16, v29
	v_mul_f32_e32 v85, v87, v85
	v_mul_f32_e32 v86, v87, v86
	v_cvt_pk_bf16_f32 v85, v85, v86
	v_lshlrev_b32_e32 v86, 16, v30
	v_mul_f32_e32 v86, v87, v86
	v_mul_f32_e32 v93, v87, v93
	v_cvt_pk_bf16_f32 v86, v86, v93
	v_lshlrev_b32_e32 v93, 16, v31
	v_mul_f32_e32 v93, v87, v93
	v_mul_f32_e32 v87, v87, v94
	v_add_u32_e32 v2, v2, v92
	v_cvt_pk_bf16_f32 v87, v93, v87
	ds_write_b128 v2, v[84:87] offset:34816
	v_ashrrev_i32_e32 v86, 6, v88
	v_add_u32_e32 v2, v91, v92
	v_lshlrev_b32_e32 v102, 5, v86
	ds_write_b128 v2, v[32:35]
	v_lshlrev_b32_e32 v2, 3, v142
	v_add_u32_e32 v87, s95, v102
	v_cvt_pk_bf16_f32 v84, v52, v53
	v_add3_u32 v87, v87, v2, v143
	v_cvt_pk_bf16_f32 v85, v54, v55
	ds_write_b64 v87, v[84:85]
	v_cvt_pk_bf16_f32 v84, v56, v57
	v_cvt_pk_bf16_f32 v85, v58, v59
	ds_write_b64 v87, v[84:85] offset:4352
	v_cvt_pk_bf16_f32 v84, v60, v61
	v_cvt_pk_bf16_f32 v85, v62, v63
	ds_write_b64 v87, v[84:85] offset:8704
	v_cvt_pk_bf16_f32 v84, v64, v65
	v_cvt_pk_bf16_f32 v85, v66, v67
	ds_write_b64 v87, v[84:85] offset:13056
	v_cvt_pk_bf16_f32 v84, v68, v69
	v_cvt_pk_bf16_f32 v85, v70, v71
	ds_write_b64 v87, v[84:85] offset:17408
	v_cvt_pk_bf16_f32 v84, v72, v73
	v_cvt_pk_bf16_f32 v85, v74, v75
	ds_write_b64 v87, v[84:85] offset:21760
	v_cvt_pk_bf16_f32 v84, v76, v77
	v_cvt_pk_bf16_f32 v85, v78, v79
	ds_write_b64 v87, v[84:85] offset:26112
	v_cvt_pk_bf16_f32 v84, v80, v81
	v_lshl_or_b32 v122, v86, 4, v90
	v_cvt_pk_bf16_f32 v85, v82, v83
	ds_write_b64 v87, v[84:85] offset:30464
	v_sub_u32_e32 v84, 0x80, v122
	v_cvt_f32_i32_e32 v84, v84
	v_and_b32_e32 v85, 0xffff0000, v36
	s_waitcnt lgkmcnt(0)
	s_barrier
; #define LAS __attribute__((address_space(3)))
; template <int DIR, bool INTRA, bool FINAL> __device__ __forceinline__ void retention_pass(LAS unsigned char* lds, const bf16* ZH, bf16* YF, bf16* MIX, const float* ld, const float* gn, int seq, int h, int n0, int ncnt, ...
;     ...
;             { const float xi = DIR == 0 ? __expf(lf * (float)(16 * w + lr + 1)) : __expf(lb * (float)(128 - 16 * w - lr));
; #pragma unroll
;               for (int ks = 0; ks < 4; ++ks) qx[ks] = __builtin_bit_cast(bf16x8, scale8(__builtin_bit_cast(v4u, qf[ks]), xi)); }
;             bf16x8 pt[4];
;             if constexpr (INTRA) {
;                 f32x4 s[8];
; #pragma unroll
;                 for (int jt = 0; jt < 8; ++jt) { s[jt] = (f32x4){0.f, 0.f, 0.f, 0.f};
; #pragma unroll
;                     for (int ks = 0; ks < 4; ++ks) { const bf16x8 a = *(const LAS bf16x8*)(lds + R_K + (16 * jt + lr) * RS + (8 * lg + 32 * ks) * 2); s[jt] = MFMA16(a, qf[ks], s[jt]); }
;                     __builtin_amdgcn_sched_barrier(0); }
;                 float Fr[4], Br[4];
; #pragma unroll
;                 for (int r = 0; r < 4; ++r) { const float br = (float)(lr - 4 * lg - r); Fr[r] = __expf(lf * br); Br[r] = __expf(-lb * br); }
; #pragma unroll
;                 for (int jt = 0; jt < 8; ++jt) { const int dt = w - jt; const float cf = __expf(lf * 16.f * (float)dt), cb = __expf(-lb * 16.f * (float)dt);
; #pragma unroll
;                     for (int r = 0; r < 4; ++r) { const float dec = dt > 0 ? Fr[r] * cf : (dt < 0 ? Br[r] * cb : ((lr - 4 * lg - r) >= 0 ? Fr[r] : Br[r])); s[jt][r] *= dec; } }
; #pragma unroll
;                 for (int ks = 0; ks < 4; ++ks) { v4u o; o.x = pk2(s[2 * ks][0], s[2 * ks][1]); o.y = pk2(s[2 * ks][2], s[2 * ks][3]); o.z = pk2(s[2 * ks + 1][0], s[2 * ks + 1][1]); o.w = pk2(s[2 * ks + 1][2], s[2 * ks + 1][3]); pt[ks] = __builtin_bit_cast(bf16x8, o); }
;             }
;             f32x4 y[8];
; #pragma unroll
;             for (int e = 0; e < 8; ++e) y[e] = (f32x4){0.f, 0.f, 0.f, 0.f};
;             { bf16x8 kwf[4];
; #pragma unroll
;               for (int ks = 0; ks < 4; ++ks) kwf[ks] = ds_tr2(trp + R_KW + (32 * ks) * RSB + (16 * w) * 2, RSB);
; #pragma unroll
;               for (int e = 0; e < 8; ++e) { st[e] = st[e] * gC;
; #pragma unroll
;                 for (int ks = 0; ks < 4; ++ks) { const bf16x8 vf = ds_tr2(trp + R_V + (32 * ks) * RSB + (16 * e) * 2, RSB);
	s_waitcnt lgkmcnt(0)
	v_mul_f32_e32 v84, v89, v84
	v_mul_f32_e32 v84, 0x3fb8aa3b, v84
	v_exp_f32_e32 v99, v84
	v_lshlrev_b32_e32 v84, 16, v36
	v_and_b32_e32 v86, 0xffff0000, v37
	v_mul_f32_e32 v84, v99, v84
	v_mul_f32_e32 v85, v99, v85
	v_cvt_pk_bf16_f32 v84, v84, v85
	v_lshlrev_b32_e32 v85, 16, v37
	v_mul_f32_e32 v85, v99, v85
	v_mul_f32_e32 v86, v99, v86
	v_cvt_pk_bf16_f32 v85, v85, v86
	v_lshlrev_b32_e32 v86, 16, v38
	v_and_b32_e32 v87, 0xffff0000, v38
	v_mul_f32_e32 v86, v99, v86
	v_mul_f32_e32 v87, v99, v87
	v_cvt_pk_bf16_f32 v86, v86, v87
	v_lshlrev_b32_e32 v87, 16, v39
	v_and_b32_e32 v88, 0xffff0000, v39
	v_mul_f32_e32 v87, v99, v87
	v_mul_f32_e32 v88, v99, v88
	v_cvt_pk_bf16_f32 v87, v87, v88
	v_lshlrev_b32_e32 v88, 16, v40
	v_and_b32_e32 v89, 0xffff0000, v40
	v_mul_f32_e32 v88, v99, v88
	v_mul_f32_e32 v89, v99, v89
	v_cvt_pk_bf16_f32 v88, v88, v89
	v_lshlrev_b32_e32 v89, 16, v41
	v_and_b32_e32 v90, 0xffff0000, v41
	v_mul_f32_e32 v89, v99, v89
	v_mul_f32_e32 v90, v99, v90
	v_cvt_pk_bf16_f32 v89, v89, v90
	v_lshlrev_b32_e32 v90, 16, v42
	v_and_b32_e32 v91, 0xffff0000, v42
	v_mul_f32_e32 v90, v99, v90
	v_mul_f32_e32 v91, v99, v91
	v_cvt_pk_bf16_f32 v90, v90, v91
	v_lshlrev_b32_e32 v91, 16, v43
	v_and_b32_e32 v92, 0xffff0000, v43
	v_mul_f32_e32 v91, v99, v91
	v_mul_f32_e32 v92, v99, v92
	v_cvt_pk_bf16_f32 v91, v91, v92
	v_lshlrev_b32_e32 v92, 16, v44
	v_and_b32_e32 v93, 0xffff0000, v44
	v_mul_f32_e32 v92, v99, v92
	v_mul_f32_e32 v93, v99, v93
	v_cvt_pk_bf16_f32 v92, v92, v93
	v_lshlrev_b32_e32 v93, 16, v45
	v_and_b32_e32 v94, 0xffff0000, v45
	v_mul_f32_e32 v93, v99, v93
	v_mul_f32_e32 v94, v99, v94
	v_cvt_pk_bf16_f32 v93, v93, v94
	v_lshlrev_b32_e32 v94, 16, v46
	v_mul_f32_e32 v94, v99, v94
	v_mul_f32_e32 v95, v99, v95
	v_cvt_pk_bf16_f32 v94, v94, v95
	v_lshlrev_b32_e32 v95, 16, v47
	v_and_b32_e32 v96, 0xffff0000, v47
	v_mul_f32_e32 v95, v99, v95
	v_mul_f32_e32 v96, v99, v96
	v_cvt_pk_bf16_f32 v95, v95, v96
	s_waitcnt vmcnt(0)
	v_lshlrev_b32_e32 v96, 16, v48
	v_and_b32_e32 v97, 0xffff0000, v48
	v_mul_f32_e32 v96, v99, v96
	v_mul_f32_e32 v97, v99, v97
	v_cvt_pk_bf16_f32 v96, v96, v97
	v_lshlrev_b32_e32 v97, 16, v49
	v_and_b32_e32 v98, 0xffff0000, v49
	v_mul_f32_e32 v97, v99, v97
	v_mul_f32_e32 v98, v99, v98
	v_cvt_pk_bf16_f32 v97, v97, v98
	v_lshlrev_b32_e32 v98, 16, v50
	v_and_b32_e32 v103, 0xffff0000, v50
	v_mul_f32_e32 v98, v99, v98
	v_mul_f32_e32 v103, v99, v103
	v_add3_u32 v123, 0, v100, v101
	v_cvt_pk_bf16_f32 v98, v98, v103
	v_lshlrev_b32_e32 v103, 16, v51
	v_and_b32_e32 v104, 0xffff0000, v51
	v_add_u32_e32 v100, v123, v102
	ds_read_b64_tr_b16 v[152:153], v100 offset:34816
	ds_read_b64_tr_b16 v[154:155], v100 offset:39424
	ds_read_b64_tr_b16 v[156:157], v100 offset:44032
	ds_read_b64_tr_b16 v[158:159], v100 offset:48640
	ds_read_b64_tr_b16 v[160:161], v100 offset:53248
	ds_read_b64_tr_b16 v[162:163], v100 offset:57856
	ds_read_b64_tr_b16 v[164:165], v100 offset:62464
	v_mul_f32_e32 v103, v99, v103
	v_mul_f32_e32 v99, v99, v104
	v_add_u32_e32 v102, 0x8800, v100
	ds_read_b64_tr_b16 v[166:167], v102 offset:32256
	v_add_u32_e32 v124, 0x11800, v123
	ds_read_b64_tr_b16 v[168:169], v124
	v_add_u32_e32 v126, 0x12a00, v123
	ds_read_b64_tr_b16 v[170:171], v126
	v_cvt_pk_bf16_f32 v99, v103, v99
	v_mov_b32_e32 v117, v116
	v_pk_mul_f32 v[54:55], v[116:117], v[54:55]
	v_pk_mul_f32 v[52:53], v[118:119], v[52:53]
	s_nop 0
	s_waitcnt lgkmcnt(0)
	v_mfma_f32_16x16x32_bf16 v[52:55], v[152:155], v[168:171], v[52:55]
	v_add_u32_e32 v124, 0x13c00, v123
	ds_read_b64_tr_b16 v[172:173], v124
	v_add_u32_e32 v126, 0x14e00, v123
	ds_read_b64_tr_b16 v[174:175], v126
	s_waitcnt lgkmcnt(0)
	v_mfma_f32_16x16x32_bf16 v[52:55], v[156:159], v[172:175], v[52:55]
	v_add_u32_e32 v124, 0x16000, v123
	ds_read_b64_tr_b16 v[176:177], v124
	v_add_u32_e32 v126, 0x17200, v123
	ds_read_b64_tr_b16 v[178:179], v126
	s_waitcnt lgkmcnt(0)
	v_mfma_f32_16x16x32_bf16 v[52:55], v[160:163], v[176:179], v[52:55]
	v_add_u32_e32 v124, 0x18400, v123
	ds_read_b64_tr_b16 v[184:185], v124
	v_add_u32_e32 v126, 0x19600, v123
	ds_read_b64_tr_b16 v[186:187], v126
	s_waitcnt lgkmcnt(0)
	v_mfma_f32_16x16x32_bf16 v[52:55], v[164:167], v[184:187], v[52:55]
	v_add_u32_e32 v124, 0x11820, v123
	ds_read_b64_tr_b16 v[168:169], v124
	v_add_u32_e32 v126, 0x12a20, v123
	ds_read_b64_tr_b16 v[170:171], v126
	v_pk_mul_f32 v[58:59], v[116:117], v[58:59]
	v_pk_mul_f32 v[56:57], v[118:119], v[56:57]
	s_nop 0
	s_waitcnt lgkmcnt(0)
	v_mfma_f32_16x16x32_bf16 v[56:59], v[152:155], v[168:171], v[56:59]
	v_add_u32_e32 v124, 0x13c20, v123
	ds_read_b64_tr_b16 v[172:173], v124
	v_add_u32_e32 v126, 0x14e20, v123
	ds_read_b64_tr_b16 v[174:175], v126
	s_waitcnt lgkmcnt(0)
	v_mfma_f32_16x16x32_bf16 v[56:59], v[156:159], v[172:175], v[56:59]
	v_add_u32_e32 v124, 0x16020, v123
	ds_read_b64_tr_b16 v[176:177], v124
	v_add_u32_e32 v126, 0x17220, v123
	ds_read_b64_tr_b16 v[178:179], v126
	s_waitcnt lgkmcnt(0)
	v_mfma_f32_16x16x32_bf16 v[56:59], v[160:163], v[176:179], v[56:59]
	v_add_u32_e32 v124, 0x18420, v123
	ds_read_b64_tr_b16 v[184:185], v124
	v_add_u32_e32 v126, 0x19620, v123
	ds_read_b64_tr_b16 v[186:187], v126
	s_waitcnt lgkmcnt(0)
	v_mfma_f32_16x16x32_bf16 v[56:59], v[164:167], v[184:187], v[56:59]
	v_add_u32_e32 v124, 0x11840, v123
	ds_read_b64_tr_b16 v[168:169], v124
	v_add_u32_e32 v126, 0x12a40, v123
	ds_read_b64_tr_b16 v[170:171], v126
	v_pk_mul_f32 v[62:63], v[116:117], v[62:63]
	v_pk_mul_f32 v[60:61], v[118:119], v[60:61]
	s_nop 0
	s_waitcnt lgkmcnt(0)
	v_mfma_f32_16x16x32_bf16 v[60:63], v[152:155], v[168:171], v[60:63]
	v_add_u32_e32 v124, 0x13c40, v123
	ds_read_b64_tr_b16 v[172:173], v124
	v_add_u32_e32 v126, 0x14e40, v123
	ds_read_b64_tr_b16 v[174:175], v126
	s_waitcnt lgkmcnt(0)
; #define MFMA16(a, b, c) __builtin_amdgcn_mfma_f32_16x16x32_bf16((a), (b), (c), 0, 0, 0)
; __device__ __forceinline__ bf16x8 ds_tr2(LAS unsigned char* p, int rstride) { const s16x4 a = ds_tr(p), b = ds_tr(p + 16 * rstride); bf16x8 r; r[0] = a[0]; r[1] = a[1]; r[2] = a[2]; r[3] = a[3]; r[4] = b[0]; r[5] = b[1]; r[6] = b[2]; r[7] = b[3]; return r; }
; template <int DIR, bool INTRA, bool FINAL> __device__ __forceinline__ void retention_pass(LAS unsigned char* lds, const bf16* ZH, bf16* YF, bf16* MIX, const float* ld, const float* gn, int seq, int h, int n0, int ncnt, ...
;     ...
;               for (int e = 0; e < 8; ++e) { st[e] = st[e] * gC;
; #pragma unroll
;                 for (int ks = 0; ks < 4; ++ks) { const bf16x8 vf = ds_tr2(trp + R_V + (32 * ks) * RSB + (16 * e) * 2, RSB);
;                     if constexpr (INTRA) y[e] = MFMA16(vf, pt[ks], y[e]);
;                     st[e] = MFMA16(kwf[ks], vf, st[e]); }
;                 __builtin_amdgcn_sched_barrier(0); } }
	v_mfma_f32_16x16x32_bf16 v[60:63], v[156:159], v[172:175], v[60:63]
	v_add_u32_e32 v124, 0x16040, v123
	ds_read_b64_tr_b16 v[176:177], v124
	v_add_u32_e32 v126, 0x17240, v123
	ds_read_b64_tr_b16 v[178:179], v126
	s_waitcnt lgkmcnt(0)
	v_mfma_f32_16x16x32_bf16 v[60:63], v[160:163], v[176:179], v[60:63]
	v_add_u32_e32 v124, 0x18440, v123
	ds_read_b64_tr_b16 v[184:185], v124
	v_add_u32_e32 v126, 0x19640, v123
	ds_read_b64_tr_b16 v[186:187], v126
	s_waitcnt lgkmcnt(0)
	v_mfma_f32_16x16x32_bf16 v[60:63], v[164:167], v[184:187], v[60:63]
	v_add_u32_e32 v124, 0x11860, v123
	ds_read_b64_tr_b16 v[168:169], v124
	v_add_u32_e32 v126, 0x12a60, v123
	ds_read_b64_tr_b16 v[170:171], v126
	v_pk_mul_f32 v[66:67], v[116:117], v[66:67]
	v_pk_mul_f32 v[64:65], v[118:119], v[64:65]
	s_nop 0
	s_waitcnt lgkmcnt(0)
	v_mfma_f32_16x16x32_bf16 v[64:67], v[152:155], v[168:171], v[64:67]
	v_add_u32_e32 v124, 0x13c60, v123
	ds_read_b64_tr_b16 v[172:173], v124
	v_add_u32_e32 v126, 0x14e60, v123
	ds_read_b64_tr_b16 v[174:175], v126
	s_waitcnt lgkmcnt(0)
	v_mfma_f32_16x16x32_bf16 v[64:67], v[156:159], v[172:175], v[64:67]
	v_add_u32_e32 v124, 0x16060, v123
	ds_read_b64_tr_b16 v[176:177], v124
	v_add_u32_e32 v126, 0x17260, v123
	ds_read_b64_tr_b16 v[178:179], v126
	s_waitcnt lgkmcnt(0)
	v_mfma_f32_16x16x32_bf16 v[64:67], v[160:163], v[176:179], v[64:67]
	v_add_u32_e32 v124, 0x18460, v123
	ds_read_b64_tr_b16 v[184:185], v124
	v_add_u32_e32 v126, 0x19660, v123
	ds_read_b64_tr_b16 v[186:187], v126
	s_waitcnt lgkmcnt(0)
	v_mfma_f32_16x16x32_bf16 v[64:67], v[164:167], v[184:187], v[64:67]
	v_add_u32_e32 v124, 0x11880, v123
	ds_read_b64_tr_b16 v[168:169], v124
	v_add_u32_e32 v126, 0x12a80, v123
	ds_read_b64_tr_b16 v[170:171], v126
	v_pk_mul_f32 v[70:71], v[116:117], v[70:71]
	v_pk_mul_f32 v[68:69], v[118:119], v[68:69]
	s_nop 0
	s_waitcnt lgkmcnt(0)
	v_mfma_f32_16x16x32_bf16 v[68:71], v[152:155], v[168:171], v[68:71]
	v_add_u32_e32 v124, 0x13c80, v123
	ds_read_b64_tr_b16 v[172:173], v124
	v_add_u32_e32 v126, 0x14e80, v123
	ds_read_b64_tr_b16 v[174:175], v126
	s_waitcnt lgkmcnt(0)
	v_mfma_f32_16x16x32_bf16 v[68:71], v[156:159], v[172:175], v[68:71]
	v_add_u32_e32 v124, 0x16080, v123
	ds_read_b64_tr_b16 v[176:177], v124
	v_add_u32_e32 v126, 0x17280, v123
	ds_read_b64_tr_b16 v[178:179], v126
	s_waitcnt lgkmcnt(0)
	v_mfma_f32_16x16x32_bf16 v[68:71], v[160:163], v[176:179], v[68:71]
	v_add_u32_e32 v124, 0x18480, v123
	ds_read_b64_tr_b16 v[184:185], v124
	v_add_u32_e32 v126, 0x19680, v123
	ds_read_b64_tr_b16 v[186:187], v126
	s_waitcnt lgkmcnt(0)
	v_mfma_f32_16x16x32_bf16 v[68:71], v[164:167], v[184:187], v[68:71]
	v_add_u32_e32 v124, 0x118a0, v123
	ds_read_b64_tr_b16 v[168:169], v124
	v_add_u32_e32 v126, 0x12aa0, v123
	ds_read_b64_tr_b16 v[170:171], v126
	v_pk_mul_f32 v[74:75], v[116:117], v[74:75]
	v_pk_mul_f32 v[72:73], v[118:119], v[72:73]
	s_nop 0
	s_waitcnt lgkmcnt(0)
	v_mfma_f32_16x16x32_bf16 v[72:75], v[152:155], v[168:171], v[72:75]
	v_add_u32_e32 v124, 0x13ca0, v123
	ds_read_b64_tr_b16 v[172:173], v124
	v_add_u32_e32 v126, 0x14ea0, v123
	ds_read_b64_tr_b16 v[174:175], v126
	s_waitcnt lgkmcnt(0)
	v_mfma_f32_16x16x32_bf16 v[72:75], v[156:159], v[172:175], v[72:75]
	v_add_u32_e32 v124, 0x160a0, v123
	ds_read_b64_tr_b16 v[176:177], v124
	v_add_u32_e32 v126, 0x172a0, v123
	ds_read_b64_tr_b16 v[178:179], v126
	s_waitcnt lgkmcnt(0)
	v_mfma_f32_16x16x32_bf16 v[72:75], v[160:163], v[176:179], v[72:75]
	v_add_u32_e32 v124, 0x184a0, v123
	ds_read_b64_tr_b16 v[184:185], v124
	v_add_u32_e32 v126, 0x196a0, v123
	ds_read_b64_tr_b16 v[186:187], v126
	s_waitcnt lgkmcnt(0)
	v_mfma_f32_16x16x32_bf16 v[72:75], v[164:167], v[184:187], v[72:75]
	v_add_u32_e32 v124, 0x118c0, v123
	ds_read_b64_tr_b16 v[168:169], v124
	v_add_u32_e32 v126, 0x12ac0, v123
	ds_read_b64_tr_b16 v[170:171], v126
	v_pk_mul_f32 v[78:79], v[116:117], v[78:79]
	v_pk_mul_f32 v[76:77], v[118:119], v[76:77]
	s_nop 0
	s_waitcnt lgkmcnt(0)
	v_mfma_f32_16x16x32_bf16 v[76:79], v[152:155], v[168:171], v[76:79]
	v_add_u32_e32 v124, 0x13cc0, v123
	ds_read_b64_tr_b16 v[172:173], v124
	v_add_u32_e32 v126, 0x14ec0, v123
	ds_read_b64_tr_b16 v[174:175], v126
	s_waitcnt lgkmcnt(0)
	v_mfma_f32_16x16x32_bf16 v[76:79], v[156:159], v[172:175], v[76:79]
	v_add_u32_e32 v124, 0x160c0, v123
	ds_read_b64_tr_b16 v[176:177], v124
	v_add_u32_e32 v126, 0x172c0, v123
	ds_read_b64_tr_b16 v[178:179], v126
	s_waitcnt lgkmcnt(0)
; #define GAS __attribute__((address_space(1)))
; #define MFMA16(a, b, c) __builtin_amdgcn_mfma_f32_16x16x32_bf16((a), (b), (c), 0, 0, 0)
; __device__ __forceinline__ bf16x8 ds_tr2(LAS unsigned char* p, int rstride) { const s16x4 a = ds_tr(p), b = ds_tr(p + 16 * rstride); bf16x8 r; r[0] = a[0]; r[1] = a[1]; r[2] = a[2]; r[3] = a[3]; r[4] = b[0]; r[5] = b[1]; r[6] = b[2]; r[7] = b[3]; return r; }
; template <int DIR, bool INTRA, bool FINAL> __device__ __forceinline__ void retention_pass(LAS unsigned char* lds, const bf16* ZH, bf16* YF, bf16* MIX, const float* ld, const float* gn, int seq, int h, int n0, int ncnt, ...
;     ...
;               for (int e = 0; e < 8; ++e) { st[e] = st[e] * gC;
; #pragma unroll
;                 for (int ks = 0; ks < 4; ++ks) { const bf16x8 vf = ds_tr2(trp + R_V + (32 * ks) * RSB + (16 * e) * 2, RSB);
;                     if constexpr (INTRA) y[e] = MFMA16(vf, pt[ks], y[e]);
;                     st[e] = MFMA16(kwf[ks], vf, st[e]); }
;                 __builtin_amdgcn_sched_barrier(0); } }
;             v2u ywv[8], gwv[8];
;             if constexpr (FINAL) { const int row_ = r0 + 16 * w + lr; const bf16* yp_ = YF + (size_t)row_ * 2048 + h * HD + 4 * lg; const bf16* gp_ = Gp + (size_t)(n * 128 + 16 * w + lr) * HD + 4 * lg;
; #pragma unroll
;                 for (int e = 0; e < 8; ++e) { ywv[e] = *(const GAS v2u*)(yp_ + 16 * e); gwv[e] = *(const GAS v2u*)(gp_ + 16 * e); } }
;             if (cn + 1 < ncnt) {
; #pragma unroll
;               for (int cc = 0; cc < 4; ++cc) { kreg[cc] = *(const GAS v4u*)(Kp + (size_t)(nn * 128 + srow + 32 * cc) * HD + 8 * sch); vreg[cc] = *(const GAS v4u*)(Vp + (size_t)(nn * 128 + srow + 32 * cc) * HD + 8 * sch); }
; #pragma unroll
;               for (int ks = 0; ks < 4; ++ks) qf[ks] = *(const GAS bf16x8*)(Qp + (size_t)(nn * 128 + 16 * w + lr) * HD + 8 * lg + 32 * ks); }
	v_mfma_f32_16x16x32_bf16 v[76:79], v[160:163], v[176:179], v[76:79]
	v_add_u32_e32 v124, 0x184c0, v123
	ds_read_b64_tr_b16 v[184:185], v124
	v_add_u32_e32 v126, 0x196c0, v123
	ds_read_b64_tr_b16 v[186:187], v126
	s_waitcnt lgkmcnt(0)
	v_mfma_f32_16x16x32_bf16 v[76:79], v[164:167], v[184:187], v[76:79]
	v_mul_f32_e64 v82, v116, v82
	v_mul_f32_e64 v83, v117, v83
	v_add_u32_e32 v117, 0x118e0, v123
	ds_read_b64_tr_b16 v[168:169], v117
	v_add_u32_e32 v117, 0x12ae0, v123
	ds_read_b64_tr_b16 v[170:171], v117
	v_pk_mul_f32 v[80:81], v[118:119], v[80:81]
	s_nop 0
	s_waitcnt lgkmcnt(0)
	v_mfma_f32_16x16x32_bf16 v[80:83], v[152:155], v[168:171], v[80:83]
	v_add_u32_e32 v112, 0x13ce0, v123
	ds_read_b64_tr_b16 v[172:173], v112
	v_add_u32_e32 v114, 0x14ee0, v123
	ds_read_b64_tr_b16 v[174:175], v114
	s_waitcnt lgkmcnt(0)
	v_mfma_f32_16x16x32_bf16 v[80:83], v[156:159], v[172:175], v[80:83]
	v_add_u32_e32 v108, 0x160e0, v123
	ds_read_b64_tr_b16 v[176:177], v108
	v_add_u32_e32 v110, 0x172e0, v123
	ds_read_b64_tr_b16 v[178:179], v110
	s_waitcnt lgkmcnt(0)
	v_mfma_f32_16x16x32_bf16 v[80:83], v[160:163], v[176:179], v[80:83]
	v_add_u32_e32 v104, 0x184e0, v123
	ds_read_b64_tr_b16 v[184:185], v104
	v_add_u32_e32 v106, 0x196e0, v123
	ds_read_b64_tr_b16 v[186:187], v106
	s_waitcnt lgkmcnt(0)
	v_mfma_f32_16x16x32_bf16 v[80:83], v[164:167], v[184:187], v[80:83]
	s_add_i32 s40, s34, s35
	v_add_u32_e32 v100, s40, v122
	v_add_u32_e32 v114, 0x80, v100
	v_add_u32_e32 v138, s35, v122
	v_ashrrev_i32_e32 v115, 31, v114
	v_add_u32_e32 v102, 0x80, v138
	v_lshlrev_b64 v[100:101], 12, v[114:115]
	v_ashrrev_i32_e32 v103, 31, v102
	v_lshl_add_u64 v[100:101], s[36:37], 0, v[100:101]
	v_lshlrev_b64 v[102:103], 8, v[102:103]
	v_lshl_add_u64 v[100:101], v[100:101], 0, v[2:3]
	v_lshl_add_u64 v[102:103], s[6:7], 0, v[102:103]
	v_lshl_add_u64 v[144:145], v[102:103], 0, v[2:3]
	global_load_dwordx2 v[134:135], v[100:101], off
	global_load_dwordx2 v[130:131], v[100:101], off offset:32
	global_load_dwordx2 v[126:127], v[100:101], off offset:64
	global_load_dwordx2 v[124:125], v[100:101], off offset:96
	global_load_dwordx2 v[122:123], v[144:145], off
	global_load_dwordx2 v[112:113], v[144:145], off offset:32
	global_load_dwordx2 v[110:111], v[144:145], off offset:64
	global_load_dwordx2 v[108:109], v[144:145], off offset:96
	global_load_dwordx2 v[140:141], v[100:101], off offset:128
	global_load_dwordx2 v[136:137], v[100:101], off offset:160
	global_load_dwordx2 v[132:133], v[100:101], off offset:192
	global_load_dwordx2 v[128:129], v[100:101], off offset:224
	global_load_dwordx2 v[106:107], v[144:145], off offset:128
	global_load_dwordx2 v[104:105], v[144:145], off offset:160
	global_load_dwordx2 v[102:103], v[144:145], off offset:192
	s_nop 0
	global_load_dwordx2 v[100:101], v[144:145], off offset:224
	s_cmpk_eq_i32 s35, 0xff80
	s_cbranch_scc1 .LBB0_712
	v_add_u32_e32 v28, s35, v121
	v_ashrrev_i32_e32 v29, 31, v28
	v_lshlrev_b64 v[4:5], 8, v[28:29]
	v_add_u32_e32 v12, 32, v28
	v_add_u32_e32 v20, 64, v28
	v_add_u32_e32 v28, 0x60, v28
	v_ashrrev_i32_e32 v139, 31, v138
	v_mov_b32_e32 v121, v3
	v_ashrrev_i32_e32 v13, 31, v12
	v_ashrrev_i32_e32 v21, 31, v20
	v_ashrrev_i32_e32 v29, 31, v28
	v_lshlrev_b64 v[36:37], 8, v[138:139]
	v_lshl_add_u64 v[30:31], s[24:25], 0, v[120:121]
	v_lshl_add_u64 v[32:33], s[26:27], 0, v[120:121]
	v_lshlrev_b64 v[12:13], 8, v[12:13]
	v_lshlrev_b64 v[20:21], 8, v[20:21]
	v_lshlrev_b64 v[28:29], 8, v[28:29]
	v_lshl_add_u64 v[36:37], s[22:23], 0, v[36:37]
	v_lshlrev_b32_e32 v2, 1, v2
	v_lshl_add_u64 v[6:7], v[30:31], 0, v[4:5]
	v_lshl_add_u64 v[8:9], v[32:33], 0, v[4:5]
	v_lshl_add_u64 v[14:15], v[30:31], 0, v[12:13]
	v_lshl_add_u64 v[16:17], v[32:33], 0, v[12:13]
	v_lshl_add_u64 v[22:23], v[30:31], 0, v[20:21]
	v_lshl_add_u64 v[24:25], v[32:33], 0, v[20:21]
	v_lshl_add_u64 v[30:31], v[30:31], 0, v[28:29]
	v_lshl_add_u64 v[32:33], v[32:33], 0, v[28:29]
	v_lshl_add_u64 v[48:49], v[36:37], 0, v[2:3]
	global_load_dwordx4 v[4:7], v[6:7], off
	s_nop 0
	global_load_dwordx4 v[8:11], v[8:9], off
	s_nop 0
	global_load_dwordx4 v[12:15], v[14:15], off
	s_nop 0
	global_load_dwordx4 v[16:19], v[16:17], off
	s_nop 0
	global_load_dwordx4 v[20:23], v[22:23], off
	s_nop 0
	global_load_dwordx4 v[24:27], v[24:25], off
	s_nop 0
	global_load_dwordx4 v[28:31], v[30:31], off
	s_nop 0
	global_load_dwordx4 v[32:35], v[32:33], off
	s_nop 0
	global_load_dwordx4 v[36:39], v[48:49], off
	global_load_dwordx4 v[40:43], v[48:49], off offset:64
	global_load_dwordx4 v[44:47], v[48:49], off offset:128
	s_nop 0
	global_load_dwordx4 v[48:51], v[48:49], off offset:192
	s_branch .LBB0_712

; #define GAS __attribute__((address_space(1)))
; #define LAS __attribute__((address_space(3)))
; __device__ __forceinline__ unsigned pk2(float lo, float hi) { return pg8::cvt_pk_bf16(lo, hi); }
; #define MFMA16(a, b, c) __builtin_amdgcn_mfma_f32_16x16x32_bf16((a), (b), (c), 0, 0, 0)
; template <int DIR, bool INTRA, bool FINAL> __device__ __forceinline__ void retention_pass(LAS unsigned char* lds, const bf16* ZH, bf16* YF, bf16* MIX, const float* ld, const float* gn, int seq, int h, int n0, int ncnt, ...
;     ...
; #pragma unroll
;             for (int e = 0; e < 8; ++e) {
; #pragma unroll
;                 for (int ks = 0; ks < 4; ++ks) { const bf16x8 sf = *(const LAS bf16x8*)(lds + R_ST + (16 * e + lr) * RS + (8 * lg + 32 * ks) * 2); y[e] = MFMA16(sf, qx[ks], y[e]); }
;                 __builtin_amdgcn_sched_barrier(0); }
;             const int row = r0 + 16 * w + lr;
;             bf16* yp = YF + (size_t)row * 2048 + h * HD + 4 * lg;
;             if constexpr (!FINAL) {
; #pragma unroll
;                 for (int e = 0; e < 8; ++e) { v2u o; o.x = pk2(y[e][0], y[e][1]); o.y = pk2(y[e][2], y[e][3]); *(GAS v2u*)(yp + 16 * e) = o; }
.LBB0_719:
	s_waitcnt lgkmcnt(0)
	v_lshlrev_b32_e32 v2, 4, v129
	v_add3_u32 v2, s95, v2, v132
	ds_read_b128 v[148:151], v2
	ds_read_b128 v[152:155], v2 offset:64
	ds_read_b128 v[156:159], v2 offset:128
	ds_read_b128 v[160:163], v2 offset:192
	ds_read_b128 v[164:167], v2 offset:4352
	ds_read_b128 v[168:171], v2 offset:4416
	ds_read_b128 v[172:175], v2 offset:4480
	ds_read_b128 v[176:179], v2 offset:4544
	s_waitcnt lgkmcnt(7)
	v_mfma_f32_16x16x32_bf16 v[100:103], v[148:151], v[84:87], 0
	ds_read_b128 v[148:151], v2 offset:8704
	s_waitcnt lgkmcnt(7)
	v_mfma_f32_16x16x32_bf16 v[100:103], v[152:155], v[88:91], v[100:103]
	ds_read_b128 v[152:155], v2 offset:8768
	s_waitcnt lgkmcnt(7)
	v_mfma_f32_16x16x32_bf16 v[100:103], v[156:159], v[92:95], v[100:103]
	ds_read_b128 v[156:159], v2 offset:8832
	s_waitcnt lgkmcnt(7)
	v_mfma_f32_16x16x32_bf16 v[100:103], v[160:163], v[96:99], v[100:103]
	ds_read_b128 v[160:163], v2 offset:8896
	s_waitcnt lgkmcnt(7)
	v_mfma_f32_16x16x32_bf16 v[104:107], v[164:167], v[84:87], 0
	ds_read_b128 v[164:167], v2 offset:13056
	s_waitcnt lgkmcnt(7)
	v_mfma_f32_16x16x32_bf16 v[104:107], v[168:171], v[88:91], v[104:107]
	ds_read_b128 v[168:171], v2 offset:13120
	s_waitcnt lgkmcnt(7)
	v_mfma_f32_16x16x32_bf16 v[104:107], v[172:175], v[92:95], v[104:107]
	ds_read_b128 v[172:175], v2 offset:13184
	s_waitcnt lgkmcnt(7)
	v_mfma_f32_16x16x32_bf16 v[104:107], v[176:179], v[96:99], v[104:107]
	ds_read_b128 v[176:179], v2 offset:13248
	s_waitcnt lgkmcnt(7)
	v_mfma_f32_16x16x32_bf16 v[108:111], v[148:151], v[84:87], 0
	ds_read_b128 v[148:151], v2 offset:17408
	s_waitcnt lgkmcnt(7)
	v_mfma_f32_16x16x32_bf16 v[108:111], v[152:155], v[88:91], v[108:111]
	ds_read_b128 v[152:155], v2 offset:17472
	s_waitcnt lgkmcnt(7)
	v_mfma_f32_16x16x32_bf16 v[108:111], v[156:159], v[92:95], v[108:111]
	ds_read_b128 v[156:159], v2 offset:17536
	s_waitcnt lgkmcnt(7)
	v_mfma_f32_16x16x32_bf16 v[108:111], v[160:163], v[96:99], v[108:111]
	ds_read_b128 v[160:163], v2 offset:17600
	s_waitcnt lgkmcnt(7)
	v_mfma_f32_16x16x32_bf16 v[112:115], v[164:167], v[84:87], 0
	ds_read_b128 v[164:167], v2 offset:21760
	s_waitcnt lgkmcnt(7)
	v_mfma_f32_16x16x32_bf16 v[112:115], v[168:171], v[88:91], v[112:115]
	ds_read_b128 v[168:171], v2 offset:21824
	s_waitcnt lgkmcnt(7)
	v_mfma_f32_16x16x32_bf16 v[112:115], v[172:175], v[92:95], v[112:115]
	ds_read_b128 v[172:175], v2 offset:21888
	s_waitcnt lgkmcnt(7)
	v_mfma_f32_16x16x32_bf16 v[112:115], v[176:179], v[96:99], v[112:115]
	ds_read_b128 v[176:179], v2 offset:21952
	s_waitcnt lgkmcnt(7)
	v_mfma_f32_16x16x32_bf16 v[132:135], v[148:151], v[84:87], 0
	ds_read_b128 v[148:151], v2 offset:26112
	s_waitcnt lgkmcnt(7)
	v_mfma_f32_16x16x32_bf16 v[132:135], v[152:155], v[88:91], v[132:135]
	ds_read_b128 v[152:155], v2 offset:26176
	s_waitcnt lgkmcnt(7)
	v_mfma_f32_16x16x32_bf16 v[132:135], v[156:159], v[92:95], v[132:135]
	ds_read_b128 v[156:159], v2 offset:26240
	s_waitcnt lgkmcnt(7)
	v_mfma_f32_16x16x32_bf16 v[132:135], v[160:163], v[96:99], v[132:135]
	ds_read_b128 v[160:163], v2 offset:26304
	s_waitcnt lgkmcnt(7)
	v_mfma_f32_16x16x32_bf16 v[136:139], v[164:167], v[84:87], 0
	ds_read_b128 v[164:167], v2 offset:30464
	s_waitcnt lgkmcnt(7)
	v_mfma_f32_16x16x32_bf16 v[136:139], v[168:171], v[88:91], v[136:139]
	ds_read_b128 v[168:171], v2 offset:30592
	s_waitcnt lgkmcnt(7)
	v_mfma_f32_16x16x32_bf16 v[136:139], v[172:175], v[92:95], v[136:139]
	ds_read_b128 v[172:175], v2 offset:30656
	s_waitcnt lgkmcnt(7)
	v_mfma_f32_16x16x32_bf16 v[136:139], v[176:179], v[96:99], v[136:139]
	s_waitcnt lgkmcnt(6)
	v_mfma_f32_16x16x32_bf16 v[140:143], v[148:151], v[84:87], 0
	s_waitcnt lgkmcnt(5)
	v_mfma_f32_16x16x32_bf16 v[140:143], v[152:155], v[88:91], v[140:143]
	s_waitcnt lgkmcnt(4)
	v_mfma_f32_16x16x32_bf16 v[140:143], v[156:159], v[92:95], v[140:143]
	s_waitcnt lgkmcnt(3)
	v_mfma_f32_16x16x32_bf16 v[140:143], v[160:163], v[96:99], v[140:143]
	s_waitcnt lgkmcnt(2)
	v_mfma_f32_16x16x32_bf16 v[84:87], v[164:167], v[84:87], 0
	ds_read_b128 v[144:147], v2 offset:30528
	s_waitcnt lgkmcnt(0)
	v_mfma_f32_16x16x32_bf16 v[84:87], v[144:147], v[88:91], v[84:87]
	v_mfma_f32_16x16x32_bf16 v[84:87], v[168:171], v[92:95], v[84:87]
	v_mfma_f32_16x16x32_bf16 v[84:87], v[172:175], v[96:99], v[84:87]
	v_or_b32_e32 v2, s8, v128
	v_add_u32_e32 v2, v2, v131
	v_subrev_u32_e32 v88, s46, v2
	v_ashrrev_i32_e32 v89, 31, v88
	v_lshlrev_b64 v[88:89], 12, v[88:89]
	v_lshl_add_u64 v[88:89], s[76:77], 0, v[88:89]
	v_lshlrev_b32_e32 v2, 1, v127
	v_lshl_add_u64 v[88:89], v[88:89], 0, v[2:3]
	v_cvt_pk_bf16_f32 v90, v100, v101
	v_cvt_pk_bf16_f32 v91, v102, v103
	global_store_dwordx2 v[88:89], v[90:91], off
	v_cvt_pk_bf16_f32 v90, v104, v105
	v_cvt_pk_bf16_f32 v91, v106, v107
	global_store_dwordx2 v[88:89], v[90:91], off offset:32
	v_cvt_pk_bf16_f32 v90, v108, v109
	v_cvt_pk_bf16_f32 v91, v110, v111
	global_store_dwordx2 v[88:89], v[90:91], off offset:64
	v_cvt_pk_bf16_f32 v90, v112, v113
	v_cvt_pk_bf16_f32 v91, v114, v115
	global_store_dwordx2 v[88:89], v[90:91], off offset:96
	v_cvt_pk_bf16_f32 v90, v132, v133
	v_cvt_pk_bf16_f32 v91, v134, v135
	s_addk_i32 s9, 0x80
	s_addk_i32 s41, 0xff80
	global_store_dwordx2 v[88:89], v[90:91], off offset:128
	v_cvt_pk_bf16_f32 v90, v136, v137
	v_cvt_pk_bf16_f32 v91, v138, v139
	s_cmpk_eq_i32 s41, 0x760
	global_store_dwordx2 v[88:89], v[90:91], off offset:160
	v_cvt_pk_bf16_f32 v90, v140, v141
	v_cvt_pk_bf16_f32 v91, v142, v143
	global_store_dwordx2 v[88:89], v[90:91], off offset:192
	v_cvt_pk_bf16_f32 v84, v84, v85
	v_cvt_pk_bf16_f32 v85, v86, v87
	global_store_dwordx2 v[88:89], v[84:85], off offset:224
	s_cbranch_scc1 .LBB0_722
; #define LAS __attribute__((address_space(3)))
; #define WG_BARRIER() do { asm volatile("s_waitcnt lgkmcnt(0)" ::: "memory"); __builtin_amdgcn_s_barrier(); asm volatile("" ::: "memory"); } while (0)
; __device__ __forceinline__ unsigned pk2(float lo, float hi) { return pg8::cvt_pk_bf16(lo, hi); }
; __device__ __forceinline__ v4u scale8(v4u x, float sc) { v4u o; o.x = pk2(bf_lo(x.x) * sc, bf_hi(x.x) * sc); o.y = pk2(bf_lo(x.y) * sc, bf_hi(x.y) * sc); o.z = pk2(bf_lo(x.z) * sc, bf_hi(x.z) * sc); o.w = pk2(bf_lo(x.w) * sc, bf_hi(x.w) * sc); return o; }
; template <int DIR, bool INTRA, bool FINAL> __device__ __forceinline__ void retention_pass(LAS unsigned char* lds, const bf16* ZH, bf16* YF, bf16* MIX, const float* ld, const float* gn, int seq, int h, int n0, int ncnt, ...
;     ...
;             const int n = DIR == 0 ? n0 + cn : n0 + ncnt - 1 - cn, nn = DIR == 0 ? n + 1 : n - 1;
;             const int r0 = rowbase + n * 128;
;             int tid = tid0; float lf = lf0, lb = lb0; asm volatile("" : "+v"(tid), "+v"(lf), "+v"(lb));
;             const int w = tid >> 6, l = tid & 63, lr = l & 15, lg = l >> 4, srow = tid >> 4, sch = tid & 15;
;             LAS unsigned char* trp = lds + (4 * lg + ((l & 15) >> 2)) * RSB + (l & 3) * 8;
;             WG_BARRIER();
; #pragma unroll
;             for (int cc = 0; cc < 4; ++cc) { const int row = srow + 32 * cc;
;                 if constexpr (INTRA) *(LAS v4u*)(lds + R_K + row * RS + 16 * sch) = kreg[cc];
;                 const float wj = DIR == 0 ? __expf(lf * (float)(127 - row)) : __expf(lb * (float)row);
;                 *(LAS v4u*)(lds + R_KW + row * RSB + 16 * sch) = scale8(kreg[cc], wj);
;                 *(LAS v4u*)(lds + R_V + row * RSB + 16 * sch) = vreg[cc]; }
; #pragma unroll
;             for (int e = 0; e < 8; ++e) { v2u o; o.x = pk2(st[e][0], st[e][1]); o.y = pk2(st[e][2], st[e][3]); *(LAS v2u*)(lds + R_ST + (16 * e + lr) * RS + (16 * w + 4 * lg) * 2) = o; }
;             WG_BARRIER();
;             bf16x8 qx[4];
;             { const float xi = DIR == 0 ? __expf(lf * (float)(16 * w + lr + 1)) : __expf(lb * (float)(128 - 16 * w - lr));
.LBB0_720:
	v_mov_b32_e32 v88, v190
	v_mov_b32_e32 v89, v126
	v_mov_b32_e32 v2, v121
	s_waitcnt vmcnt(11)
	v_and_b32_e32 v85, 0xffff0000, v4
	v_ashrrev_i32_e32 v130, 4, v88
	v_cvt_f32_i32_e32 v84, v130
	s_waitcnt lgkmcnt(0)
	s_barrier
	v_mul_f32_e32 v84, v89, v84
	v_mul_f32_e32 v84, 0x3fb8aa3b, v84
	v_exp_f32_e32 v87, v84
	v_lshlrev_b32_e32 v84, 16, v4
	v_and_b32_e32 v86, 0xffff0000, v5
	v_bfe_u32 v129, v88, 4, 2
	v_mul_f32_e32 v84, v87, v84
	v_mul_f32_e32 v85, v87, v85
	v_cvt_pk_bf16_f32 v84, v84, v85
	v_lshlrev_b32_e32 v85, 16, v5
	v_mul_f32_e32 v85, v87, v85
	v_mul_f32_e32 v86, v87, v86
	v_lshlrev_b32_e32 v127, 2, v129
	v_bfe_u32 v2, v88, 2, 2
	v_cvt_pk_bf16_f32 v85, v85, v86
	v_lshlrev_b32_e32 v86, 16, v6
	v_and_b32_e32 v92, 0xffff0000, v6
	v_or_b32_e32 v2, v127, v2
	v_mul_f32_e32 v86, v87, v86
	v_mul_f32_e32 v92, v87, v92
	v_and_b32_e32 v128, 15, v88
	v_mul_u32_u24_e32 v100, 0x120, v2
	v_lshlrev_b32_e32 v2, 3, v88
	v_cvt_pk_bf16_f32 v86, v86, v92
	v_lshlrev_b32_e32 v92, 16, v7
	v_and_b32_e32 v93, 0xffff0000, v7
	v_and_b32_e32 v101, 24, v2
	v_lshlrev_b32_e32 v2, 4, v128
	v_mul_f32_e32 v92, v87, v92
	v_mul_f32_e32 v87, v87, v93
	v_add_u32_e32 v90, 0, v2
	v_cvt_pk_bf16_f32 v87, v92, v87
	v_mul_lo_u32 v92, v130, s74
	v_add_u32_e32 v91, s93, v2
	v_add_u32_e32 v93, v90, v92
	ds_write_b128 v93, v[84:87] offset:34816
	v_add_u32_e32 v84, v91, v92
	s_waitcnt vmcnt(10)
	ds_write_b128 v84, v[8:11]
	v_add_u32_e32 v84, 32, v130
	v_cvt_f32_i32_e32 v84, v84
	s_waitcnt vmcnt(9)
	v_and_b32_e32 v85, 0xffff0000, v12
	v_and_b32_e32 v86, 0xffff0000, v13
	v_and_b32_e32 v93, 0xffff0000, v14
	v_mul_f32_e32 v84, v89, v84
	v_mul_f32_e32 v84, 0x3fb8aa3b, v84
	v_exp_f32_e32 v87, v84
	v_lshlrev_b32_e32 v84, 16, v12
	v_and_b32_e32 v94, 0xffff0000, v15
	v_lshlrev_b32_e32 v133, 3, v129
	v_mul_f32_e32 v84, v87, v84
	v_mul_f32_e32 v85, v87, v85
	v_cvt_pk_bf16_f32 v84, v84, v85
	v_lshlrev_b32_e32 v85, 16, v13
	v_mul_f32_e32 v85, v87, v85
	v_mul_f32_e32 v86, v87, v86
	v_cvt_pk_bf16_f32 v85, v85, v86
	v_lshlrev_b32_e32 v86, 16, v14
	v_mul_f32_e32 v86, v87, v86
	v_mul_f32_e32 v93, v87, v93
	v_cvt_pk_bf16_f32 v86, v86, v93
	v_lshlrev_b32_e32 v93, 16, v15
	v_mul_f32_e32 v93, v87, v93
	v_mul_f32_e32 v87, v87, v94
	v_cvt_pk_bf16_f32 v87, v93, v87
	v_add_u32_e32 v93, 0x2400, v92
	v_add_u32_e32 v94, v90, v93
	ds_write_b128 v94, v[84:87] offset:34816
	v_add_u32_e32 v84, v91, v93
	s_waitcnt vmcnt(8)
	ds_write_b128 v84, v[16:19]
	v_add_u32_e32 v84, 64, v130
	v_cvt_f32_i32_e32 v84, v84
	s_waitcnt vmcnt(7)
	v_and_b32_e32 v85, 0xffff0000, v20
	v_and_b32_e32 v86, 0xffff0000, v21
	v_and_b32_e32 v93, 0xffff0000, v22
	v_mul_f32_e32 v84, v89, v84
	v_mul_f32_e32 v84, 0x3fb8aa3b, v84
	v_exp_f32_e32 v87, v84
	v_lshlrev_b32_e32 v84, 16, v20
	v_and_b32_e32 v94, 0xffff0000, v23
	v_mul_u32_u24_e32 v132, 0x110, v128
	v_mul_f32_e32 v84, v87, v84
	v_mul_f32_e32 v85, v87, v85
	v_cvt_pk_bf16_f32 v84, v84, v85
	v_lshlrev_b32_e32 v85, 16, v21
	v_mul_f32_e32 v85, v87, v85
	v_mul_f32_e32 v86, v87, v86
	v_cvt_pk_bf16_f32 v85, v85, v86
	v_lshlrev_b32_e32 v86, 16, v22
	v_mul_f32_e32 v86, v87, v86
	v_mul_f32_e32 v93, v87, v93
	v_cvt_pk_bf16_f32 v86, v86, v93
	v_lshlrev_b32_e32 v93, 16, v23
	v_mul_f32_e32 v93, v87, v93
	v_mul_f32_e32 v87, v87, v94
	v_cvt_pk_bf16_f32 v87, v93, v87
	v_add_u32_e32 v93, 0x4800, v92
	v_add_u32_e32 v94, v90, v93
	ds_write_b128 v94, v[84:87] offset:34816
	v_add_u32_e32 v84, v91, v93
	s_waitcnt vmcnt(6)
	ds_write_b128 v84, v[24:27]
	v_add_u32_e32 v84, 0x60, v130
	v_cvt_f32_i32_e32 v84, v84
	s_waitcnt vmcnt(5)
	v_and_b32_e32 v85, 0xffff0000, v28
	v_and_b32_e32 v86, 0xffff0000, v29
	v_and_b32_e32 v93, 0xffff0000, v30
	v_mul_f32_e32 v84, v89, v84
	v_mul_f32_e32 v84, 0x3fb8aa3b, v84
	v_exp_f32_e32 v87, v84
	v_lshlrev_b32_e32 v84, 16, v28
	v_and_b32_e32 v94, 0xffff0000, v31
	v_add_u32_e32 v92, 0x6c00, v92
	v_mul_f32_e32 v84, v87, v84
	v_mul_f32_e32 v85, v87, v85
	v_cvt_pk_bf16_f32 v84, v84, v85
	v_lshlrev_b32_e32 v85, 16, v29
	v_mul_f32_e32 v85, v87, v85
	v_mul_f32_e32 v86, v87, v86
	v_cvt_pk_bf16_f32 v85, v85, v86
	v_lshlrev_b32_e32 v86, 16, v30
	v_mul_f32_e32 v86, v87, v86
	v_mul_f32_e32 v93, v87, v93
	v_cvt_pk_bf16_f32 v86, v86, v93
	v_lshlrev_b32_e32 v93, 16, v31
	v_mul_f32_e32 v93, v87, v93
	v_mul_f32_e32 v87, v87, v94
	v_add_u32_e32 v90, v90, v92
	v_cvt_pk_bf16_f32 v87, v93, v87
	ds_write_b128 v90, v[84:87] offset:34816
	v_ashrrev_i32_e32 v86, 6, v88
	v_lshlrev_b32_e32 v102, 5, v86
	v_add_u32_e32 v84, v91, v92
	v_add_u32_e32 v87, s95, v102
	s_waitcnt vmcnt(4)
	ds_write_b128 v84, v[32:35]
	v_cvt_pk_bf16_f32 v84, v80, v81
	v_add3_u32 v87, v87, v133, v132
	v_cvt_pk_bf16_f32 v85, v82, v83
	ds_write_b64 v87, v[84:85]
	v_cvt_pk_bf16_f32 v84, v76, v77
	v_cvt_pk_bf16_f32 v85, v78, v79
	ds_write_b64 v87, v[84:85] offset:4352
	v_cvt_pk_bf16_f32 v84, v72, v73
	v_cvt_pk_bf16_f32 v85, v74, v75
	ds_write_b64 v87, v[84:85] offset:8704
	v_cvt_pk_bf16_f32 v84, v68, v69
	v_cvt_pk_bf16_f32 v85, v70, v71
	ds_write_b64 v87, v[84:85] offset:13056
	v_cvt_pk_bf16_f32 v84, v64, v65
	v_cvt_pk_bf16_f32 v85, v66, v67
	ds_write_b64 v87, v[84:85] offset:17408
	v_cvt_pk_bf16_f32 v84, v56, v57
	v_cvt_pk_bf16_f32 v85, v58, v59
	ds_write_b64 v87, v[84:85] offset:21760
	v_cvt_pk_bf16_f32 v84, v52, v53
	v_cvt_pk_bf16_f32 v85, v54, v55
	ds_write_b64 v87, v[84:85] offset:26112
	v_cvt_pk_bf16_f32 v84, v60, v61
	v_lshlrev_b32_e32 v131, 4, v86
	v_cvt_pk_bf16_f32 v85, v62, v63
	ds_write_b64 v87, v[84:85] offset:30464
	v_or_b32_e32 v84, v128, v131
	v_sub_u32_e32 v84, 0x80, v84
	v_cvt_f32_i32_e32 v84, v84
	s_waitcnt vmcnt(3)
	v_and_b32_e32 v85, 0xffff0000, v36
	s_waitcnt lgkmcnt(0)
	s_barrier
; #define LAS __attribute__((address_space(3)))
; template <int DIR, bool INTRA, bool FINAL> __device__ __forceinline__ void retention_pass(LAS unsigned char* lds, const bf16* ZH, bf16* YF, bf16* MIX, const float* ld, const float* gn, int seq, int h, int n0, int ncnt, ...
;     ...
;             { const float xi = DIR == 0 ? __expf(lf * (float)(16 * w + lr + 1)) : __expf(lb * (float)(128 - 16 * w - lr));
; #pragma unroll
;               for (int ks = 0; ks < 4; ++ks) qx[ks] = __builtin_bit_cast(bf16x8, scale8(__builtin_bit_cast(v4u, qf[ks]), xi)); }
;             bf16x8 pt[4];
;             if constexpr (INTRA) {
;                 f32x4 s[8];
; #pragma unroll
;                 for (int jt = 0; jt < 8; ++jt) { s[jt] = (f32x4){0.f, 0.f, 0.f, 0.f};
; #pragma unroll
;                     for (int ks = 0; ks < 4; ++ks) { const bf16x8 a = *(const LAS bf16x8*)(lds + R_K + (16 * jt + lr) * RS + (8 * lg + 32 * ks) * 2); s[jt] = MFMA16(a, qf[ks], s[jt]); }
;                     __builtin_amdgcn_sched_barrier(0); }
;                 float Fr[4], Br[4];
; #pragma unroll
;                 for (int r = 0; r < 4; ++r) { const float br = (float)(lr - 4 * lg - r); Fr[r] = __expf(lf * br); Br[r] = __expf(-lb * br); }
; #pragma unroll
;                 for (int jt = 0; jt < 8; ++jt) { const int dt = w - jt; const float cf = __expf(lf * 16.f * (float)dt), cb = __expf(-lb * 16.f * (float)dt);
; #pragma unroll
;                     for (int r = 0; r < 4; ++r) { const float dec = dt > 0 ? Fr[r] * cf : (dt < 0 ? Br[r] * cb : ((lr - 4 * lg - r) >= 0 ? Fr[r] : Br[r])); s[jt][r] *= dec; } }
; #pragma unroll
;                 for (int ks = 0; ks < 4; ++ks) { v4u o; o.x = pk2(s[2 * ks][0], s[2 * ks][1]); o.y = pk2(s[2 * ks][2], s[2 * ks][3]); o.z = pk2(s[2 * ks + 1][0], s[2 * ks + 1][1]); o.w = pk2(s[2 * ks + 1][2], s[2 * ks + 1][3]); pt[ks] = __builtin_bit_cast(bf16x8, o); }
;             }
;             f32x4 y[8];
; #pragma unroll
;             for (int e = 0; e < 8; ++e) y[e] = (f32x4){0.f, 0.f, 0.f, 0.f};
;             { bf16x8 kwf[4];
; #pragma unroll
;               for (int ks = 0; ks < 4; ++ks) kwf[ks] = ds_tr2(trp + R_KW + (32 * ks) * RSB + (16 * w) * 2, RSB);
; #pragma unroll
;               for (int e = 0; e < 8; ++e) { st[e] = st[e] * gC;
; #pragma unroll
;                 for (int ks = 0; ks < 4; ++ks) { const bf16x8 vf = ds_tr2(trp + R_V + (32 * ks) * RSB + (16 * e) * 2, RSB);
	s_waitcnt lgkmcnt(0)
	v_mul_f32_e32 v84, v89, v84
	v_mul_f32_e32 v84, 0x3fb8aa3b, v84
	v_exp_f32_e32 v99, v84
	v_lshlrev_b32_e32 v84, 16, v36
	v_and_b32_e32 v86, 0xffff0000, v37
	v_mul_f32_e32 v84, v99, v84
	v_mul_f32_e32 v85, v99, v85
	v_cvt_pk_bf16_f32 v84, v84, v85
	v_lshlrev_b32_e32 v85, 16, v37
	v_mul_f32_e32 v85, v99, v85
	v_mul_f32_e32 v86, v99, v86
	v_cvt_pk_bf16_f32 v85, v85, v86
	v_lshlrev_b32_e32 v86, 16, v38
	v_and_b32_e32 v87, 0xffff0000, v38
	v_mul_f32_e32 v86, v99, v86
	v_mul_f32_e32 v87, v99, v87
	v_cvt_pk_bf16_f32 v86, v86, v87
	v_lshlrev_b32_e32 v87, 16, v39
	v_and_b32_e32 v88, 0xffff0000, v39
	v_mul_f32_e32 v87, v99, v87
	v_mul_f32_e32 v88, v99, v88
	v_cvt_pk_bf16_f32 v87, v87, v88
	s_waitcnt vmcnt(2)
	v_lshlrev_b32_e32 v88, 16, v40
	v_and_b32_e32 v89, 0xffff0000, v40
	v_mul_f32_e32 v88, v99, v88
	v_mul_f32_e32 v89, v99, v89
	v_cvt_pk_bf16_f32 v88, v88, v89
	v_lshlrev_b32_e32 v89, 16, v41
	v_and_b32_e32 v90, 0xffff0000, v41
	v_mul_f32_e32 v89, v99, v89
	v_mul_f32_e32 v90, v99, v90
	v_cvt_pk_bf16_f32 v89, v89, v90
	v_lshlrev_b32_e32 v90, 16, v42
	v_and_b32_e32 v91, 0xffff0000, v42
	v_mul_f32_e32 v90, v99, v90
	v_mul_f32_e32 v91, v99, v91
	v_cvt_pk_bf16_f32 v90, v90, v91
	v_lshlrev_b32_e32 v91, 16, v43
	v_and_b32_e32 v92, 0xffff0000, v43
	v_mul_f32_e32 v91, v99, v91
	v_mul_f32_e32 v92, v99, v92
	v_cvt_pk_bf16_f32 v91, v91, v92
	s_waitcnt vmcnt(1)
	v_lshlrev_b32_e32 v92, 16, v44
	v_and_b32_e32 v93, 0xffff0000, v44
	v_mul_f32_e32 v92, v99, v92
	v_mul_f32_e32 v93, v99, v93
	v_cvt_pk_bf16_f32 v92, v92, v93
	v_lshlrev_b32_e32 v93, 16, v45
	v_and_b32_e32 v94, 0xffff0000, v45
	v_mul_f32_e32 v93, v99, v93
	v_mul_f32_e32 v94, v99, v94
	v_cvt_pk_bf16_f32 v93, v93, v94
	v_lshlrev_b32_e32 v94, 16, v46
	v_and_b32_e32 v95, 0xffff0000, v46
	v_mul_f32_e32 v94, v99, v94
	v_mul_f32_e32 v95, v99, v95
	v_cvt_pk_bf16_f32 v94, v94, v95
	v_lshlrev_b32_e32 v95, 16, v47
	v_and_b32_e32 v96, 0xffff0000, v47
	v_mul_f32_e32 v95, v99, v95
	v_mul_f32_e32 v96, v99, v96
	v_cvt_pk_bf16_f32 v95, v95, v96
	s_waitcnt vmcnt(0)
	v_lshlrev_b32_e32 v96, 16, v48
	v_and_b32_e32 v97, 0xffff0000, v48
	v_mul_f32_e32 v96, v99, v96
	v_mul_f32_e32 v97, v99, v97
	v_cvt_pk_bf16_f32 v96, v96, v97
	v_lshlrev_b32_e32 v97, 16, v49
	v_and_b32_e32 v98, 0xffff0000, v49
	v_mul_f32_e32 v97, v99, v97
	v_mul_f32_e32 v98, v99, v98
	v_cvt_pk_bf16_f32 v97, v97, v98
	v_lshlrev_b32_e32 v98, 16, v50
	v_and_b32_e32 v103, 0xffff0000, v50
	v_mul_f32_e32 v98, v99, v98
	v_mul_f32_e32 v103, v99, v103
	v_add3_u32 v134, 0, v100, v101
	v_cvt_pk_bf16_f32 v98, v98, v103
	v_lshlrev_b32_e32 v103, 16, v51
	v_and_b32_e32 v104, 0xffff0000, v51
	v_add_u32_e32 v100, v134, v102
	ds_read_b64_tr_b16 v[140:141], v100 offset:34816
	ds_read_b64_tr_b16 v[142:143], v100 offset:39424
	ds_read_b64_tr_b16 v[144:145], v100 offset:44032
	ds_read_b64_tr_b16 v[146:147], v100 offset:48640
	ds_read_b64_tr_b16 v[148:149], v100 offset:53248
	ds_read_b64_tr_b16 v[150:151], v100 offset:57856
	v_mul_f32_e32 v103, v99, v103
	v_mul_f32_e32 v99, v99, v104
	v_add_u32_e32 v102, 0x8800, v100
	v_add_u32_e32 v135, 0x11800, v134
	ds_read_b64_tr_b16 v[152:153], v135
	v_cvt_pk_bf16_f32 v99, v103, v99
	ds_read_b64_tr_b16 v[100:101], v100 offset:62464
	ds_read_b64_tr_b16 v[102:103], v102 offset:32256
	v_add_u32_e32 v135, 0x12a00, v134
	ds_read_b64_tr_b16 v[154:155], v135
	v_mov_b32_e32 v123, v122
	v_pk_mul_f32 v[82:83], v[122:123], v[82:83]
	v_pk_mul_f32 v[80:81], v[124:125], v[80:81]
	v_add_u32_e32 v135, 0x13c00, v134
	ds_read_b64_tr_b16 v[156:157], v135
	s_waitcnt lgkmcnt(1)
	v_mfma_f32_16x16x32_bf16 v[80:83], v[140:143], v[152:155], v[80:83]
	v_add_u32_e32 v135, 0x14e00, v134
	ds_read_b64_tr_b16 v[158:159], v135
	v_add_u32_e32 v135, 0x16000, v134
	ds_read_b64_tr_b16 v[160:161], v135
	s_waitcnt lgkmcnt(1)
	v_mfma_f32_16x16x32_bf16 v[80:83], v[144:147], v[156:159], v[80:83]
	v_add_u32_e32 v135, 0x17200, v134
	ds_read_b64_tr_b16 v[162:163], v135
	v_add_u32_e32 v135, 0x18400, v134
	ds_read_b64_tr_b16 v[164:165], v135
	s_waitcnt lgkmcnt(1)
	v_mfma_f32_16x16x32_bf16 v[80:83], v[148:151], v[160:163], v[80:83]
	v_add_u32_e32 v135, 0x19600, v134
	ds_read_b64_tr_b16 v[166:167], v135
	s_waitcnt lgkmcnt(0)
	v_mfma_f32_16x16x32_bf16 v[80:83], v[100:103], v[164:167], v[80:83]
	v_add_u32_e32 v135, 0x11820, v134
	ds_read_b64_tr_b16 v[168:169], v135
	v_add_u32_e32 v135, 0x12a20, v134
	ds_read_b64_tr_b16 v[170:171], v135
	v_pk_mul_f32 v[78:79], v[122:123], v[78:79]
	v_pk_mul_f32 v[76:77], v[124:125], v[76:77]
	v_add_u32_e32 v135, 0x13c20, v134
	ds_read_b64_tr_b16 v[152:153], v135
	s_waitcnt lgkmcnt(1)
	v_mfma_f32_16x16x32_bf16 v[76:79], v[140:143], v[168:171], v[76:79]
	v_add_u32_e32 v135, 0x14e20, v134
	ds_read_b64_tr_b16 v[154:155], v135
	v_add_u32_e32 v135, 0x16020, v134
	ds_read_b64_tr_b16 v[156:157], v135
	s_waitcnt lgkmcnt(1)
	v_mfma_f32_16x16x32_bf16 v[76:79], v[144:147], v[152:155], v[76:79]
	v_add_u32_e32 v135, 0x17220, v134
	ds_read_b64_tr_b16 v[158:159], v135
	v_add_u32_e32 v135, 0x18420, v134
	ds_read_b64_tr_b16 v[160:161], v135
	s_waitcnt lgkmcnt(1)
	v_mfma_f32_16x16x32_bf16 v[76:79], v[148:151], v[156:159], v[76:79]
	v_add_u32_e32 v135, 0x19620, v134
	ds_read_b64_tr_b16 v[162:163], v135
	s_waitcnt lgkmcnt(0)
	v_mfma_f32_16x16x32_bf16 v[76:79], v[100:103], v[160:163], v[76:79]
	v_add_u32_e32 v135, 0x11840, v134
	ds_read_b64_tr_b16 v[164:165], v135
	v_add_u32_e32 v135, 0x12a40, v134
	ds_read_b64_tr_b16 v[166:167], v135
	v_pk_mul_f32 v[74:75], v[122:123], v[74:75]
	v_pk_mul_f32 v[72:73], v[124:125], v[72:73]
	v_add_u32_e32 v135, 0x13c40, v134
	ds_read_b64_tr_b16 v[168:169], v135
	s_waitcnt lgkmcnt(1)
; #define MFMA16(a, b, c) __builtin_amdgcn_mfma_f32_16x16x32_bf16((a), (b), (c), 0, 0, 0)
; __device__ __forceinline__ bf16x8 ds_tr2(LAS unsigned char* p, int rstride) { const s16x4 a = ds_tr(p), b = ds_tr(p + 16 * rstride); bf16x8 r; r[0] = a[0]; r[1] = a[1]; r[2] = a[2]; r[3] = a[3]; r[4] = b[0]; r[5] = b[1]; r[6] = b[2]; r[7] = b[3]; return r; }
; template <int DIR, bool INTRA, bool FINAL> __device__ __forceinline__ void retention_pass(LAS unsigned char* lds, const bf16* ZH, bf16* YF, bf16* MIX, const float* ld, const float* gn, int seq, int h, int n0, int ncnt, ...
;     ...
;               for (int e = 0; e < 8; ++e) { st[e] = st[e] * gC;
; #pragma unroll
;                 for (int ks = 0; ks < 4; ++ks) { const bf16x8 vf = ds_tr2(trp + R_V + (32 * ks) * RSB + (16 * e) * 2, RSB);
;                     if constexpr (INTRA) y[e] = MFMA16(vf, pt[ks], y[e]);
;                     st[e] = MFMA16(kwf[ks], vf, st[e]); }
;                 __builtin_amdgcn_sched_barrier(0); } }
	v_mfma_f32_16x16x32_bf16 v[72:75], v[140:143], v[164:167], v[72:75]
	v_add_u32_e32 v135, 0x14e40, v134
	ds_read_b64_tr_b16 v[170:171], v135
	v_add_u32_e32 v135, 0x16040, v134
	ds_read_b64_tr_b16 v[152:153], v135
	s_waitcnt lgkmcnt(1)
	v_mfma_f32_16x16x32_bf16 v[72:75], v[144:147], v[168:171], v[72:75]
	v_add_u32_e32 v135, 0x17240, v134
	ds_read_b64_tr_b16 v[154:155], v135
	v_add_u32_e32 v135, 0x18440, v134
	ds_read_b64_tr_b16 v[156:157], v135
	s_waitcnt lgkmcnt(1)
	v_mfma_f32_16x16x32_bf16 v[72:75], v[148:151], v[152:155], v[72:75]
	v_add_u32_e32 v135, 0x19640, v134
	ds_read_b64_tr_b16 v[158:159], v135
	s_waitcnt lgkmcnt(0)
	v_mfma_f32_16x16x32_bf16 v[72:75], v[100:103], v[156:159], v[72:75]
	v_add_u32_e32 v135, 0x11860, v134
	ds_read_b64_tr_b16 v[160:161], v135
	v_add_u32_e32 v135, 0x12a60, v134
	ds_read_b64_tr_b16 v[162:163], v135
	v_pk_mul_f32 v[70:71], v[122:123], v[70:71]
	v_pk_mul_f32 v[68:69], v[124:125], v[68:69]
	v_add_u32_e32 v135, 0x13c60, v134
	ds_read_b64_tr_b16 v[164:165], v135
	s_waitcnt lgkmcnt(1)
	v_mfma_f32_16x16x32_bf16 v[68:71], v[140:143], v[160:163], v[68:71]
	v_add_u32_e32 v135, 0x14e60, v134
	ds_read_b64_tr_b16 v[166:167], v135
	v_add_u32_e32 v135, 0x16060, v134
	ds_read_b64_tr_b16 v[168:169], v135
	s_waitcnt lgkmcnt(1)
	v_mfma_f32_16x16x32_bf16 v[68:71], v[144:147], v[164:167], v[68:71]
	v_add_u32_e32 v135, 0x17260, v134
	ds_read_b64_tr_b16 v[170:171], v135
	v_add_u32_e32 v135, 0x18460, v134
	ds_read_b64_tr_b16 v[152:153], v135
	s_waitcnt lgkmcnt(1)
	v_mfma_f32_16x16x32_bf16 v[68:71], v[148:151], v[168:171], v[68:71]
	v_add_u32_e32 v135, 0x19660, v134
	ds_read_b64_tr_b16 v[154:155], v135
	s_waitcnt lgkmcnt(0)
	v_mfma_f32_16x16x32_bf16 v[68:71], v[100:103], v[152:155], v[68:71]
	v_add_u32_e32 v135, 0x11880, v134
	ds_read_b64_tr_b16 v[156:157], v135
	v_add_u32_e32 v135, 0x12a80, v134
	ds_read_b64_tr_b16 v[158:159], v135
	v_pk_mul_f32 v[66:67], v[122:123], v[66:67]
	v_pk_mul_f32 v[64:65], v[124:125], v[64:65]
	v_add_u32_e32 v135, 0x13c80, v134
	ds_read_b64_tr_b16 v[160:161], v135
	s_waitcnt lgkmcnt(1)
	v_mfma_f32_16x16x32_bf16 v[64:67], v[140:143], v[156:159], v[64:67]
	v_add_u32_e32 v135, 0x14e80, v134
	ds_read_b64_tr_b16 v[162:163], v135
	v_add_u32_e32 v135, 0x16080, v134
	ds_read_b64_tr_b16 v[164:165], v135
	s_waitcnt lgkmcnt(1)
	v_mfma_f32_16x16x32_bf16 v[64:67], v[144:147], v[160:163], v[64:67]
	v_add_u32_e32 v135, 0x17280, v134
	ds_read_b64_tr_b16 v[166:167], v135
	v_add_u32_e32 v135, 0x18480, v134
	ds_read_b64_tr_b16 v[168:169], v135
	s_waitcnt lgkmcnt(1)
	v_mfma_f32_16x16x32_bf16 v[64:67], v[148:151], v[164:167], v[64:67]
	v_add_u32_e32 v135, 0x19680, v134
	ds_read_b64_tr_b16 v[170:171], v135
	s_waitcnt lgkmcnt(0)
	v_mfma_f32_16x16x32_bf16 v[64:67], v[100:103], v[168:171], v[64:67]
	v_add_u32_e32 v135, 0x118a0, v134
	ds_read_b64_tr_b16 v[152:153], v135
	v_add_u32_e32 v135, 0x12aa0, v134
	ds_read_b64_tr_b16 v[154:155], v135
	v_pk_mul_f32 v[58:59], v[122:123], v[58:59]
	v_pk_mul_f32 v[56:57], v[124:125], v[56:57]
	v_add_u32_e32 v135, 0x13ca0, v134
	ds_read_b64_tr_b16 v[156:157], v135
	s_waitcnt lgkmcnt(1)
	v_mfma_f32_16x16x32_bf16 v[56:59], v[140:143], v[152:155], v[56:59]
	v_add_u32_e32 v135, 0x14ea0, v134
	ds_read_b64_tr_b16 v[158:159], v135
	v_add_u32_e32 v135, 0x160a0, v134
	ds_read_b64_tr_b16 v[160:161], v135
	s_waitcnt lgkmcnt(1)
	v_mfma_f32_16x16x32_bf16 v[56:59], v[144:147], v[156:159], v[56:59]
	v_add_u32_e32 v135, 0x172a0, v134
	ds_read_b64_tr_b16 v[162:163], v135
	v_add_u32_e32 v135, 0x184a0, v134
	ds_read_b64_tr_b16 v[164:165], v135
	s_waitcnt lgkmcnt(1)
	v_mfma_f32_16x16x32_bf16 v[56:59], v[148:151], v[160:163], v[56:59]
	v_add_u32_e32 v135, 0x196a0, v134
	ds_read_b64_tr_b16 v[166:167], v135
	s_waitcnt lgkmcnt(0)
	v_mfma_f32_16x16x32_bf16 v[56:59], v[100:103], v[164:167], v[56:59]
	v_add_u32_e32 v135, 0x118c0, v134
	ds_read_b64_tr_b16 v[168:169], v135
	v_add_u32_e32 v135, 0x12ac0, v134
	ds_read_b64_tr_b16 v[170:171], v135
	v_pk_mul_f32 v[54:55], v[122:123], v[54:55]
	v_pk_mul_f32 v[52:53], v[124:125], v[52:53]
	v_add_u32_e32 v135, 0x13cc0, v134
	ds_read_b64_tr_b16 v[152:153], v135
	s_waitcnt lgkmcnt(1)
	v_mfma_f32_16x16x32_bf16 v[52:55], v[140:143], v[168:171], v[52:55]
	v_add_u32_e32 v135, 0x14ec0, v134
	ds_read_b64_tr_b16 v[154:155], v135
	v_add_u32_e32 v135, 0x160c0, v134
	ds_read_b64_tr_b16 v[156:157], v135
	s_waitcnt lgkmcnt(1)
	v_mfma_f32_16x16x32_bf16 v[52:55], v[144:147], v[152:155], v[52:55]
	v_add_u32_e32 v135, 0x172c0, v134
	ds_read_b64_tr_b16 v[158:159], v135
	v_add_u32_e32 v135, 0x184c0, v134
	ds_read_b64_tr_b16 v[160:161], v135
	s_waitcnt lgkmcnt(1)
	v_mfma_f32_16x16x32_bf16 v[52:55], v[148:151], v[156:159], v[52:55]
	v_add_u32_e32 v135, 0x196c0, v134
	ds_read_b64_tr_b16 v[162:163], v135
	s_waitcnt lgkmcnt(0)
	v_mfma_f32_16x16x32_bf16 v[52:55], v[100:103], v[160:163], v[52:55]
	v_mul_f32_e64 v62, v122, v62
	v_mul_f32_e64 v63, v123, v63
	v_add_u32_e32 v123, 0x118e0, v134
	ds_read_b64_tr_b16 v[136:137], v123
	v_add_u32_e32 v123, 0x12ae0, v134
	ds_read_b64_tr_b16 v[138:139], v123
	v_pk_mul_f32 v[60:61], v[124:125], v[60:61]
	s_nop 0
	s_waitcnt lgkmcnt(0)
	v_mfma_f32_16x16x32_bf16 v[60:63], v[140:143], v[136:139], v[60:63]
	v_add_u32_e32 v112, 0x13ce0, v134
	v_add_u32_e32 v114, 0x14ee0, v134
	ds_read_b64_tr_b16 v[112:113], v112
	ds_read_b64_tr_b16 v[114:115], v114
	s_waitcnt lgkmcnt(0)
	v_mfma_f32_16x16x32_bf16 v[60:63], v[144:147], v[112:115], v[60:63]
	v_add_u32_e32 v108, 0x160e0, v134
	v_add_u32_e32 v110, 0x172e0, v134
	ds_read_b64_tr_b16 v[108:109], v108
	ds_read_b64_tr_b16 v[110:111], v110
	s_waitcnt lgkmcnt(0)
	v_mfma_f32_16x16x32_bf16 v[60:63], v[148:151], v[108:111], v[60:63]
	v_add_u32_e32 v104, 0x184e0, v134
	v_add_u32_e32 v106, 0x196e0, v134
	ds_read_b64_tr_b16 v[104:105], v104
	ds_read_b64_tr_b16 v[106:107], v106
	s_waitcnt lgkmcnt(0)
	v_mfma_f32_16x16x32_bf16 v[60:63], v[100:103], v[104:107], v[60:63]
	s_cmpk_eq_i32 s41, 0x7e0
	s_movk_i32 s46, 0x780
	s_cbranch_scc1 .LBB0_719
; #define GAS __attribute__((address_space(1)))
; template <int DIR, bool INTRA, bool FINAL> __device__ __forceinline__ void retention_pass(LAS unsigned char* lds, const bf16* ZH, bf16* YF, bf16* MIX, const float* ld, const float* gn, int seq, int h, int n0, int ncnt, ...
;     ...
;             if (cn + 1 < ncnt) {
; #pragma unroll
;               for (int cc = 0; cc < 4; ++cc) { kreg[cc] = *(const GAS v4u*)(Kp + (size_t)(nn * 128 + srow + 32 * cc) * HD + 8 * sch); vreg[cc] = *(const GAS v4u*)(Vp + (size_t)(nn * 128 + srow + 32 * cc) * HD + 8 * sch); }
; #pragma unroll
;               for (int ks = 0; ks < 4; ++ks) qf[ks] = *(const GAS bf16x8*)(Qp + (size_t)(nn * 128 + 16 * w + lr) * HD + 8 * lg + 32 * ks); }
	v_lshl_add_u64 v[30:31], s[60:61], 0, v[2:3]
	v_lshl_add_u64 v[32:33], s[72:73], 0, v[2:3]
	v_add3_u32 v2, v131, v128, s41
	v_add_u32_e32 v28, s41, v130
	v_add_u32_e32 v36, 0xffffffa0, v2
	v_add_u32_e32 v4, 0xffffffa0, v28
	v_subrev_u32_e32 v12, 64, v28
	v_subrev_u32_e32 v20, 32, v28
	v_ashrrev_i32_e32 v37, 31, v36
	v_ashrrev_i32_e32 v5, 31, v4
	v_ashrrev_i32_e32 v13, 31, v12
	v_ashrrev_i32_e32 v21, 31, v20
	v_ashrrev_i32_e32 v29, 31, v28
	v_lshlrev_b64 v[36:37], 8, v[36:37]
	v_lshlrev_b64 v[4:5], 8, v[4:5]
	v_lshlrev_b64 v[12:13], 8, v[12:13]
	v_lshlrev_b64 v[20:21], 8, v[20:21]
	v_lshlrev_b64 v[28:29], 8, v[28:29]
	v_lshl_add_u64 v[36:37], s[36:37], 0, v[36:37]
	v_lshlrev_b32_e32 v2, 1, v133
	v_lshl_add_u64 v[6:7], v[30:31], 0, v[4:5]
	v_lshl_add_u64 v[8:9], v[32:33], 0, v[4:5]
	v_lshl_add_u64 v[14:15], v[30:31], 0, v[12:13]
	v_lshl_add_u64 v[16:17], v[32:33], 0, v[12:13]
	v_lshl_add_u64 v[22:23], v[30:31], 0, v[20:21]
	v_lshl_add_u64 v[24:25], v[32:33], 0, v[20:21]
	v_lshl_add_u64 v[30:31], v[30:31], 0, v[28:29]
	v_lshl_add_u64 v[32:33], v[32:33], 0, v[28:29]
	v_lshl_add_u64 v[48:49], v[36:37], 0, v[2:3]
	global_load_dwordx4 v[4:7], v[6:7], off
	s_nop 0
	global_load_dwordx4 v[8:11], v[8:9], off
	s_nop 0
	global_load_dwordx4 v[12:15], v[14:15], off
	s_nop 0
	global_load_dwordx4 v[16:19], v[16:17], off
	s_nop 0
	global_load_dwordx4 v[20:23], v[22:23], off
	s_nop 0
	global_load_dwordx4 v[24:27], v[24:25], off
	s_nop 0
	global_load_dwordx4 v[28:31], v[30:31], off
	s_nop 0
	global_load_dwordx4 v[32:35], v[32:33], off
	s_nop 0
	global_load_dwordx4 v[36:39], v[48:49], off
	global_load_dwordx4 v[40:43], v[48:49], off offset:64
	global_load_dwordx4 v[44:47], v[48:49], off offset:128
	s_nop 0
	global_load_dwordx4 v[48:51], v[48:49], off offset:192
	s_mov_b32 s46, s9
	s_branch .LBB0_719

; #define GAS __attribute__((address_space(1)))
; #define LAS __attribute__((address_space(3)))
; __device__ __forceinline__ unsigned pk2(float lo, float hi) { return pg8::cvt_pk_bf16(lo, hi); }
; __device__ __forceinline__ float bf_lo(unsigned w) { return __uint_as_float(w << 16); }
; __device__ __forceinline__ float bf_hi(unsigned w) { return __uint_as_float(w & 0xffff0000u); }
; #define MFMA16(a, b, c) __builtin_amdgcn_mfma_f32_16x16x32_bf16((a), (b), (c), 0, 0, 0)
; template <int DIR, bool INTRA, bool FINAL> __device__ __forceinline__ void retention_pass(LAS unsigned char* lds, const bf16* ZH, bf16* YF, bf16* MIX, const float* ld, const float* gn, int seq, int h, int n0, int ncnt, ...
;     ...
; #pragma unroll
;             for (int e = 0; e < 8; ++e) {
; #pragma unroll
;                 for (int ks = 0; ks < 4; ++ks) { const bf16x8 sf = *(const LAS bf16x8*)(lds + R_ST + (16 * e + lr) * RS + (8 * lg + 32 * ks) * 2); y[e] = MFMA16(sf, qx[ks], y[e]); }
;                 __builtin_amdgcn_sched_barrier(0); }
;             const int row = r0 + 16 * w + lr;
;             bf16* yp = YF + (size_t)row * 2048 + h * HD + 4 * lg;
;             if constexpr (!FINAL) {
; #pragma unroll
;                 for (int e = 0; e < 8; ++e) { v2u o; o.x = pk2(y[e][0], y[e][1]); o.y = pk2(y[e][2], y[e][3]); *(GAS v2u*)(yp + 16 * e) = o; }
;             } else {
;                 float sum = 0.f;
; #pragma unroll
;                 for (int e = 0; e < 8; ++e) { const v2u yw = ywv[e]; y[e][0] += bf_lo(yw.x); y[e][1] += bf_hi(yw.x); y[e][2] += bf_lo(yw.y); y[e][3] += bf_hi(yw.y); sum += (y[e][0] + y[e][1]) + (y[e][2] + y[e][3]); }
.LBB0_729:
	s_waitcnt lgkmcnt(0)
	v_add3_u32 v161, s95, v174, v175
	ds_read_b128 v[212:215], v161
	ds_read_b128 v[216:219], v161 offset:64
	ds_read_b128 v[220:223], v161 offset:128
	ds_read_b128 v[224:227], v161 offset:192
	ds_read_b128 v[240:243], v161 offset:4352
	ds_read_b128 v[244:247], v161 offset:4416
	ds_read_b128 v[248:251], v161 offset:4480
	s_waitcnt lgkmcnt(6)
	v_mfma_f32_16x16x32_bf16 v[120:123], v[212:215], v[84:87], v[120:123]
	ds_read_b128 v[212:215], v161 offset:4544
	s_waitcnt lgkmcnt(6)
	v_mfma_f32_16x16x32_bf16 v[120:123], v[216:219], v[88:91], v[120:123]
	ds_read_b128 v[216:219], v161 offset:8704
	s_waitcnt lgkmcnt(6)
	v_mfma_f32_16x16x32_bf16 v[120:123], v[220:223], v[92:95], v[120:123]
	ds_read_b128 v[220:223], v161 offset:8768
	s_waitcnt lgkmcnt(6)
	v_mfma_f32_16x16x32_bf16 v[120:123], v[224:227], v[96:99], v[120:123]
	ds_read_b128 v[224:227], v161 offset:8832
	s_waitcnt lgkmcnt(6)
	v_mfma_f32_16x16x32_bf16 v[136:139], v[240:243], v[84:87], v[136:139]
	ds_read_b128 v[240:243], v161 offset:8896
	s_waitcnt lgkmcnt(6)
	v_mfma_f32_16x16x32_bf16 v[136:139], v[244:247], v[88:91], v[136:139]
	ds_read_b128 v[244:247], v161 offset:13056
	s_waitcnt lgkmcnt(6)
	v_mfma_f32_16x16x32_bf16 v[136:139], v[248:251], v[92:95], v[136:139]
	ds_read_b128 v[248:251], v161 offset:13120
	s_waitcnt lgkmcnt(6)
	v_mfma_f32_16x16x32_bf16 v[176:179], v[212:215], v[96:99], v[136:139]
	ds_read_b128 v[212:215], v161 offset:13184
	s_nop 4
	s_waitcnt lgkmcnt(6)
	v_mfma_f32_16x16x32_bf16 v[136:139], v[216:219], v[84:87], v[140:143]
	ds_read_b128 v[216:219], v161 offset:13248
	s_nop 2
	s_waitcnt lgkmcnt(6)
	v_mfma_f32_16x16x32_bf16 v[136:139], v[220:223], v[88:91], v[136:139]
	ds_read_b128 v[220:223], v161 offset:17408
	s_waitcnt lgkmcnt(6)
	v_mfma_f32_16x16x32_bf16 v[136:139], v[224:227], v[92:95], v[136:139]
	ds_read_b128 v[224:227], v161 offset:17472
	s_waitcnt lgkmcnt(6)
	v_mfma_f32_16x16x32_bf16 v[184:187], v[240:243], v[96:99], v[136:139]
	ds_read_b128 v[240:243], v161 offset:17536
	s_nop 4
	s_waitcnt lgkmcnt(6)
	v_mfma_f32_16x16x32_bf16 v[136:139], v[244:247], v[84:87], v[144:147]
	ds_read_b128 v[244:247], v161 offset:17600
	s_waitcnt lgkmcnt(6)
	v_mfma_f32_16x16x32_bf16 v[136:139], v[248:251], v[88:91], v[136:139]
	ds_read_b128 v[248:251], v161 offset:21760
	s_waitcnt lgkmcnt(6)
	v_mfma_f32_16x16x32_bf16 v[136:139], v[212:215], v[92:95], v[136:139]
	ds_read_b128 v[212:215], v161 offset:21824
	s_waitcnt lgkmcnt(6)
	v_mfma_f32_16x16x32_bf16 v[144:147], v[216:219], v[96:99], v[136:139]
	ds_read_b128 v[216:219], v161 offset:21888
	s_nop 4
	s_waitcnt lgkmcnt(6)
	v_mfma_f32_16x16x32_bf16 v[136:139], v[220:223], v[84:87], v[148:151]
	ds_read_b128 v[220:223], v161 offset:21952
	s_waitcnt lgkmcnt(6)
	v_mfma_f32_16x16x32_bf16 v[136:139], v[224:227], v[88:91], v[136:139]
	ds_read_b128 v[224:227], v161 offset:26112
	s_waitcnt lgkmcnt(6)
	v_mfma_f32_16x16x32_bf16 v[136:139], v[240:243], v[92:95], v[136:139]
	ds_read_b128 v[240:243], v161 offset:26176
	s_waitcnt lgkmcnt(6)
	v_mfma_f32_16x16x32_bf16 v[148:151], v[244:247], v[96:99], v[136:139]
	ds_read_b128 v[244:247], v161 offset:26240
	s_nop 4
	s_waitcnt lgkmcnt(6)
	v_mfma_f32_16x16x32_bf16 v[136:139], v[248:251], v[84:87], v[152:155]
	ds_read_b128 v[248:251], v161 offset:26304
	s_waitcnt lgkmcnt(6)
	v_mfma_f32_16x16x32_bf16 v[136:139], v[212:215], v[88:91], v[136:139]
	ds_read_b128 v[212:215], v161 offset:30464
	s_waitcnt lgkmcnt(6)
	v_mfma_f32_16x16x32_bf16 v[136:139], v[216:219], v[92:95], v[136:139]
	ds_read_b128 v[216:219], v161 offset:30528
	s_waitcnt lgkmcnt(6)
	v_mfma_f32_16x16x32_bf16 v[152:155], v[220:223], v[96:99], v[136:139]
	ds_read_b128 v[220:223], v161 offset:30592
	s_nop 4
	s_waitcnt lgkmcnt(6)
	v_mfma_f32_16x16x32_bf16 v[136:139], v[224:227], v[84:87], v[156:159]
	ds_read_b128 v[224:227], v161 offset:30656
	s_waitcnt lgkmcnt(6)
	v_mfma_f32_16x16x32_bf16 v[136:139], v[240:243], v[88:91], v[136:139]
	s_waitcnt lgkmcnt(5)
	v_mfma_f32_16x16x32_bf16 v[136:139], v[244:247], v[92:95], v[136:139]
	s_waitcnt lgkmcnt(4)
	v_mfma_f32_16x16x32_bf16 v[156:159], v[248:251], v[96:99], v[136:139]
	s_nop 4
	s_waitcnt lgkmcnt(3)
	v_mfma_f32_16x16x32_bf16 v[84:87], v[212:215], v[84:87], v[100:103]
	s_nop 2
	s_waitcnt lgkmcnt(2)
	v_mfma_f32_16x16x32_bf16 v[84:87], v[216:219], v[88:91], v[84:87]
	s_waitcnt lgkmcnt(1)
	v_mfma_f32_16x16x32_bf16 v[84:87], v[220:223], v[92:95], v[84:87]
	s_waitcnt lgkmcnt(0)
	v_mfma_f32_16x16x32_bf16 v[206:209], v[224:227], v[96:99], v[84:87]
	s_waitcnt vmcnt(15)
	s_nop 3
	v_lshlrev_b32_e32 v84, 16, v170
	v_and_b32_e32 v85, 0xffff0000, v170
	v_pk_add_f32 v[142:143], v[120:121], v[84:85]
	v_lshlrev_b32_e32 v84, 16, v171
	v_and_b32_e32 v85, 0xffff0000, v171
	v_pk_add_f32 v[140:141], v[122:123], v[84:85]
	s_waitcnt vmcnt(14)
	v_lshlrev_b32_e32 v84, 16, v132
	v_and_b32_e32 v85, 0xffff0000, v132
	v_pk_add_f32 v[138:139], v[176:177], v[84:85]
	v_lshlrev_b32_e32 v84, 16, v133
	v_and_b32_e32 v85, 0xffff0000, v133
	v_pk_add_f32 v[136:137], v[178:179], v[84:85]
	v_mov_b32_e32 v84, v142
	v_mov_b32_e32 v85, v138
	v_mov_b32_e32 v86, v143
	v_mov_b32_e32 v87, v139
	v_pk_add_f32 v[84:85], v[84:85], v[86:87]
	v_mov_b32_e32 v86, v140
	v_mov_b32_e32 v87, v136
	v_mov_b32_e32 v88, v141
	v_mov_b32_e32 v89, v137
	v_pk_add_f32 v[86:87], v[86:87], v[88:89]
	s_waitcnt vmcnt(7)
; __device__ __forceinline__ float bf_lo(unsigned w) { return __uint_as_float(w << 16); }
; __device__ __forceinline__ float bf_hi(unsigned w) { return __uint_as_float(w & 0xffff0000u); }
; __device__ __forceinline__ float fast_rsqrt(float x) { return __builtin_amdgcn_rsqf(x); }
; template <int DIR, bool INTRA, bool FINAL> __device__ __forceinline__ void retention_pass(LAS unsigned char* lds, const bf16* ZH, bf16* YF, bf16* MIX, const float* ld, const float* gn, int seq, int h, int n0, int ncnt, ...
;     ...
;                 float sum = 0.f;
; #pragma unroll
;                 for (int e = 0; e < 8; ++e) { const v2u yw = ywv[e]; y[e][0] += bf_lo(yw.x); y[e][1] += bf_hi(yw.x); y[e][2] += bf_lo(yw.y); y[e][3] += bf_hi(yw.y); sum += (y[e][0] + y[e][1]) + (y[e][2] + y[e][3]); }
;                 sum += __shfl_xor(sum, 16); sum += __shfl_xor(sum, 32);
;                 const float mu = sum * (1.f / 128.f); float q = 0.f;
; #pragma unroll
;                 for (int e = 0; e < 8; ++e) { y[e] = y[e] - mu; q += (y[e][0] * y[e][0] + y[e][1] * y[e][1]) + (y[e][2] * y[e][2] + y[e][3] * y[e][3]); }
;                 q += __shfl_xor(q, 16); q += __shfl_xor(q, 32);
;                 const float rstd = fast_rsqrt(q * (1.f / 128.f) + GN_EPS);
	v_lshlrev_b32_e32 v92, 16, v134
	v_pk_add_f32 v[84:85], v[84:85], v[86:87]
	v_lshlrev_b32_e32 v86, 16, v168
	v_and_b32_e32 v87, 0xffff0000, v168
	v_pk_add_f32 v[132:133], v[184:185], v[86:87]
	v_lshlrev_b32_e32 v86, 16, v169
	v_and_b32_e32 v87, 0xffff0000, v169
	v_pk_add_f32 v[122:123], v[186:187], v[86:87]
	v_mov_b32_e32 v86, v132
	v_mov_b32_e32 v87, v122
	v_mov_b32_e32 v88, v133
	v_mov_b32_e32 v89, v123
	v_pk_add_f32 v[86:87], v[86:87], v[88:89]
	v_lshlrev_b32_e32 v88, 16, v166
	v_and_b32_e32 v89, 0xffff0000, v166
	v_pk_add_f32 v[120:121], v[144:145], v[88:89]
	v_lshlrev_b32_e32 v88, 16, v167
	v_and_b32_e32 v89, 0xffff0000, v167
	v_and_b32_e32 v93, 0xffff0000, v134
	v_pk_add_f32 v[102:103], v[146:147], v[88:89]
	v_pk_add_f32 v[100:101], v[148:149], v[92:93]
	v_lshlrev_b32_e32 v92, 16, v135
	v_and_b32_e32 v93, 0xffff0000, v135
	v_add_f32_e32 v84, 0, v84
	v_pk_add_f32 v[86:87], v[86:87], v[86:87] op_sel:[0,1] op_sel_hi:[1,0]
	v_pk_add_f32 v[88:89], v[120:121], v[120:121] op_sel:[0,1] op_sel_hi:[1,0]
	v_pk_add_f32 v[90:91], v[102:103], v[102:103] op_sel:[0,1] op_sel_hi:[1,0]
	v_pk_add_f32 v[96:97], v[150:151], v[92:93]
	v_add_f32_e32 v84, v84, v85
	v_mov_b32_e32 v85, v100
	v_mov_b32_e32 v87, v101
	v_mov_b32_e32 v89, v96
	v_mov_b32_e32 v91, v97
	v_pk_add_f32 v[84:85], v[84:85], v[86:87]
	v_pk_add_f32 v[86:87], v[88:89], v[90:91]
	s_addk_i32 s42, 0x80
	v_pk_add_f32 v[84:85], v[84:85], v[86:87]
	s_cmpk_lg_i32 s42, 0x10e0
	v_pk_add_f32 v[98:99], v[84:85], v[84:85] op_sel:[0,1] op_sel_hi:[1,0]
	s_waitcnt vmcnt(6)
	v_lshlrev_b32_e32 v84, 16, v130
	v_and_b32_e32 v85, 0xffff0000, v130
	v_pk_add_f32 v[94:95], v[152:153], v[84:85]
	v_lshlrev_b32_e32 v84, 16, v131
	v_and_b32_e32 v85, 0xffff0000, v131
	v_pk_add_f32 v[92:93], v[154:155], v[84:85]
	v_mov_b32_e32 v84, v94
	v_mov_b32_e32 v85, v92
	v_mov_b32_e32 v86, v95
	v_mov_b32_e32 v87, v93
	v_pk_add_f32 v[84:85], v[84:85], v[86:87]
	s_nop 0
	v_pk_add_f32 v[130:131], v[84:85], v[84:85] op_sel:[0,1] op_sel_hi:[1,0]
	s_waitcnt vmcnt(5)
	v_lshlrev_b32_e32 v84, 16, v128
	v_and_b32_e32 v85, 0xffff0000, v128
	v_pk_add_f32 v[90:91], v[156:157], v[84:85]
	v_lshlrev_b32_e32 v84, 16, v129
	v_and_b32_e32 v85, 0xffff0000, v129
	v_pk_add_f32 v[88:89], v[158:159], v[84:85]
	s_waitcnt vmcnt(4)
	v_lshlrev_b32_e32 v84, 16, v126
	v_and_b32_e32 v85, 0xffff0000, v126
	v_pk_add_f32 v[86:87], v[206:207], v[84:85]
	v_lshlrev_b32_e32 v84, 16, v127
	v_and_b32_e32 v85, 0xffff0000, v127
	v_pk_add_f32 v[128:129], v[90:91], v[90:91] op_sel:[0,1] op_sel_hi:[1,0]
	v_pk_add_f32 v[134:135], v[88:89], v[88:89] op_sel:[0,1] op_sel_hi:[1,0]
	v_pk_add_f32 v[84:85], v[208:209], v[84:85]
	v_mov_b32_e32 v99, v86
	v_mov_b32_e32 v131, v87
	v_mov_b32_e32 v129, v84
	v_mov_b32_e32 v135, v85
	v_pk_add_f32 v[98:99], v[98:99], v[130:131]
	v_pk_add_f32 v[126:127], v[128:129], v[134:135]
	s_nop 0
	v_pk_add_f32 v[98:99], v[98:99], v[126:127]
	v_and_b32_e32 v126, 64, v235
	v_add_f32_e32 v98, v98, v99
	v_xor_b32_e32 v99, 16, v235
	v_add_u32_e32 v126, 64, v126
	v_cmp_lt_i32_e32 vcc, v99, v126
	s_nop 1
	v_cndmask_b32_e32 v99, v235, v99, vcc
	v_lshlrev_b32_e32 v146, 2, v99
	ds_bpermute_b32 v99, v146, v98
	s_waitcnt lgkmcnt(0)
	v_add_f32_e32 v98, v98, v99
	v_xor_b32_e32 v99, 32, v235
	v_cmp_lt_i32_e32 vcc, v99, v126
	s_nop 1
	v_cndmask_b32_e32 v99, v235, v99, vcc
	v_lshlrev_b32_e32 v147, 2, v99
	ds_bpermute_b32 v99, v147, v98
	s_waitcnt lgkmcnt(0)
	v_add_f32_e32 v148, v98, v99
	v_fmamk_f32 v126, v148, 0xbc000000, v141
	v_fmamk_f32 v134, v148, 0xbc000000, v143
	v_fmamk_f32 v127, v148, 0xbc000000, v137
	v_fmac_f32_e32 v136, 0xbc000000, v148
	v_fmamk_f32 v135, v148, 0xbc000000, v139
	v_fmac_f32_e32 v138, 0xbc000000, v148
	v_fmac_f32_e32 v140, 0xbc000000, v148
	v_fmac_f32_e32 v142, 0xbc000000, v148
	v_mov_b32_e32 v143, v138
	v_pk_mul_f32 v[98:99], v[134:135], v[134:135]
	v_mov_b32_e32 v141, v136
	v_pk_mul_f32 v[128:129], v[126:127], v[126:127]
	v_pk_fma_f32 v[98:99], v[142:143], v[142:143], v[98:99]
	v_pk_fma_f32 v[128:129], v[140:141], v[140:141], v[128:129]
	v_fmamk_f32 v133, v148, 0xbc000000, v133
	v_pk_add_f32 v[98:99], v[98:99], v[128:129]
	v_fmac_f32_e32 v132, 0xbc000000, v148
	v_fmamk_f32 v123, v148, 0xbc000000, v123
	v_fmac_f32_e32 v122, 0xbc000000, v148
	v_pk_add_f32 v[98:99], v[98:99], v[98:99] op_sel_hi:[0,1]
	v_pk_mul_f32 v[128:129], v[122:123], v[122:123]
	v_pk_mul_f32 v[130:131], v[132:133], v[132:133]
	v_fmac_f32_e32 v120, 0xbc000000, v148
	v_pk_mov_b32 v[144:145], v[130:131], v[128:129] op_sel:[1,0]
	v_mov_b32_e32 v131, v129
	v_fmamk_f32 v121, v148, 0xbc000000, v121
	v_fmac_f32_e32 v102, 0xbc000000, v148
	v_mul_f32_e32 v98, v120, v120
	v_pk_add_f32 v[128:129], v[144:145], v[130:131]
	v_fmamk_f32 v103, v148, 0xbc000000, v103
	v_pk_fma_f32 v[130:131], v[120:121], v[120:121], v[98:99] op_sel_hi:[1,1,0]
	v_mul_f32_e32 v98, v102, v102
	v_pk_add_f32 v[128:129], v[128:129], v[128:129] op_sel_hi:[0,1]
	v_pk_fma_f32 v[144:145], v[102:103], v[102:103], v[98:99] op_sel_hi:[1,1,0]
	v_fmamk_f32 v137, v148, 0xbc000000, v97
	v_fmac_f32_e32 v96, 0xbc000000, v148
	v_fmamk_f32 v139, v148, 0xbc000000, v101
	v_fmac_f32_e32 v100, 0xbc000000, v148
	v_mul_f32_e32 v130, v100, v100
	v_mul_f32_e32 v144, v139, v139
	v_mul_f32_e32 v128, v96, v96
	v_mul_f32_e32 v98, v137, v137
	v_pk_add_f32 v[130:131], v[130:131], v[144:145]
	v_pk_add_f32 v[98:99], v[128:129], v[98:99]
	v_fmamk_f32 v95, v148, 0xbc000000, v95
	v_pk_add_f32 v[98:99], v[130:131], v[98:99]
	v_fmac_f32_e32 v94, 0xbc000000, v148
	v_fmamk_f32 v93, v148, 0xbc000000, v93
	v_fmac_f32_e32 v92, 0xbc000000, v148
	v_pk_add_f32 v[98:99], v[98:99], v[98:99] op_sel_hi:[0,1]
	v_pk_mul_f32 v[128:129], v[92:93], v[92:93]
	v_pk_mul_f32 v[130:131], v[94:95], v[94:95]
	v_fmac_f32_e32 v90, 0xbc000000, v148
	v_pk_mov_b32 v[144:145], v[130:131], v[128:129] op_sel:[1,0]
	v_mov_b32_e32 v131, v129
	v_fmamk_f32 v91, v148, 0xbc000000, v91
	v_fmac_f32_e32 v88, 0xbc000000, v148
	v_mul_f32_e32 v98, v90, v90
	v_pk_add_f32 v[128:129], v[144:145], v[130:131]
	v_fmamk_f32 v89, v148, 0xbc000000, v89
	v_pk_fma_f32 v[130:131], v[90:91], v[90:91], v[98:99] op_sel_hi:[1,1,0]
	v_mul_f32_e32 v98, v88, v88
	v_pk_add_f32 v[128:129], v[128:129], v[128:129] op_sel_hi:[0,1]
	v_pk_fma_f32 v[144:145], v[88:89], v[88:89], v[98:99] op_sel_hi:[1,1,0]
	v_fmamk_f32 v85, v148, 0xbc000000, v85
	v_fmac_f32_e32 v84, 0xbc000000, v148
	v_fmamk_f32 v97, v148, 0xbc000000, v87
	v_fmac_f32_e32 v86, 0xbc000000, v148
	v_mul_f32_e32 v130, v86, v86
	v_mul_f32_e32 v144, v97, v97
	v_mul_f32_e32 v128, v84, v84
	v_mul_f32_e32 v98, v85, v85
	v_pk_add_f32 v[130:131], v[130:131], v[144:145]
	v_pk_add_f32 v[98:99], v[128:129], v[98:99]
	v_lshlrev_b32_e32 v144, 16, v125
	v_pk_add_f32 v[98:99], v[130:131], v[98:99]
	s_nop 0
	v_add_f32_e32 v87, v98, v99
	ds_bpermute_b32 v98, v146, v87
	v_and_b32_e32 v146, 0xffff0000, v125
	s_waitcnt lgkmcnt(0)
; __device__ __forceinline__ float fast_sigmoid(float x) { return __builtin_amdgcn_rcpf(1.0f + __expf(-x)); }
; #define GAS __attribute__((address_space(1)))
; #define LAS __attribute__((address_space(3)))
; __device__ __forceinline__ unsigned pk2(float lo, float hi) { return pg8::cvt_pk_bf16(lo, hi); }
; __device__ __forceinline__ float bf_lo(unsigned w) { return __uint_as_float(w << 16); }
; __device__ __forceinline__ float bf_hi(unsigned w) { return __uint_as_float(w & 0xffff0000u); }
; __device__ __forceinline__ float fast_rsqrt(float x) { return __builtin_amdgcn_rsqf(x); }
; template <int DIR, bool INTRA, bool FINAL> __device__ __forceinline__ void retention_pass(LAS unsigned char* lds, const bf16* ZH, bf16* YF, bf16* MIX, const float* ld, const float* gn, int seq, int h, int n0, int ncnt, ...
;     ...
;                 const float rstd = fast_rsqrt(q * (1.f / 128.f) + GN_EPS);
;                 bf16* mp = MIX + (size_t)row * D + h * HD + 4 * lg;
; #pragma unroll
;                 for (int e = 0; e < 8; ++e) { const v2u gw2 = gwv[e]; const f32x4 gg = *(const LAS f32x4*)(lds + R_GN + (16 * e + 4 * lg) * 4);
;                     const float g0 = bf_lo(gw2.x), g1 = bf_hi(gw2.x), g2 = bf_lo(gw2.y), g3 = bf_hi(gw2.y);
;                     v2u o; o.x = pk2(g0 * pg8::fast_sigmoid(g0) * (y[e][0] * rstd * gg.x), g1 * pg8::fast_sigmoid(g1) * (y[e][1] * rstd * gg.y));
;                     o.y = pk2(g2 * pg8::fast_sigmoid(g2) * (y[e][2] * rstd * gg.z), g3 * pg8::fast_sigmoid(g3) * (y[e][3] * rstd * gg.w));
;                     *(GAS v2u*)(mp + 16 * e) = o; }
	v_add_f32_e32 v87, v87, v98
	ds_bpermute_b32 v98, v147, v87
	s_waitcnt lgkmcnt(0)
	v_add_f32_e32 v87, v87, v98
	v_lshlrev_b64 v[98:99], 13, v[118:119]
	v_lshlrev_b32_e32 v118, 16, v124
	v_mul_f32_e32 v101, 0xbfb8aa3b, v118
	v_exp_f32_e32 v101, v101
	v_lshl_add_u64 v[98:99], s[54:55], 0, v[98:99]
	v_lshl_add_u64 v[98:99], v[98:99], 0, v[2:3]
	v_add_u32_e32 v2, 0, v174
	v_and_b32_e32 v124, 0xffff0000, v124
	v_add_f32_e32 v101, 1.0, v101
	v_add_u32_e32 v2, 0x23000, v2
	v_rcp_f32_e32 v148, v101
	v_mul_f32_e32 v101, 0xbfb8aa3b, v124
	ds_read_b128 v[128:131], v2
	v_exp_f32_e32 v101, v101
	v_fmamk_f32 v87, v87, 0x3c000000, v234
	v_rsq_f32_e32 v87, v87
	v_add_f32_e32 v101, 1.0, v101
	s_waitcnt lgkmcnt(0)
	v_mov_b32_e32 v149, v128
	v_rcp_f32_e32 v128, v101
	v_mul_f32_e32 v119, v142, v87
	v_pk_mul_f32 v[118:119], v[148:149], v[118:119]
	v_mul_f32_e32 v125, v134, v87
	v_mul_f32_e32 v141, v118, v119
	v_mul_f32_e32 v101, 0xbfb8aa3b, v144
	v_pk_mul_f32 v[118:119], v[128:129], v[124:125]
	v_exp_f32_e32 v101, v101
	v_mul_f32_e32 v118, v118, v119
	v_mul_f32_e32 v119, 0xbfb8aa3b, v146
	v_exp_f32_e32 v119, v119
	v_add_f32_e32 v101, 1.0, v101
	v_rcp_f32_e32 v124, v101
	v_mov_b32_e32 v125, v130
	v_add_f32_e32 v101, 1.0, v119
	v_rcp_f32_e32 v130, v101
	v_mul_f32_e32 v145, v140, v87
	v_pk_mul_f32 v[124:125], v[124:125], v[144:145]
	v_mul_f32_e32 v147, v126, v87
	v_mul_f32_e32 v101, v124, v125
	v_pk_mul_f32 v[124:125], v[130:131], v[146:147]
	v_cvt_pk_bf16_f32 v118, v141, v118
	v_and_b32_e32 v126, 0xffff0000, v117
	v_mul_f32_e32 v119, v124, v125
	v_cvt_pk_bf16_f32 v119, v101, v119
	global_store_dwordx2 v[98:99], v[118:119], off
	v_lshlrev_b32_e32 v118, 16, v116
	v_mul_f32_e32 v101, 0xbfb8aa3b, v118
	v_exp_f32_e32 v101, v101
	v_and_b32_e32 v116, 0xffff0000, v116
	ds_read_b128 v[128:131], v2 offset:64
	v_lshlrev_b32_e32 v124, 16, v117
	v_add_f32_e32 v101, 1.0, v101
	v_rcp_f32_e32 v140, v101
	v_mul_f32_e32 v101, 0xbfb8aa3b, v116
	v_exp_f32_e32 v101, v101
	s_waitcnt lgkmcnt(0)
	v_mov_b32_e32 v141, v128
	v_mul_f32_e32 v117, v135, v87
	v_mul_f32_e32 v119, v138, v87
	v_add_f32_e32 v101, 1.0, v101
	v_rcp_f32_e32 v128, v101
	v_mul_f32_e32 v101, 0xbfb8aa3b, v124
	v_exp_f32_e32 v101, v101
	v_pk_mul_f32 v[118:119], v[140:141], v[118:119]
	v_pk_mul_f32 v[116:117], v[128:129], v[116:117]
	v_mul_f32_e32 v118, v118, v119
	v_mul_f32_e32 v116, v116, v117
	v_mul_f32_e32 v117, 0xbfb8aa3b, v126
	v_exp_f32_e32 v117, v117
	v_add_f32_e32 v101, 1.0, v101
	v_cvt_pk_bf16_f32 v116, v118, v116
	v_rcp_f32_e32 v118, v101
	v_add_f32_e32 v101, 1.0, v117
	v_mov_b32_e32 v119, v130
	v_rcp_f32_e32 v130, v101
	v_mul_f32_e32 v125, v136, v87
	v_pk_mul_f32 v[118:119], v[118:119], v[124:125]
	v_mul_f32_e32 v127, v127, v87
	v_mul_f32_e32 v101, v118, v119
	v_pk_mul_f32 v[118:119], v[130:131], v[126:127]
	v_lshlrev_b32_e32 v124, 16, v114
	v_mul_f32_e32 v117, v118, v119
	v_cvt_pk_bf16_f32 v117, v101, v117
	v_mul_f32_e32 v101, 0xbfb8aa3b, v124
	v_exp_f32_e32 v101, v101
	v_and_b32_e32 v114, 0xffff0000, v114
	global_store_dwordx2 v[98:99], v[116:117], off offset:32
	ds_read_b128 v[116:119], v2 offset:128
	v_add_f32_e32 v101, 1.0, v101
	v_rcp_f32_e32 v130, v101
	v_mul_f32_e32 v101, 0xbfb8aa3b, v114
	v_exp_f32_e32 v101, v101
	s_waitcnt lgkmcnt(0)
	v_mov_b32_e32 v131, v116
	v_lshlrev_b32_e32 v126, 16, v115
	v_and_b32_e32 v128, 0xffff0000, v115
	v_add_f32_e32 v101, 1.0, v101
	v_rcp_f32_e32 v116, v101
	v_mul_f32_e32 v115, v133, v87
	v_mul_f32_e32 v101, 0xbfb8aa3b, v126
	v_exp_f32_e32 v101, v101
	v_pk_mul_f32 v[114:115], v[116:117], v[114:115]
	v_mov_b32_e32 v117, v118
	v_mul_f32_e32 v114, v114, v115
	v_mul_f32_e32 v115, 0xbfb8aa3b, v128
	v_exp_f32_e32 v115, v115
	v_add_f32_e32 v101, 1.0, v101
	v_rcp_f32_e32 v116, v101
	v_mul_f32_e32 v127, v122, v87
	v_add_f32_e32 v101, 1.0, v115
	v_rcp_f32_e32 v118, v101
	v_pk_mul_f32 v[116:117], v[116:117], v[126:127]
	v_mul_f32_e32 v129, v123, v87
	v_mul_f32_e32 v125, v132, v87
	v_mul_f32_e32 v101, v116, v117
	v_pk_mul_f32 v[116:117], v[118:119], v[128:129]
	v_pk_mul_f32 v[124:125], v[130:131], v[124:125]
	v_mul_f32_e32 v115, v116, v117
	v_lshlrev_b32_e32 v118, 16, v112
	v_mul_f32_e32 v124, v124, v125
	v_cvt_pk_bf16_f32 v114, v124, v114
	v_cvt_pk_bf16_f32 v115, v101, v115
	v_mul_f32_e32 v101, 0xbfb8aa3b, v118
	v_exp_f32_e32 v101, v101
	v_and_b32_e32 v112, 0xffff0000, v112
	global_store_dwordx2 v[98:99], v[114:115], off offset:64
	ds_read_b128 v[114:117], v2 offset:192
	v_add_f32_e32 v101, 1.0, v101
	v_rcp_f32_e32 v126, v101
	v_mul_f32_e32 v101, 0xbfb8aa3b, v112
	v_exp_f32_e32 v101, v101
	s_waitcnt lgkmcnt(0)
	v_mov_b32_e32 v127, v114
	v_lshlrev_b32_e32 v122, 16, v113
	v_and_b32_e32 v124, 0xffff0000, v113
	v_add_f32_e32 v101, 1.0, v101
	v_rcp_f32_e32 v114, v101
	v_mul_f32_e32 v113, v121, v87
	v_mul_f32_e32 v101, 0xbfb8aa3b, v122
	v_exp_f32_e32 v101, v101
	v_pk_mul_f32 v[112:113], v[114:115], v[112:113]
	v_mov_b32_e32 v115, v116
	v_mul_f32_e32 v112, v112, v113
	v_mul_f32_e32 v113, 0xbfb8aa3b, v124
	v_exp_f32_e32 v113, v113
	v_add_f32_e32 v101, 1.0, v101
	v_rcp_f32_e32 v114, v101
	v_mul_f32_e32 v125, v103, v87
	v_add_f32_e32 v101, 1.0, v113
	v_rcp_f32_e32 v116, v101
	v_mul_f32_e32 v119, v120, v87
	v_mul_f32_e32 v123, v102, v87
	v_pk_mul_f32 v[118:119], v[126:127], v[118:119]
	v_pk_mul_f32 v[102:103], v[116:117], v[124:125]
	v_pk_mul_f32 v[114:115], v[114:115], v[122:123]
	v_mul_f32_e32 v102, v102, v103
	v_mul_f32_e32 v118, v118, v119
	v_cvt_pk_bf16_f32 v112, v118, v112
	v_mul_f32_e32 v101, v114, v115
	v_cvt_pk_bf16_f32 v113, v101, v102
	s_waitcnt vmcnt(6)
; __device__ __forceinline__ float fast_sigmoid(float x) { return __builtin_amdgcn_rcpf(1.0f + __expf(-x)); }
; #define GAS __attribute__((address_space(1)))
; #define LAS __attribute__((address_space(3)))
; __device__ __forceinline__ unsigned pk2(float lo, float hi) { return pg8::cvt_pk_bf16(lo, hi); }
; __device__ __forceinline__ float bf_lo(unsigned w) { return __uint_as_float(w << 16); }
; __device__ __forceinline__ float bf_hi(unsigned w) { return __uint_as_float(w & 0xffff0000u); }
; template <int DIR, bool INTRA, bool FINAL> __device__ __forceinline__ void retention_pass(LAS unsigned char* lds, const bf16* ZH, bf16* YF, bf16* MIX, const float* ld, const float* gn, int seq, int h, int n0, int ncnt, ...
;     ...
;                 bf16* mp = MIX + (size_t)row * D + h * HD + 4 * lg;
; #pragma unroll
;                 for (int e = 0; e < 8; ++e) { const v2u gw2 = gwv[e]; const f32x4 gg = *(const LAS f32x4*)(lds + R_GN + (16 * e + 4 * lg) * 4);
;                     const float g0 = bf_lo(gw2.x), g1 = bf_hi(gw2.x), g2 = bf_lo(gw2.y), g3 = bf_hi(gw2.y);
;                     v2u o; o.x = pk2(g0 * pg8::fast_sigmoid(g0) * (y[e][0] * rstd * gg.x), g1 * pg8::fast_sigmoid(g1) * (y[e][1] * rstd * gg.y));
;                     o.y = pk2(g2 * pg8::fast_sigmoid(g2) * (y[e][2] * rstd * gg.z), g3 * pg8::fast_sigmoid(g3) * (y[e][3] * rstd * gg.w));
;                     *(GAS v2u*)(mp + 16 * e) = o; }
	v_lshlrev_b32_e32 v102, 16, v110
	v_mul_f32_e32 v101, 0xbfb8aa3b, v102
	v_exp_f32_e32 v101, v101
	global_store_dwordx2 v[98:99], v[112:113], off offset:96
	ds_read_b128 v[112:115], v2 offset:256
	v_and_b32_e32 v110, 0xffff0000, v110
	v_add_f32_e32 v101, 1.0, v101
	v_rcp_f32_e32 v120, v101
	v_mul_f32_e32 v103, v100, v87
	v_mul_f32_e32 v100, 0xbfb8aa3b, v110
	v_lshlrev_b32_e32 v116, 16, v111
	v_and_b32_e32 v118, 0xffff0000, v111
	v_exp_f32_e32 v111, v100
	s_waitcnt lgkmcnt(0)
	v_mov_b32_e32 v121, v112
	v_pk_mul_f32 v[100:101], v[120:121], v[102:103]
	v_mul_f32_e32 v117, v96, v87
	v_mul_f32_e32 v102, v100, v101
	v_add_f32_e32 v100, 1.0, v111
	v_rcp_f32_e32 v112, v100
	v_mul_f32_e32 v111, v139, v87
	v_mul_f32_e32 v100, 0xbfb8aa3b, v116
	v_exp_f32_e32 v103, v100
	v_pk_mul_f32 v[100:101], v[112:113], v[110:111]
	v_mul_f32_e32 v119, v137, v87
	v_mul_f32_e32 v100, v100, v101
	v_cvt_pk_bf16_f32 v100, v102, v100
	v_mul_f32_e32 v102, 0xbfb8aa3b, v118
	v_exp_f32_e32 v110, v102
	v_add_f32_e32 v101, 1.0, v103
	v_rcp_f32_e32 v102, v101
	v_mov_b32_e32 v103, v114
	v_add_f32_e32 v96, 1.0, v110
	v_rcp_f32_e32 v114, v96
	v_pk_mul_f32 v[102:103], v[102:103], v[116:117]
	s_waitcnt vmcnt(6)
	v_lshlrev_b32_e32 v110, 16, v108
	v_mul_f32_e32 v96, v102, v103
	v_pk_mul_f32 v[102:103], v[114:115], v[118:119]
	v_and_b32_e32 v108, 0xffff0000, v108
	v_mul_f32_e32 v101, v102, v103
	v_cvt_pk_bf16_f32 v101, v96, v101
	v_mul_f32_e32 v117, v94, v87
	v_mul_f32_e32 v94, 0xbfb8aa3b, v108
	global_store_dwordx2 v[98:99], v[100:101], off offset:128
	ds_read_b128 v[100:103], v2 offset:320
	v_exp_f32_e32 v94, v94
	v_lshlrev_b32_e32 v112, 16, v109
	v_and_b32_e32 v114, 0xffff0000, v109
	v_mul_f32_e32 v95, v95, v87
	v_add_f32_e32 v94, 1.0, v94
	s_waitcnt lgkmcnt(0)
	v_mov_b32_e32 v111, v100
	v_rcp_f32_e32 v94, v94
	v_mul_f32_e32 v100, 0xbfb8aa3b, v112
	v_exp_f32_e32 v100, v100
	v_mov_b32_e32 v109, v101
	v_pk_mul_f32 v[94:95], v[94:95], v[108:109]
	v_mul_f32_e32 v96, 0xbfb8aa3b, v110
	v_mul_f32_e32 v94, v94, v95
	v_add_f32_e32 v95, 1.0, v100
	v_exp_f32_e32 v96, v96
	v_rcp_f32_e32 v100, v95
	v_mul_f32_e32 v95, 0xbfb8aa3b, v114
	v_exp_f32_e32 v95, v95
	v_add_f32_e32 v96, 1.0, v96
	v_rcp_f32_e32 v116, v96
	v_mul_f32_e32 v101, v92, v87
	v_add_f32_e32 v92, 1.0, v95
	v_rcp_f32_e32 v92, v92
	v_mov_b32_e32 v113, v102
	v_pk_mul_f32 v[110:111], v[116:117], v[110:111]
	v_pk_mul_f32 v[100:101], v[100:101], v[112:113]
	v_mul_f32_e32 v93, v93, v87
	v_mov_b32_e32 v115, v103
	v_mul_f32_e32 v96, v110, v111
	v_mul_f32_e32 v95, v100, v101
	v_pk_mul_f32 v[92:93], v[92:93], v[114:115]
	s_waitcnt vmcnt(6)
	v_lshlrev_b32_e32 v100, 16, v106
	v_and_b32_e32 v102, 0xffff0000, v106
	v_cvt_pk_bf16_f32 v94, v96, v94
	v_mul_f32_e32 v92, v92, v93
	v_cvt_pk_bf16_f32 v95, v95, v92
	v_mul_f32_e32 v96, 0xbfb8aa3b, v100
	v_mul_f32_e32 v111, v90, v87
	v_mul_f32_e32 v90, 0xbfb8aa3b, v102
	global_store_dwordx2 v[98:99], v[94:95], off offset:160
	ds_read_b128 v[92:95], v2 offset:384
	v_exp_f32_e32 v96, v96
	v_exp_f32_e32 v90, v90
	v_lshlrev_b32_e32 v106, 16, v107
	v_mul_f32_e32 v91, v91, v87
	v_add_f32_e32 v96, 1.0, v96
	v_add_f32_e32 v90, 1.0, v90
	v_rcp_f32_e32 v110, v96
	v_rcp_f32_e32 v90, v90
	s_waitcnt lgkmcnt(0)
	v_mov_b32_e32 v103, v93
	v_mul_f32_e32 v93, 0xbfb8aa3b, v106
	v_exp_f32_e32 v93, v93
	v_mov_b32_e32 v101, v92
	v_pk_mul_f32 v[100:101], v[110:111], v[100:101]
	v_pk_mul_f32 v[90:91], v[90:91], v[102:103]
	v_and_b32_e32 v108, 0xffff0000, v107
	v_mul_f32_e32 v92, v100, v101
	v_mul_f32_e32 v90, v90, v91
	v_add_f32_e32 v91, 1.0, v93
	v_cvt_pk_bf16_f32 v90, v92, v90
	v_rcp_f32_e32 v92, v91
	v_mul_f32_e32 v91, 0xbfb8aa3b, v108
	v_exp_f32_e32 v91, v91
	v_mul_f32_e32 v93, v88, v87
	v_mov_b32_e32 v107, v94
	v_pk_mul_f32 v[92:93], v[92:93], v[106:107]
	v_add_f32_e32 v88, 1.0, v91
	v_rcp_f32_e32 v88, v88
	v_mul_f32_e32 v89, v89, v87
	v_mov_b32_e32 v109, v95
	v_mul_f32_e32 v91, v92, v93
	v_pk_mul_f32 v[88:89], v[88:89], v[108:109]
	s_waitcnt vmcnt(6)
	v_lshlrev_b32_e32 v92, 16, v104
	v_mul_f32_e32 v88, v88, v89
	v_cvt_pk_bf16_f32 v91, v91, v88
	global_store_dwordx2 v[98:99], v[90:91], off offset:192
	ds_read_b128 v[88:91], v2 offset:448
	v_mul_f32_e32 v2, 0xbfb8aa3b, v92
	v_exp_f32_e32 v2, v2
	v_and_b32_e32 v94, 0xffff0000, v104
	v_mul_f32_e32 v103, v86, v87
	s_waitcnt lgkmcnt(0)
	v_mov_b32_e32 v93, v88
	v_add_f32_e32 v2, 1.0, v2
	v_rcp_f32_e32 v102, v2
	v_mul_f32_e32 v2, 0xbfb8aa3b, v94
	v_exp_f32_e32 v2, v2
	v_lshlrev_b32_e32 v96, 16, v105
	v_pk_mul_f32 v[92:93], v[102:103], v[92:93]
	v_mov_b32_e32 v95, v89
	v_add_f32_e32 v2, 1.0, v2
	v_mul_f32_e32 v86, v92, v93
	v_rcp_f32_e32 v92, v2
	v_mul_f32_e32 v2, 0xbfb8aa3b, v96
	v_exp_f32_e32 v2, v2
	v_mul_f32_e32 v93, v97, v87
	v_pk_mul_f32 v[88:89], v[92:93], v[94:95]
	v_and_b32_e32 v100, 0xffff0000, v105
	v_mul_f32_e32 v88, v88, v89
	v_add_f32_e32 v2, 1.0, v2
	v_cvt_pk_bf16_f32 v86, v86, v88
	v_rcp_f32_e32 v88, v2
	v_mul_f32_e32 v2, 0xbfb8aa3b, v100
	v_exp_f32_e32 v2, v2
	v_mul_f32_e32 v89, v84, v87
	v_mov_b32_e32 v97, v90
	v_mul_f32_e32 v85, v85, v87
	v_add_f32_e32 v2, 1.0, v2
	v_rcp_f32_e32 v84, v2
	v_mov_b32_e32 v101, v91
	v_pk_mul_f32 v[88:89], v[88:89], v[96:97]
	v_pk_mul_f32 v[84:85], v[84:85], v[100:101]
	v_mul_f32_e32 v2, v88, v89
	v_mul_f32_e32 v84, v84, v85
	v_cvt_pk_bf16_f32 v87, v2, v84
	global_store_dwordx2 v[98:99], v[86:87], off offset:224
	s_cbranch_scc0 .LBB0_988
; #define LAS __attribute__((address_space(3)))
; #define WG_BARRIER() do { asm volatile("s_waitcnt lgkmcnt(0)" ::: "memory"); __builtin_amdgcn_s_barrier(); asm volatile("" ::: "memory"); } while (0)
; __device__ __forceinline__ unsigned pk2(float lo, float hi) { return pg8::cvt_pk_bf16(lo, hi); }
; __device__ __forceinline__ v4u scale8(v4u x, float sc) { v4u o; o.x = pk2(bf_lo(x.x) * sc, bf_hi(x.x) * sc); o.y = pk2(bf_lo(x.y) * sc, bf_hi(x.y) * sc); o.z = pk2(bf_lo(x.z) * sc, bf_hi(x.z) * sc); o.w = pk2(bf_lo(x.w) * sc, bf_hi(x.w) * sc); return o; }
; template <int DIR, bool INTRA, bool FINAL> __device__ __forceinline__ void retention_pass(LAS unsigned char* lds, const bf16* ZH, bf16* YF, bf16* MIX, const float* ld, const float* gn, int seq, int h, int n0, int ncnt, ...
;     ...
;             const int n = DIR == 0 ? n0 + cn : n0 + ncnt - 1 - cn, nn = DIR == 0 ? n + 1 : n - 1;
;             const int r0 = rowbase + n * 128;
;             int tid = tid0; float lf = lf0, lb = lb0; asm volatile("" : "+v"(tid), "+v"(lf), "+v"(lb));
;             const int w = tid >> 6, l = tid & 63, lr = l & 15, lg = l >> 4, srow = tid >> 4, sch = tid & 15;
;             LAS unsigned char* trp = lds + (4 * lg + ((l & 15) >> 2)) * RSB + (l & 3) * 8;
;             WG_BARRIER();
; #pragma unroll
;             for (int cc = 0; cc < 4; ++cc) { const int row = srow + 32 * cc;
;                 if constexpr (INTRA) *(LAS v4u*)(lds + R_K + row * RS + 16 * sch) = kreg[cc];
;                 const float wj = DIR == 0 ? __expf(lf * (float)(127 - row)) : __expf(lb * (float)row);
;                 *(LAS v4u*)(lds + R_KW + row * RSB + 16 * sch) = scale8(kreg[cc], wj);
;                 *(LAS v4u*)(lds + R_V + row * RSB + 16 * sch) = vreg[cc]; }
; #pragma unroll
;             for (int e = 0; e < 8; ++e) { v2u o; o.x = pk2(st[e][0], st[e][1]); o.y = pk2(st[e][2], st[e][3]); *(LAS v2u*)(lds + R_ST + (16 * e + lr) * RS + (16 * w + 4 * lg) * 2) = o; }
;             WG_BARRIER();
;             bf16x8 qx[4];
;             { const float xi = DIR == 0 ? __expf(lf * (float)(16 * w + lr + 1)) : __expf(lb * (float)(128 - 16 * w - lr));
.LBB0_730:
	s_waitcnt vmcnt(28)
	v_mov_b32_e32 v136, v173
	v_mov_b32_e32 v138, v172
	v_mov_b32_e32 v132, v190
	s_waitcnt vmcnt(27)
	v_and_b32_e32 v85, 0xffff0000, v4
	v_ashrrev_i32_e32 v165, 4, v132
	v_sub_u32_e32 v84, 0x7f, v165
	v_cvt_f32_i32_e32 v84, v84
	v_and_b32_e32 v167, 15, v132
	v_lshlrev_b32_e32 v164, 4, v167
	v_add_u32_e32 v2, 0, v164
	v_mul_f32_e32 v84, v138, v84
	v_mul_f32_e32 v84, 0x3fb8aa3b, v84
	v_exp_f32_e32 v87, v84
	v_lshlrev_b32_e32 v84, 16, v4
	v_mad_u64_u32 v[88:89], s[6:7], v165, s33, v[2:3]
	v_mul_f32_e32 v84, v87, v84
	v_mul_f32_e32 v85, v87, v85
	s_waitcnt lgkmcnt(0)
	s_barrier
	ds_write_b128 v88, v[4:7]
	v_cvt_pk_bf16_f32 v84, v84, v85
	v_lshlrev_b32_e32 v85, 16, v5
	v_and_b32_e32 v86, 0xffff0000, v5
	v_mul_f32_e32 v85, v87, v85
	v_mul_f32_e32 v86, v87, v86
	v_cvt_pk_bf16_f32 v85, v85, v86
	v_lshlrev_b32_e32 v86, 16, v6
	v_and_b32_e32 v89, 0xffff0000, v6
	v_mul_f32_e32 v86, v87, v86
	v_mul_f32_e32 v89, v87, v89
	v_cvt_pk_bf16_f32 v86, v86, v89
	v_lshlrev_b32_e32 v89, 16, v7
	v_and_b32_e32 v91, 0xffff0000, v7
	v_mul_f32_e32 v89, v87, v89
	v_mul_f32_e32 v87, v87, v91
	v_cvt_pk_bf16_f32 v87, v89, v87
	v_mul_lo_u32 v89, v165, s74
	v_add_u32_e32 v90, s93, v164
	v_add_u32_e32 v91, v2, v89
	ds_write_b128 v91, v[84:87] offset:34816
	v_add_u32_e32 v84, v90, v89
	s_waitcnt vmcnt(26)
	ds_write_b128 v84, v[8:11]
	s_waitcnt vmcnt(25)
	ds_write_b128 v88, v[12:15] offset:8704
	v_sub_u32_e32 v84, 0x5f, v165
	v_cvt_f32_i32_e32 v84, v84
	v_and_b32_e32 v85, 0xffff0000, v12
	v_and_b32_e32 v86, 0xffff0000, v13
	v_and_b32_e32 v91, 0xffff0000, v14
	v_mul_f32_e32 v84, v138, v84
	v_mul_f32_e32 v84, 0x3fb8aa3b, v84
	v_exp_f32_e32 v87, v84
	v_lshlrev_b32_e32 v84, 16, v12
	v_and_b32_e32 v92, 0xffff0000, v15
	v_ashrrev_i32_e32 v134, 6, v132
	v_mul_f32_e32 v84, v87, v84
	v_mul_f32_e32 v85, v87, v85
	v_cvt_pk_bf16_f32 v84, v84, v85
	v_lshlrev_b32_e32 v85, 16, v13
	v_mul_f32_e32 v85, v87, v85
	v_mul_f32_e32 v86, v87, v86
	v_cvt_pk_bf16_f32 v85, v85, v86
	v_lshlrev_b32_e32 v86, 16, v14
	v_mul_f32_e32 v86, v87, v86
	v_mul_f32_e32 v91, v87, v91
	v_cvt_pk_bf16_f32 v86, v86, v91
	v_lshlrev_b32_e32 v91, 16, v15
	v_mul_f32_e32 v91, v87, v91
	v_mul_f32_e32 v87, v87, v92
	v_cvt_pk_bf16_f32 v87, v91, v87
	v_add_u32_e32 v91, 0x2400, v89
	v_add_u32_e32 v92, v2, v91
	ds_write_b128 v92, v[84:87] offset:34816
	v_add_u32_e32 v84, v90, v91
	s_waitcnt vmcnt(24)
	ds_write_b128 v84, v[16:19]
	s_waitcnt vmcnt(23)
	ds_write_b128 v88, v[20:23] offset:17408
	v_sub_u32_e32 v84, 63, v165
	v_cvt_f32_i32_e32 v84, v84
	v_and_b32_e32 v85, 0xffff0000, v20
	v_and_b32_e32 v86, 0xffff0000, v21
	v_and_b32_e32 v91, 0xffff0000, v22
	v_mul_f32_e32 v84, v138, v84
	v_mul_f32_e32 v84, 0x3fb8aa3b, v84
	v_exp_f32_e32 v87, v84
	v_lshlrev_b32_e32 v84, 16, v20
	v_and_b32_e32 v92, 0xffff0000, v23
	v_bfe_u32 v100, v132, 4, 2
	v_mul_f32_e32 v84, v87, v84
	v_mul_f32_e32 v85, v87, v85
	v_cvt_pk_bf16_f32 v84, v84, v85
	v_lshlrev_b32_e32 v85, 16, v21
	v_mul_f32_e32 v85, v87, v85
	v_mul_f32_e32 v86, v87, v86
	v_cvt_pk_bf16_f32 v85, v85, v86
	v_lshlrev_b32_e32 v86, 16, v22
	v_mul_f32_e32 v86, v87, v86
	v_mul_f32_e32 v91, v87, v91
	v_cvt_pk_bf16_f32 v86, v86, v91
	v_lshlrev_b32_e32 v91, 16, v23
	v_mul_f32_e32 v91, v87, v91
	v_mul_f32_e32 v87, v87, v92
	v_cvt_pk_bf16_f32 v87, v91, v87
	v_add_u32_e32 v91, 0x4800, v89
	v_add_u32_e32 v92, v2, v91
	ds_write_b128 v92, v[84:87] offset:34816
	v_add_u32_e32 v84, v90, v91
	s_waitcnt vmcnt(22)
	ds_write_b128 v84, v[24:27]
	s_waitcnt vmcnt(21)
	ds_write_b128 v88, v[28:31] offset:26112
	v_sub_u32_e32 v84, 31, v165
	v_cvt_f32_i32_e32 v84, v84
	v_and_b32_e32 v85, 0xffff0000, v28
	v_and_b32_e32 v86, 0xffff0000, v29
	v_and_b32_e32 v88, 0xffff0000, v30
	v_mul_f32_e32 v84, v138, v84
	v_mul_f32_e32 v84, 0x3fb8aa3b, v84
	v_exp_f32_e32 v87, v84
	v_lshlrev_b32_e32 v84, 16, v28
	v_and_b32_e32 v91, 0xffff0000, v31
	v_lshlrev_b32_e32 v133, 5, v134
	v_mul_f32_e32 v84, v87, v84
	v_mul_f32_e32 v85, v87, v85
	v_cvt_pk_bf16_f32 v84, v84, v85
	v_lshlrev_b32_e32 v85, 16, v29
	v_mul_f32_e32 v85, v87, v85
	v_mul_f32_e32 v86, v87, v86
	v_cvt_pk_bf16_f32 v85, v85, v86
	v_lshlrev_b32_e32 v86, 16, v30
	v_mul_f32_e32 v86, v87, v86
	v_mul_f32_e32 v88, v87, v88
	v_cvt_pk_bf16_f32 v86, v86, v88
	v_lshlrev_b32_e32 v88, 16, v31
	v_mul_f32_e32 v88, v87, v88
	v_mul_f32_e32 v87, v87, v91
	v_cvt_pk_bf16_f32 v87, v88, v87
	v_add_u32_e32 v88, 0x6c00, v89
	v_add_u32_e32 v2, v2, v88
	ds_write_b128 v2, v[84:87] offset:34816
	v_add_u32_e32 v2, v90, v88
	s_waitcnt vmcnt(20)
	ds_write_b128 v2, v[32:35]
	v_lshlrev_b32_e32 v176, 3, v100
	v_add_u32_e32 v2, s95, v133
	v_mul_u32_u24_e32 v175, 0x110, v167
	s_waitcnt vmcnt(15)
	v_cvt_pk_bf16_f32 v84, v80, v81
	s_waitcnt vmcnt(14)
	v_cvt_pk_bf16_f32 v85, v82, v83
	v_add3_u32 v2, v2, v176, v175
	ds_write_b64 v2, v[84:85]
	s_waitcnt vmcnt(13)
	v_cvt_pk_bf16_f32 v84, v52, v53
	s_waitcnt vmcnt(12)
	v_cvt_pk_bf16_f32 v85, v54, v55
	ds_write_b64 v2, v[84:85] offset:4352
	s_waitcnt vmcnt(11)
	v_cvt_pk_bf16_f32 v84, v56, v57
	s_waitcnt vmcnt(10)
	v_cvt_pk_bf16_f32 v85, v58, v59
	ds_write_b64 v2, v[84:85] offset:8704
	s_waitcnt vmcnt(9)
	v_cvt_pk_bf16_f32 v84, v60, v61
	s_waitcnt vmcnt(8)
	v_cvt_pk_bf16_f32 v85, v62, v63
	ds_write_b64 v2, v[84:85] offset:13056
	s_waitcnt vmcnt(7)
	v_cvt_pk_bf16_f32 v84, v64, v65
	s_waitcnt vmcnt(6)
	v_cvt_pk_bf16_f32 v85, v66, v67
	ds_write_b64 v2, v[84:85] offset:17408
	s_waitcnt vmcnt(5)
	v_cvt_pk_bf16_f32 v84, v68, v69
	s_waitcnt vmcnt(4)
	v_cvt_pk_bf16_f32 v85, v70, v71
	ds_write_b64 v2, v[84:85] offset:21760
	s_waitcnt vmcnt(3)
	v_cvt_pk_bf16_f32 v84, v72, v73
	s_waitcnt vmcnt(2)
	v_cvt_pk_bf16_f32 v85, v74, v75
	ds_write_b64 v2, v[84:85] offset:26112
	s_waitcnt vmcnt(1)
	v_cvt_pk_bf16_f32 v84, v76, v77
	s_waitcnt vmcnt(0)
	v_cvt_pk_bf16_f32 v85, v78, v79
	ds_write_b64 v2, v[84:85] offset:30464
	v_lshlrev_b32_e32 v2, 4, v134
	v_or_b32_e32 v84, v167, v2
	v_add_u32_e32 v84, 1, v84
	v_cvt_f32_i32_e32 v84, v84
	v_and_b32_e32 v85, 0xffff0000, v36
	s_waitcnt lgkmcnt(0)
	s_barrier
; #define LAS __attribute__((address_space(3)))
; #define MFMA16(a, b, c) __builtin_amdgcn_mfma_f32_16x16x32_bf16((a), (b), (c), 0, 0, 0)
; __device__ __forceinline__ v4u scale8(v4u x, float sc) { v4u o; o.x = pk2(bf_lo(x.x) * sc, bf_hi(x.x) * sc); o.y = pk2(bf_lo(x.y) * sc, bf_hi(x.y) * sc); o.z = pk2(bf_lo(x.z) * sc, bf_hi(x.z) * sc); o.w = pk2(bf_lo(x.w) * sc, bf_hi(x.w) * sc); return o; }
; template <int DIR, bool INTRA, bool FINAL> __device__ __forceinline__ void retention_pass(LAS unsigned char* lds, const bf16* ZH, bf16* YF, bf16* MIX, const float* ld, const float* gn, int seq, int h, int n0, int ncnt, ...
;     ...
;             { const float xi = DIR == 0 ? __expf(lf * (float)(16 * w + lr + 1)) : __expf(lb * (float)(128 - 16 * w - lr));
; #pragma unroll
;               for (int ks = 0; ks < 4; ++ks) qx[ks] = __builtin_bit_cast(bf16x8, scale8(__builtin_bit_cast(v4u, qf[ks]), xi)); }
;             bf16x8 pt[4];
;             if constexpr (INTRA) {
;                 f32x4 s[8];
; #pragma unroll
;                 for (int jt = 0; jt < 8; ++jt) { s[jt] = (f32x4){0.f, 0.f, 0.f, 0.f};
; #pragma unroll
;                     for (int ks = 0; ks < 4; ++ks) { const bf16x8 a = *(const LAS bf16x8*)(lds + R_K + (16 * jt + lr) * RS + (8 * lg + 32 * ks) * 2); s[jt] = MFMA16(a, qf[ks], s[jt]); }
;                     __builtin_amdgcn_sched_barrier(0); }
	s_waitcnt lgkmcnt(0)
	v_mul_f32_e32 v84, v138, v84
	v_mul_f32_e32 v84, 0x3fb8aa3b, v84
	v_exp_f32_e32 v99, v84
	v_lshlrev_b32_e32 v84, 16, v36
	v_and_b32_e32 v86, 0xffff0000, v37
	v_mul_f32_e32 v84, v99, v84
	v_mul_f32_e32 v85, v99, v85
	v_cvt_pk_bf16_f32 v84, v84, v85
	v_lshlrev_b32_e32 v85, 16, v37
	v_mul_f32_e32 v85, v99, v85
	v_mul_f32_e32 v86, v99, v86
	v_cvt_pk_bf16_f32 v85, v85, v86
	v_lshlrev_b32_e32 v86, 16, v38
	v_and_b32_e32 v87, 0xffff0000, v38
	v_mul_f32_e32 v86, v99, v86
	v_mul_f32_e32 v87, v99, v87
	v_cvt_pk_bf16_f32 v86, v86, v87
	v_lshlrev_b32_e32 v87, 16, v39
	v_and_b32_e32 v88, 0xffff0000, v39
	v_mul_f32_e32 v87, v99, v87
	v_mul_f32_e32 v88, v99, v88
	v_cvt_pk_bf16_f32 v87, v87, v88
	v_lshlrev_b32_e32 v88, 16, v40
	v_and_b32_e32 v89, 0xffff0000, v40
	v_mul_f32_e32 v88, v99, v88
	v_mul_f32_e32 v89, v99, v89
	v_cvt_pk_bf16_f32 v88, v88, v89
	v_lshlrev_b32_e32 v89, 16, v41
	v_and_b32_e32 v90, 0xffff0000, v41
	v_mul_f32_e32 v89, v99, v89
	v_mul_f32_e32 v90, v99, v90
	v_cvt_pk_bf16_f32 v89, v89, v90
	v_lshlrev_b32_e32 v90, 16, v42
	v_and_b32_e32 v91, 0xffff0000, v42
	v_mul_f32_e32 v90, v99, v90
	v_mul_f32_e32 v91, v99, v91
	v_cvt_pk_bf16_f32 v90, v90, v91
	v_lshlrev_b32_e32 v91, 16, v43
	v_and_b32_e32 v92, 0xffff0000, v43
	v_mul_f32_e32 v91, v99, v91
	v_mul_f32_e32 v92, v99, v92
	v_cvt_pk_bf16_f32 v91, v91, v92
	v_lshlrev_b32_e32 v92, 16, v44
	v_and_b32_e32 v93, 0xffff0000, v44
	v_mul_f32_e32 v92, v99, v92
	v_mul_f32_e32 v93, v99, v93
	v_cvt_pk_bf16_f32 v92, v92, v93
	v_lshlrev_b32_e32 v93, 16, v45
	v_and_b32_e32 v94, 0xffff0000, v45
	v_mul_f32_e32 v93, v99, v93
	v_mul_f32_e32 v94, v99, v94
	v_cvt_pk_bf16_f32 v93, v93, v94
	v_lshlrev_b32_e32 v94, 16, v46
	v_and_b32_e32 v95, 0xffff0000, v46
	v_mul_f32_e32 v94, v99, v94
	v_mul_f32_e32 v95, v99, v95
	v_cvt_pk_bf16_f32 v94, v94, v95
	v_lshlrev_b32_e32 v95, 16, v47
	v_and_b32_e32 v96, 0xffff0000, v47
	v_mul_f32_e32 v95, v99, v95
	v_mul_f32_e32 v96, v99, v96
	v_cvt_pk_bf16_f32 v95, v95, v96
	v_lshlrev_b32_e32 v96, 16, v48
	v_and_b32_e32 v97, 0xffff0000, v48
	v_mul_f32_e32 v96, v99, v96
	v_mul_f32_e32 v97, v99, v97
	v_cvt_pk_bf16_f32 v96, v96, v97
	v_lshlrev_b32_e32 v97, 16, v49
	v_and_b32_e32 v98, 0xffff0000, v49
	v_mul_f32_e32 v97, v99, v97
	v_mul_f32_e32 v98, v99, v98
	v_cvt_pk_bf16_f32 v97, v97, v98
	v_lshlrev_b32_e32 v98, 16, v50
	v_and_b32_e32 v101, 0xffff0000, v50
	v_mul_f32_e32 v98, v99, v98
	v_mul_f32_e32 v101, v99, v101
	v_cvt_pk_bf16_f32 v98, v98, v101
	v_lshlrev_b32_e32 v101, 16, v51
	v_and_b32_e32 v102, 0xffff0000, v51
	v_lshlrev_b32_e32 v174, 4, v100
	v_mul_f32_e32 v101, v99, v101
	v_mul_f32_e32 v99, v99, v102
	v_add3_u32 v135, 0, v174, v175
	ds_read_b128 v[144:147], v135
	ds_read_b128 v[152:155], v135 offset:64
	ds_read_b128 v[156:159], v135 offset:128
	ds_read_b128 v[168:171], v135 offset:192
	ds_read_b128 v[184:187], v135 offset:4352
	ds_read_b128 v[206:209], v135 offset:4416
	ds_read_b128 v[212:215], v135 offset:4480
	ds_read_b128 v[216:219], v135 offset:4544
	v_lshlrev_b32_e32 v166, 2, v100
	v_cvt_pk_bf16_f32 v99, v101, v99
	s_waitcnt lgkmcnt(7)
	v_mfma_f32_16x16x32_bf16 v[100:103], v[144:147], v[36:39], 0
	ds_read_b128 v[144:147], v135 offset:8704
	s_waitcnt lgkmcnt(7)
	v_mfma_f32_16x16x32_bf16 v[100:103], v[152:155], v[40:43], v[100:103]
	ds_read_b128 v[152:155], v135 offset:8768
	s_waitcnt lgkmcnt(7)
	v_mfma_f32_16x16x32_bf16 v[100:103], v[156:159], v[44:47], v[100:103]
	ds_read_b128 v[156:159], v135 offset:8832
	s_waitcnt lgkmcnt(7)
	v_mfma_f32_16x16x32_bf16 v[100:103], v[168:171], v[48:51], v[100:103]
	ds_read_b128 v[168:171], v135 offset:8896
	s_waitcnt lgkmcnt(7)
	v_mfma_f32_16x16x32_bf16 v[104:107], v[184:187], v[36:39], 0
	ds_read_b128 v[184:187], v135 offset:13056
	s_waitcnt lgkmcnt(7)
	v_mfma_f32_16x16x32_bf16 v[104:107], v[206:209], v[40:43], v[104:107]
	ds_read_b128 v[206:209], v135 offset:13120
	s_waitcnt lgkmcnt(7)
; #define LAS __attribute__((address_space(3)))
; #define MFMA16(a, b, c) __builtin_amdgcn_mfma_f32_16x16x32_bf16((a), (b), (c), 0, 0, 0)
; template <int DIR, bool INTRA, bool FINAL> __device__ __forceinline__ void retention_pass(LAS unsigned char* lds, const bf16* ZH, bf16* YF, bf16* MIX, const float* ld, const float* gn, int seq, int h, int n0, int ncnt, ...
;     ...
;                 for (int jt = 0; jt < 8; ++jt) { s[jt] = (f32x4){0.f, 0.f, 0.f, 0.f};
; #pragma unroll
;                     for (int ks = 0; ks < 4; ++ks) { const bf16x8 a = *(const LAS bf16x8*)(lds + R_K + (16 * jt + lr) * RS + (8 * lg + 32 * ks) * 2); s[jt] = MFMA16(a, qf[ks], s[jt]); }
;                     __builtin_amdgcn_sched_barrier(0); }
;                 float Fr[4], Br[4];
; #pragma unroll
;                 for (int r = 0; r < 4; ++r) { const float br = (float)(lr - 4 * lg - r); Fr[r] = __expf(lf * br); Br[r] = __expf(-lb * br); }
; #pragma unroll
;                 for (int jt = 0; jt < 8; ++jt) { const int dt = w - jt; const float cf = __expf(lf * 16.f * (float)dt), cb = __expf(-lb * 16.f * (float)dt);
; #pragma unroll
;                     for (int r = 0; r < 4; ++r) { const float dec = dt > 0 ? Fr[r] * cf : (dt < 0 ? Br[r] * cb : ((lr - 4 * lg - r) >= 0 ? Fr[r] : Br[r])); s[jt][r] *= dec; } }
	v_mfma_f32_16x16x32_bf16 v[104:107], v[212:215], v[44:47], v[104:107]
	ds_read_b128 v[212:215], v135 offset:13184
	s_waitcnt lgkmcnt(7)
	v_mfma_f32_16x16x32_bf16 v[104:107], v[216:219], v[48:51], v[104:107]
	ds_read_b128 v[216:219], v135 offset:13248
	s_waitcnt lgkmcnt(7)
	v_mfma_f32_16x16x32_bf16 v[108:111], v[144:147], v[36:39], 0
	ds_read_b128 v[144:147], v135 offset:17408
	s_waitcnt lgkmcnt(7)
	v_mfma_f32_16x16x32_bf16 v[108:111], v[152:155], v[40:43], v[108:111]
	ds_read_b128 v[152:155], v135 offset:17472
	s_waitcnt lgkmcnt(7)
	v_mfma_f32_16x16x32_bf16 v[108:111], v[156:159], v[44:47], v[108:111]
	ds_read_b128 v[156:159], v135 offset:17536
	s_waitcnt lgkmcnt(7)
	v_mfma_f32_16x16x32_bf16 v[108:111], v[168:171], v[48:51], v[108:111]
	ds_read_b128 v[168:171], v135 offset:17600
	s_waitcnt lgkmcnt(7)
	v_mfma_f32_16x16x32_bf16 v[112:115], v[184:187], v[36:39], 0
	ds_read_b128 v[184:187], v135 offset:21760
	s_waitcnt lgkmcnt(7)
	v_mfma_f32_16x16x32_bf16 v[112:115], v[206:209], v[40:43], v[112:115]
	ds_read_b128 v[206:209], v135 offset:21824
	s_waitcnt lgkmcnt(7)
	v_mfma_f32_16x16x32_bf16 v[112:115], v[212:215], v[44:47], v[112:115]
	ds_read_b128 v[212:215], v135 offset:21888
	s_waitcnt lgkmcnt(7)
	v_mfma_f32_16x16x32_bf16 v[112:115], v[216:219], v[48:51], v[112:115]
	ds_read_b128 v[216:219], v135 offset:21952
	s_waitcnt lgkmcnt(7)
	v_mfma_f32_16x16x32_bf16 v[116:119], v[144:147], v[36:39], 0
	ds_read_b128 v[144:147], v135 offset:26112
	s_waitcnt lgkmcnt(7)
	v_mfma_f32_16x16x32_bf16 v[116:119], v[152:155], v[40:43], v[116:119]
	ds_read_b128 v[152:155], v135 offset:26176
	s_waitcnt lgkmcnt(7)
	v_mfma_f32_16x16x32_bf16 v[116:119], v[156:159], v[44:47], v[116:119]
	ds_read_b128 v[156:159], v135 offset:26240
	s_waitcnt lgkmcnt(7)
	v_mfma_f32_16x16x32_bf16 v[116:119], v[168:171], v[48:51], v[116:119]
	ds_read_b128 v[168:171], v135 offset:26304
	s_waitcnt lgkmcnt(7)
	v_mfma_f32_16x16x32_bf16 v[120:123], v[184:187], v[36:39], 0
	ds_read_b128 v[184:187], v135 offset:30464
	s_waitcnt lgkmcnt(7)
	v_mfma_f32_16x16x32_bf16 v[120:123], v[206:209], v[40:43], v[120:123]
	ds_read_b128 v[206:209], v135 offset:30528
	s_waitcnt lgkmcnt(7)
	v_mfma_f32_16x16x32_bf16 v[120:123], v[212:215], v[44:47], v[120:123]
	ds_read_b128 v[212:215], v135 offset:30592
	s_waitcnt lgkmcnt(7)
	v_mfma_f32_16x16x32_bf16 v[120:123], v[216:219], v[48:51], v[120:123]
	s_waitcnt lgkmcnt(6)
	v_mfma_f32_16x16x32_bf16 v[124:127], v[144:147], v[36:39], 0
	s_waitcnt lgkmcnt(5)
	v_mfma_f32_16x16x32_bf16 v[124:127], v[152:155], v[40:43], v[124:127]
	s_waitcnt lgkmcnt(4)
	v_mfma_f32_16x16x32_bf16 v[124:127], v[156:159], v[44:47], v[124:127]
	s_waitcnt lgkmcnt(3)
	v_mfma_f32_16x16x32_bf16 v[128:131], v[168:171], v[48:51], v[124:127]
	s_nop 4
	s_waitcnt lgkmcnt(2)
	v_mfma_f32_16x16x32_bf16 v[124:127], v[184:187], v[36:39], 0
	s_waitcnt lgkmcnt(1)
	v_mfma_f32_16x16x32_bf16 v[124:127], v[206:209], v[40:43], v[124:127]
	s_waitcnt lgkmcnt(0)
	v_mfma_f32_16x16x32_bf16 v[124:127], v[212:215], v[44:47], v[124:127]
	ds_read_b128 v[140:143], v135 offset:30656
	s_waitcnt lgkmcnt(0)
	v_mfma_f32_16x16x32_bf16 v[124:127], v[140:143], v[48:51], v[124:127]
	v_sub_u32_e32 v135, v167, v166
	v_cvt_f32_i32_e32 v135, v135
	v_cvt_f32_i32_e32 v137, v134
	v_mul_f32_e32 v151, 0xc1800000, v136
	v_cmp_gt_i32_e64 s[6:7], 1, v134
	v_mul_f32_e32 v139, v138, v135
	v_mul_f32_e64 v135, -v136, v135
	v_mul_f32_e32 v135, 0x3fb8aa3b, v135
	v_exp_f32_e32 v140, v135
	v_mul_f32_e32 v135, v151, v137
	v_mul_f32_e32 v139, 0x3fb8aa3b, v139
	v_mul_f32_e32 v135, 0x3fb8aa3b, v135
	v_exp_f32_e32 v139, v139
	v_exp_f32_e32 v150, v135
	v_cmp_lt_i32_e32 vcc, -1, v134
	s_and_saveexec_b64 s[8:9], s[6:7]
	s_xor_b64 s[34:35], exec, s[8:9]
	s_cbranch_execz .LBB0_736
	s_and_saveexec_b64 s[8:9], vcc
	s_xor_b64 s[46:47], exec, s[8:9]
	v_cmp_lt_u32_e64 s[8:9], v167, v166
	s_nop 1
	v_cndmask_b32_e64 v135, v139, v140, s[8:9]
	s_andn2_saveexec_b64 s[8:9], s[46:47]
	v_mul_f32_e32 v135, v150, v140
	s_or_b64 exec, exec, s[8:9]

; __device__ __forceinline__ unsigned pk2(float lo, float hi) { return pg8::cvt_pk_bf16(lo, hi); }
; #define MFMA16(a, b, c) __builtin_amdgcn_mfma_f32_16x16x32_bf16((a), (b), (c), 0, 0, 0)
; __device__ __forceinline__ bf16x8 ds_tr2(LAS unsigned char* p, int rstride) { const s16x4 a = ds_tr(p), b = ds_tr(p + 16 * rstride); bf16x8 r; r[0] = a[0]; r[1] = a[1]; r[2] = a[2]; r[3] = a[3]; r[4] = b[0]; r[5] = b[1]; r[6] = b[2]; r[7] = b[3]; return r; }
; template <int DIR, bool INTRA, bool FINAL> __device__ __forceinline__ void retention_pass(LAS unsigned char* lds, const bf16* ZH, bf16* YF, bf16* MIX, const float* ld, const float* gn, int seq, int h, int n0, int ncnt, ...
;     ...
;                     for (int r = 0; r < 4; ++r) { const float dec = dt > 0 ? Fr[r] * cf : (dt < 0 ? Br[r] * cb : ((lr - 4 * lg - r) >= 0 ? Fr[r] : Br[r])); s[jt][r] *= dec; } }
; #pragma unroll
;                 for (int ks = 0; ks < 4; ++ks) { v4u o; o.x = pk2(s[2 * ks][0], s[2 * ks][1]); o.y = pk2(s[2 * ks][2], s[2 * ks][3]); o.z = pk2(s[2 * ks + 1][0], s[2 * ks + 1][1]); o.w = pk2(s[2 * ks + 1][2], s[2 * ks + 1][3]); pt[ks] = __builtin_bit_cast(bf16x8, o); }
;             }
;             f32x4 y[8];
; #pragma unroll
;             for (int e = 0; e < 8; ++e) y[e] = (f32x4){0.f, 0.f, 0.f, 0.f};
;             { bf16x8 kwf[4];
; #pragma unroll
;               for (int ks = 0; ks < 4; ++ks) kwf[ks] = ds_tr2(trp + R_KW + (32 * ks) * RSB + (16 * w) * 2, RSB);
; #pragma unroll
;               for (int e = 0; e < 8; ++e) { st[e] = st[e] * gC;
; #pragma unroll
;                 for (int ks = 0; ks < 4; ++ks) { const bf16x8 vf = ds_tr2(trp + R_V + (32 * ks) * RSB + (16 * e) * 2, RSB);
;                     if constexpr (INTRA) y[e] = MFMA16(vf, pt[ks], y[e]);
;                     st[e] = MFMA16(kwf[ks], vf, st[e]); }
;                 __builtin_amdgcn_sched_barrier(0); } }
.LBB0_986:
	s_waitcnt lgkmcnt(0)
	s_or_b64 exec, exec, s[6:7]
	v_mul_f32_e32 v145, v116, v170
	v_lshrrev_b32_e32 v116, 2, v167
	v_or_b32_e32 v116, v166, v116
	v_mul_f32_e32 v100, v100, v135
	v_mul_u32_u24_e32 v135, 0x120, v116
	v_lshlrev_b32_e32 v116, 3, v132
	v_and_b32_e32 v132, 24, v116
	v_mul_f32_e32 v114, v114, v168
	v_mul_f32_e32 v104, v104, v150
	v_add3_u32 v168, 0, v135, v132
	v_mul_f32_e32 v140, v126, v141
	v_mul_f32_e32 v139, v125, v139
	v_mul_f32_e32 v134, v124, v134
	v_mul_f32_e32 v122, v122, v183
	v_mul_f32_e32 v120, v120, v179
	v_mul_f32_e32 v111, v111, v158
	v_mul_f32_e32 v110, v110, v157
	v_mul_f32_e32 v109, v109, v156
	v_mul_f32_e32 v108, v108, v155
	v_mul_f32_e32 v106, v106, v153
	v_mul_f32_e32 v105, v105, v152
	v_mul_f32_e32 v103, v103, v138
	v_mul_f32_e32 v102, v102, v137
	v_mul_f32_e32 v101, v101, v136
	v_cvt_pk_bf16_f32 v124, v100, v101
	v_cvt_pk_bf16_f32 v125, v102, v103
	v_cvt_pk_bf16_f32 v126, v104, v105
	v_add_u32_e32 v104, v168, v133
	ds_read_b64_tr_b16 v[212:213], v104 offset:34816
	ds_read_b64_tr_b16 v[214:215], v104 offset:39424
	ds_read_b64_tr_b16 v[216:217], v104 offset:44032
	ds_read_b64_tr_b16 v[218:219], v104 offset:48640
	ds_read_b64_tr_b16 v[220:221], v104 offset:53248
	ds_read_b64_tr_b16 v[222:223], v104 offset:57856
	ds_read_b64_tr_b16 v[224:225], v104 offset:62464
	v_mul_f32_e32 v131, v131, v188
	v_mul_f32_e32 v130, v130, v187
	v_mul_f32_e32 v129, v129, v186
	v_mul_f32_e32 v128, v128, v185
	v_mul_f32_e32 v123, v123, v184
	v_mul_f32_e32 v121, v121, v181
	v_mul_f32_e32 v141, v119, v178
	v_mul_f32_e32 v143, v118, v177
	v_mul_f32_e32 v144, v117, v171
	v_mul_f32_e32 v115, v115, v169
	v_mul_f32_e32 v113, v113, v161
	v_mul_f32_e32 v112, v112, v159
	v_mul_f32_e32 v107, v107, v154
	v_mul_f32_e32 v136, v127, v142
	v_cvt_pk_bf16_f32 v127, v106, v107
	v_cvt_pk_bf16_f32 v116, v108, v109
	v_cvt_pk_bf16_f32 v117, v110, v111
	v_cvt_pk_bf16_f32 v118, v112, v113
	v_cvt_pk_bf16_f32 v119, v114, v115
	v_cvt_pk_bf16_f32 v108, v145, v144
	v_cvt_pk_bf16_f32 v109, v143, v141
	v_cvt_pk_bf16_f32 v110, v120, v121
	v_cvt_pk_bf16_f32 v111, v122, v123
	v_add_u32_e32 v106, 0x8800, v104
	ds_read_b64_tr_b16 v[226:227], v106 offset:32256
	v_add_u32_e32 v120, 0x11800, v168
	ds_read_b64_tr_b16 v[240:241], v120
	v_add_u32_e32 v122, 0x12a00, v168
	ds_read_b64_tr_b16 v[242:243], v122
	v_cvt_pk_bf16_f32 v100, v128, v129
	v_cvt_pk_bf16_f32 v101, v130, v131
	v_cvt_pk_bf16_f32 v102, v134, v139
	v_cvt_pk_bf16_f32 v103, v140, v136
	v_mov_b32_e32 v161, v160
	v_pk_mul_f32 v[82:83], v[160:161], v[82:83]
	v_pk_mul_f32 v[80:81], v[162:163], v[80:81]
	s_waitcnt lgkmcnt(0)
	v_mfma_f32_16x16x32_bf16 v[136:139], v[240:243], v[124:127], 0
	v_mfma_f32_16x16x32_bf16 v[80:83], v[212:215], v[240:243], v[80:83]
	v_add_u32_e32 v120, 0x13c00, v168
	ds_read_b64_tr_b16 v[244:245], v120
	v_add_u32_e32 v122, 0x14e00, v168
	ds_read_b64_tr_b16 v[246:247], v122
	s_waitcnt lgkmcnt(0)
	v_mfma_f32_16x16x32_bf16 v[136:139], v[244:247], v[116:119], v[136:139]
	v_mfma_f32_16x16x32_bf16 v[80:83], v[216:219], v[244:247], v[80:83]
	v_add_u32_e32 v120, 0x16000, v168
	ds_read_b64_tr_b16 v[248:249], v120
	v_add_u32_e32 v122, 0x17200, v168
	ds_read_b64_tr_b16 v[250:251], v122
	s_waitcnt lgkmcnt(0)
	v_mfma_f32_16x16x32_bf16 v[136:139], v[248:251], v[108:111], v[136:139]
	v_mfma_f32_16x16x32_bf16 v[80:83], v[220:223], v[248:251], v[80:83]
	v_add_u32_e32 v120, 0x18400, v168
	ds_read_b64_tr_b16 v[240:241], v120
	v_add_u32_e32 v120, 0x19600, v168
	ds_read_b64_tr_b16 v[242:243], v120
	s_waitcnt lgkmcnt(0)
	v_mfma_f32_16x16x32_bf16 v[120:123], v[240:243], v[100:103], v[136:139]
	v_mfma_f32_16x16x32_bf16 v[80:83], v[224:227], v[240:243], v[80:83]
	s_nop 1
	v_add_u32_e32 v136, 0x11820, v168
	ds_read_b64_tr_b16 v[244:245], v136
	v_add_u32_e32 v138, 0x12a20, v168
	ds_read_b64_tr_b16 v[246:247], v138
	v_pk_mul_f32 v[54:55], v[160:161], v[54:55]
	v_pk_mul_f32 v[52:53], v[162:163], v[52:53]
	s_waitcnt lgkmcnt(0)
	v_mfma_f32_16x16x32_bf16 v[140:143], v[244:247], v[124:127], 0
	v_mfma_f32_16x16x32_bf16 v[52:55], v[212:215], v[244:247], v[52:55]
	v_add_u32_e32 v136, 0x13c20, v168
	ds_read_b64_tr_b16 v[248:249], v136
	v_add_u32_e32 v138, 0x14e20, v168
	ds_read_b64_tr_b16 v[250:251], v138
	s_waitcnt lgkmcnt(0)
	v_mfma_f32_16x16x32_bf16 v[140:143], v[248:251], v[116:119], v[140:143]
	v_mfma_f32_16x16x32_bf16 v[52:55], v[216:219], v[248:251], v[52:55]
	v_add_u32_e32 v136, 0x16020, v168
	ds_read_b64_tr_b16 v[240:241], v136
	v_add_u32_e32 v138, 0x17220, v168
	ds_read_b64_tr_b16 v[242:243], v138
	s_waitcnt lgkmcnt(0)
	v_mfma_f32_16x16x32_bf16 v[140:143], v[240:243], v[108:111], v[140:143]
	v_mfma_f32_16x16x32_bf16 v[52:55], v[220:223], v[240:243], v[52:55]
	v_add_u32_e32 v136, 0x18420, v168
	ds_read_b64_tr_b16 v[244:245], v136
	v_add_u32_e32 v136, 0x19620, v168
	ds_read_b64_tr_b16 v[246:247], v136
	s_waitcnt lgkmcnt(0)
	v_mfma_f32_16x16x32_bf16 v[136:139], v[244:247], v[100:103], v[140:143]
	v_mfma_f32_16x16x32_bf16 v[52:55], v[224:227], v[244:247], v[52:55]
	s_nop 1
	v_add_u32_e32 v140, 0x11840, v168
	ds_read_b64_tr_b16 v[248:249], v140
	v_add_u32_e32 v142, 0x12a40, v168
	ds_read_b64_tr_b16 v[250:251], v142
	v_pk_mul_f32 v[58:59], v[160:161], v[58:59]
	v_pk_mul_f32 v[56:57], v[162:163], v[56:57]
	s_waitcnt lgkmcnt(0)
	v_mfma_f32_16x16x32_bf16 v[144:147], v[248:251], v[124:127], 0
	v_mfma_f32_16x16x32_bf16 v[56:59], v[212:215], v[248:251], v[56:59]
	v_add_u32_e32 v140, 0x13c40, v168
	ds_read_b64_tr_b16 v[240:241], v140
	v_add_u32_e32 v142, 0x14e40, v168
	ds_read_b64_tr_b16 v[242:243], v142
	s_waitcnt lgkmcnt(0)
; #define MFMA16(a, b, c) __builtin_amdgcn_mfma_f32_16x16x32_bf16((a), (b), (c), 0, 0, 0)
; __device__ __forceinline__ bf16x8 ds_tr2(LAS unsigned char* p, int rstride) { const s16x4 a = ds_tr(p), b = ds_tr(p + 16 * rstride); bf16x8 r; r[0] = a[0]; r[1] = a[1]; r[2] = a[2]; r[3] = a[3]; r[4] = b[0]; r[5] = b[1]; r[6] = b[2]; r[7] = b[3]; return r; }
; template <int DIR, bool INTRA, bool FINAL> __device__ __forceinline__ void retention_pass(LAS unsigned char* lds, const bf16* ZH, bf16* YF, bf16* MIX, const float* ld, const float* gn, int seq, int h, int n0, int ncnt, ...
;     ...
;               for (int e = 0; e < 8; ++e) { st[e] = st[e] * gC;
; #pragma unroll
;                 for (int ks = 0; ks < 4; ++ks) { const bf16x8 vf = ds_tr2(trp + R_V + (32 * ks) * RSB + (16 * e) * 2, RSB);
;                     if constexpr (INTRA) y[e] = MFMA16(vf, pt[ks], y[e]);
;                     st[e] = MFMA16(kwf[ks], vf, st[e]); }
;                 __builtin_amdgcn_sched_barrier(0); } }
	v_mfma_f32_16x16x32_bf16 v[144:147], v[240:243], v[116:119], v[144:147]
	v_mfma_f32_16x16x32_bf16 v[56:59], v[216:219], v[240:243], v[56:59]
	v_add_u32_e32 v140, 0x16040, v168
	ds_read_b64_tr_b16 v[244:245], v140
	v_add_u32_e32 v142, 0x17240, v168
	ds_read_b64_tr_b16 v[246:247], v142
	s_waitcnt lgkmcnt(0)
	v_mfma_f32_16x16x32_bf16 v[144:147], v[244:247], v[108:111], v[144:147]
	v_mfma_f32_16x16x32_bf16 v[56:59], v[220:223], v[244:247], v[56:59]
	v_add_u32_e32 v140, 0x18440, v168
	ds_read_b64_tr_b16 v[248:249], v140
	v_add_u32_e32 v140, 0x19640, v168
	ds_read_b64_tr_b16 v[250:251], v140
	s_waitcnt lgkmcnt(0)
	v_mfma_f32_16x16x32_bf16 v[140:143], v[248:251], v[100:103], v[144:147]
	v_mfma_f32_16x16x32_bf16 v[56:59], v[224:227], v[248:251], v[56:59]
	s_nop 1
	v_add_u32_e32 v144, 0x11860, v168
	ds_read_b64_tr_b16 v[240:241], v144
	v_add_u32_e32 v146, 0x12a60, v168
	ds_read_b64_tr_b16 v[242:243], v146
	v_pk_mul_f32 v[62:63], v[160:161], v[62:63]
	v_pk_mul_f32 v[60:61], v[162:163], v[60:61]
	s_waitcnt lgkmcnt(0)
	v_mfma_f32_16x16x32_bf16 v[148:151], v[240:243], v[124:127], 0
	v_mfma_f32_16x16x32_bf16 v[60:63], v[212:215], v[240:243], v[60:63]
	v_add_u32_e32 v144, 0x13c60, v168
	ds_read_b64_tr_b16 v[244:245], v144
	v_add_u32_e32 v146, 0x14e60, v168
	ds_read_b64_tr_b16 v[246:247], v146
	s_waitcnt lgkmcnt(0)
	v_mfma_f32_16x16x32_bf16 v[148:151], v[244:247], v[116:119], v[148:151]
	v_mfma_f32_16x16x32_bf16 v[60:63], v[216:219], v[244:247], v[60:63]
	v_add_u32_e32 v144, 0x16060, v168
	ds_read_b64_tr_b16 v[248:249], v144
	v_add_u32_e32 v146, 0x17260, v168
	ds_read_b64_tr_b16 v[250:251], v146
	s_waitcnt lgkmcnt(0)
	v_mfma_f32_16x16x32_bf16 v[148:151], v[248:251], v[108:111], v[148:151]
	v_mfma_f32_16x16x32_bf16 v[60:63], v[220:223], v[248:251], v[60:63]
	v_add_u32_e32 v144, 0x18460, v168
	ds_read_b64_tr_b16 v[240:241], v144
	v_add_u32_e32 v144, 0x19660, v168
	ds_read_b64_tr_b16 v[242:243], v144
	s_waitcnt lgkmcnt(0)
	v_mfma_f32_16x16x32_bf16 v[144:147], v[240:243], v[100:103], v[148:151]
	v_mfma_f32_16x16x32_bf16 v[60:63], v[224:227], v[240:243], v[60:63]
	s_nop 1
	v_add_u32_e32 v148, 0x11880, v168
	ds_read_b64_tr_b16 v[244:245], v148
	v_add_u32_e32 v150, 0x12a80, v168
	ds_read_b64_tr_b16 v[246:247], v150
	v_pk_mul_f32 v[66:67], v[160:161], v[66:67]
	v_pk_mul_f32 v[64:65], v[162:163], v[64:65]
	s_waitcnt lgkmcnt(0)
	v_mfma_f32_16x16x32_bf16 v[152:155], v[244:247], v[124:127], 0
	v_mfma_f32_16x16x32_bf16 v[64:67], v[212:215], v[244:247], v[64:67]
	v_add_u32_e32 v148, 0x13c80, v168
	ds_read_b64_tr_b16 v[248:249], v148
	v_add_u32_e32 v150, 0x14e80, v168
	ds_read_b64_tr_b16 v[250:251], v150
	s_waitcnt lgkmcnt(0)
	v_mfma_f32_16x16x32_bf16 v[152:155], v[248:251], v[116:119], v[152:155]
	v_mfma_f32_16x16x32_bf16 v[64:67], v[216:219], v[248:251], v[64:67]
	v_add_u32_e32 v148, 0x16080, v168
	ds_read_b64_tr_b16 v[240:241], v148
	v_add_u32_e32 v150, 0x17280, v168
	ds_read_b64_tr_b16 v[242:243], v150
	s_waitcnt lgkmcnt(0)
	v_mfma_f32_16x16x32_bf16 v[152:155], v[240:243], v[108:111], v[152:155]
	v_mfma_f32_16x16x32_bf16 v[64:67], v[220:223], v[240:243], v[64:67]
	v_add_u32_e32 v148, 0x18480, v168
	ds_read_b64_tr_b16 v[244:245], v148
	v_add_u32_e32 v148, 0x19680, v168
	ds_read_b64_tr_b16 v[246:247], v148
	s_waitcnt lgkmcnt(0)
	v_mfma_f32_16x16x32_bf16 v[148:151], v[244:247], v[100:103], v[152:155]
	v_mfma_f32_16x16x32_bf16 v[64:67], v[224:227], v[244:247], v[64:67]
	s_nop 1
	v_add_u32_e32 v152, 0x118a0, v168
	ds_read_b64_tr_b16 v[248:249], v152
	v_add_u32_e32 v154, 0x12aa0, v168
	ds_read_b64_tr_b16 v[250:251], v154
	v_pk_mul_f32 v[70:71], v[160:161], v[70:71]
	v_pk_mul_f32 v[68:69], v[162:163], v[68:69]
	s_waitcnt lgkmcnt(0)
	v_mfma_f32_16x16x32_bf16 v[156:159], v[248:251], v[124:127], 0
	v_mfma_f32_16x16x32_bf16 v[68:71], v[212:215], v[248:251], v[68:71]
	v_add_u32_e32 v152, 0x13ca0, v168
	ds_read_b64_tr_b16 v[240:241], v152
	v_add_u32_e32 v154, 0x14ea0, v168
	ds_read_b64_tr_b16 v[242:243], v154
	s_waitcnt lgkmcnt(0)
	v_mfma_f32_16x16x32_bf16 v[156:159], v[240:243], v[116:119], v[156:159]
	v_mfma_f32_16x16x32_bf16 v[68:71], v[216:219], v[240:243], v[68:71]
	v_add_u32_e32 v152, 0x160a0, v168
	ds_read_b64_tr_b16 v[244:245], v152
	v_add_u32_e32 v154, 0x172a0, v168
	ds_read_b64_tr_b16 v[246:247], v154
	s_waitcnt lgkmcnt(0)
	v_mfma_f32_16x16x32_bf16 v[156:159], v[244:247], v[108:111], v[156:159]
	v_mfma_f32_16x16x32_bf16 v[68:71], v[220:223], v[244:247], v[68:71]
	v_add_u32_e32 v152, 0x184a0, v168
	ds_read_b64_tr_b16 v[248:249], v152
	v_add_u32_e32 v152, 0x196a0, v168
	ds_read_b64_tr_b16 v[250:251], v152
	s_waitcnt lgkmcnt(0)
	v_mfma_f32_16x16x32_bf16 v[152:155], v[248:251], v[100:103], v[156:159]
	v_mfma_f32_16x16x32_bf16 v[68:71], v[224:227], v[248:251], v[68:71]
	s_nop 1
	v_add_u32_e32 v156, 0x118c0, v168
	ds_read_b64_tr_b16 v[240:241], v156
	v_add_u32_e32 v158, 0x12ac0, v168
	ds_read_b64_tr_b16 v[242:243], v158
	v_pk_mul_f32 v[74:75], v[160:161], v[74:75]
	v_pk_mul_f32 v[72:73], v[162:163], v[72:73]
	s_waitcnt lgkmcnt(0)
	v_mfma_f32_16x16x32_bf16 v[184:187], v[240:243], v[124:127], 0
	v_mfma_f32_16x16x32_bf16 v[72:75], v[212:215], v[240:243], v[72:75]
	v_add_u32_e32 v156, 0x13cc0, v168
	ds_read_b64_tr_b16 v[244:245], v156
	v_add_u32_e32 v158, 0x14ec0, v168
	ds_read_b64_tr_b16 v[246:247], v158
	s_waitcnt lgkmcnt(0)
; #define GAS __attribute__((address_space(1)))
; #define MFMA16(a, b, c) __builtin_amdgcn_mfma_f32_16x16x32_bf16((a), (b), (c), 0, 0, 0)
; __device__ __forceinline__ bf16x8 ds_tr2(LAS unsigned char* p, int rstride) { const s16x4 a = ds_tr(p), b = ds_tr(p + 16 * rstride); bf16x8 r; r[0] = a[0]; r[1] = a[1]; r[2] = a[2]; r[3] = a[3]; r[4] = b[0]; r[5] = b[1]; r[6] = b[2]; r[7] = b[3]; return r; }
; template <int DIR, bool INTRA, bool FINAL> __device__ __forceinline__ void retention_pass(LAS unsigned char* lds, const bf16* ZH, bf16* YF, bf16* MIX, const float* ld, const float* gn, int seq, int h, int n0, int ncnt, ...
;     ...
;               for (int e = 0; e < 8; ++e) { st[e] = st[e] * gC;
; #pragma unroll
;                 for (int ks = 0; ks < 4; ++ks) { const bf16x8 vf = ds_tr2(trp + R_V + (32 * ks) * RSB + (16 * e) * 2, RSB);
;                     if constexpr (INTRA) y[e] = MFMA16(vf, pt[ks], y[e]);
;                     st[e] = MFMA16(kwf[ks], vf, st[e]); }
;                 __builtin_amdgcn_sched_barrier(0); } }
;             v2u ywv[8], gwv[8];
;             if constexpr (FINAL) { const int row_ = r0 + 16 * w + lr; const bf16* yp_ = YF + (size_t)row_ * 2048 + h * HD + 4 * lg; const bf16* gp_ = Gp + (size_t)(n * 128 + 16 * w + lr) * HD + 4 * lg;
; #pragma unroll
;                 for (int e = 0; e < 8; ++e) { ywv[e] = *(const GAS v2u*)(yp_ + 16 * e); gwv[e] = *(const GAS v2u*)(gp_ + 16 * e); } }
;             if (cn + 1 < ncnt) {
; #pragma unroll
;               for (int cc = 0; cc < 4; ++cc) { kreg[cc] = *(const GAS v4u*)(Kp + (size_t)(nn * 128 + srow + 32 * cc) * HD + 8 * sch); vreg[cc] = *(const GAS v4u*)(Vp + (size_t)(nn * 128 + srow + 32 * cc) * HD + 8 * sch); }
; #pragma unroll
;               for (int ks = 0; ks < 4; ++ks) qf[ks] = *(const GAS bf16x8*)(Qp + (size_t)(nn * 128 + 16 * w + lr) * HD + 8 * lg + 32 * ks); }
	v_mfma_f32_16x16x32_bf16 v[184:187], v[244:247], v[116:119], v[184:187]
	v_mfma_f32_16x16x32_bf16 v[72:75], v[216:219], v[244:247], v[72:75]
	v_add_u32_e32 v156, 0x160c0, v168
	ds_read_b64_tr_b16 v[248:249], v156
	v_add_u32_e32 v158, 0x172c0, v168
	ds_read_b64_tr_b16 v[250:251], v158
	s_waitcnt lgkmcnt(0)
	v_mfma_f32_16x16x32_bf16 v[184:187], v[248:251], v[108:111], v[184:187]
	v_mfma_f32_16x16x32_bf16 v[72:75], v[220:223], v[248:251], v[72:75]
	v_add_u32_e32 v156, 0x184c0, v168
	ds_read_b64_tr_b16 v[206:207], v156
	v_add_u32_e32 v156, 0x196c0, v168
	ds_read_b64_tr_b16 v[208:209], v156
	s_waitcnt lgkmcnt(0)
	v_mfma_f32_16x16x32_bf16 v[156:159], v[206:209], v[100:103], v[184:187]
	v_mfma_f32_16x16x32_bf16 v[72:75], v[224:227], v[206:209], v[72:75]
	v_mul_f32_e64 v78, v160, v78
	v_mul_f32_e64 v79, v161, v79
	v_add_u32_e32 v161, 0x118e0, v168
	ds_read_b64_tr_b16 v[184:185], v161
	v_add_u32_e32 v161, 0x12ae0, v168
	ds_read_b64_tr_b16 v[186:187], v161
	v_pk_mul_f32 v[76:77], v[162:163], v[76:77]
	s_waitcnt lgkmcnt(0)
	v_mfma_f32_16x16x32_bf16 v[124:127], v[184:187], v[124:127], 0
	v_mfma_f32_16x16x32_bf16 v[76:79], v[212:215], v[184:187], v[76:79]
	v_add_u32_e32 v132, 0x13ce0, v168
	ds_read_b64_tr_b16 v[240:241], v132
	v_add_u32_e32 v134, 0x14ee0, v168
	ds_read_b64_tr_b16 v[242:243], v134
	s_waitcnt lgkmcnt(0)
	v_mfma_f32_16x16x32_bf16 v[116:119], v[240:243], v[116:119], v[124:127]
	s_nop 2
	v_add_u32_e32 v124, 0x160e0, v168
	ds_read_b64_tr_b16 v[244:245], v124
	v_add_u32_e32 v126, 0x172e0, v168
	ds_read_b64_tr_b16 v[246:247], v126
	v_mfma_f32_16x16x32_bf16 v[76:79], v[216:219], v[240:243], v[76:79]
	s_waitcnt lgkmcnt(0)
	v_mfma_f32_16x16x32_bf16 v[76:79], v[220:223], v[244:247], v[76:79]
	v_add_u32_e32 v112, 0x184e0, v168
	ds_read_b64_tr_b16 v[248:249], v112
	v_add_u32_e32 v114, 0x196e0, v168
	ds_read_b64_tr_b16 v[250:251], v114
	v_mfma_f32_16x16x32_bf16 v[108:111], v[244:247], v[108:111], v[116:119]
	s_waitcnt lgkmcnt(0)
	v_mfma_f32_16x16x32_bf16 v[100:103], v[248:251], v[100:103], v[108:111]
	v_mfma_f32_16x16x32_bf16 v[76:79], v[224:227], v[248:251], v[76:79]
	v_add_u32_e32 v106, v2, v167
	s_add_i32 s6, s65, s42
	v_add_u32_e32 v2, s6, v106
	v_add_u32_e32 v118, 0xffffff20, v2
	v_add_u32_e32 v161, s42, v106
	v_ashrrev_i32_e32 v119, 31, v118
	v_add_u32_e32 v106, 0xffffff20, v161
	v_lshlrev_b64 v[104:105], 12, v[118:119]
	v_ashrrev_i32_e32 v107, 31, v106
	v_lshl_add_u64 v[104:105], s[76:77], 0, v[104:105]
	v_lshlrev_b32_e32 v2, 1, v166
	v_lshlrev_b64 v[106:107], 8, v[106:107]
	v_lshl_add_u64 v[104:105], v[104:105], 0, v[2:3]
	v_lshl_add_u64 v[106:107], s[40:41], 0, v[106:107]
	v_lshl_add_u64 v[178:179], v[106:107], 0, v[2:3]
	global_load_dwordx2 v[170:171], v[104:105], off
	global_load_dwordx2 v[132:133], v[104:105], off offset:32
	global_load_dwordx2 v[168:169], v[104:105], off offset:64
	global_load_dwordx2 v[166:167], v[104:105], off offset:96
	global_load_dwordx2 v[124:125], v[178:179], off
	global_load_dwordx2 v[116:117], v[178:179], off offset:32
	global_load_dwordx2 v[114:115], v[178:179], off offset:64
	global_load_dwordx2 v[112:113], v[178:179], off offset:96
	global_load_dwordx2 v[134:135], v[104:105], off offset:128
	global_load_dwordx2 v[130:131], v[104:105], off offset:160
	global_load_dwordx2 v[128:129], v[104:105], off offset:192
	global_load_dwordx2 v[126:127], v[104:105], off offset:224
	global_load_dwordx2 v[110:111], v[178:179], off offset:128
	global_load_dwordx2 v[108:109], v[178:179], off offset:160
	global_load_dwordx2 v[106:107], v[178:179], off offset:192
	s_nop 0
	global_load_dwordx2 v[104:105], v[178:179], off offset:224
	s_cmpk_eq_i32 s42, 0x1060
	s_cbranch_scc1 .LBB0_729
	v_add_u32_e32 v28, s42, v165
	v_add_u32_e32 v36, 0xffffffa0, v161
	v_add_u32_e32 v4, 0xffffffa0, v28
	v_subrev_u32_e32 v12, 64, v28
	v_subrev_u32_e32 v20, 32, v28
	v_ashrrev_i32_e32 v37, 31, v36
	v_mov_b32_e32 v165, v3
	v_ashrrev_i32_e32 v5, 31, v4
	v_ashrrev_i32_e32 v13, 31, v12
	v_ashrrev_i32_e32 v21, 31, v20
	v_ashrrev_i32_e32 v29, 31, v28
	v_lshlrev_b64 v[36:37], 8, v[36:37]
	v_lshl_add_u64 v[30:31], s[60:61], 0, v[164:165]
	v_lshl_add_u64 v[32:33], s[72:73], 0, v[164:165]
	v_lshlrev_b64 v[4:5], 8, v[4:5]
	v_lshlrev_b64 v[12:13], 8, v[12:13]
	v_lshlrev_b64 v[20:21], 8, v[20:21]
	v_lshlrev_b64 v[28:29], 8, v[28:29]
	v_lshl_add_u64 v[36:37], s[36:37], 0, v[36:37]
	v_lshlrev_b32_e32 v38, 1, v176
	v_mov_b32_e32 v39, v3
	v_lshl_add_u64 v[6:7], v[30:31], 0, v[4:5]
	v_lshl_add_u64 v[8:9], v[32:33], 0, v[4:5]
	v_lshl_add_u64 v[14:15], v[30:31], 0, v[12:13]
	v_lshl_add_u64 v[16:17], v[32:33], 0, v[12:13]
	v_lshl_add_u64 v[22:23], v[30:31], 0, v[20:21]
	v_lshl_add_u64 v[24:25], v[32:33], 0, v[20:21]
	v_lshl_add_u64 v[30:31], v[30:31], 0, v[28:29]
	v_lshl_add_u64 v[32:33], v[32:33], 0, v[28:29]
	v_lshl_add_u64 v[48:49], v[36:37], 0, v[38:39]
	global_load_dwordx4 v[4:7], v[6:7], off
	s_nop 0
	global_load_dwordx4 v[8:11], v[8:9], off
	s_nop 0
	global_load_dwordx4 v[12:15], v[14:15], off
	s_nop 0
	global_load_dwordx4 v[16:19], v[16:17], off
	s_nop 0
	global_load_dwordx4 v[20:23], v[22:23], off
	s_nop 0
	global_load_dwordx4 v[24:27], v[24:25], off
	s_nop 0
	global_load_dwordx4 v[28:31], v[30:31], off
	s_nop 0
	global_load_dwordx4 v[32:35], v[32:33], off
	s_nop 0
	global_load_dwordx4 v[36:39], v[48:49], off
	global_load_dwordx4 v[40:43], v[48:49], off offset:64
	global_load_dwordx4 v[44:47], v[48:49], off offset:128
	s_nop 0
	global_load_dwordx4 v[48:51], v[48:49], off offset:192
	s_branch .LBB0_729

; #define GAS __attribute__((address_space(1)))
; #define LAS __attribute__((address_space(3)))
; __device__ __forceinline__ unsigned pk2(float lo, float hi) { return pg8::cvt_pk_bf16(lo, hi); }
; #define MFMA16(a, b, c) __builtin_amdgcn_mfma_f32_16x16x32_bf16((a), (b), (c), 0, 0, 0)
; template <int DIR, bool INTRA, bool FINAL> __device__ __forceinline__ void retention_pass(LAS unsigned char* lds, const bf16* ZH, bf16* YF, bf16* MIX, const float* ld, const float* gn, int seq, int h, int n0, int ncnt, ...
;     ...
;             for (int e = 0; e < 8; ++e) {
; #pragma unroll
;                 for (int ks = 0; ks < 4; ++ks) { const bf16x8 sf = *(const LAS bf16x8*)(lds + R_ST + (16 * e + lr) * RS + (8 * lg + 32 * ks) * 2); y[e] = MFMA16(sf, qx[ks], y[e]); }
;                 __builtin_amdgcn_sched_barrier(0); }
;             const int row = r0 + 16 * w + lr;
;             bf16* yp = YF + (size_t)row * 2048 + h * HD + 4 * lg;
;             if constexpr (!FINAL) {
; #pragma unroll
;                 for (int e = 0; e < 8; ++e) { v2u o; o.x = pk2(y[e][0], y[e][1]); o.y = pk2(y[e][2], y[e][3]); *(GAS v2u*)(yp + 16 * e) = o; }
.LBB0_991:
	s_waitcnt lgkmcnt(0)
	v_add3_u32 v2, s95, v213, v209
	ds_read_b128 v[214:217], v2
	ds_read_b128 v[218:221], v2 offset:64
	ds_read_b128 v[222:225], v2 offset:128
	ds_read_b128 v[226:229], v2 offset:192
	ds_read_b128 v[240:243], v2 offset:4352
	ds_read_b128 v[244:247], v2 offset:4416
	ds_read_b128 v[248:251], v2 offset:4480
	s_waitcnt lgkmcnt(6)
	v_mfma_f32_16x16x32_bf16 v[36:39], v[214:217], v[84:87], v[120:123]
	ds_read_b128 v[214:217], v2 offset:4544
	s_waitcnt lgkmcnt(6)
	v_mfma_f32_16x16x32_bf16 v[36:39], v[218:221], v[88:91], v[36:39]
	ds_read_b128 v[218:221], v2 offset:8704
	s_waitcnt lgkmcnt(6)
	v_mfma_f32_16x16x32_bf16 v[36:39], v[222:225], v[92:95], v[36:39]
	ds_read_b128 v[222:225], v2 offset:8768
	s_waitcnt lgkmcnt(6)
	v_mfma_f32_16x16x32_bf16 v[36:39], v[226:229], v[96:99], v[36:39]
	ds_read_b128 v[226:229], v2 offset:8832
	s_waitcnt lgkmcnt(6)
	v_mfma_f32_16x16x32_bf16 v[40:43], v[240:243], v[84:87], v[136:139]
	ds_read_b128 v[240:243], v2 offset:8896
	s_waitcnt lgkmcnt(6)
	v_mfma_f32_16x16x32_bf16 v[40:43], v[244:247], v[88:91], v[40:43]
	ds_read_b128 v[244:247], v2 offset:13056
	s_waitcnt lgkmcnt(6)
	v_mfma_f32_16x16x32_bf16 v[40:43], v[248:251], v[92:95], v[40:43]
	ds_read_b128 v[248:251], v2 offset:13120
	s_waitcnt lgkmcnt(6)
	v_mfma_f32_16x16x32_bf16 v[40:43], v[214:217], v[96:99], v[40:43]
	ds_read_b128 v[214:217], v2 offset:13184
	s_waitcnt lgkmcnt(6)
	v_mfma_f32_16x16x32_bf16 v[44:47], v[218:221], v[84:87], v[140:143]
	ds_read_b128 v[218:221], v2 offset:13248
	s_waitcnt lgkmcnt(6)
	v_mfma_f32_16x16x32_bf16 v[44:47], v[222:225], v[88:91], v[44:47]
	ds_read_b128 v[222:225], v2 offset:17408
	s_waitcnt lgkmcnt(6)
	v_mfma_f32_16x16x32_bf16 v[44:47], v[226:229], v[92:95], v[44:47]
	ds_read_b128 v[226:229], v2 offset:17472
	s_waitcnt lgkmcnt(6)
	v_mfma_f32_16x16x32_bf16 v[44:47], v[240:243], v[96:99], v[44:47]
	ds_read_b128 v[240:243], v2 offset:17536
	s_waitcnt lgkmcnt(6)
	v_mfma_f32_16x16x32_bf16 v[48:51], v[244:247], v[84:87], v[144:147]
	ds_read_b128 v[244:247], v2 offset:17600
	s_waitcnt lgkmcnt(6)
	v_mfma_f32_16x16x32_bf16 v[48:51], v[248:251], v[88:91], v[48:51]
	ds_read_b128 v[248:251], v2 offset:21760
	s_waitcnt lgkmcnt(6)
	v_mfma_f32_16x16x32_bf16 v[48:51], v[214:217], v[92:95], v[48:51]
	ds_read_b128 v[214:217], v2 offset:21824
	s_waitcnt lgkmcnt(6)
	v_mfma_f32_16x16x32_bf16 v[48:51], v[218:221], v[96:99], v[48:51]
	ds_read_b128 v[218:221], v2 offset:21888
	s_waitcnt lgkmcnt(6)
	v_mfma_f32_16x16x32_bf16 v[52:55], v[222:225], v[84:87], v[148:151]
	ds_read_b128 v[222:225], v2 offset:21952
	s_waitcnt lgkmcnt(6)
	v_mfma_f32_16x16x32_bf16 v[52:55], v[226:229], v[88:91], v[52:55]
	ds_read_b128 v[226:229], v2 offset:26112
	s_waitcnt lgkmcnt(6)
	v_mfma_f32_16x16x32_bf16 v[52:55], v[240:243], v[92:95], v[52:55]
	ds_read_b128 v[240:243], v2 offset:26176
	s_waitcnt lgkmcnt(6)
	v_mfma_f32_16x16x32_bf16 v[52:55], v[244:247], v[96:99], v[52:55]
	ds_read_b128 v[244:247], v2 offset:26240
	s_waitcnt lgkmcnt(6)
	v_mfma_f32_16x16x32_bf16 v[56:59], v[248:251], v[84:87], v[152:155]
	ds_read_b128 v[248:251], v2 offset:26304
	s_waitcnt lgkmcnt(6)
	v_mfma_f32_16x16x32_bf16 v[56:59], v[214:217], v[88:91], v[56:59]
	ds_read_b128 v[214:217], v2 offset:30464
	s_waitcnt lgkmcnt(6)
	v_mfma_f32_16x16x32_bf16 v[56:59], v[218:221], v[92:95], v[56:59]
	ds_read_b128 v[218:221], v2 offset:30528
	s_waitcnt lgkmcnt(6)
	v_mfma_f32_16x16x32_bf16 v[56:59], v[222:225], v[96:99], v[56:59]
	ds_read_b128 v[222:225], v2 offset:30592
	s_waitcnt lgkmcnt(6)
	v_mfma_f32_16x16x32_bf16 v[60:63], v[226:229], v[84:87], v[156:159]
	ds_read_b128 v[226:229], v2 offset:30656
	s_waitcnt lgkmcnt(6)
	v_mfma_f32_16x16x32_bf16 v[60:63], v[240:243], v[88:91], v[60:63]
	s_waitcnt lgkmcnt(5)
	v_mfma_f32_16x16x32_bf16 v[60:63], v[244:247], v[92:95], v[60:63]
	s_waitcnt lgkmcnt(4)
	v_mfma_f32_16x16x32_bf16 v[60:63], v[248:251], v[96:99], v[60:63]
	s_waitcnt lgkmcnt(3)
	v_mfma_f32_16x16x32_bf16 v[64:67], v[214:217], v[84:87], v[176:179]
	s_waitcnt lgkmcnt(2)
	v_mfma_f32_16x16x32_bf16 v[64:67], v[218:221], v[88:91], v[64:67]
	s_waitcnt lgkmcnt(1)
	v_mfma_f32_16x16x32_bf16 v[64:67], v[222:225], v[92:95], v[64:67]
	s_waitcnt lgkmcnt(0)
	v_mfma_f32_16x16x32_bf16 v[64:67], v[226:229], v[96:99], v[64:67]
	s_add_i32 s6, s65, s76
	v_add_u32_e32 v2, s6, v187
	v_add_u32_e32 v68, 0xffffff20, v2
	v_ashrrev_i32_e32 v69, 31, v68
	v_lshlrev_b64 v[68:69], 12, v[68:69]
	v_lshl_add_u64 v[68:69], s[20:21], 0, v[68:69]
	v_lshlrev_b32_e32 v2, 1, v181
	v_lshl_add_u64 v[68:69], v[68:69], 0, v[2:3]
	v_cvt_pk_bf16_f32 v36, v36, v37
	v_cvt_pk_bf16_f32 v37, v38, v39
	global_store_dwordx2 v[68:69], v[36:37], off
	v_cvt_pk_bf16_f32 v36, v40, v41
	v_cvt_pk_bf16_f32 v37, v42, v43
	global_store_dwordx2 v[68:69], v[36:37], off offset:32
	v_cvt_pk_bf16_f32 v36, v44, v45
	v_cvt_pk_bf16_f32 v37, v46, v47
	global_store_dwordx2 v[68:69], v[36:37], off offset:64
	v_cvt_pk_bf16_f32 v36, v48, v49
	v_cvt_pk_bf16_f32 v37, v50, v51
	global_store_dwordx2 v[68:69], v[36:37], off offset:96
	v_cvt_pk_bf16_f32 v36, v52, v53
	v_cvt_pk_bf16_f32 v37, v54, v55
	global_store_dwordx2 v[68:69], v[36:37], off offset:128
	v_cvt_pk_bf16_f32 v36, v56, v57
	v_cvt_pk_bf16_f32 v37, v58, v59
	global_store_dwordx2 v[68:69], v[36:37], off offset:160
	v_cvt_pk_bf16_f32 v36, v60, v61
	v_cvt_pk_bf16_f32 v37, v62, v63
	global_store_dwordx2 v[68:69], v[36:37], off offset:192
	v_cvt_pk_bf16_f32 v36, v64, v65
	v_cvt_pk_bf16_f32 v37, v66, v67
	global_store_dwordx2 v[68:69], v[36:37], off offset:224
	s_addk_i32 s76, 0x80
	s_waitcnt vmcnt(11)
	v_mov_b64_e32 v[60:61], v[160:161]
	s_waitcnt vmcnt(10)
	v_mov_b64_e32 v[64:65], v[164:165]
	s_waitcnt vmcnt(9)
	v_mov_b64_e32 v[68:69], v[168:169]
	s_waitcnt vmcnt(8)
	v_mov_b64_e32 v[72:73], v[172:173]
	v_mov_b64_e32 v[40:41], v[104:105]
	v_mov_b64_e32 v[48:49], v[112:113]
	v_mov_b64_e32 v[56:57], v[124:125]
	v_mov_b64_e32 v[76:77], v[132:133]
	v_mov_b64_e32 v[36:37], v[100:101]
	v_mov_b64_e32 v[44:45], v[108:109]
	v_mov_b64_e32 v[52:53], v[116:117]
	v_mov_b64_e32 v[80:81], v[128:129]
	s_cmpk_eq_i32 s76, 0x8e0
	v_mov_b64_e32 v[62:63], v[162:163]
	v_mov_b64_e32 v[66:67], v[166:167]
	v_mov_b64_e32 v[70:71], v[170:171]
	v_mov_b64_e32 v[74:75], v[174:175]
	v_mov_b64_e32 v[42:43], v[106:107]
	v_mov_b64_e32 v[50:51], v[114:115]
	v_mov_b64_e32 v[58:59], v[126:127]
	v_mov_b64_e32 v[78:79], v[134:135]
	v_mov_b64_e32 v[38:39], v[102:103]
	v_mov_b64_e32 v[46:47], v[110:111]
	v_mov_b64_e32 v[54:55], v[118:119]
	v_mov_b64_e32 v[82:83], v[130:131]
	s_cbranch_scc1 .LBB0_1252
; #define LAS __attribute__((address_space(3)))
; #define WG_BARRIER() do { asm volatile("s_waitcnt lgkmcnt(0)" ::: "memory"); __builtin_amdgcn_s_barrier(); asm volatile("" ::: "memory"); } while (0)
; __device__ __forceinline__ unsigned pk2(float lo, float hi) { return pg8::cvt_pk_bf16(lo, hi); }
; __device__ __forceinline__ v4u scale8(v4u x, float sc) { v4u o; o.x = pk2(bf_lo(x.x) * sc, bf_hi(x.x) * sc); o.y = pk2(bf_lo(x.y) * sc, bf_hi(x.y) * sc); o.z = pk2(bf_lo(x.z) * sc, bf_hi(x.z) * sc); o.w = pk2(bf_lo(x.w) * sc, bf_hi(x.w) * sc); return o; }
; template <int DIR, bool INTRA, bool FINAL> __device__ __forceinline__ void retention_pass(LAS unsigned char* lds, const bf16* ZH, bf16* YF, bf16* MIX, const float* ld, const float* gn, int seq, int h, int n0, int ncnt, ...
;     ...
;             const int w = tid >> 6, l = tid & 63, lr = l & 15, lg = l >> 4, srow = tid >> 4, sch = tid & 15;
;             LAS unsigned char* trp = lds + (4 * lg + ((l & 15) >> 2)) * RSB + (l & 3) * 8;
;             WG_BARRIER();
; #pragma unroll
;             for (int cc = 0; cc < 4; ++cc) { const int row = srow + 32 * cc;
;                 if constexpr (INTRA) *(LAS v4u*)(lds + R_K + row * RS + 16 * sch) = kreg[cc];
;                 const float wj = DIR == 0 ? __expf(lf * (float)(127 - row)) : __expf(lb * (float)row);
;                 *(LAS v4u*)(lds + R_KW + row * RSB + 16 * sch) = scale8(kreg[cc], wj);
;                 *(LAS v4u*)(lds + R_V + row * RSB + 16 * sch) = vreg[cc]; }
; #pragma unroll
;             for (int e = 0; e < 8; ++e) { v2u o; o.x = pk2(st[e][0], st[e][1]); o.y = pk2(st[e][2], st[e][3]); *(LAS v2u*)(lds + R_ST + (16 * e + lr) * RS + (16 * w + 4 * lg) * 2) = o; }
;             WG_BARRIER();
.LBB0_992:
	v_mov_b32_e32 v132, v190
	s_waitcnt vmcnt(12)
	v_mov_b32_e32 v136, v206
	v_mov_b32_e32 v138, v191
	s_waitcnt vmcnt(11)
	v_and_b32_e32 v87, 0xffff0000, v36
	v_ashrrev_i32_e32 v208, 4, v132
	v_sub_u32_e32 v86, 0x7f, v208
	v_cvt_f32_i32_e32 v86, v86
	v_and_b32_e32 v207, 15, v132
	v_lshlrev_b32_e32 v2, 4, v207
	v_add_u32_e32 v84, 0, v2
	v_mul_f32_e32 v86, v138, v86
	v_mul_f32_e32 v86, 0x3fb8aa3b, v86
	v_exp_f32_e32 v89, v86
	v_add_u32_e32 v85, s93, v2
	v_lshlrev_b32_e32 v86, 16, v36
	v_mad_u64_u32 v[90:91], s[6:7], v208, s33, v[84:85]
	v_mul_f32_e32 v86, v89, v86
	v_mul_f32_e32 v87, v89, v87
	s_waitcnt lgkmcnt(0)
	s_barrier
	ds_write_b128 v90, v[36:39]
	v_cvt_pk_bf16_f32 v86, v86, v87
	v_lshlrev_b32_e32 v87, 16, v37
	v_and_b32_e32 v88, 0xffff0000, v37
	v_mul_f32_e32 v87, v89, v87
	v_mul_f32_e32 v88, v89, v88
	v_cvt_pk_bf16_f32 v87, v87, v88
	v_lshlrev_b32_e32 v88, 16, v38
	v_and_b32_e32 v91, 0xffff0000, v38
	v_mul_f32_e32 v88, v89, v88
	v_mul_f32_e32 v91, v89, v91
	v_cvt_pk_bf16_f32 v88, v88, v91
	v_lshlrev_b32_e32 v91, 16, v39
	v_and_b32_e32 v92, 0xffff0000, v39
	v_mul_f32_e32 v91, v89, v91
	v_mul_f32_e32 v89, v89, v92
	v_cvt_pk_bf16_f32 v89, v91, v89
	v_mul_lo_u32 v91, v208, s74
	v_add_u32_e32 v92, v84, v91
	ds_write_b128 v92, v[86:89] offset:34816
	v_add_u32_e32 v86, v85, v91
	s_waitcnt vmcnt(10)
	ds_write_b128 v86, v[40:43]
	s_waitcnt vmcnt(9)
	ds_write_b128 v90, v[44:47] offset:8704
	v_sub_u32_e32 v86, 0x5f, v208
	v_cvt_f32_i32_e32 v86, v86
	v_and_b32_e32 v87, 0xffff0000, v44
	v_and_b32_e32 v88, 0xffff0000, v45
	v_and_b32_e32 v92, 0xffff0000, v46
	v_mul_f32_e32 v86, v138, v86
	v_mul_f32_e32 v86, 0x3fb8aa3b, v86
	v_exp_f32_e32 v89, v86
	v_lshlrev_b32_e32 v86, 16, v44
	v_and_b32_e32 v93, 0xffff0000, v47
	v_ashrrev_i32_e32 v134, 6, v132
	v_mul_f32_e32 v86, v89, v86
	v_mul_f32_e32 v87, v89, v87
	v_cvt_pk_bf16_f32 v86, v86, v87
	v_lshlrev_b32_e32 v87, 16, v45
	v_mul_f32_e32 v87, v89, v87
	v_mul_f32_e32 v88, v89, v88
	v_cvt_pk_bf16_f32 v87, v87, v88
	v_lshlrev_b32_e32 v88, 16, v46
	v_mul_f32_e32 v88, v89, v88
	v_mul_f32_e32 v92, v89, v92
	v_cvt_pk_bf16_f32 v88, v88, v92
	v_lshlrev_b32_e32 v92, 16, v47
	v_mul_f32_e32 v92, v89, v92
	v_mul_f32_e32 v89, v89, v93
	v_cvt_pk_bf16_f32 v89, v92, v89
	v_add_u32_e32 v92, 0x2400, v91
	v_add_u32_e32 v93, v84, v92
	ds_write_b128 v93, v[86:89] offset:34816
	v_add_u32_e32 v86, v85, v92
	s_waitcnt vmcnt(8)
	ds_write_b128 v86, v[48:51]
	s_waitcnt vmcnt(7)
	ds_write_b128 v90, v[52:55] offset:17408
	v_sub_u32_e32 v86, 63, v208
	v_cvt_f32_i32_e32 v86, v86
	v_and_b32_e32 v87, 0xffff0000, v52
	v_and_b32_e32 v88, 0xffff0000, v53
	v_and_b32_e32 v92, 0xffff0000, v54
	v_mul_f32_e32 v86, v138, v86
	v_mul_f32_e32 v86, 0x3fb8aa3b, v86
	v_exp_f32_e32 v89, v86
	v_lshlrev_b32_e32 v86, 16, v52
	v_and_b32_e32 v93, 0xffff0000, v55
	v_bfe_u32 v100, v132, 4, 2
	v_mul_f32_e32 v86, v89, v86
	v_mul_f32_e32 v87, v89, v87
	v_cvt_pk_bf16_f32 v86, v86, v87
	v_lshlrev_b32_e32 v87, 16, v53
	v_mul_f32_e32 v87, v89, v87
	v_mul_f32_e32 v88, v89, v88
	v_cvt_pk_bf16_f32 v87, v87, v88
	v_lshlrev_b32_e32 v88, 16, v54
	v_mul_f32_e32 v88, v89, v88
	v_mul_f32_e32 v92, v89, v92
	v_cvt_pk_bf16_f32 v88, v88, v92
	v_lshlrev_b32_e32 v92, 16, v55
	v_mul_f32_e32 v92, v89, v92
	v_mul_f32_e32 v89, v89, v93
	v_cvt_pk_bf16_f32 v89, v92, v89
	v_add_u32_e32 v92, 0x4800, v91
	v_add_u32_e32 v93, v84, v92
	ds_write_b128 v93, v[86:89] offset:34816
	v_add_u32_e32 v86, v85, v92
	s_waitcnt vmcnt(6)
	ds_write_b128 v86, v[56:59]
	s_waitcnt vmcnt(1)
	ds_write_b128 v90, v[80:83] offset:26112
	v_sub_u32_e32 v86, 31, v208
	v_cvt_f32_i32_e32 v86, v86
	v_and_b32_e32 v87, 0xffff0000, v80
	v_and_b32_e32 v88, 0xffff0000, v81
	v_and_b32_e32 v90, 0xffff0000, v82
	v_mul_f32_e32 v86, v138, v86
	v_mul_f32_e32 v86, 0x3fb8aa3b, v86
	v_exp_f32_e32 v89, v86
	v_lshlrev_b32_e32 v86, 16, v80
	v_and_b32_e32 v92, 0xffff0000, v83
	v_lshlrev_b32_e32 v133, 5, v134
	v_mul_f32_e32 v86, v89, v86
	v_mul_f32_e32 v87, v89, v87
	v_cvt_pk_bf16_f32 v86, v86, v87
	v_lshlrev_b32_e32 v87, 16, v81
	v_mul_f32_e32 v87, v89, v87
	v_mul_f32_e32 v88, v89, v88
	v_cvt_pk_bf16_f32 v87, v87, v88
	v_lshlrev_b32_e32 v88, 16, v82
	v_mul_f32_e32 v88, v89, v88
	v_mul_f32_e32 v90, v89, v90
	v_cvt_pk_bf16_f32 v88, v88, v90
	v_lshlrev_b32_e32 v90, 16, v83
	v_mul_f32_e32 v90, v89, v90
	v_mul_f32_e32 v89, v89, v92
	v_cvt_pk_bf16_f32 v89, v90, v89
	v_add_u32_e32 v90, 0x6c00, v91
	v_add_u32_e32 v84, v84, v90
	ds_write_b128 v84, v[86:89] offset:34816
	v_add_u32_e32 v84, v85, v90
	v_lshlrev_b32_e32 v212, 3, v100
	v_add_u32_e32 v86, s95, v133
	v_mul_u32_u24_e32 v209, 0x110, v207
	s_waitcnt vmcnt(0)
	ds_write_b128 v84, v[76:79]
	v_cvt_pk_bf16_f32 v84, v32, v33
	v_add3_u32 v86, v86, v212, v209
	v_cvt_pk_bf16_f32 v85, v34, v35
	ds_write_b64 v86, v[84:85]
	v_cvt_pk_bf16_f32 v84, v28, v29
	v_cvt_pk_bf16_f32 v85, v30, v31
	ds_write_b64 v86, v[84:85] offset:4352
	v_cvt_pk_bf16_f32 v84, v24, v25
	v_cvt_pk_bf16_f32 v85, v26, v27
	ds_write_b64 v86, v[84:85] offset:8704
	v_cvt_pk_bf16_f32 v84, v20, v21
	v_cvt_pk_bf16_f32 v85, v22, v23
	ds_write_b64 v86, v[84:85] offset:13056
	v_cvt_pk_bf16_f32 v84, v16, v17
	v_cvt_pk_bf16_f32 v85, v18, v19
	ds_write_b64 v86, v[84:85] offset:17408
	v_cvt_pk_bf16_f32 v84, v12, v13
	v_cvt_pk_bf16_f32 v85, v14, v15
	ds_write_b64 v86, v[84:85] offset:21760
	v_cvt_pk_bf16_f32 v84, v8, v9
	v_cvt_pk_bf16_f32 v85, v10, v11
	ds_write_b64 v86, v[84:85] offset:26112
	v_cvt_pk_bf16_f32 v84, v4, v5
	v_lshlrev_b32_e32 v214, 4, v134
	v_cvt_pk_bf16_f32 v85, v6, v7
	ds_write_b64 v86, v[84:85] offset:30464
	v_or_b32_e32 v84, v207, v214
	v_add_u32_e32 v84, 1, v84
	v_cvt_f32_i32_e32 v84, v84
	v_and_b32_e32 v85, 0xffff0000, v60
	s_waitcnt lgkmcnt(0)
	s_barrier
; #define LAS __attribute__((address_space(3)))
; #define MFMA16(a, b, c) __builtin_amdgcn_mfma_f32_16x16x32_bf16((a), (b), (c), 0, 0, 0)
; __device__ __forceinline__ v4u scale8(v4u x, float sc) { v4u o; o.x = pk2(bf_lo(x.x) * sc, bf_hi(x.x) * sc); o.y = pk2(bf_lo(x.y) * sc, bf_hi(x.y) * sc); o.z = pk2(bf_lo(x.z) * sc, bf_hi(x.z) * sc); o.w = pk2(bf_lo(x.w) * sc, bf_hi(x.w) * sc); return o; }
; template <int DIR, bool INTRA, bool FINAL> __device__ __forceinline__ void retention_pass(LAS unsigned char* lds, const bf16* ZH, bf16* YF, bf16* MIX, const float* ld, const float* gn, int seq, int h, int n0, int ncnt, ...
;     ...
;             { const float xi = DIR == 0 ? __expf(lf * (float)(16 * w + lr + 1)) : __expf(lb * (float)(128 - 16 * w - lr));
; #pragma unroll
;               for (int ks = 0; ks < 4; ++ks) qx[ks] = __builtin_bit_cast(bf16x8, scale8(__builtin_bit_cast(v4u, qf[ks]), xi)); }
;             bf16x8 pt[4];
;             if constexpr (INTRA) {
;                 f32x4 s[8];
; #pragma unroll
;                 for (int jt = 0; jt < 8; ++jt) { s[jt] = (f32x4){0.f, 0.f, 0.f, 0.f};
; #pragma unroll
;                     for (int ks = 0; ks < 4; ++ks) { const bf16x8 a = *(const LAS bf16x8*)(lds + R_K + (16 * jt + lr) * RS + (8 * lg + 32 * ks) * 2); s[jt] = MFMA16(a, qf[ks], s[jt]); }
;                     __builtin_amdgcn_sched_barrier(0); }
	s_waitcnt lgkmcnt(0)
	v_mul_f32_e32 v84, v138, v84
	v_mul_f32_e32 v84, 0x3fb8aa3b, v84
	v_exp_f32_e32 v99, v84
	v_lshlrev_b32_e32 v84, 16, v60
	v_and_b32_e32 v86, 0xffff0000, v61
	v_mul_f32_e32 v84, v99, v84
	v_mul_f32_e32 v85, v99, v85
	v_cvt_pk_bf16_f32 v84, v84, v85
	v_lshlrev_b32_e32 v85, 16, v61
	v_mul_f32_e32 v85, v99, v85
	v_mul_f32_e32 v86, v99, v86
	v_cvt_pk_bf16_f32 v85, v85, v86
	v_lshlrev_b32_e32 v86, 16, v62
	v_and_b32_e32 v87, 0xffff0000, v62
	v_mul_f32_e32 v86, v99, v86
	v_mul_f32_e32 v87, v99, v87
	v_cvt_pk_bf16_f32 v86, v86, v87
	v_lshlrev_b32_e32 v87, 16, v63
	v_and_b32_e32 v88, 0xffff0000, v63
	v_mul_f32_e32 v87, v99, v87
	v_mul_f32_e32 v88, v99, v88
	v_cvt_pk_bf16_f32 v87, v87, v88
	v_lshlrev_b32_e32 v88, 16, v64
	v_and_b32_e32 v89, 0xffff0000, v64
	v_mul_f32_e32 v88, v99, v88
	v_mul_f32_e32 v89, v99, v89
	v_cvt_pk_bf16_f32 v88, v88, v89
	v_lshlrev_b32_e32 v89, 16, v65
	v_and_b32_e32 v90, 0xffff0000, v65
	v_mul_f32_e32 v89, v99, v89
	v_mul_f32_e32 v90, v99, v90
	v_cvt_pk_bf16_f32 v89, v89, v90
	v_lshlrev_b32_e32 v90, 16, v66
	v_and_b32_e32 v91, 0xffff0000, v66
	v_mul_f32_e32 v90, v99, v90
	v_mul_f32_e32 v91, v99, v91
	v_cvt_pk_bf16_f32 v90, v90, v91
	v_lshlrev_b32_e32 v91, 16, v67
	v_and_b32_e32 v92, 0xffff0000, v67
	v_mul_f32_e32 v91, v99, v91
	v_mul_f32_e32 v92, v99, v92
	v_cvt_pk_bf16_f32 v91, v91, v92
	v_lshlrev_b32_e32 v92, 16, v68
	v_and_b32_e32 v93, 0xffff0000, v68
	v_mul_f32_e32 v92, v99, v92
	v_mul_f32_e32 v93, v99, v93
	v_cvt_pk_bf16_f32 v92, v92, v93
	v_lshlrev_b32_e32 v93, 16, v69
	v_and_b32_e32 v94, 0xffff0000, v69
	v_mul_f32_e32 v93, v99, v93
	v_mul_f32_e32 v94, v99, v94
	v_cvt_pk_bf16_f32 v93, v93, v94
	v_lshlrev_b32_e32 v94, 16, v70
	v_and_b32_e32 v95, 0xffff0000, v70
	v_mul_f32_e32 v94, v99, v94
	v_mul_f32_e32 v95, v99, v95
	v_cvt_pk_bf16_f32 v94, v94, v95
	v_lshlrev_b32_e32 v95, 16, v71
	v_and_b32_e32 v96, 0xffff0000, v71
	v_mul_f32_e32 v95, v99, v95
	v_mul_f32_e32 v96, v99, v96
	v_cvt_pk_bf16_f32 v95, v95, v96
	v_lshlrev_b32_e32 v96, 16, v72
	v_and_b32_e32 v97, 0xffff0000, v72
	v_mul_f32_e32 v96, v99, v96
	v_mul_f32_e32 v97, v99, v97
	v_cvt_pk_bf16_f32 v96, v96, v97
	v_lshlrev_b32_e32 v97, 16, v73
	v_and_b32_e32 v98, 0xffff0000, v73
	v_mul_f32_e32 v97, v99, v97
	v_mul_f32_e32 v98, v99, v98
	v_cvt_pk_bf16_f32 v97, v97, v98
	v_lshlrev_b32_e32 v98, 16, v74
	v_and_b32_e32 v101, 0xffff0000, v74
	v_mul_f32_e32 v98, v99, v98
	v_mul_f32_e32 v101, v99, v101
	v_cvt_pk_bf16_f32 v98, v98, v101
	v_lshlrev_b32_e32 v101, 16, v75
	v_and_b32_e32 v102, 0xffff0000, v75
	v_lshlrev_b32_e32 v213, 4, v100
	v_mul_f32_e32 v101, v99, v101
	v_mul_f32_e32 v99, v99, v102
	v_add3_u32 v135, 0, v213, v209
	ds_read_b128 v[144:147], v135
	ds_read_b128 v[152:155], v135 offset:64
	ds_read_b128 v[156:159], v135 offset:128
	ds_read_b128 v[160:163], v135 offset:192
	ds_read_b128 v[164:167], v135 offset:4352
	ds_read_b128 v[168:171], v135 offset:4416
	ds_read_b128 v[172:175], v135 offset:4480
	ds_read_b128 v[176:179], v135 offset:4544
	v_lshlrev_b32_e32 v181, 2, v100
	v_cvt_pk_bf16_f32 v99, v101, v99
	s_waitcnt lgkmcnt(7)
	v_mfma_f32_16x16x32_bf16 v[100:103], v[144:147], v[60:63], 0
	ds_read_b128 v[144:147], v135 offset:8704
	s_waitcnt lgkmcnt(7)
	v_mfma_f32_16x16x32_bf16 v[100:103], v[152:155], v[64:67], v[100:103]
	ds_read_b128 v[152:155], v135 offset:8768
	s_waitcnt lgkmcnt(7)
	v_mfma_f32_16x16x32_bf16 v[100:103], v[156:159], v[68:71], v[100:103]
	ds_read_b128 v[156:159], v135 offset:8832
	s_waitcnt lgkmcnt(7)
	v_mfma_f32_16x16x32_bf16 v[100:103], v[160:163], v[72:75], v[100:103]
	ds_read_b128 v[160:163], v135 offset:8896
	s_waitcnt lgkmcnt(7)
	v_mfma_f32_16x16x32_bf16 v[104:107], v[164:167], v[60:63], 0
	ds_read_b128 v[164:167], v135 offset:13056
	s_waitcnt lgkmcnt(7)
	v_mfma_f32_16x16x32_bf16 v[104:107], v[168:171], v[64:67], v[104:107]
	ds_read_b128 v[168:171], v135 offset:13120
	s_waitcnt lgkmcnt(7)
; #define LAS __attribute__((address_space(3)))
; #define MFMA16(a, b, c) __builtin_amdgcn_mfma_f32_16x16x32_bf16((a), (b), (c), 0, 0, 0)
; template <int DIR, bool INTRA, bool FINAL> __device__ __forceinline__ void retention_pass(LAS unsigned char* lds, const bf16* ZH, bf16* YF, bf16* MIX, const float* ld, const float* gn, int seq, int h, int n0, int ncnt, ...
;     ...
; #pragma unroll
;                 for (int jt = 0; jt < 8; ++jt) { s[jt] = (f32x4){0.f, 0.f, 0.f, 0.f};
; #pragma unroll
;                     for (int ks = 0; ks < 4; ++ks) { const bf16x8 a = *(const LAS bf16x8*)(lds + R_K + (16 * jt + lr) * RS + (8 * lg + 32 * ks) * 2); s[jt] = MFMA16(a, qf[ks], s[jt]); }
;                     __builtin_amdgcn_sched_barrier(0); }
;                 float Fr[4], Br[4];
; #pragma unroll
;                 for (int r = 0; r < 4; ++r) { const float br = (float)(lr - 4 * lg - r); Fr[r] = __expf(lf * br); Br[r] = __expf(-lb * br); }
; #pragma unroll
;                 for (int jt = 0; jt < 8; ++jt) { const int dt = w - jt; const float cf = __expf(lf * 16.f * (float)dt), cb = __expf(-lb * 16.f * (float)dt);
; #pragma unroll
;                     for (int r = 0; r < 4; ++r) { const float dec = dt > 0 ? Fr[r] * cf : (dt < 0 ? Br[r] * cb : ((lr - 4 * lg - r) >= 0 ? Fr[r] : Br[r])); s[jt][r] *= dec; } }
	v_mfma_f32_16x16x32_bf16 v[104:107], v[172:175], v[68:71], v[104:107]
	ds_read_b128 v[172:175], v135 offset:13184
	s_waitcnt lgkmcnt(7)
	v_mfma_f32_16x16x32_bf16 v[104:107], v[176:179], v[72:75], v[104:107]
	ds_read_b128 v[176:179], v135 offset:13248
	s_waitcnt lgkmcnt(7)
	v_mfma_f32_16x16x32_bf16 v[108:111], v[144:147], v[60:63], 0
	ds_read_b128 v[144:147], v135 offset:17408
	s_waitcnt lgkmcnt(7)
	v_mfma_f32_16x16x32_bf16 v[108:111], v[152:155], v[64:67], v[108:111]
	ds_read_b128 v[152:155], v135 offset:17472
	s_waitcnt lgkmcnt(7)
	v_mfma_f32_16x16x32_bf16 v[108:111], v[156:159], v[68:71], v[108:111]
	ds_read_b128 v[156:159], v135 offset:17536
	s_waitcnt lgkmcnt(7)
	v_mfma_f32_16x16x32_bf16 v[108:111], v[160:163], v[72:75], v[108:111]
	ds_read_b128 v[160:163], v135 offset:17600
	s_waitcnt lgkmcnt(7)
	v_mfma_f32_16x16x32_bf16 v[112:115], v[164:167], v[60:63], 0
	ds_read_b128 v[164:167], v135 offset:21760
	s_waitcnt lgkmcnt(7)
	v_mfma_f32_16x16x32_bf16 v[112:115], v[168:171], v[64:67], v[112:115]
	ds_read_b128 v[168:171], v135 offset:21824
	s_waitcnt lgkmcnt(7)
	v_mfma_f32_16x16x32_bf16 v[112:115], v[172:175], v[68:71], v[112:115]
	ds_read_b128 v[172:175], v135 offset:21888
	s_waitcnt lgkmcnt(7)
	v_mfma_f32_16x16x32_bf16 v[112:115], v[176:179], v[72:75], v[112:115]
	ds_read_b128 v[176:179], v135 offset:21952
	s_waitcnt lgkmcnt(7)
	v_mfma_f32_16x16x32_bf16 v[116:119], v[144:147], v[60:63], 0
	ds_read_b128 v[144:147], v135 offset:26112
	s_waitcnt lgkmcnt(7)
	v_mfma_f32_16x16x32_bf16 v[116:119], v[152:155], v[64:67], v[116:119]
	ds_read_b128 v[152:155], v135 offset:26176
	s_waitcnt lgkmcnt(7)
	v_mfma_f32_16x16x32_bf16 v[116:119], v[156:159], v[68:71], v[116:119]
	ds_read_b128 v[156:159], v135 offset:26240
	s_waitcnt lgkmcnt(7)
	v_mfma_f32_16x16x32_bf16 v[116:119], v[160:163], v[72:75], v[116:119]
	ds_read_b128 v[160:163], v135 offset:26304
	s_waitcnt lgkmcnt(7)
	v_mfma_f32_16x16x32_bf16 v[120:123], v[164:167], v[60:63], 0
	ds_read_b128 v[164:167], v135 offset:30464
	s_waitcnt lgkmcnt(7)
	v_mfma_f32_16x16x32_bf16 v[120:123], v[168:171], v[64:67], v[120:123]
	ds_read_b128 v[168:171], v135 offset:30528
	s_waitcnt lgkmcnt(7)
	v_mfma_f32_16x16x32_bf16 v[120:123], v[172:175], v[68:71], v[120:123]
	ds_read_b128 v[172:175], v135 offset:30592
	s_waitcnt lgkmcnt(7)
	v_mfma_f32_16x16x32_bf16 v[120:123], v[176:179], v[72:75], v[120:123]
	s_waitcnt lgkmcnt(6)
	v_mfma_f32_16x16x32_bf16 v[124:127], v[144:147], v[60:63], 0
	s_waitcnt lgkmcnt(5)
	v_mfma_f32_16x16x32_bf16 v[124:127], v[152:155], v[64:67], v[124:127]
	s_waitcnt lgkmcnt(4)
	v_mfma_f32_16x16x32_bf16 v[124:127], v[156:159], v[68:71], v[124:127]
	s_waitcnt lgkmcnt(3)
	v_mfma_f32_16x16x32_bf16 v[128:131], v[160:163], v[72:75], v[124:127]
	s_nop 4
	s_waitcnt lgkmcnt(2)
	v_mfma_f32_16x16x32_bf16 v[124:127], v[164:167], v[60:63], 0
	s_waitcnt lgkmcnt(1)
	v_mfma_f32_16x16x32_bf16 v[124:127], v[168:171], v[64:67], v[124:127]
	s_waitcnt lgkmcnt(0)
	v_mfma_f32_16x16x32_bf16 v[124:127], v[172:175], v[68:71], v[124:127]
	ds_read_b128 v[140:143], v135 offset:30656
	s_waitcnt lgkmcnt(0)
	v_mfma_f32_16x16x32_bf16 v[124:127], v[140:143], v[72:75], v[124:127]
	v_sub_u32_e32 v135, v207, v181
	v_cvt_f32_i32_e32 v135, v135
	v_cvt_f32_i32_e32 v137, v134
	v_mul_f32_e32 v151, 0xc1800000, v136
	v_cmp_gt_i32_e64 s[6:7], 1, v134
	v_mul_f32_e32 v139, v138, v135
	v_mul_f32_e64 v135, -v136, v135
	v_mul_f32_e32 v135, 0x3fb8aa3b, v135
	v_exp_f32_e32 v140, v135
	v_mul_f32_e32 v135, v151, v137
	v_mul_f32_e32 v139, 0x3fb8aa3b, v139
	v_mul_f32_e32 v135, 0x3fb8aa3b, v135
	v_exp_f32_e32 v139, v139
	v_exp_f32_e32 v150, v135
	v_cmp_lt_i32_e32 vcc, -1, v134
	s_and_saveexec_b64 s[8:9], s[6:7]
	s_xor_b64 s[34:35], exec, s[8:9]
	s_cbranch_execz .LBB0_998
	s_and_saveexec_b64 s[8:9], vcc
	s_xor_b64 s[46:47], exec, s[8:9]
	v_cmp_lt_u32_e64 s[8:9], v207, v181
	s_nop 1
	v_cndmask_b32_e64 v135, v139, v140, s[8:9]
	s_andn2_saveexec_b64 s[8:9], s[46:47]
	v_mul_f32_e32 v135, v150, v140
	s_or_b64 exec, exec, s[8:9]

; __device__ __forceinline__ unsigned pk2(float lo, float hi) { return pg8::cvt_pk_bf16(lo, hi); }
; #define MFMA16(a, b, c) __builtin_amdgcn_mfma_f32_16x16x32_bf16((a), (b), (c), 0, 0, 0)
; __device__ __forceinline__ bf16x8 ds_tr2(LAS unsigned char* p, int rstride) { const s16x4 a = ds_tr(p), b = ds_tr(p + 16 * rstride); bf16x8 r; r[0] = a[0]; r[1] = a[1]; r[2] = a[2]; r[3] = a[3]; r[4] = b[0]; r[5] = b[1]; r[6] = b[2]; r[7] = b[3]; return r; }
; template <int DIR, bool INTRA, bool FINAL> __device__ __forceinline__ void retention_pass(LAS unsigned char* lds, const bf16* ZH, bf16* YF, bf16* MIX, const float* ld, const float* gn, int seq, int h, int n0, int ncnt, ...
;     ...
;                 float Fr[4], Br[4];
; #pragma unroll
;                 for (int r = 0; r < 4; ++r) { const float br = (float)(lr - 4 * lg - r); Fr[r] = __expf(lf * br); Br[r] = __expf(-lb * br); }
; #pragma unroll
;                 for (int jt = 0; jt < 8; ++jt) { const int dt = w - jt; const float cf = __expf(lf * 16.f * (float)dt), cb = __expf(-lb * 16.f * (float)dt);
; #pragma unroll
;                     for (int r = 0; r < 4; ++r) { const float dec = dt > 0 ? Fr[r] * cf : (dt < 0 ? Br[r] * cb : ((lr - 4 * lg - r) >= 0 ? Fr[r] : Br[r])); s[jt][r] *= dec; } }
; #pragma unroll
;                 for (int ks = 0; ks < 4; ++ks) { v4u o; o.x = pk2(s[2 * ks][0], s[2 * ks][1]); o.y = pk2(s[2 * ks][2], s[2 * ks][3]); o.z = pk2(s[2 * ks + 1][0], s[2 * ks + 1][1]); o.w = pk2(s[2 * ks + 1][2], s[2 * ks + 1][3]); pt[ks] = __builtin_bit_cast(bf16x8, o); }
;             }
;             f32x4 y[8];
; #pragma unroll
;             for (int e = 0; e < 8; ++e) y[e] = (f32x4){0.f, 0.f, 0.f, 0.f};
;             { bf16x8 kwf[4];
; #pragma unroll
;               for (int ks = 0; ks < 4; ++ks) kwf[ks] = ds_tr2(trp + R_KW + (32 * ks) * RSB + (16 * w) * 2, RSB);
; #pragma unroll
;               for (int e = 0; e < 8; ++e) { st[e] = st[e] * gC;
; #pragma unroll
;                 for (int ks = 0; ks < 4; ++ks) { const bf16x8 vf = ds_tr2(trp + R_V + (32 * ks) * RSB + (16 * e) * 2, RSB);
;                     if constexpr (INTRA) y[e] = MFMA16(vf, pt[ks], y[e]);
;                     st[e] = MFMA16(kwf[ks], vf, st[e]); }
;                 __builtin_amdgcn_sched_barrier(0); } }
.LBB0_1248:
	s_waitcnt lgkmcnt(0)
	s_or_b64 exec, exec, s[6:7]
	v_mul_f32_e32 v145, v116, v163
	v_lshrrev_b32_e32 v116, 2, v207
	v_or_b32_e32 v116, v181, v116
	v_mul_f32_e32 v100, v100, v135
	v_mul_u32_u24_e32 v135, 0x120, v116
	v_lshlrev_b32_e32 v116, 3, v132
	v_and_b32_e32 v132, 24, v116
	v_mul_f32_e32 v113, v113, v160
	v_mul_f32_e32 v104, v104, v150
	v_add3_u32 v160, 0, v135, v132
	v_mul_f32_e32 v140, v126, v141
	v_mul_f32_e32 v139, v125, v139
	v_mul_f32_e32 v134, v124, v134
	v_mul_f32_e32 v122, v122, v169
	v_mul_f32_e32 v120, v120, v167
	v_mul_f32_e32 v111, v111, v158
	v_mul_f32_e32 v110, v110, v157
	v_mul_f32_e32 v109, v109, v156
	v_mul_f32_e32 v108, v108, v155
	v_mul_f32_e32 v106, v106, v153
	v_mul_f32_e32 v105, v105, v152
	v_mul_f32_e32 v103, v103, v138
	v_mul_f32_e32 v102, v102, v137
	v_mul_f32_e32 v101, v101, v136
	v_cvt_pk_bf16_f32 v124, v100, v101
	v_cvt_pk_bf16_f32 v125, v102, v103
	v_cvt_pk_bf16_f32 v126, v104, v105
	v_add_u32_e32 v104, v160, v133
	ds_read_b64_tr_b16 v[216:217], v104 offset:34816
	ds_read_b64_tr_b16 v[218:219], v104 offset:39424
	ds_read_b64_tr_b16 v[220:221], v104 offset:53248
	ds_read_b64_tr_b16 v[222:223], v104 offset:57856
	v_mul_f32_e32 v131, v131, v174
	v_mul_f32_e32 v130, v130, v173
	v_mul_f32_e32 v129, v129, v172
	v_mul_f32_e32 v128, v128, v171
	v_mul_f32_e32 v123, v123, v170
	v_mul_f32_e32 v121, v121, v168
	v_mul_f32_e32 v141, v119, v166
	v_mul_f32_e32 v143, v118, v165
	v_mul_f32_e32 v144, v117, v164
	v_mul_f32_e32 v115, v115, v162
	v_mul_f32_e32 v114, v114, v161
	v_mul_f32_e32 v112, v112, v159
	v_mul_f32_e32 v107, v107, v154
	v_mul_f32_e32 v136, v127, v142
	v_cvt_pk_bf16_f32 v127, v106, v107
	v_cvt_pk_bf16_f32 v116, v108, v109
	v_cvt_pk_bf16_f32 v117, v110, v111
	v_cvt_pk_bf16_f32 v118, v112, v113
	v_cvt_pk_bf16_f32 v119, v114, v115
	v_cvt_pk_bf16_f32 v108, v145, v144
	v_cvt_pk_bf16_f32 v109, v143, v141
	v_cvt_pk_bf16_f32 v110, v120, v121
	v_cvt_pk_bf16_f32 v111, v122, v123
	v_add_u32_e32 v106, 0x8800, v104
	v_add_u32_e32 v120, 0x11800, v160
	ds_read_b64_tr_b16 v[224:225], v120
	v_add_u32_e32 v122, 0x12a00, v160
	ds_read_b64_tr_b16 v[226:227], v122
	v_cvt_pk_bf16_f32 v100, v128, v129
	v_cvt_pk_bf16_f32 v101, v130, v131
	v_cvt_pk_bf16_f32 v102, v134, v139
	v_cvt_pk_bf16_f32 v103, v140, v136
	ds_read_b64_tr_b16 v[128:129], v104 offset:44032
	ds_read_b64_tr_b16 v[130:131], v104 offset:48640
	ds_read_b64_tr_b16 v[104:105], v104 offset:62464
	ds_read_b64_tr_b16 v[106:107], v106 offset:32256
	v_mov_b32_e32 v187, v186
	v_pk_mul_f32 v[34:35], v[186:187], v[34:35]
	v_pk_mul_f32 v[32:33], v[188:189], v[32:33]
	s_waitcnt lgkmcnt(4)
	v_mfma_f32_16x16x32_bf16 v[136:139], v[224:227], v[124:127], 0
	v_mfma_f32_16x16x32_bf16 v[32:35], v[216:219], v[224:227], v[32:35]
	v_add_u32_e32 v120, 0x13c00, v160
	ds_read_b64_tr_b16 v[240:241], v120
	v_add_u32_e32 v122, 0x14e00, v160
	ds_read_b64_tr_b16 v[242:243], v122
	s_waitcnt lgkmcnt(0)
	v_mfma_f32_16x16x32_bf16 v[136:139], v[240:243], v[116:119], v[136:139]
	v_mfma_f32_16x16x32_bf16 v[32:35], v[128:131], v[240:243], v[32:35]
	v_add_u32_e32 v120, 0x16000, v160
	ds_read_b64_tr_b16 v[244:245], v120
	v_add_u32_e32 v122, 0x17200, v160
	ds_read_b64_tr_b16 v[246:247], v122
	s_waitcnt lgkmcnt(0)
	v_mfma_f32_16x16x32_bf16 v[136:139], v[244:247], v[108:111], v[136:139]
	v_mfma_f32_16x16x32_bf16 v[32:35], v[220:223], v[244:247], v[32:35]
	v_add_u32_e32 v120, 0x18400, v160
	ds_read_b64_tr_b16 v[248:249], v120
	v_add_u32_e32 v120, 0x19600, v160
	ds_read_b64_tr_b16 v[250:251], v120
	s_waitcnt lgkmcnt(0)
	v_mfma_f32_16x16x32_bf16 v[120:123], v[248:251], v[100:103], v[136:139]
	v_mfma_f32_16x16x32_bf16 v[32:35], v[104:107], v[248:251], v[32:35]
	s_nop 1
	v_add_u32_e32 v136, 0x11820, v160
	ds_read_b64_tr_b16 v[224:225], v136
	v_add_u32_e32 v138, 0x12a20, v160
	ds_read_b64_tr_b16 v[226:227], v138
	v_pk_mul_f32 v[30:31], v[186:187], v[30:31]
	v_pk_mul_f32 v[28:29], v[188:189], v[28:29]
	s_waitcnt lgkmcnt(0)
	v_mfma_f32_16x16x32_bf16 v[140:143], v[224:227], v[124:127], 0
	v_mfma_f32_16x16x32_bf16 v[28:31], v[216:219], v[224:227], v[28:31]
	v_add_u32_e32 v136, 0x13c20, v160
	ds_read_b64_tr_b16 v[240:241], v136
	v_add_u32_e32 v138, 0x14e20, v160
	ds_read_b64_tr_b16 v[242:243], v138
	s_waitcnt lgkmcnt(0)
	v_mfma_f32_16x16x32_bf16 v[140:143], v[240:243], v[116:119], v[140:143]
	v_mfma_f32_16x16x32_bf16 v[28:31], v[128:131], v[240:243], v[28:31]
	v_add_u32_e32 v136, 0x16020, v160
	ds_read_b64_tr_b16 v[244:245], v136
	v_add_u32_e32 v138, 0x17220, v160
	ds_read_b64_tr_b16 v[246:247], v138
	s_waitcnt lgkmcnt(0)
	v_mfma_f32_16x16x32_bf16 v[140:143], v[244:247], v[108:111], v[140:143]
	v_mfma_f32_16x16x32_bf16 v[28:31], v[220:223], v[244:247], v[28:31]
	v_add_u32_e32 v136, 0x18420, v160
	ds_read_b64_tr_b16 v[248:249], v136
	v_add_u32_e32 v136, 0x19620, v160
	ds_read_b64_tr_b16 v[250:251], v136
	s_waitcnt lgkmcnt(0)
	v_mfma_f32_16x16x32_bf16 v[136:139], v[248:251], v[100:103], v[140:143]
	v_mfma_f32_16x16x32_bf16 v[28:31], v[104:107], v[248:251], v[28:31]
	s_nop 1
	v_add_u32_e32 v140, 0x11840, v160
	ds_read_b64_tr_b16 v[224:225], v140
	v_add_u32_e32 v142, 0x12a40, v160
	ds_read_b64_tr_b16 v[226:227], v142
	v_pk_mul_f32 v[26:27], v[186:187], v[26:27]
	v_pk_mul_f32 v[24:25], v[188:189], v[24:25]
	s_waitcnt lgkmcnt(0)
	v_mfma_f32_16x16x32_bf16 v[144:147], v[224:227], v[124:127], 0
	v_mfma_f32_16x16x32_bf16 v[24:27], v[216:219], v[224:227], v[24:27]
	v_add_u32_e32 v140, 0x13c40, v160
	ds_read_b64_tr_b16 v[240:241], v140
	v_add_u32_e32 v142, 0x14e40, v160
	ds_read_b64_tr_b16 v[242:243], v142
	s_waitcnt lgkmcnt(0)
; #define MFMA16(a, b, c) __builtin_amdgcn_mfma_f32_16x16x32_bf16((a), (b), (c), 0, 0, 0)
; __device__ __forceinline__ bf16x8 ds_tr2(LAS unsigned char* p, int rstride) { const s16x4 a = ds_tr(p), b = ds_tr(p + 16 * rstride); bf16x8 r; r[0] = a[0]; r[1] = a[1]; r[2] = a[2]; r[3] = a[3]; r[4] = b[0]; r[5] = b[1]; r[6] = b[2]; r[7] = b[3]; return r; }
; template <int DIR, bool INTRA, bool FINAL> __device__ __forceinline__ void retention_pass(LAS unsigned char* lds, const bf16* ZH, bf16* YF, bf16* MIX, const float* ld, const float* gn, int seq, int h, int n0, int ncnt, ...
;     ...
;               for (int e = 0; e < 8; ++e) { st[e] = st[e] * gC;
; #pragma unroll
;                 for (int ks = 0; ks < 4; ++ks) { const bf16x8 vf = ds_tr2(trp + R_V + (32 * ks) * RSB + (16 * e) * 2, RSB);
;                     if constexpr (INTRA) y[e] = MFMA16(vf, pt[ks], y[e]);
;                     st[e] = MFMA16(kwf[ks], vf, st[e]); }
;                 __builtin_amdgcn_sched_barrier(0); } }
	v_mfma_f32_16x16x32_bf16 v[144:147], v[240:243], v[116:119], v[144:147]
	v_mfma_f32_16x16x32_bf16 v[24:27], v[128:131], v[240:243], v[24:27]
	v_add_u32_e32 v140, 0x16040, v160
	ds_read_b64_tr_b16 v[244:245], v140
	v_add_u32_e32 v142, 0x17240, v160
	ds_read_b64_tr_b16 v[246:247], v142
	s_waitcnt lgkmcnt(0)
	v_mfma_f32_16x16x32_bf16 v[144:147], v[244:247], v[108:111], v[144:147]
	v_mfma_f32_16x16x32_bf16 v[24:27], v[220:223], v[244:247], v[24:27]
	v_add_u32_e32 v140, 0x18440, v160
	ds_read_b64_tr_b16 v[248:249], v140
	v_add_u32_e32 v140, 0x19640, v160
	ds_read_b64_tr_b16 v[250:251], v140
	s_waitcnt lgkmcnt(0)
	v_mfma_f32_16x16x32_bf16 v[140:143], v[248:251], v[100:103], v[144:147]
	v_mfma_f32_16x16x32_bf16 v[24:27], v[104:107], v[248:251], v[24:27]
	s_nop 1
	v_add_u32_e32 v144, 0x11860, v160
	ds_read_b64_tr_b16 v[224:225], v144
	v_add_u32_e32 v146, 0x12a60, v160
	ds_read_b64_tr_b16 v[226:227], v146
	v_pk_mul_f32 v[22:23], v[186:187], v[22:23]
	v_pk_mul_f32 v[20:21], v[188:189], v[20:21]
	s_waitcnt lgkmcnt(0)
	v_mfma_f32_16x16x32_bf16 v[148:151], v[224:227], v[124:127], 0
	v_mfma_f32_16x16x32_bf16 v[20:23], v[216:219], v[224:227], v[20:23]
	v_add_u32_e32 v144, 0x13c60, v160
	ds_read_b64_tr_b16 v[240:241], v144
	v_add_u32_e32 v146, 0x14e60, v160
	ds_read_b64_tr_b16 v[242:243], v146
	s_waitcnt lgkmcnt(0)
	v_mfma_f32_16x16x32_bf16 v[148:151], v[240:243], v[116:119], v[148:151]
	v_mfma_f32_16x16x32_bf16 v[20:23], v[128:131], v[240:243], v[20:23]
	v_add_u32_e32 v144, 0x16060, v160
	ds_read_b64_tr_b16 v[244:245], v144
	v_add_u32_e32 v146, 0x17260, v160
	ds_read_b64_tr_b16 v[246:247], v146
	s_waitcnt lgkmcnt(0)
	v_mfma_f32_16x16x32_bf16 v[148:151], v[244:247], v[108:111], v[148:151]
	v_mfma_f32_16x16x32_bf16 v[20:23], v[220:223], v[244:247], v[20:23]
	v_add_u32_e32 v144, 0x18460, v160
	ds_read_b64_tr_b16 v[248:249], v144
	v_add_u32_e32 v144, 0x19660, v160
	ds_read_b64_tr_b16 v[250:251], v144
	s_waitcnt lgkmcnt(0)
	v_mfma_f32_16x16x32_bf16 v[144:147], v[248:251], v[100:103], v[148:151]
	v_mfma_f32_16x16x32_bf16 v[20:23], v[104:107], v[248:251], v[20:23]
	s_nop 1
	v_add_u32_e32 v148, 0x11880, v160
	ds_read_b64_tr_b16 v[224:225], v148
	v_add_u32_e32 v150, 0x12a80, v160
	ds_read_b64_tr_b16 v[226:227], v150
	v_pk_mul_f32 v[18:19], v[186:187], v[18:19]
	v_pk_mul_f32 v[16:17], v[188:189], v[16:17]
	s_waitcnt lgkmcnt(0)
	v_mfma_f32_16x16x32_bf16 v[152:155], v[224:227], v[124:127], 0
	v_mfma_f32_16x16x32_bf16 v[16:19], v[216:219], v[224:227], v[16:19]
	v_add_u32_e32 v148, 0x13c80, v160
	ds_read_b64_tr_b16 v[240:241], v148
	v_add_u32_e32 v150, 0x14e80, v160
	ds_read_b64_tr_b16 v[242:243], v150
	s_waitcnt lgkmcnt(0)
	v_mfma_f32_16x16x32_bf16 v[152:155], v[240:243], v[116:119], v[152:155]
	v_mfma_f32_16x16x32_bf16 v[16:19], v[128:131], v[240:243], v[16:19]
	v_add_u32_e32 v148, 0x16080, v160
	ds_read_b64_tr_b16 v[244:245], v148
	v_add_u32_e32 v150, 0x17280, v160
	ds_read_b64_tr_b16 v[246:247], v150
	s_waitcnt lgkmcnt(0)
	v_mfma_f32_16x16x32_bf16 v[152:155], v[244:247], v[108:111], v[152:155]
	v_mfma_f32_16x16x32_bf16 v[16:19], v[220:223], v[244:247], v[16:19]
	v_add_u32_e32 v148, 0x18480, v160
	ds_read_b64_tr_b16 v[248:249], v148
	v_add_u32_e32 v148, 0x19680, v160
	ds_read_b64_tr_b16 v[250:251], v148
	s_waitcnt lgkmcnt(0)
	v_mfma_f32_16x16x32_bf16 v[148:151], v[248:251], v[100:103], v[152:155]
	v_mfma_f32_16x16x32_bf16 v[16:19], v[104:107], v[248:251], v[16:19]
	s_nop 1
	v_add_u32_e32 v152, 0x118a0, v160
	ds_read_b64_tr_b16 v[224:225], v152
	v_add_u32_e32 v154, 0x12aa0, v160
	ds_read_b64_tr_b16 v[226:227], v154
	v_pk_mul_f32 v[14:15], v[186:187], v[14:15]
	v_pk_mul_f32 v[12:13], v[188:189], v[12:13]
	s_waitcnt lgkmcnt(0)
	v_mfma_f32_16x16x32_bf16 v[156:159], v[224:227], v[124:127], 0
	v_mfma_f32_16x16x32_bf16 v[12:15], v[216:219], v[224:227], v[12:15]
	v_add_u32_e32 v152, 0x13ca0, v160
	ds_read_b64_tr_b16 v[240:241], v152
	v_add_u32_e32 v154, 0x14ea0, v160
	ds_read_b64_tr_b16 v[242:243], v154
	s_waitcnt lgkmcnt(0)
	v_mfma_f32_16x16x32_bf16 v[156:159], v[240:243], v[116:119], v[156:159]
	v_mfma_f32_16x16x32_bf16 v[12:15], v[128:131], v[240:243], v[12:15]
	v_add_u32_e32 v152, 0x160a0, v160
	ds_read_b64_tr_b16 v[244:245], v152
	v_add_u32_e32 v154, 0x172a0, v160
	ds_read_b64_tr_b16 v[246:247], v154
	s_waitcnt lgkmcnt(0)
	v_mfma_f32_16x16x32_bf16 v[156:159], v[244:247], v[108:111], v[156:159]
	v_mfma_f32_16x16x32_bf16 v[12:15], v[220:223], v[244:247], v[12:15]
	v_add_u32_e32 v152, 0x184a0, v160
	ds_read_b64_tr_b16 v[248:249], v152
	v_add_u32_e32 v152, 0x196a0, v160
	ds_read_b64_tr_b16 v[250:251], v152
	s_waitcnt lgkmcnt(0)
; #define GAS __attribute__((address_space(1)))
; #define MFMA16(a, b, c) __builtin_amdgcn_mfma_f32_16x16x32_bf16((a), (b), (c), 0, 0, 0)
; __device__ __forceinline__ bf16x8 ds_tr2(LAS unsigned char* p, int rstride) { const s16x4 a = ds_tr(p), b = ds_tr(p + 16 * rstride); bf16x8 r; r[0] = a[0]; r[1] = a[1]; r[2] = a[2]; r[3] = a[3]; r[4] = b[0]; r[5] = b[1]; r[6] = b[2]; r[7] = b[3]; return r; }
; template <int DIR, bool INTRA, bool FINAL> __device__ __forceinline__ void retention_pass(LAS unsigned char* lds, const bf16* ZH, bf16* YF, bf16* MIX, const float* ld, const float* gn, int seq, int h, int n0, int ncnt, ...
;     ...
;               for (int e = 0; e < 8; ++e) { st[e] = st[e] * gC;
; #pragma unroll
;                 for (int ks = 0; ks < 4; ++ks) { const bf16x8 vf = ds_tr2(trp + R_V + (32 * ks) * RSB + (16 * e) * 2, RSB);
;                     if constexpr (INTRA) y[e] = MFMA16(vf, pt[ks], y[e]);
;                     st[e] = MFMA16(kwf[ks], vf, st[e]); }
;                 __builtin_amdgcn_sched_barrier(0); } }
;             v2u ywv[8], gwv[8];
;             if constexpr (FINAL) { const int row_ = r0 + 16 * w + lr; const bf16* yp_ = YF + (size_t)row_ * 2048 + h * HD + 4 * lg; const bf16* gp_ = Gp + (size_t)(n * 128 + 16 * w + lr) * HD + 4 * lg;
; #pragma unroll
;                 for (int e = 0; e < 8; ++e) { ywv[e] = *(const GAS v2u*)(yp_ + 16 * e); gwv[e] = *(const GAS v2u*)(gp_ + 16 * e); } }
;             if (cn + 1 < ncnt) {
; #pragma unroll
;               for (int cc = 0; cc < 4; ++cc) { kreg[cc] = *(const GAS v4u*)(Kp + (size_t)(nn * 128 + srow + 32 * cc) * HD + 8 * sch); vreg[cc] = *(const GAS v4u*)(Vp + (size_t)(nn * 128 + srow + 32 * cc) * HD + 8 * sch); }
; #pragma unroll
;               for (int ks = 0; ks < 4; ++ks) qf[ks] = *(const GAS bf16x8*)(Qp + (size_t)(nn * 128 + 16 * w + lr) * HD + 8 * lg + 32 * ks); }
	v_mfma_f32_16x16x32_bf16 v[152:155], v[248:251], v[100:103], v[156:159]
	v_mfma_f32_16x16x32_bf16 v[12:15], v[104:107], v[248:251], v[12:15]
	s_nop 1
	v_add_u32_e32 v156, 0x118c0, v160
	ds_read_b64_tr_b16 v[224:225], v156
	v_add_u32_e32 v158, 0x12ac0, v160
	ds_read_b64_tr_b16 v[226:227], v158
	v_pk_mul_f32 v[10:11], v[186:187], v[10:11]
	v_pk_mul_f32 v[8:9], v[188:189], v[8:9]
	s_waitcnt lgkmcnt(0)
	v_mfma_f32_16x16x32_bf16 v[162:165], v[224:227], v[124:127], 0
	v_mfma_f32_16x16x32_bf16 v[8:11], v[216:219], v[224:227], v[8:11]
	v_add_u32_e32 v156, 0x13cc0, v160
	ds_read_b64_tr_b16 v[240:241], v156
	v_add_u32_e32 v158, 0x14ec0, v160
	ds_read_b64_tr_b16 v[242:243], v158
	s_waitcnt lgkmcnt(0)
	v_mfma_f32_16x16x32_bf16 v[162:165], v[240:243], v[116:119], v[162:165]
	v_mfma_f32_16x16x32_bf16 v[8:11], v[128:131], v[240:243], v[8:11]
	v_add_u32_e32 v156, 0x160c0, v160
	ds_read_b64_tr_b16 v[244:245], v156
	v_add_u32_e32 v158, 0x172c0, v160
	ds_read_b64_tr_b16 v[246:247], v158
	s_waitcnt lgkmcnt(0)
	v_mfma_f32_16x16x32_bf16 v[162:165], v[244:247], v[108:111], v[162:165]
	v_mfma_f32_16x16x32_bf16 v[8:11], v[220:223], v[244:247], v[8:11]
	v_add_u32_e32 v156, 0x184c0, v160
	ds_read_b64_tr_b16 v[166:167], v156
	v_add_u32_e32 v156, 0x196c0, v160
	ds_read_b64_tr_b16 v[168:169], v156
	s_waitcnt lgkmcnt(0)
	v_mfma_f32_16x16x32_bf16 v[156:159], v[166:169], v[100:103], v[162:165]
	v_mfma_f32_16x16x32_bf16 v[8:11], v[104:107], v[166:169], v[8:11]
	v_add_u32_e32 v161, 0x118e0, v160
	s_nop 0
	ds_read_b64_tr_b16 v[162:163], v161
	v_add_u32_e32 v161, 0x12ae0, v160
	ds_read_b64_tr_b16 v[164:165], v161
	v_pk_mul_f32 v[6:7], v[186:187], v[6:7]
	v_pk_mul_f32 v[4:5], v[188:189], v[4:5]
	s_waitcnt lgkmcnt(0)
	v_mfma_f32_16x16x32_bf16 v[124:127], v[162:165], v[124:127], 0
	v_mfma_f32_16x16x32_bf16 v[4:7], v[216:219], v[162:165], v[4:7]
	v_add_u32_e32 v132, 0x13ce0, v160
	v_add_u32_e32 v134, 0x14ee0, v160
	ds_read_b64_tr_b16 v[132:133], v132
	ds_read_b64_tr_b16 v[134:135], v134
	s_waitcnt lgkmcnt(0)
	v_mfma_f32_16x16x32_bf16 v[116:119], v[132:135], v[116:119], v[124:127]
	s_nop 2
	v_add_u32_e32 v124, 0x160e0, v160
	v_add_u32_e32 v126, 0x172e0, v160
	ds_read_b64_tr_b16 v[124:125], v124
	ds_read_b64_tr_b16 v[126:127], v126
	v_mfma_f32_16x16x32_bf16 v[4:7], v[128:131], v[132:135], v[4:7]
	s_waitcnt lgkmcnt(0)
	v_mfma_f32_16x16x32_bf16 v[4:7], v[220:223], v[124:127], v[4:7]
	v_add_u32_e32 v112, 0x184e0, v160
	v_add_u32_e32 v114, 0x196e0, v160
	ds_read_b64_tr_b16 v[112:113], v112
	ds_read_b64_tr_b16 v[114:115], v114
	v_mfma_f32_16x16x32_bf16 v[108:111], v[124:127], v[108:111], v[116:119]
	s_waitcnt lgkmcnt(0)
	v_mfma_f32_16x16x32_bf16 v[176:179], v[112:115], v[100:103], v[108:111]
	v_mfma_f32_16x16x32_bf16 v[4:7], v[104:107], v[112:115], v[4:7]
	s_mov_b64 s[6:7], -1
	s_cmpk_lg_i32 s76, 0x860
	v_add_u32_e32 v215, v214, v207
	s_cbranch_scc0 .LBB0_1250
	v_add_u32_e32 v187, v214, v207
	v_lshl_add_u64 v[130:131], s[60:61], 0, v[2:3]
	v_lshl_add_u64 v[132:133], s[72:73], 0, v[2:3]
	v_add_u32_e32 v2, s76, v187
	v_add_u32_e32 v128, s76, v208
	v_add_u32_e32 v160, 0xffffffa0, v2
	v_add_u32_e32 v100, 0xffffffa0, v128
	v_subrev_u32_e32 v108, 64, v128
	v_subrev_u32_e32 v116, 32, v128
	v_ashrrev_i32_e32 v161, 31, v160
	v_ashrrev_i32_e32 v101, 31, v100
	v_ashrrev_i32_e32 v109, 31, v108
	v_ashrrev_i32_e32 v117, 31, v116
	v_ashrrev_i32_e32 v129, 31, v128
	v_lshlrev_b64 v[160:161], 8, v[160:161]
	v_lshlrev_b64 v[100:101], 8, v[100:101]
	v_lshlrev_b64 v[108:109], 8, v[108:109]
	v_lshlrev_b64 v[116:117], 8, v[116:117]
	v_lshlrev_b64 v[128:129], 8, v[128:129]
	v_lshl_add_u64 v[160:161], s[36:37], 0, v[160:161]
	v_lshlrev_b32_e32 v2, 1, v212
	v_lshl_add_u64 v[102:103], v[130:131], 0, v[100:101]
	v_lshl_add_u64 v[104:105], v[132:133], 0, v[100:101]
	v_lshl_add_u64 v[110:111], v[130:131], 0, v[108:109]
	v_lshl_add_u64 v[112:113], v[132:133], 0, v[108:109]
	v_lshl_add_u64 v[118:119], v[130:131], 0, v[116:117]
	v_lshl_add_u64 v[124:125], v[132:133], 0, v[116:117]
	v_lshl_add_u64 v[130:131], v[130:131], 0, v[128:129]
	v_lshl_add_u64 v[132:133], v[132:133], 0, v[128:129]
	v_lshl_add_u64 v[172:173], v[160:161], 0, v[2:3]
	global_load_dwordx4 v[100:103], v[102:103], off
	s_nop 0
	global_load_dwordx4 v[104:107], v[104:105], off
	s_nop 0
	global_load_dwordx4 v[108:111], v[110:111], off
	s_nop 0
	global_load_dwordx4 v[112:115], v[112:113], off
	s_nop 0
	global_load_dwordx4 v[116:119], v[118:119], off
	s_nop 0
	global_load_dwordx4 v[124:127], v[124:125], off
	s_nop 0
	global_load_dwordx4 v[128:131], v[130:131], off
	s_nop 0
	global_load_dwordx4 v[132:135], v[132:133], off
	s_nop 0
	global_load_dwordx4 v[160:163], v[172:173], off
	global_load_dwordx4 v[164:167], v[172:173], off offset:64
	global_load_dwordx4 v[168:171], v[172:173], off offset:128
	s_nop 0
	global_load_dwordx4 v[172:175], v[172:173], off offset:192
	s_mov_b64 s[6:7], 0

; #define GAS __attribute__((address_space(1)))
; #define LAS __attribute__((address_space(3)))
; __device__ __forceinline__ unsigned pk2(float lo, float hi) { return pg8::cvt_pk_bf16(lo, hi); }
; __device__ __forceinline__ float bf_lo(unsigned w) { return __uint_as_float(w << 16); }
; __device__ __forceinline__ float bf_hi(unsigned w) { return __uint_as_float(w & 0xffff0000u); }
; #define MFMA16(a, b, c) __builtin_amdgcn_mfma_f32_16x16x32_bf16((a), (b), (c), 0, 0, 0)
; template <int DIR, bool INTRA, bool FINAL> __device__ __forceinline__ void retention_pass(LAS unsigned char* lds, const bf16* ZH, bf16* YF, bf16* MIX, const float* ld, const float* gn, int seq, int h, int n0, int ncnt, ...
;     ...
;             for (int e = 0; e < 8; ++e) {
; #pragma unroll
;                 for (int ks = 0; ks < 4; ++ks) { const bf16x8 sf = *(const LAS bf16x8*)(lds + R_ST + (16 * e + lr) * RS + (8 * lg + 32 * ks) * 2); y[e] = MFMA16(sf, qx[ks], y[e]); }
;                 __builtin_amdgcn_sched_barrier(0); }
;             const int row = r0 + 16 * w + lr;
;             bf16* yp = YF + (size_t)row * 2048 + h * HD + 4 * lg;
;             if constexpr (!FINAL) {
; #pragma unroll
;                 for (int e = 0; e < 8; ++e) { v2u o; o.x = pk2(y[e][0], y[e][1]); o.y = pk2(y[e][2], y[e][3]); *(GAS v2u*)(yp + 16 * e) = o; }
;             } else {
;                 float sum = 0.f;
; #pragma unroll
;                 for (int e = 0; e < 8; ++e) { const v2u yw = ywv[e]; y[e][0] += bf_lo(yw.x); y[e][1] += bf_hi(yw.x); y[e][2] += bf_lo(yw.y); y[e][3] += bf_hi(yw.y); sum += (y[e][0] + y[e][1]) + (y[e][2] + y[e][3]); }
.LBB0_1259:
	s_waitcnt lgkmcnt(0)
	v_lshlrev_b32_e32 v117, 4, v142
	v_add3_u32 v2, s95, v117, v143
	ds_read_b128 v[180:183], v2
	ds_read_b128 v[184:187], v2 offset:64
	ds_read_b128 v[204:207], v2 offset:128
	ds_read_b128 v[208:211], v2 offset:192
	ds_read_b128 v[212:215], v2 offset:4352
	ds_read_b128 v[216:219], v2 offset:4416
	ds_read_b128 v[220:223], v2 offset:4480
	ds_read_b128 v[224:227], v2 offset:4544
	s_waitcnt lgkmcnt(7)
	v_mfma_f32_16x16x32_bf16 v[142:145], v[180:183], v[84:87], 0
	ds_read_b128 v[180:183], v2 offset:8704
	s_waitcnt lgkmcnt(7)
	v_mfma_f32_16x16x32_bf16 v[142:145], v[184:187], v[88:91], v[142:145]
	ds_read_b128 v[184:187], v2 offset:8768
	s_waitcnt lgkmcnt(7)
	v_mfma_f32_16x16x32_bf16 v[142:145], v[204:207], v[92:95], v[142:145]
	ds_read_b128 v[204:207], v2 offset:8832
	s_waitcnt lgkmcnt(7)
	v_mfma_f32_16x16x32_bf16 v[142:145], v[208:211], v[96:99], v[142:145]
	ds_read_b128 v[208:211], v2 offset:8896
	s_waitcnt lgkmcnt(7)
	v_mfma_f32_16x16x32_bf16 v[152:155], v[212:215], v[84:87], 0
	ds_read_b128 v[212:215], v2 offset:13056
	s_waitcnt lgkmcnt(7)
	v_mfma_f32_16x16x32_bf16 v[152:155], v[216:219], v[88:91], v[152:155]
	ds_read_b128 v[216:219], v2 offset:13120
	s_waitcnt lgkmcnt(7)
	v_mfma_f32_16x16x32_bf16 v[152:155], v[220:223], v[92:95], v[152:155]
	ds_read_b128 v[220:223], v2 offset:13184
	s_waitcnt lgkmcnt(7)
	v_mfma_f32_16x16x32_bf16 v[152:155], v[224:227], v[96:99], v[152:155]
	ds_read_b128 v[224:227], v2 offset:13248
	s_waitcnt lgkmcnt(7)
	v_mfma_f32_16x16x32_bf16 v[156:159], v[180:183], v[84:87], 0
	ds_read_b128 v[180:183], v2 offset:17408
	s_waitcnt lgkmcnt(7)
	v_mfma_f32_16x16x32_bf16 v[156:159], v[184:187], v[88:91], v[156:159]
	ds_read_b128 v[184:187], v2 offset:17472
	s_waitcnt lgkmcnt(7)
	v_mfma_f32_16x16x32_bf16 v[156:159], v[204:207], v[92:95], v[156:159]
	ds_read_b128 v[204:207], v2 offset:17536
	s_waitcnt lgkmcnt(7)
	v_mfma_f32_16x16x32_bf16 v[156:159], v[208:211], v[96:99], v[156:159]
	ds_read_b128 v[208:211], v2 offset:17600
	s_waitcnt lgkmcnt(7)
	v_mfma_f32_16x16x32_bf16 v[160:163], v[212:215], v[84:87], 0
	ds_read_b128 v[212:215], v2 offset:21760
	s_waitcnt lgkmcnt(7)
	v_mfma_f32_16x16x32_bf16 v[160:163], v[216:219], v[88:91], v[160:163]
	ds_read_b128 v[216:219], v2 offset:21824
	s_waitcnt lgkmcnt(7)
	v_mfma_f32_16x16x32_bf16 v[160:163], v[220:223], v[92:95], v[160:163]
	ds_read_b128 v[220:223], v2 offset:21888
	s_waitcnt lgkmcnt(7)
	v_mfma_f32_16x16x32_bf16 v[160:163], v[224:227], v[96:99], v[160:163]
	ds_read_b128 v[224:227], v2 offset:21952
	s_waitcnt lgkmcnt(7)
	v_mfma_f32_16x16x32_bf16 v[164:167], v[180:183], v[84:87], 0
	ds_read_b128 v[180:183], v2 offset:26112
	s_waitcnt lgkmcnt(7)
	v_mfma_f32_16x16x32_bf16 v[164:167], v[184:187], v[88:91], v[164:167]
	ds_read_b128 v[184:187], v2 offset:26176
	s_waitcnt lgkmcnt(7)
	v_mfma_f32_16x16x32_bf16 v[164:167], v[204:207], v[92:95], v[164:167]
	ds_read_b128 v[204:207], v2 offset:26240
	s_waitcnt lgkmcnt(7)
	v_mfma_f32_16x16x32_bf16 v[164:167], v[208:211], v[96:99], v[164:167]
	ds_read_b128 v[208:211], v2 offset:26304
	s_waitcnt lgkmcnt(7)
	v_mfma_f32_16x16x32_bf16 v[168:171], v[212:215], v[84:87], 0
	ds_read_b128 v[212:215], v2 offset:30464
	s_waitcnt lgkmcnt(7)
	v_mfma_f32_16x16x32_bf16 v[168:171], v[216:219], v[88:91], v[168:171]
	ds_read_b128 v[216:219], v2 offset:30528
	s_waitcnt lgkmcnt(7)
	v_mfma_f32_16x16x32_bf16 v[168:171], v[220:223], v[92:95], v[168:171]
	ds_read_b128 v[220:223], v2 offset:30592
	s_waitcnt lgkmcnt(7)
	v_mfma_f32_16x16x32_bf16 v[168:171], v[224:227], v[96:99], v[168:171]
	ds_read_b128 v[224:227], v2 offset:30656
	s_waitcnt lgkmcnt(7)
	v_mfma_f32_16x16x32_bf16 v[172:175], v[180:183], v[84:87], 0
	s_waitcnt lgkmcnt(6)
	v_mfma_f32_16x16x32_bf16 v[172:175], v[184:187], v[88:91], v[172:175]
	s_waitcnt lgkmcnt(5)
	v_mfma_f32_16x16x32_bf16 v[172:175], v[204:207], v[92:95], v[172:175]
	s_waitcnt lgkmcnt(4)
	v_mfma_f32_16x16x32_bf16 v[172:175], v[208:211], v[96:99], v[172:175]
	s_waitcnt lgkmcnt(3)
	v_mfma_f32_16x16x32_bf16 v[84:87], v[212:215], v[84:87], 0
	s_waitcnt lgkmcnt(2)
	v_mfma_f32_16x16x32_bf16 v[84:87], v[216:219], v[88:91], v[84:87]
	s_waitcnt lgkmcnt(1)
	v_mfma_f32_16x16x32_bf16 v[84:87], v[220:223], v[92:95], v[84:87]
	s_waitcnt lgkmcnt(0)
	v_mfma_f32_16x16x32_bf16 v[176:179], v[224:227], v[96:99], v[84:87]
	s_waitcnt vmcnt(15)
	s_nop 3
	v_lshlrev_b32_e32 v84, 16, v134
	v_and_b32_e32 v85, 0xffff0000, v134
	v_pk_add_f32 v[146:147], v[142:143], v[84:85]
	v_lshlrev_b32_e32 v84, 16, v135
	v_and_b32_e32 v85, 0xffff0000, v135
	v_pk_add_f32 v[144:145], v[144:145], v[84:85]
	s_waitcnt vmcnt(14)
	v_lshlrev_b32_e32 v84, 16, v130
	v_and_b32_e32 v85, 0xffff0000, v130
	v_pk_add_f32 v[142:143], v[152:153], v[84:85]
	v_lshlrev_b32_e32 v84, 16, v131
	v_and_b32_e32 v85, 0xffff0000, v131
	v_pk_add_f32 v[138:139], v[154:155], v[84:85]
	v_mov_b32_e32 v84, v146
	v_mov_b32_e32 v85, v142
	v_mov_b32_e32 v86, v147
	v_mov_b32_e32 v87, v143
	v_pk_add_f32 v[84:85], v[84:85], v[86:87]
	v_mov_b32_e32 v86, v144
	v_mov_b32_e32 v87, v138
	v_mov_b32_e32 v88, v145
	v_mov_b32_e32 v89, v139
	v_pk_add_f32 v[86:87], v[86:87], v[88:89]
	s_waitcnt vmcnt(7)
; __device__ __forceinline__ float bf_lo(unsigned w) { return __uint_as_float(w << 16); }
; __device__ __forceinline__ float bf_hi(unsigned w) { return __uint_as_float(w & 0xffff0000u); }
; __device__ __forceinline__ float fast_rsqrt(float x) { return __builtin_amdgcn_rsqf(x); }
; template <int DIR, bool INTRA, bool FINAL> __device__ __forceinline__ void retention_pass(LAS unsigned char* lds, const bf16* ZH, bf16* YF, bf16* MIX, const float* ld, const float* gn, int seq, int h, int n0, int ncnt, ...
;     ...
;                 float sum = 0.f;
; #pragma unroll
;                 for (int e = 0; e < 8; ++e) { const v2u yw = ywv[e]; y[e][0] += bf_lo(yw.x); y[e][1] += bf_hi(yw.x); y[e][2] += bf_lo(yw.y); y[e][3] += bf_hi(yw.y); sum += (y[e][0] + y[e][1]) + (y[e][2] + y[e][3]); }
;                 sum += __shfl_xor(sum, 16); sum += __shfl_xor(sum, 32);
;                 const float mu = sum * (1.f / 128.f); float q = 0.f;
; #pragma unroll
;                 for (int e = 0; e < 8; ++e) { y[e] = y[e] - mu; q += (y[e][0] * y[e][0] + y[e][1] * y[e][1]) + (y[e][2] * y[e][2] + y[e][3] * y[e][3]); }
;                 q += __shfl_xor(q, 16); q += __shfl_xor(q, 32);
;                 const float rstd = fast_rsqrt(q * (1.f / 128.f) + GN_EPS);
	v_lshlrev_b32_e32 v92, 16, v140
	v_pk_add_f32 v[84:85], v[84:85], v[86:87]
	v_lshlrev_b32_e32 v86, 16, v126
	v_and_b32_e32 v87, 0xffff0000, v126
	v_pk_add_f32 v[134:135], v[156:157], v[86:87]
	v_lshlrev_b32_e32 v86, 16, v127
	v_and_b32_e32 v87, 0xffff0000, v127
	v_pk_add_f32 v[130:131], v[158:159], v[86:87]
	v_mov_b32_e32 v86, v134
	v_mov_b32_e32 v87, v130
	v_mov_b32_e32 v88, v135
	v_mov_b32_e32 v89, v131
	v_pk_add_f32 v[86:87], v[86:87], v[88:89]
	v_lshlrev_b32_e32 v88, 16, v124
	v_and_b32_e32 v89, 0xffff0000, v124
	v_pk_add_f32 v[126:127], v[160:161], v[88:89]
	v_lshlrev_b32_e32 v88, 16, v125
	v_and_b32_e32 v89, 0xffff0000, v125
	v_and_b32_e32 v93, 0xffff0000, v140
	v_pk_add_f32 v[124:125], v[162:163], v[88:89]
	v_pk_add_f32 v[120:121], v[164:165], v[92:93]
	v_lshlrev_b32_e32 v92, 16, v141
	v_and_b32_e32 v93, 0xffff0000, v141
	v_add_f32_e32 v2, 0, v84
	v_pk_add_f32 v[86:87], v[86:87], v[86:87] op_sel:[0,1] op_sel_hi:[1,0]
	v_pk_add_f32 v[88:89], v[126:127], v[126:127] op_sel:[0,1] op_sel_hi:[1,0]
	v_pk_add_f32 v[90:91], v[124:125], v[124:125] op_sel:[0,1] op_sel_hi:[1,0]
	v_pk_add_f32 v[96:97], v[166:167], v[92:93]
	v_add_f32_e32 v84, v2, v85
	v_mov_b32_e32 v85, v120
	v_mov_b32_e32 v87, v121
	v_mov_b32_e32 v89, v96
	v_mov_b32_e32 v91, v97
	v_pk_add_f32 v[84:85], v[84:85], v[86:87]
	v_pk_add_f32 v[86:87], v[88:89], v[90:91]
	s_addk_i32 s16, 0xff80
	v_pk_add_f32 v[84:85], v[84:85], v[86:87]
	s_cmpk_lg_i32 s16, 0xff00
	v_pk_add_f32 v[98:99], v[84:85], v[84:85] op_sel:[0,1] op_sel_hi:[1,0]
	s_waitcnt vmcnt(6)
	v_lshlrev_b32_e32 v84, 16, v136
	v_and_b32_e32 v85, 0xffff0000, v136
	v_pk_add_f32 v[94:95], v[168:169], v[84:85]
	v_lshlrev_b32_e32 v84, 16, v137
	v_and_b32_e32 v85, 0xffff0000, v137
	v_pk_add_f32 v[92:93], v[170:171], v[84:85]
	v_mov_b32_e32 v84, v94
	v_mov_b32_e32 v85, v92
	v_mov_b32_e32 v86, v95
	v_mov_b32_e32 v87, v93
	v_pk_add_f32 v[84:85], v[84:85], v[86:87]
	s_nop 0
	v_pk_add_f32 v[136:137], v[84:85], v[84:85] op_sel:[0,1] op_sel_hi:[1,0]
	s_waitcnt vmcnt(5)
	v_lshlrev_b32_e32 v84, 16, v132
	v_and_b32_e32 v85, 0xffff0000, v132
	v_pk_add_f32 v[90:91], v[172:173], v[84:85]
	v_lshlrev_b32_e32 v84, 16, v133
	v_and_b32_e32 v85, 0xffff0000, v133
	v_pk_add_f32 v[88:89], v[174:175], v[84:85]
	s_waitcnt vmcnt(4)
	v_lshlrev_b32_e32 v84, 16, v128
	v_and_b32_e32 v85, 0xffff0000, v128
	v_pk_add_f32 v[86:87], v[176:177], v[84:85]
	v_lshlrev_b32_e32 v84, 16, v129
	v_and_b32_e32 v85, 0xffff0000, v129
	v_pk_add_f32 v[132:133], v[90:91], v[90:91] op_sel:[0,1] op_sel_hi:[1,0]
	v_pk_add_f32 v[140:141], v[88:89], v[88:89] op_sel:[0,1] op_sel_hi:[1,0]
	v_pk_add_f32 v[84:85], v[178:179], v[84:85]
	v_mov_b32_e32 v99, v86
	v_mov_b32_e32 v137, v87
	v_mov_b32_e32 v133, v84
	v_mov_b32_e32 v141, v85
	v_pk_add_f32 v[98:99], v[98:99], v[136:137]
	v_pk_add_f32 v[128:129], v[132:133], v[140:141]
	s_nop 0
	v_pk_add_f32 v[98:99], v[98:99], v[128:129]
	s_nop 0
	v_add_f32_e32 v2, v98, v99
	v_and_b32_e32 v99, 64, v235
	v_xor_b32_e32 v98, 16, v235
	v_add_u32_e32 v99, 64, v99
	v_cmp_lt_i32_e32 vcc, v98, v99
	s_nop 1
	v_cndmask_b32_e32 v98, v235, v98, vcc
	v_lshlrev_b32_e32 v151, 2, v98
	ds_bpermute_b32 v98, v151, v2
	s_waitcnt lgkmcnt(0)
	v_add_f32_e32 v2, v2, v98
	v_xor_b32_e32 v98, 32, v235
	v_cmp_lt_i32_e32 vcc, v98, v99
	s_nop 1
	v_cndmask_b32_e32 v98, v235, v98, vcc
	v_lshlrev_b32_e32 v154, 2, v98
	ds_bpermute_b32 v98, v154, v2
	s_waitcnt lgkmcnt(0)
	v_add_f32_e32 v155, v2, v98
	v_fmamk_f32 v128, v155, 0xbc000000, v145
	v_fmamk_f32 v132, v155, 0xbc000000, v147
	v_fmamk_f32 v129, v155, 0xbc000000, v139
	v_fmac_f32_e32 v138, 0xbc000000, v155
	v_fmamk_f32 v133, v155, 0xbc000000, v143
	v_fmac_f32_e32 v142, 0xbc000000, v155
	v_fmac_f32_e32 v144, 0xbc000000, v155
	v_fmac_f32_e32 v146, 0xbc000000, v155
	v_mov_b32_e32 v147, v142
	v_pk_mul_f32 v[98:99], v[132:133], v[132:133]
	v_mov_b32_e32 v145, v138
	v_pk_mul_f32 v[136:137], v[128:129], v[128:129]
	v_pk_fma_f32 v[98:99], v[146:147], v[146:147], v[98:99]
	v_pk_fma_f32 v[136:137], v[144:145], v[144:145], v[136:137]
	v_fmamk_f32 v135, v155, 0xbc000000, v135
	v_fmac_f32_e32 v134, 0xbc000000, v155
	v_fmamk_f32 v131, v155, 0xbc000000, v131
	v_fmac_f32_e32 v130, 0xbc000000, v155
	v_pk_add_f32 v[98:99], v[98:99], v[136:137]
	v_pk_mul_f32 v[136:137], v[130:131], v[130:131]
	v_pk_mul_f32 v[140:141], v[134:135], v[134:135]
	v_fmac_f32_e32 v126, 0xbc000000, v155
	v_pk_mov_b32 v[152:153], v[140:141], v[136:137] op_sel:[1,0]
	v_mov_b32_e32 v141, v137
	v_fmamk_f32 v127, v155, 0xbc000000, v127
	v_fmac_f32_e32 v124, 0xbc000000, v155
	v_mul_f32_e32 v2, v126, v126
	v_pk_add_f32 v[136:137], v[152:153], v[140:141]
	v_fmamk_f32 v125, v155, 0xbc000000, v125
	v_pk_fma_f32 v[140:141], v[126:127], v[126:127], v[2:3] op_sel_hi:[1,1,0]
	v_mul_f32_e32 v2, v124, v124
	v_pk_add_f32 v[98:99], v[98:99], v[98:99] op_sel_hi:[0,1]
	v_pk_add_f32 v[136:137], v[136:137], v[136:137] op_sel_hi:[0,1]
	v_pk_fma_f32 v[152:153], v[124:125], v[124:125], v[2:3] op_sel_hi:[1,1,0]
	v_fmamk_f32 v139, v155, 0xbc000000, v97
	v_fmac_f32_e32 v96, 0xbc000000, v155
	v_fmamk_f32 v121, v155, 0xbc000000, v121
	v_fmac_f32_e32 v120, 0xbc000000, v155
	v_mul_f32_e32 v140, v120, v120
	v_mul_f32_e32 v152, v121, v121
	v_mul_f32_e32 v136, v96, v96
	v_mul_f32_e32 v98, v139, v139
	v_pk_add_f32 v[140:141], v[140:141], v[152:153]
	v_pk_add_f32 v[98:99], v[136:137], v[98:99]
	v_fmamk_f32 v95, v155, 0xbc000000, v95
	v_fmac_f32_e32 v94, 0xbc000000, v155
	v_fmamk_f32 v93, v155, 0xbc000000, v93
	v_fmac_f32_e32 v92, 0xbc000000, v155
	v_pk_add_f32 v[98:99], v[140:141], v[98:99]
	v_pk_mul_f32 v[136:137], v[92:93], v[92:93]
	v_pk_mul_f32 v[140:141], v[94:95], v[94:95]
	v_fmac_f32_e32 v90, 0xbc000000, v155
	v_pk_mov_b32 v[152:153], v[140:141], v[136:137] op_sel:[1,0]
	v_mov_b32_e32 v141, v137
	v_fmamk_f32 v91, v155, 0xbc000000, v91
	v_fmac_f32_e32 v88, 0xbc000000, v155
	v_mul_f32_e32 v2, v90, v90
	v_pk_add_f32 v[136:137], v[152:153], v[140:141]
	v_fmamk_f32 v89, v155, 0xbc000000, v89
	v_pk_fma_f32 v[140:141], v[90:91], v[90:91], v[2:3] op_sel_hi:[1,1,0]
	v_mul_f32_e32 v2, v88, v88
	v_pk_add_f32 v[98:99], v[98:99], v[98:99] op_sel_hi:[0,1]
	v_pk_add_f32 v[136:137], v[136:137], v[136:137] op_sel_hi:[0,1]
	v_pk_fma_f32 v[152:153], v[88:89], v[88:89], v[2:3] op_sel_hi:[1,1,0]
	v_fmamk_f32 v85, v155, 0xbc000000, v85
	v_fmac_f32_e32 v84, 0xbc000000, v155
	v_fmamk_f32 v97, v155, 0xbc000000, v87
	v_fmac_f32_e32 v86, 0xbc000000, v155
	v_mul_f32_e32 v140, v86, v86
	v_mul_f32_e32 v152, v97, v97
	v_mul_f32_e32 v136, v84, v84
	v_mul_f32_e32 v98, v85, v85
	v_pk_add_f32 v[140:141], v[140:141], v[152:153]
	v_pk_add_f32 v[98:99], v[136:137], v[98:99]
	v_lshlrev_b32_e32 v136, 16, v123
	v_pk_add_f32 v[98:99], v[140:141], v[98:99]
	v_and_b32_e32 v140, 0xffff0000, v123
	v_add_f32_e32 v2, v98, v99
	ds_bpermute_b32 v87, v151, v2
	v_lshlrev_b64 v[98:99], 13, v[114:115]
	v_lshlrev_b32_e32 v114, 16, v122
	v_mul_f32_e32 v115, 0xbfb8aa3b, v114
	v_lshl_add_u64 v[98:99], s[8:9], 0, v[98:99]
	s_waitcnt lgkmcnt(0)
; __device__ __forceinline__ float fast_sigmoid(float x) { return __builtin_amdgcn_rcpf(1.0f + __expf(-x)); }
; #define GAS __attribute__((address_space(1)))
; #define LAS __attribute__((address_space(3)))
; __device__ __forceinline__ unsigned pk2(float lo, float hi) { return pg8::cvt_pk_bf16(lo, hi); }
; __device__ __forceinline__ float bf_lo(unsigned w) { return __uint_as_float(w << 16); }
; __device__ __forceinline__ float bf_hi(unsigned w) { return __uint_as_float(w & 0xffff0000u); }
; template <int DIR, bool INTRA, bool FINAL> __device__ __forceinline__ void retention_pass(LAS unsigned char* lds, const bf16* ZH, bf16* YF, bf16* MIX, const float* ld, const float* gn, int seq, int h, int n0, int ncnt, ...
;     ...
;                 bf16* mp = MIX + (size_t)row * D + h * HD + 4 * lg;
; #pragma unroll
;                 for (int e = 0; e < 8; ++e) { const v2u gw2 = gwv[e]; const f32x4 gg = *(const LAS f32x4*)(lds + R_GN + (16 * e + 4 * lg) * 4);
;                     const float g0 = bf_lo(gw2.x), g1 = bf_hi(gw2.x), g2 = bf_lo(gw2.y), g3 = bf_hi(gw2.y);
;                     v2u o; o.x = pk2(g0 * pg8::fast_sigmoid(g0) * (y[e][0] * rstd * gg.x), g1 * pg8::fast_sigmoid(g1) * (y[e][1] * rstd * gg.y));
;                     o.y = pk2(g2 * pg8::fast_sigmoid(g2) * (y[e][2] * rstd * gg.z), g3 * pg8::fast_sigmoid(g3) * (y[e][3] * rstd * gg.w));
;                     *(GAS v2u*)(mp + 16 * e) = o; }
	v_add_f32_e32 v2, v2, v87
	ds_bpermute_b32 v87, v154, v2
	v_exp_f32_e32 v115, v115
	v_and_b32_e32 v122, 0xffff0000, v122
	s_waitcnt lgkmcnt(0)
	v_add_f32_e32 v2, v2, v87
	v_fmamk_f32 v2, v2, 0x3c000000, v234
	v_rsq_f32_e32 v87, v2
	v_lshlrev_b32_e32 v2, 1, v150
	v_lshl_add_u64 v[98:99], v[98:99], 0, v[2:3]
	v_add_u32_e32 v2, 0, v117
	v_add_u32_e32 v2, 0x23000, v2
	ds_read_b128 v[150:153], v2
	v_add_f32_e32 v115, 1.0, v115
	v_rcp_f32_e32 v154, v115
	v_mul_f32_e32 v117, 0xbfb8aa3b, v122
	v_exp_f32_e32 v117, v117
	v_mul_f32_e32 v115, v146, v87
	s_waitcnt lgkmcnt(0)
	v_mov_b32_e32 v155, v150
	v_pk_mul_f32 v[114:115], v[154:155], v[114:115]
	v_mul_f32_e32 v123, v132, v87
	v_mul_f32_e32 v137, v114, v115
	v_add_f32_e32 v114, 1.0, v117
	v_rcp_f32_e32 v150, v114
	v_mul_f32_e32 v114, 0xbfb8aa3b, v136
	v_exp_f32_e32 v117, v114
	v_mul_f32_e32 v141, v128, v87
	v_pk_mul_f32 v[114:115], v[150:151], v[122:123]
	v_mov_b32_e32 v123, v152
	v_mul_f32_e32 v114, v114, v115
	v_add_f32_e32 v115, 1.0, v117
	v_mul_f32_e32 v117, 0xbfb8aa3b, v140
	v_exp_f32_e32 v117, v117
	v_rcp_f32_e32 v122, v115
	v_cvt_pk_bf16_f32 v114, v137, v114
	v_mul_f32_e32 v137, v144, v87
	v_add_f32_e32 v115, 1.0, v117
	v_rcp_f32_e32 v152, v115
	v_pk_mul_f32 v[122:123], v[122:123], v[136:137]
	v_and_b32_e32 v128, 0xffff0000, v113
	v_mul_f32_e32 v115, v122, v123
	v_pk_mul_f32 v[122:123], v[152:153], v[140:141]
	v_mul_f32_e32 v129, v129, v87
	v_mul_f32_e32 v117, v122, v123
	v_cvt_pk_bf16_f32 v115, v115, v117
	global_store_dwordx2 v[98:99], v[114:115], off
	v_lshlrev_b32_e32 v114, 16, v112
	v_mul_f32_e32 v115, 0xbfb8aa3b, v114
	v_exp_f32_e32 v115, v115
	v_and_b32_e32 v112, 0xffff0000, v112
	v_lshlrev_b32_e32 v122, 16, v113
	ds_read_b128 v[144:147], v2 offset:64
	v_add_f32_e32 v113, 1.0, v115
	v_rcp_f32_e32 v136, v113
	v_mul_f32_e32 v113, 0xbfb8aa3b, v112
	v_exp_f32_e32 v113, v113
	v_mul_f32_e32 v115, v142, v87
	s_waitcnt lgkmcnt(0)
	v_mov_b32_e32 v137, v144
	v_pk_mul_f32 v[114:115], v[136:137], v[114:115]
	v_add_f32_e32 v113, 1.0, v113
	v_rcp_f32_e32 v144, v113
	v_mul_f32_e32 v114, v114, v115
	v_mul_f32_e32 v115, 0xbfb8aa3b, v122
	v_exp_f32_e32 v115, v115
	v_mul_f32_e32 v113, v133, v87
	v_pk_mul_f32 v[112:113], v[144:145], v[112:113]
	v_mul_f32_e32 v123, v138, v87
	v_mul_f32_e32 v112, v112, v113
	v_cvt_pk_bf16_f32 v112, v114, v112
	v_add_f32_e32 v113, 1.0, v115
	v_mul_f32_e32 v114, 0xbfb8aa3b, v128
	v_exp_f32_e32 v117, v114
	v_rcp_f32_e32 v114, v113
	v_mov_b32_e32 v115, v146
	v_and_b32_e32 v132, 0xffff0000, v111
	v_add_f32_e32 v113, 1.0, v117
	v_pk_mul_f32 v[114:115], v[114:115], v[122:123]
	v_lshlrev_b32_e32 v122, 16, v110
	v_mul_f32_e32 v117, 0xbfb8aa3b, v122
	v_rcp_f32_e32 v146, v113
	v_exp_f32_e32 v117, v117
	v_mul_f32_e32 v113, v114, v115
	v_and_b32_e32 v110, 0xffff0000, v110
	v_pk_mul_f32 v[114:115], v[146:147], v[128:129]
	v_lshlrev_b32_e32 v128, 16, v111
	v_add_f32_e32 v111, 1.0, v117
	v_mul_f32_e32 v114, v114, v115
	v_cvt_pk_bf16_f32 v113, v113, v114
	v_rcp_f32_e32 v136, v111
	v_mul_f32_e32 v111, 0xbfb8aa3b, v110
	global_store_dwordx2 v[98:99], v[112:113], off offset:32
	ds_read_b128 v[112:115], v2 offset:128
	v_exp_f32_e32 v111, v111
	v_mul_f32_e32 v123, v134, v87
	v_mul_f32_e32 v129, v130, v87
	v_mul_f32_e32 v133, v131, v87
	v_add_f32_e32 v111, 1.0, v111
	s_waitcnt lgkmcnt(0)
	v_mov_b32_e32 v137, v112
	v_rcp_f32_e32 v112, v111
	v_pk_mul_f32 v[122:123], v[136:137], v[122:123]
	v_mul_f32_e32 v111, v135, v87
	v_mul_f32_e32 v117, v122, v123
	v_mul_f32_e32 v122, 0xbfb8aa3b, v128
	v_pk_mul_f32 v[110:111], v[112:113], v[110:111]
	v_exp_f32_e32 v122, v122
	v_mul_f32_e32 v110, v110, v111
	v_mul_f32_e32 v112, 0xbfb8aa3b, v132
	v_cvt_pk_bf16_f32 v110, v117, v110
	v_exp_f32_e32 v117, v112
	v_add_f32_e32 v111, 1.0, v122
	v_rcp_f32_e32 v112, v111
	v_mov_b32_e32 v113, v114
	v_add_f32_e32 v111, 1.0, v117
	v_rcp_f32_e32 v114, v111
	v_pk_mul_f32 v[112:113], v[112:113], v[128:129]
	v_lshlrev_b32_e32 v122, 16, v109
	v_mul_f32_e32 v111, v112, v113
	v_pk_mul_f32 v[112:113], v[114:115], v[132:133]
	v_lshlrev_b32_e32 v114, 16, v108
	v_mul_f32_e32 v115, 0xbfb8aa3b, v114
	v_exp_f32_e32 v115, v115
	v_and_b32_e32 v108, 0xffff0000, v108
	v_and_b32_e32 v128, 0xffff0000, v109
	v_mul_f32_e32 v112, v112, v113
	v_add_f32_e32 v109, 1.0, v115
	v_cvt_pk_bf16_f32 v111, v111, v112
	v_rcp_f32_e32 v130, v109
	v_mul_f32_e32 v109, 0xbfb8aa3b, v108
	global_store_dwordx2 v[98:99], v[110:111], off offset:64
	ds_read_b128 v[110:113], v2 offset:192
	v_exp_f32_e32 v109, v109
	v_mul_f32_e32 v115, v126, v87
	v_mul_f32_e32 v123, v124, v87
	v_mul_f32_e32 v129, v125, v87
	v_add_f32_e32 v109, 1.0, v109
	s_waitcnt lgkmcnt(0)
	v_mov_b32_e32 v131, v110
	v_rcp_f32_e32 v110, v109
	v_pk_mul_f32 v[114:115], v[130:131], v[114:115]
	v_mul_f32_e32 v109, v127, v87
	v_mul_f32_e32 v114, v114, v115
	v_mul_f32_e32 v115, 0xbfb8aa3b, v122
	v_pk_mul_f32 v[108:109], v[110:111], v[108:109]
	v_exp_f32_e32 v115, v115
	v_mul_f32_e32 v108, v108, v109
	v_mul_f32_e32 v110, 0xbfb8aa3b, v128
	v_cvt_pk_bf16_f32 v108, v114, v108
	v_exp_f32_e32 v114, v110
	v_add_f32_e32 v109, 1.0, v115
	v_rcp_f32_e32 v110, v109
	v_mov_b32_e32 v111, v112
	v_add_f32_e32 v109, 1.0, v114
	v_rcp_f32_e32 v112, v109
	v_pk_mul_f32 v[110:111], v[110:111], v[122:123]
	s_waitcnt vmcnt(6)
	v_lshlrev_b32_e32 v114, 16, v107
	v_mul_f32_e32 v109, v110, v111
	v_pk_mul_f32 v[110:111], v[112:113], v[128:129]
	v_lshlrev_b32_e32 v112, 16, v106
	v_mul_f32_e32 v113, 0xbfb8aa3b, v112
	v_exp_f32_e32 v113, v113
	v_and_b32_e32 v106, 0xffff0000, v106
	v_and_b32_e32 v122, 0xffff0000, v107
	v_mul_f32_e32 v110, v110, v111
	v_add_f32_e32 v107, 1.0, v113
	v_cvt_pk_bf16_f32 v109, v109, v110
	v_rcp_f32_e32 v124, v107
	v_mul_f32_e32 v107, 0xbfb8aa3b, v106
	global_store_dwordx2 v[98:99], v[108:109], off offset:96
	ds_read_b128 v[108:111], v2 offset:256
	v_exp_f32_e32 v107, v107
	v_mul_f32_e32 v113, v120, v87
	v_mul_f32_e32 v115, v96, v87
	v_mul_f32_e32 v123, v139, v87
	v_add_f32_e32 v107, 1.0, v107
	s_waitcnt lgkmcnt(0)
; __device__ __forceinline__ float fast_sigmoid(float x) { return __builtin_amdgcn_rcpf(1.0f + __expf(-x)); }
; #define GAS __attribute__((address_space(1)))
; #define LAS __attribute__((address_space(3)))
; __device__ __forceinline__ unsigned pk2(float lo, float hi) { return pg8::cvt_pk_bf16(lo, hi); }
; __device__ __forceinline__ float bf_lo(unsigned w) { return __uint_as_float(w << 16); }
; __device__ __forceinline__ float bf_hi(unsigned w) { return __uint_as_float(w & 0xffff0000u); }
; template <int DIR, bool INTRA, bool FINAL> __device__ __forceinline__ void retention_pass(LAS unsigned char* lds, const bf16* ZH, bf16* YF, bf16* MIX, const float* ld, const float* gn, int seq, int h, int n0, int ncnt, ...
;     ...
;                 for (int e = 0; e < 8; ++e) { const v2u gw2 = gwv[e]; const f32x4 gg = *(const LAS f32x4*)(lds + R_GN + (16 * e + 4 * lg) * 4);
;                     const float g0 = bf_lo(gw2.x), g1 = bf_hi(gw2.x), g2 = bf_lo(gw2.y), g3 = bf_hi(gw2.y);
;                     v2u o; o.x = pk2(g0 * pg8::fast_sigmoid(g0) * (y[e][0] * rstd * gg.x), g1 * pg8::fast_sigmoid(g1) * (y[e][1] * rstd * gg.y));
;                     o.y = pk2(g2 * pg8::fast_sigmoid(g2) * (y[e][2] * rstd * gg.z), g3 * pg8::fast_sigmoid(g3) * (y[e][3] * rstd * gg.w));
;                     *(GAS v2u*)(mp + 16 * e) = o; }
	v_mov_b32_e32 v125, v108
	v_rcp_f32_e32 v108, v107
	v_pk_mul_f32 v[112:113], v[124:125], v[112:113]
	v_mul_f32_e32 v107, v121, v87
	v_mul_f32_e32 v112, v112, v113
	v_mul_f32_e32 v113, 0xbfb8aa3b, v114
	v_pk_mul_f32 v[106:107], v[108:109], v[106:107]
	v_exp_f32_e32 v113, v113
	v_mul_f32_e32 v106, v106, v107
	v_mul_f32_e32 v108, 0xbfb8aa3b, v122
	v_cvt_pk_bf16_f32 v106, v112, v106
	v_exp_f32_e32 v112, v108
	v_add_f32_e32 v107, 1.0, v113
	v_rcp_f32_e32 v108, v107
	v_mov_b32_e32 v109, v110
	v_add_f32_e32 v96, 1.0, v112
	v_rcp_f32_e32 v110, v96
	v_pk_mul_f32 v[108:109], v[108:109], v[114:115]
	v_mul_f32_e32 v121, v94, v87
	v_mul_f32_e32 v96, v108, v109
	v_pk_mul_f32 v[108:109], v[110:111], v[122:123]
	s_waitcnt vmcnt(6)
	v_lshlrev_b32_e32 v110, 16, v104
	v_mul_f32_e32 v107, v108, v109
	v_and_b32_e32 v104, 0xffff0000, v104
	v_cvt_pk_bf16_f32 v107, v96, v107
	v_mul_f32_e32 v94, 0xbfb8aa3b, v104
	global_store_dwordx2 v[98:99], v[106:107], off offset:128
	ds_read_b128 v[106:109], v2 offset:320
	v_exp_f32_e32 v94, v94
	v_lshlrev_b32_e32 v112, 16, v105
	v_and_b32_e32 v114, 0xffff0000, v105
	v_mul_f32_e32 v95, v95, v87
	v_add_f32_e32 v94, 1.0, v94
	s_waitcnt lgkmcnt(0)
	v_mov_b32_e32 v111, v106
	v_rcp_f32_e32 v94, v94
	v_mul_f32_e32 v106, 0xbfb8aa3b, v112
	v_exp_f32_e32 v106, v106
	v_mov_b32_e32 v105, v107
	v_pk_mul_f32 v[94:95], v[94:95], v[104:105]
	v_mul_f32_e32 v96, 0xbfb8aa3b, v110
	v_mul_f32_e32 v94, v94, v95
	v_add_f32_e32 v95, 1.0, v106
	v_exp_f32_e32 v96, v96
	v_rcp_f32_e32 v104, v95
	v_mul_f32_e32 v95, 0xbfb8aa3b, v114
	v_exp_f32_e32 v95, v95
	v_add_f32_e32 v96, 1.0, v96
	v_rcp_f32_e32 v120, v96
	v_mul_f32_e32 v105, v92, v87
	v_add_f32_e32 v92, 1.0, v95
	v_rcp_f32_e32 v92, v92
	v_mov_b32_e32 v113, v108
	v_pk_mul_f32 v[110:111], v[120:121], v[110:111]
	v_pk_mul_f32 v[104:105], v[104:105], v[112:113]
	v_mul_f32_e32 v93, v93, v87
	v_mov_b32_e32 v115, v109
	v_mul_f32_e32 v96, v110, v111
	v_mul_f32_e32 v95, v104, v105
	v_pk_mul_f32 v[92:93], v[92:93], v[114:115]
	s_waitcnt vmcnt(6)
	v_lshlrev_b32_e32 v104, 16, v102
	v_and_b32_e32 v102, 0xffff0000, v102
	v_cvt_pk_bf16_f32 v94, v96, v94
	v_mul_f32_e32 v92, v92, v93
	v_cvt_pk_bf16_f32 v95, v95, v92
	v_mul_f32_e32 v96, 0xbfb8aa3b, v104
	v_mul_f32_e32 v111, v90, v87
	v_mul_f32_e32 v90, 0xbfb8aa3b, v102
	global_store_dwordx2 v[98:99], v[94:95], off offset:160
	ds_read_b128 v[92:95], v2 offset:384
	v_exp_f32_e32 v96, v96
	v_exp_f32_e32 v90, v90
	v_lshlrev_b32_e32 v106, 16, v103
	v_and_b32_e32 v108, 0xffff0000, v103
	v_add_f32_e32 v96, 1.0, v96
	v_add_f32_e32 v90, 1.0, v90
	v_rcp_f32_e32 v110, v96
	v_rcp_f32_e32 v90, v90
	s_waitcnt lgkmcnt(0)
	v_mov_b32_e32 v103, v93
	v_mul_f32_e32 v93, 0xbfb8aa3b, v106
	v_exp_f32_e32 v93, v93
	v_mov_b32_e32 v105, v92
	v_mul_f32_e32 v91, v91, v87
	v_pk_mul_f32 v[104:105], v[110:111], v[104:105]
	v_pk_mul_f32 v[90:91], v[90:91], v[102:103]
	v_mul_f32_e32 v92, v104, v105
	v_mul_f32_e32 v90, v90, v91
	v_add_f32_e32 v91, 1.0, v93
	v_cvt_pk_bf16_f32 v90, v92, v90
	v_rcp_f32_e32 v92, v91
	v_mul_f32_e32 v91, 0xbfb8aa3b, v108
	v_exp_f32_e32 v91, v91
	v_mul_f32_e32 v93, v88, v87
	v_mov_b32_e32 v107, v94
	v_pk_mul_f32 v[92:93], v[92:93], v[106:107]
	v_add_f32_e32 v88, 1.0, v91
	v_rcp_f32_e32 v88, v88
	v_mul_f32_e32 v89, v89, v87
	v_mov_b32_e32 v109, v95
	v_mul_f32_e32 v91, v92, v93
	v_pk_mul_f32 v[88:89], v[88:89], v[108:109]
	s_waitcnt vmcnt(6)
	v_lshlrev_b32_e32 v92, 16, v100
	v_mul_f32_e32 v88, v88, v89
	v_cvt_pk_bf16_f32 v91, v91, v88
	global_store_dwordx2 v[98:99], v[90:91], off offset:192
	ds_read_b128 v[88:91], v2 offset:448
	v_mul_f32_e32 v2, 0xbfb8aa3b, v92
	v_exp_f32_e32 v2, v2
	v_and_b32_e32 v94, 0xffff0000, v100
	v_mul_f32_e32 v103, v86, v87
	s_waitcnt lgkmcnt(0)
	v_mov_b32_e32 v93, v88
	v_add_f32_e32 v2, 1.0, v2
	v_rcp_f32_e32 v102, v2
	v_mul_f32_e32 v2, 0xbfb8aa3b, v94
	v_exp_f32_e32 v2, v2
	v_lshlrev_b32_e32 v96, 16, v101
	v_pk_mul_f32 v[92:93], v[102:103], v[92:93]
	v_mov_b32_e32 v95, v89
	v_add_f32_e32 v2, 1.0, v2
	v_mul_f32_e32 v86, v92, v93
	v_rcp_f32_e32 v92, v2
	v_mul_f32_e32 v2, 0xbfb8aa3b, v96
	v_exp_f32_e32 v2, v2
	v_mul_f32_e32 v93, v97, v87
	v_pk_mul_f32 v[88:89], v[92:93], v[94:95]
	v_and_b32_e32 v100, 0xffff0000, v101
	v_mul_f32_e32 v88, v88, v89
	v_add_f32_e32 v2, 1.0, v2
	v_cvt_pk_bf16_f32 v86, v86, v88
	v_rcp_f32_e32 v88, v2
	v_mul_f32_e32 v2, 0xbfb8aa3b, v100
	v_exp_f32_e32 v2, v2
	v_mul_f32_e32 v89, v84, v87
	v_mov_b32_e32 v97, v90
	v_mul_f32_e32 v85, v85, v87
	v_add_f32_e32 v2, 1.0, v2
	v_rcp_f32_e32 v84, v2
	v_mov_b32_e32 v101, v91
	v_pk_mul_f32 v[88:89], v[88:89], v[96:97]
	v_pk_mul_f32 v[84:85], v[84:85], v[100:101]
	v_mul_f32_e32 v2, v88, v89
	v_mul_f32_e32 v84, v84, v85
	v_cvt_pk_bf16_f32 v87, v2, v84
	global_store_dwordx2 v[98:99], v[86:87], off offset:224
	s_cbranch_scc0 .LBB0_329
; #define LAS __attribute__((address_space(3)))
; #define WG_BARRIER() do { asm volatile("s_waitcnt lgkmcnt(0)" ::: "memory"); __builtin_amdgcn_s_barrier(); asm volatile("" ::: "memory"); } while (0)
; __device__ __forceinline__ unsigned pk2(float lo, float hi) { return pg8::cvt_pk_bf16(lo, hi); }
; __device__ __forceinline__ v4u scale8(v4u x, float sc) { v4u o; o.x = pk2(bf_lo(x.x) * sc, bf_hi(x.x) * sc); o.y = pk2(bf_lo(x.y) * sc, bf_hi(x.y) * sc); o.z = pk2(bf_lo(x.z) * sc, bf_hi(x.z) * sc); o.w = pk2(bf_lo(x.w) * sc, bf_hi(x.w) * sc); return o; }
; template <int DIR, bool INTRA, bool FINAL> __device__ __forceinline__ void retention_pass(LAS unsigned char* lds, const bf16* ZH, bf16* YF, bf16* MIX, const float* ld, const float* gn, int seq, int h, int n0, int ncnt, ...
;     ...
;             const int w = tid >> 6, l = tid & 63, lr = l & 15, lg = l >> 4, srow = tid >> 4, sch = tid & 15;
;             LAS unsigned char* trp = lds + (4 * lg + ((l & 15) >> 2)) * RSB + (l & 3) * 8;
;             WG_BARRIER();
; #pragma unroll
;             for (int cc = 0; cc < 4; ++cc) { const int row = srow + 32 * cc;
;                 if constexpr (INTRA) *(LAS v4u*)(lds + R_K + row * RS + 16 * sch) = kreg[cc];
;                 const float wj = DIR == 0 ? __expf(lf * (float)(127 - row)) : __expf(lb * (float)row);
;                 *(LAS v4u*)(lds + R_KW + row * RSB + 16 * sch) = scale8(kreg[cc], wj);
;                 *(LAS v4u*)(lds + R_V + row * RSB + 16 * sch) = vreg[cc]; }
; #pragma unroll
;             for (int e = 0; e < 8; ++e) { v2u o; o.x = pk2(st[e][0], st[e][1]); o.y = pk2(st[e][2], st[e][3]); *(LAS v2u*)(lds + R_ST + (16 * e + lr) * RS + (16 * w + 4 * lg) * 2) = o; }
;             WG_BARRIER();
.LBB0_1260:
	v_mov_b32_e32 v2, v190
	v_mov_b32_e32 v88, v149
	v_mov_b32_e32 v84, v148
	s_waitcnt vmcnt(27)
	v_and_b32_e32 v85, 0xffff0000, v4
	v_bfe_u32 v142, v2, 4, 2
	v_lshlrev_b32_e32 v150, 2, v142
	v_bfe_u32 v84, v2, 2, 2
	v_or_b32_e32 v84, v150, v84
	v_ashrrev_i32_e32 v121, 4, v2
	v_mul_u32_u24_e32 v100, 0x120, v84
	v_lshlrev_b32_e32 v84, 3, v2
	v_and_b32_e32 v101, 24, v84
	v_cvt_f32_i32_e32 v84, v121
	s_waitcnt lgkmcnt(0)
	s_barrier
	v_mul_f32_e32 v84, v88, v84
	v_mul_f32_e32 v84, 0x3fb8aa3b, v84
	v_exp_f32_e32 v87, v84
	v_lshlrev_b32_e32 v84, 16, v4
	v_and_b32_e32 v86, 0xffff0000, v5
	v_and_b32_e32 v92, 0xffff0000, v6
	v_mul_f32_e32 v84, v87, v84
	v_mul_f32_e32 v85, v87, v85
	v_cvt_pk_bf16_f32 v84, v84, v85
	v_lshlrev_b32_e32 v85, 16, v5
	v_mul_f32_e32 v85, v87, v85
	v_mul_f32_e32 v86, v87, v86
	v_cvt_pk_bf16_f32 v85, v85, v86
	v_lshlrev_b32_e32 v86, 16, v6
	v_mul_f32_e32 v86, v87, v86
	v_mul_f32_e32 v92, v87, v92
	v_and_b32_e32 v89, 15, v2
	v_cvt_pk_bf16_f32 v86, v86, v92
	v_lshlrev_b32_e32 v92, 16, v7
	v_and_b32_e32 v93, 0xffff0000, v7
	v_lshlrev_b32_e32 v120, 4, v89
	v_mul_f32_e32 v92, v87, v92
	v_mul_f32_e32 v87, v87, v93
	v_add_u32_e32 v90, 0, v120
	v_cvt_pk_bf16_f32 v87, v92, v87
	v_mul_lo_u32 v92, v121, s74
	v_add_u32_e32 v91, s93, v120
	v_add_u32_e32 v93, v90, v92
	ds_write_b128 v93, v[84:87] offset:34816
	v_add_u32_e32 v84, v91, v92
	s_waitcnt vmcnt(26)
	ds_write_b128 v84, v[8:11]
	v_add_u32_e32 v84, 32, v121
	v_cvt_f32_i32_e32 v84, v84
	s_waitcnt vmcnt(25)
	v_and_b32_e32 v85, 0xffff0000, v12
	v_and_b32_e32 v86, 0xffff0000, v13
	v_and_b32_e32 v93, 0xffff0000, v14
	v_mul_f32_e32 v84, v88, v84
	v_mul_f32_e32 v84, 0x3fb8aa3b, v84
	v_exp_f32_e32 v87, v84
	v_lshlrev_b32_e32 v84, 16, v12
	v_and_b32_e32 v94, 0xffff0000, v15
	v_mul_u32_u24_e32 v143, 0x110, v89
	v_mul_f32_e32 v84, v87, v84
	v_mul_f32_e32 v85, v87, v85
	v_cvt_pk_bf16_f32 v84, v84, v85
	v_lshlrev_b32_e32 v85, 16, v13
	v_mul_f32_e32 v85, v87, v85
	v_mul_f32_e32 v86, v87, v86
	v_cvt_pk_bf16_f32 v85, v85, v86
	v_lshlrev_b32_e32 v86, 16, v14
	v_mul_f32_e32 v86, v87, v86
	v_mul_f32_e32 v93, v87, v93
	v_cvt_pk_bf16_f32 v86, v86, v93
	v_lshlrev_b32_e32 v93, 16, v15
	v_mul_f32_e32 v93, v87, v93
	v_mul_f32_e32 v87, v87, v94
	v_cvt_pk_bf16_f32 v87, v93, v87
	v_add_u32_e32 v93, 0x2400, v92
	v_add_u32_e32 v94, v90, v93
	ds_write_b128 v94, v[84:87] offset:34816
	v_add_u32_e32 v84, v91, v93
	s_waitcnt vmcnt(24)
	ds_write_b128 v84, v[16:19]
	v_add_u32_e32 v84, 64, v121
	v_cvt_f32_i32_e32 v84, v84
	s_waitcnt vmcnt(23)
	v_and_b32_e32 v85, 0xffff0000, v20
	v_and_b32_e32 v86, 0xffff0000, v21
	v_and_b32_e32 v93, 0xffff0000, v22
	v_mul_f32_e32 v84, v88, v84
	v_mul_f32_e32 v84, 0x3fb8aa3b, v84
	v_exp_f32_e32 v87, v84
	v_lshlrev_b32_e32 v84, 16, v20
	v_and_b32_e32 v94, 0xffff0000, v23
	s_waitcnt vmcnt(17)
	v_and_b32_e32 v95, 0xffff0000, v46
	v_mul_f32_e32 v84, v87, v84
	v_mul_f32_e32 v85, v87, v85
	v_cvt_pk_bf16_f32 v84, v84, v85
	v_lshlrev_b32_e32 v85, 16, v21
	v_mul_f32_e32 v85, v87, v85
	v_mul_f32_e32 v86, v87, v86
	v_cvt_pk_bf16_f32 v85, v85, v86
	v_lshlrev_b32_e32 v86, 16, v22
	v_mul_f32_e32 v86, v87, v86
	v_mul_f32_e32 v93, v87, v93
	v_cvt_pk_bf16_f32 v86, v86, v93
	v_lshlrev_b32_e32 v93, 16, v23
	v_mul_f32_e32 v93, v87, v93
	v_mul_f32_e32 v87, v87, v94
	v_cvt_pk_bf16_f32 v87, v93, v87
	v_add_u32_e32 v93, 0x4800, v92
	v_add_u32_e32 v94, v90, v93
	ds_write_b128 v94, v[84:87] offset:34816
	v_add_u32_e32 v84, v91, v93
	ds_write_b128 v84, v[24:27]
	v_add_u32_e32 v84, 0x60, v121
	v_cvt_f32_i32_e32 v84, v84
	v_and_b32_e32 v85, 0xffff0000, v28
	v_and_b32_e32 v86, 0xffff0000, v29
	v_and_b32_e32 v93, 0xffff0000, v30
	v_mul_f32_e32 v84, v88, v84
	v_mul_f32_e32 v84, 0x3fb8aa3b, v84
	v_exp_f32_e32 v87, v84
	v_lshlrev_b32_e32 v84, 16, v28
	v_and_b32_e32 v94, 0xffff0000, v31
	v_add_u32_e32 v92, 0x6c00, v92
	v_mul_f32_e32 v84, v87, v84
	v_mul_f32_e32 v85, v87, v85
	v_cvt_pk_bf16_f32 v84, v84, v85
	v_lshlrev_b32_e32 v85, 16, v29
	v_mul_f32_e32 v85, v87, v85
	v_mul_f32_e32 v86, v87, v86
	v_cvt_pk_bf16_f32 v85, v85, v86
	v_lshlrev_b32_e32 v86, 16, v30
	v_mul_f32_e32 v86, v87, v86
	v_mul_f32_e32 v93, v87, v93
	v_cvt_pk_bf16_f32 v86, v86, v93
	v_lshlrev_b32_e32 v93, 16, v31
	v_mul_f32_e32 v93, v87, v93
	v_mul_f32_e32 v87, v87, v94
	v_add_u32_e32 v90, v90, v92
	v_cvt_pk_bf16_f32 v87, v93, v87
	ds_write_b128 v90, v[84:87] offset:34816
	v_ashrrev_i32_e32 v86, 6, v2
	v_lshlrev_b32_e32 v102, 5, v86
	v_add_u32_e32 v84, v91, v92
	v_lshlrev_b32_e32 v2, 3, v142
	v_add_u32_e32 v87, s95, v102
	ds_write_b128 v84, v[32:35]
	s_waitcnt vmcnt(15)
	v_cvt_pk_bf16_f32 v84, v76, v77
	v_add3_u32 v87, v87, v2, v143
	s_waitcnt vmcnt(14)
	v_cvt_pk_bf16_f32 v85, v78, v79
	ds_write_b64 v87, v[84:85]
	s_waitcnt vmcnt(13)
	v_cvt_pk_bf16_f32 v84, v52, v53
	s_waitcnt vmcnt(12)
	v_cvt_pk_bf16_f32 v85, v54, v55
	ds_write_b64 v87, v[84:85] offset:4352
	s_waitcnt vmcnt(11)
	v_cvt_pk_bf16_f32 v84, v56, v57
	s_waitcnt vmcnt(10)
	v_cvt_pk_bf16_f32 v85, v58, v59
	ds_write_b64 v87, v[84:85] offset:8704
	s_waitcnt vmcnt(9)
	v_cvt_pk_bf16_f32 v84, v60, v61
	s_waitcnt vmcnt(8)
	v_cvt_pk_bf16_f32 v85, v62, v63
	ds_write_b64 v87, v[84:85] offset:13056
	s_waitcnt vmcnt(7)
	v_cvt_pk_bf16_f32 v84, v64, v65
	s_waitcnt vmcnt(6)
	v_cvt_pk_bf16_f32 v85, v66, v67
	ds_write_b64 v87, v[84:85] offset:17408
	s_waitcnt vmcnt(5)
	v_cvt_pk_bf16_f32 v84, v68, v69
	s_waitcnt vmcnt(4)
	v_cvt_pk_bf16_f32 v85, v70, v71
	ds_write_b64 v87, v[84:85] offset:21760
	s_waitcnt vmcnt(3)
	v_cvt_pk_bf16_f32 v84, v72, v73
	s_waitcnt vmcnt(2)
	v_cvt_pk_bf16_f32 v85, v74, v75
	ds_write_b64 v87, v[84:85] offset:26112
	s_waitcnt vmcnt(1)
	v_cvt_pk_bf16_f32 v84, v80, v81
	v_lshl_or_b32 v122, v86, 4, v89
	s_waitcnt vmcnt(0)
	v_cvt_pk_bf16_f32 v85, v82, v83
	ds_write_b64 v87, v[84:85] offset:30464
	v_sub_u32_e32 v84, 0x80, v122
	v_cvt_f32_i32_e32 v84, v84
	v_and_b32_e32 v85, 0xffff0000, v36
	s_waitcnt lgkmcnt(0)
	s_barrier
; #define LAS __attribute__((address_space(3)))
; template <int DIR, bool INTRA, bool FINAL> __device__ __forceinline__ void retention_pass(LAS unsigned char* lds, const bf16* ZH, bf16* YF, bf16* MIX, const float* ld, const float* gn, int seq, int h, int n0, int ncnt, ...
;     ...
;             { const float xi = DIR == 0 ? __expf(lf * (float)(16 * w + lr + 1)) : __expf(lb * (float)(128 - 16 * w - lr));
; #pragma unroll
;               for (int ks = 0; ks < 4; ++ks) qx[ks] = __builtin_bit_cast(bf16x8, scale8(__builtin_bit_cast(v4u, qf[ks]), xi)); }
;             bf16x8 pt[4];
;             if constexpr (INTRA) {
;                 f32x4 s[8];
; #pragma unroll
;                 for (int jt = 0; jt < 8; ++jt) { s[jt] = (f32x4){0.f, 0.f, 0.f, 0.f};
; #pragma unroll
;                     for (int ks = 0; ks < 4; ++ks) { const bf16x8 a = *(const LAS bf16x8*)(lds + R_K + (16 * jt + lr) * RS + (8 * lg + 32 * ks) * 2); s[jt] = MFMA16(a, qf[ks], s[jt]); }
;                     __builtin_amdgcn_sched_barrier(0); }
;                 float Fr[4], Br[4];
; #pragma unroll
;                 for (int r = 0; r < 4; ++r) { const float br = (float)(lr - 4 * lg - r); Fr[r] = __expf(lf * br); Br[r] = __expf(-lb * br); }
; #pragma unroll
;                 for (int jt = 0; jt < 8; ++jt) { const int dt = w - jt; const float cf = __expf(lf * 16.f * (float)dt), cb = __expf(-lb * 16.f * (float)dt);
; #pragma unroll
;                     for (int r = 0; r < 4; ++r) { const float dec = dt > 0 ? Fr[r] * cf : (dt < 0 ? Br[r] * cb : ((lr - 4 * lg - r) >= 0 ? Fr[r] : Br[r])); s[jt][r] *= dec; } }
; #pragma unroll
;                 for (int ks = 0; ks < 4; ++ks) { v4u o; o.x = pk2(s[2 * ks][0], s[2 * ks][1]); o.y = pk2(s[2 * ks][2], s[2 * ks][3]); o.z = pk2(s[2 * ks + 1][0], s[2 * ks + 1][1]); o.w = pk2(s[2 * ks + 1][2], s[2 * ks + 1][3]); pt[ks] = __builtin_bit_cast(bf16x8, o); }
;             }
;             f32x4 y[8];
; #pragma unroll
;             for (int e = 0; e < 8; ++e) y[e] = (f32x4){0.f, 0.f, 0.f, 0.f};
;             { bf16x8 kwf[4];
; #pragma unroll
;               for (int ks = 0; ks < 4; ++ks) kwf[ks] = ds_tr2(trp + R_KW + (32 * ks) * RSB + (16 * w) * 2, RSB);
; #pragma unroll
;               for (int e = 0; e < 8; ++e) { st[e] = st[e] * gC;
; #pragma unroll
;                 for (int ks = 0; ks < 4; ++ks) { const bf16x8 vf = ds_tr2(trp + R_V + (32 * ks) * RSB + (16 * e) * 2, RSB);
	s_waitcnt lgkmcnt(0)
	v_mul_f32_e32 v84, v88, v84
	v_mul_f32_e32 v84, 0x3fb8aa3b, v84
	v_exp_f32_e32 v99, v84
	v_lshlrev_b32_e32 v84, 16, v36
	v_and_b32_e32 v86, 0xffff0000, v37
	v_mul_f32_e32 v84, v99, v84
	v_mul_f32_e32 v85, v99, v85
	v_cvt_pk_bf16_f32 v84, v84, v85
	v_lshlrev_b32_e32 v85, 16, v37
	v_mul_f32_e32 v85, v99, v85
	v_mul_f32_e32 v86, v99, v86
	v_cvt_pk_bf16_f32 v85, v85, v86
	v_lshlrev_b32_e32 v86, 16, v38
	v_and_b32_e32 v87, 0xffff0000, v38
	v_mul_f32_e32 v86, v99, v86
	v_mul_f32_e32 v87, v99, v87
	v_cvt_pk_bf16_f32 v86, v86, v87
	v_lshlrev_b32_e32 v87, 16, v39
	v_and_b32_e32 v88, 0xffff0000, v39
	v_mul_f32_e32 v87, v99, v87
	v_mul_f32_e32 v88, v99, v88
	v_cvt_pk_bf16_f32 v87, v87, v88
	v_lshlrev_b32_e32 v88, 16, v40
	v_and_b32_e32 v89, 0xffff0000, v40
	v_mul_f32_e32 v88, v99, v88
	v_mul_f32_e32 v89, v99, v89
	v_cvt_pk_bf16_f32 v88, v88, v89
	v_lshlrev_b32_e32 v89, 16, v41
	v_and_b32_e32 v90, 0xffff0000, v41
	v_mul_f32_e32 v89, v99, v89
	v_mul_f32_e32 v90, v99, v90
	v_cvt_pk_bf16_f32 v89, v89, v90
	v_lshlrev_b32_e32 v90, 16, v42
	v_and_b32_e32 v91, 0xffff0000, v42
	v_mul_f32_e32 v90, v99, v90
	v_mul_f32_e32 v91, v99, v91
	v_cvt_pk_bf16_f32 v90, v90, v91
	v_lshlrev_b32_e32 v91, 16, v43
	v_and_b32_e32 v92, 0xffff0000, v43
	v_mul_f32_e32 v91, v99, v91
	v_mul_f32_e32 v92, v99, v92
	v_cvt_pk_bf16_f32 v91, v91, v92
	v_lshlrev_b32_e32 v92, 16, v44
	v_and_b32_e32 v93, 0xffff0000, v44
	v_mul_f32_e32 v92, v99, v92
	v_mul_f32_e32 v93, v99, v93
	v_cvt_pk_bf16_f32 v92, v92, v93
	v_lshlrev_b32_e32 v93, 16, v45
	v_and_b32_e32 v94, 0xffff0000, v45
	v_mul_f32_e32 v93, v99, v93
	v_mul_f32_e32 v94, v99, v94
	v_cvt_pk_bf16_f32 v93, v93, v94
	v_lshlrev_b32_e32 v94, 16, v46
	v_mul_f32_e32 v94, v99, v94
	v_mul_f32_e32 v95, v99, v95
	v_cvt_pk_bf16_f32 v94, v94, v95
	v_lshlrev_b32_e32 v95, 16, v47
	v_and_b32_e32 v96, 0xffff0000, v47
	v_mul_f32_e32 v95, v99, v95
	v_mul_f32_e32 v96, v99, v96
	v_cvt_pk_bf16_f32 v95, v95, v96
	v_lshlrev_b32_e32 v96, 16, v48
	v_and_b32_e32 v97, 0xffff0000, v48
	v_mul_f32_e32 v96, v99, v96
	v_mul_f32_e32 v97, v99, v97
	v_cvt_pk_bf16_f32 v96, v96, v97
	v_lshlrev_b32_e32 v97, 16, v49
	v_and_b32_e32 v98, 0xffff0000, v49
	v_mul_f32_e32 v97, v99, v97
	v_mul_f32_e32 v98, v99, v98
	v_cvt_pk_bf16_f32 v97, v97, v98
	v_lshlrev_b32_e32 v98, 16, v50
	v_and_b32_e32 v103, 0xffff0000, v50
	v_mul_f32_e32 v98, v99, v98
	v_mul_f32_e32 v103, v99, v103
	v_add3_u32 v123, 0, v100, v101
	v_cvt_pk_bf16_f32 v98, v98, v103
	v_lshlrev_b32_e32 v103, 16, v51
	v_and_b32_e32 v104, 0xffff0000, v51
	v_add_u32_e32 v100, v123, v102
	ds_read_b64_tr_b16 v[152:153], v100 offset:34816
	ds_read_b64_tr_b16 v[154:155], v100 offset:39424
	ds_read_b64_tr_b16 v[156:157], v100 offset:44032
	ds_read_b64_tr_b16 v[158:159], v100 offset:48640
	ds_read_b64_tr_b16 v[160:161], v100 offset:53248
	ds_read_b64_tr_b16 v[162:163], v100 offset:57856
	ds_read_b64_tr_b16 v[164:165], v100 offset:62464
	v_mul_f32_e32 v103, v99, v103
	v_mul_f32_e32 v99, v99, v104
	v_add_u32_e32 v102, 0x8800, v100
	ds_read_b64_tr_b16 v[166:167], v102 offset:32256
	v_add_u32_e32 v124, 0x11800, v123
	ds_read_b64_tr_b16 v[168:169], v124
	v_add_u32_e32 v126, 0x12a00, v123
	ds_read_b64_tr_b16 v[170:171], v126
	v_cvt_pk_bf16_f32 v99, v103, v99
	v_mov_b32_e32 v117, v116
	v_pk_mul_f32 v[78:79], v[116:117], v[78:79]
	v_pk_mul_f32 v[76:77], v[118:119], v[76:77]
	s_nop 0
	s_waitcnt lgkmcnt(0)
	v_mfma_f32_16x16x32_bf16 v[76:79], v[152:155], v[168:171], v[76:79]
	v_add_u32_e32 v124, 0x13c00, v123
	ds_read_b64_tr_b16 v[172:173], v124
	v_add_u32_e32 v126, 0x14e00, v123
	ds_read_b64_tr_b16 v[174:175], v126
	s_waitcnt lgkmcnt(0)
	v_mfma_f32_16x16x32_bf16 v[76:79], v[156:159], v[172:175], v[76:79]
	v_add_u32_e32 v124, 0x16000, v123
	ds_read_b64_tr_b16 v[176:177], v124
	v_add_u32_e32 v126, 0x17200, v123
	ds_read_b64_tr_b16 v[178:179], v126
	s_waitcnt lgkmcnt(0)
	v_mfma_f32_16x16x32_bf16 v[76:79], v[160:163], v[176:179], v[76:79]
	v_add_u32_e32 v124, 0x18400, v123
	ds_read_b64_tr_b16 v[180:181], v124
	v_add_u32_e32 v126, 0x19600, v123
	ds_read_b64_tr_b16 v[182:183], v126
	s_waitcnt lgkmcnt(0)
	v_mfma_f32_16x16x32_bf16 v[76:79], v[164:167], v[180:183], v[76:79]
	v_add_u32_e32 v124, 0x11820, v123
	ds_read_b64_tr_b16 v[168:169], v124
	v_add_u32_e32 v126, 0x12a20, v123
	ds_read_b64_tr_b16 v[170:171], v126
	v_pk_mul_f32 v[54:55], v[116:117], v[54:55]
	v_pk_mul_f32 v[52:53], v[118:119], v[52:53]
	s_nop 0
	s_waitcnt lgkmcnt(0)
	v_mfma_f32_16x16x32_bf16 v[52:55], v[152:155], v[168:171], v[52:55]
	v_add_u32_e32 v124, 0x13c20, v123
	ds_read_b64_tr_b16 v[172:173], v124
	v_add_u32_e32 v126, 0x14e20, v123
	ds_read_b64_tr_b16 v[174:175], v126
	s_waitcnt lgkmcnt(0)
	v_mfma_f32_16x16x32_bf16 v[52:55], v[156:159], v[172:175], v[52:55]
	v_add_u32_e32 v124, 0x16020, v123
	ds_read_b64_tr_b16 v[176:177], v124
	v_add_u32_e32 v126, 0x17220, v123
	ds_read_b64_tr_b16 v[178:179], v126
	s_waitcnt lgkmcnt(0)
	v_mfma_f32_16x16x32_bf16 v[52:55], v[160:163], v[176:179], v[52:55]
	v_add_u32_e32 v124, 0x18420, v123
	ds_read_b64_tr_b16 v[180:181], v124
	v_add_u32_e32 v126, 0x19620, v123
	ds_read_b64_tr_b16 v[182:183], v126
	s_waitcnt lgkmcnt(0)
	v_mfma_f32_16x16x32_bf16 v[52:55], v[164:167], v[180:183], v[52:55]
	v_add_u32_e32 v124, 0x11840, v123
	ds_read_b64_tr_b16 v[168:169], v124
	v_add_u32_e32 v126, 0x12a40, v123
	ds_read_b64_tr_b16 v[170:171], v126
	v_pk_mul_f32 v[58:59], v[116:117], v[58:59]
	v_pk_mul_f32 v[56:57], v[118:119], v[56:57]
	s_nop 0
	s_waitcnt lgkmcnt(0)
	v_mfma_f32_16x16x32_bf16 v[56:59], v[152:155], v[168:171], v[56:59]
	v_add_u32_e32 v124, 0x13c40, v123
	ds_read_b64_tr_b16 v[172:173], v124
	v_add_u32_e32 v126, 0x14e40, v123
	ds_read_b64_tr_b16 v[174:175], v126
	s_waitcnt lgkmcnt(0)
; #define MFMA16(a, b, c) __builtin_amdgcn_mfma_f32_16x16x32_bf16((a), (b), (c), 0, 0, 0)
; __device__ __forceinline__ bf16x8 ds_tr2(LAS unsigned char* p, int rstride) { const s16x4 a = ds_tr(p), b = ds_tr(p + 16 * rstride); bf16x8 r; r[0] = a[0]; r[1] = a[1]; r[2] = a[2]; r[3] = a[3]; r[4] = b[0]; r[5] = b[1]; r[6] = b[2]; r[7] = b[3]; return r; }
; template <int DIR, bool INTRA, bool FINAL> __device__ __forceinline__ void retention_pass(LAS unsigned char* lds, const bf16* ZH, bf16* YF, bf16* MIX, const float* ld, const float* gn, int seq, int h, int n0, int ncnt, ...
;     ...
;               for (int e = 0; e < 8; ++e) { st[e] = st[e] * gC;
; #pragma unroll
;                 for (int ks = 0; ks < 4; ++ks) { const bf16x8 vf = ds_tr2(trp + R_V + (32 * ks) * RSB + (16 * e) * 2, RSB);
;                     if constexpr (INTRA) y[e] = MFMA16(vf, pt[ks], y[e]);
;                     st[e] = MFMA16(kwf[ks], vf, st[e]); }
;                 __builtin_amdgcn_sched_barrier(0); } }
	v_mfma_f32_16x16x32_bf16 v[56:59], v[156:159], v[172:175], v[56:59]
	v_add_u32_e32 v124, 0x16040, v123
	ds_read_b64_tr_b16 v[176:177], v124
	v_add_u32_e32 v126, 0x17240, v123
	ds_read_b64_tr_b16 v[178:179], v126
	s_waitcnt lgkmcnt(0)
	v_mfma_f32_16x16x32_bf16 v[56:59], v[160:163], v[176:179], v[56:59]
	v_add_u32_e32 v124, 0x18440, v123
	ds_read_b64_tr_b16 v[180:181], v124
	v_add_u32_e32 v126, 0x19640, v123
	ds_read_b64_tr_b16 v[182:183], v126
	s_waitcnt lgkmcnt(0)
	v_mfma_f32_16x16x32_bf16 v[56:59], v[164:167], v[180:183], v[56:59]
	v_add_u32_e32 v124, 0x11860, v123
	ds_read_b64_tr_b16 v[168:169], v124
	v_add_u32_e32 v126, 0x12a60, v123
	ds_read_b64_tr_b16 v[170:171], v126
	v_pk_mul_f32 v[62:63], v[116:117], v[62:63]
	v_pk_mul_f32 v[60:61], v[118:119], v[60:61]
	s_nop 0
	s_waitcnt lgkmcnt(0)
	v_mfma_f32_16x16x32_bf16 v[60:63], v[152:155], v[168:171], v[60:63]
	v_add_u32_e32 v124, 0x13c60, v123
	ds_read_b64_tr_b16 v[172:173], v124
	v_add_u32_e32 v126, 0x14e60, v123
	ds_read_b64_tr_b16 v[174:175], v126
	s_waitcnt lgkmcnt(0)
	v_mfma_f32_16x16x32_bf16 v[60:63], v[156:159], v[172:175], v[60:63]
	v_add_u32_e32 v124, 0x16060, v123
	ds_read_b64_tr_b16 v[176:177], v124
	v_add_u32_e32 v126, 0x17260, v123
	ds_read_b64_tr_b16 v[178:179], v126
	s_waitcnt lgkmcnt(0)
	v_mfma_f32_16x16x32_bf16 v[60:63], v[160:163], v[176:179], v[60:63]
	v_add_u32_e32 v124, 0x18460, v123
	ds_read_b64_tr_b16 v[180:181], v124
	v_add_u32_e32 v126, 0x19660, v123
	ds_read_b64_tr_b16 v[182:183], v126
	s_waitcnt lgkmcnt(0)
	v_mfma_f32_16x16x32_bf16 v[60:63], v[164:167], v[180:183], v[60:63]
	v_add_u32_e32 v124, 0x11880, v123
	ds_read_b64_tr_b16 v[168:169], v124
	v_add_u32_e32 v126, 0x12a80, v123
	ds_read_b64_tr_b16 v[170:171], v126
	v_pk_mul_f32 v[66:67], v[116:117], v[66:67]
	v_pk_mul_f32 v[64:65], v[118:119], v[64:65]
	s_nop 0
	s_waitcnt lgkmcnt(0)
	v_mfma_f32_16x16x32_bf16 v[64:67], v[152:155], v[168:171], v[64:67]
	v_add_u32_e32 v124, 0x13c80, v123
	ds_read_b64_tr_b16 v[172:173], v124
	v_add_u32_e32 v126, 0x14e80, v123
	ds_read_b64_tr_b16 v[174:175], v126
	s_waitcnt lgkmcnt(0)
	v_mfma_f32_16x16x32_bf16 v[64:67], v[156:159], v[172:175], v[64:67]
	v_add_u32_e32 v124, 0x16080, v123
	ds_read_b64_tr_b16 v[176:177], v124
	v_add_u32_e32 v126, 0x17280, v123
	ds_read_b64_tr_b16 v[178:179], v126
	s_waitcnt lgkmcnt(0)
	v_mfma_f32_16x16x32_bf16 v[64:67], v[160:163], v[176:179], v[64:67]
	v_add_u32_e32 v124, 0x18480, v123
	ds_read_b64_tr_b16 v[180:181], v124
	v_add_u32_e32 v126, 0x19680, v123
	ds_read_b64_tr_b16 v[182:183], v126
	s_waitcnt lgkmcnt(0)
	v_mfma_f32_16x16x32_bf16 v[64:67], v[164:167], v[180:183], v[64:67]
	v_add_u32_e32 v124, 0x118a0, v123
	ds_read_b64_tr_b16 v[168:169], v124
	v_add_u32_e32 v126, 0x12aa0, v123
	ds_read_b64_tr_b16 v[170:171], v126
	v_pk_mul_f32 v[70:71], v[116:117], v[70:71]
	v_pk_mul_f32 v[68:69], v[118:119], v[68:69]
	s_nop 0
	s_waitcnt lgkmcnt(0)
	v_mfma_f32_16x16x32_bf16 v[68:71], v[152:155], v[168:171], v[68:71]
	v_add_u32_e32 v124, 0x13ca0, v123
	ds_read_b64_tr_b16 v[172:173], v124
	v_add_u32_e32 v126, 0x14ea0, v123
	ds_read_b64_tr_b16 v[174:175], v126
	s_waitcnt lgkmcnt(0)
	v_mfma_f32_16x16x32_bf16 v[68:71], v[156:159], v[172:175], v[68:71]
	v_add_u32_e32 v124, 0x160a0, v123
	ds_read_b64_tr_b16 v[176:177], v124
	v_add_u32_e32 v126, 0x172a0, v123
	ds_read_b64_tr_b16 v[178:179], v126
	s_waitcnt lgkmcnt(0)
	v_mfma_f32_16x16x32_bf16 v[68:71], v[160:163], v[176:179], v[68:71]
	v_add_u32_e32 v124, 0x184a0, v123
	ds_read_b64_tr_b16 v[180:181], v124
	v_add_u32_e32 v126, 0x196a0, v123
	ds_read_b64_tr_b16 v[182:183], v126
	s_waitcnt lgkmcnt(0)
	v_mfma_f32_16x16x32_bf16 v[68:71], v[164:167], v[180:183], v[68:71]
	v_add_u32_e32 v124, 0x118c0, v123
	ds_read_b64_tr_b16 v[168:169], v124
	v_add_u32_e32 v126, 0x12ac0, v123
	ds_read_b64_tr_b16 v[170:171], v126
	v_pk_mul_f32 v[74:75], v[116:117], v[74:75]
	v_pk_mul_f32 v[72:73], v[118:119], v[72:73]
	s_nop 0
	s_waitcnt lgkmcnt(0)
	v_mfma_f32_16x16x32_bf16 v[72:75], v[152:155], v[168:171], v[72:75]
	v_add_u32_e32 v124, 0x13cc0, v123
	ds_read_b64_tr_b16 v[172:173], v124
	v_add_u32_e32 v126, 0x14ec0, v123
	ds_read_b64_tr_b16 v[174:175], v126
	s_waitcnt lgkmcnt(0)
	v_mfma_f32_16x16x32_bf16 v[72:75], v[156:159], v[172:175], v[72:75]
	v_add_u32_e32 v124, 0x160c0, v123
	ds_read_b64_tr_b16 v[176:177], v124
	v_add_u32_e32 v126, 0x172c0, v123
	ds_read_b64_tr_b16 v[178:179], v126
	s_waitcnt lgkmcnt(0)
; #define GAS __attribute__((address_space(1)))
; #define MFMA16(a, b, c) __builtin_amdgcn_mfma_f32_16x16x32_bf16((a), (b), (c), 0, 0, 0)
; __device__ __forceinline__ bf16x8 ds_tr2(LAS unsigned char* p, int rstride) { const s16x4 a = ds_tr(p), b = ds_tr(p + 16 * rstride); bf16x8 r; r[0] = a[0]; r[1] = a[1]; r[2] = a[2]; r[3] = a[3]; r[4] = b[0]; r[5] = b[1]; r[6] = b[2]; r[7] = b[3]; return r; }
; template <int DIR, bool INTRA, bool FINAL> __device__ __forceinline__ void retention_pass(LAS unsigned char* lds, const bf16* ZH, bf16* YF, bf16* MIX, const float* ld, const float* gn, int seq, int h, int n0, int ncnt, ...
;     ...
;               for (int e = 0; e < 8; ++e) { st[e] = st[e] * gC;
; #pragma unroll
;                 for (int ks = 0; ks < 4; ++ks) { const bf16x8 vf = ds_tr2(trp + R_V + (32 * ks) * RSB + (16 * e) * 2, RSB);
;                     if constexpr (INTRA) y[e] = MFMA16(vf, pt[ks], y[e]);
;                     st[e] = MFMA16(kwf[ks], vf, st[e]); }
;                 __builtin_amdgcn_sched_barrier(0); } }
;             v2u ywv[8], gwv[8];
;             if constexpr (FINAL) { const int row_ = r0 + 16 * w + lr; const bf16* yp_ = YF + (size_t)row_ * 2048 + h * HD + 4 * lg; const bf16* gp_ = Gp + (size_t)(n * 128 + 16 * w + lr) * HD + 4 * lg;
; #pragma unroll
;                 for (int e = 0; e < 8; ++e) { ywv[e] = *(const GAS v2u*)(yp_ + 16 * e); gwv[e] = *(const GAS v2u*)(gp_ + 16 * e); } }
;             if (cn + 1 < ncnt) {
; #pragma unroll
;               for (int cc = 0; cc < 4; ++cc) { kreg[cc] = *(const GAS v4u*)(Kp + (size_t)(nn * 128 + srow + 32 * cc) * HD + 8 * sch); vreg[cc] = *(const GAS v4u*)(Vp + (size_t)(nn * 128 + srow + 32 * cc) * HD + 8 * sch); }
; #pragma unroll
;               for (int ks = 0; ks < 4; ++ks) qf[ks] = *(const GAS bf16x8*)(Qp + (size_t)(nn * 128 + 16 * w + lr) * HD + 8 * lg + 32 * ks); }
	v_mfma_f32_16x16x32_bf16 v[72:75], v[160:163], v[176:179], v[72:75]
	v_add_u32_e32 v124, 0x184c0, v123
	ds_read_b64_tr_b16 v[180:181], v124
	v_add_u32_e32 v126, 0x196c0, v123
	ds_read_b64_tr_b16 v[182:183], v126
	s_waitcnt lgkmcnt(0)
	v_mfma_f32_16x16x32_bf16 v[72:75], v[164:167], v[180:183], v[72:75]
	v_mul_f32_e64 v82, v116, v82
	v_mul_f32_e64 v83, v117, v83
	v_add_u32_e32 v117, 0x118e0, v123
	ds_read_b64_tr_b16 v[168:169], v117
	v_add_u32_e32 v117, 0x12ae0, v123
	ds_read_b64_tr_b16 v[170:171], v117
	v_pk_mul_f32 v[80:81], v[118:119], v[80:81]
	s_nop 0
	s_waitcnt lgkmcnt(0)
	v_mfma_f32_16x16x32_bf16 v[80:83], v[152:155], v[168:171], v[80:83]
	v_add_u32_e32 v112, 0x13ce0, v123
	ds_read_b64_tr_b16 v[172:173], v112
	v_add_u32_e32 v114, 0x14ee0, v123
	ds_read_b64_tr_b16 v[174:175], v114
	s_waitcnt lgkmcnt(0)
	v_mfma_f32_16x16x32_bf16 v[80:83], v[156:159], v[172:175], v[80:83]
	v_add_u32_e32 v108, 0x160e0, v123
	ds_read_b64_tr_b16 v[176:177], v108
	v_add_u32_e32 v110, 0x172e0, v123
	ds_read_b64_tr_b16 v[178:179], v110
	s_waitcnt lgkmcnt(0)
	v_mfma_f32_16x16x32_bf16 v[80:83], v[160:163], v[176:179], v[80:83]
	v_add_u32_e32 v104, 0x184e0, v123
	ds_read_b64_tr_b16 v[180:181], v104
	v_add_u32_e32 v106, 0x196e0, v123
	ds_read_b64_tr_b16 v[182:183], v106
	s_waitcnt lgkmcnt(0)
	v_mfma_f32_16x16x32_bf16 v[80:83], v[164:167], v[180:183], v[80:83]
	s_add_i32 s17, s65, s16
	v_add_u32_e32 v100, s17, v122
	v_add_u32_e32 v114, 0x80, v100
	v_add_u32_e32 v138, s16, v122
	v_ashrrev_i32_e32 v115, 31, v114
	v_add_u32_e32 v102, 0x80, v138
	v_lshlrev_b64 v[100:101], 12, v[114:115]
	v_ashrrev_i32_e32 v103, 31, v102
	v_lshl_add_u64 v[100:101], s[20:21], 0, v[100:101]
	v_lshlrev_b64 v[102:103], 8, v[102:103]
	v_lshl_add_u64 v[100:101], v[100:101], 0, v[2:3]
	v_lshl_add_u64 v[102:103], s[6:7], 0, v[102:103]
	v_lshl_add_u64 v[144:145], v[102:103], 0, v[2:3]
	global_load_dwordx2 v[134:135], v[100:101], off
	global_load_dwordx2 v[130:131], v[100:101], off offset:32
	global_load_dwordx2 v[126:127], v[100:101], off offset:64
	global_load_dwordx2 v[124:125], v[100:101], off offset:96
	global_load_dwordx2 v[122:123], v[144:145], off
	global_load_dwordx2 v[112:113], v[144:145], off offset:32
	global_load_dwordx2 v[110:111], v[144:145], off offset:64
	global_load_dwordx2 v[108:109], v[144:145], off offset:96
	global_load_dwordx2 v[140:141], v[100:101], off offset:128
	global_load_dwordx2 v[136:137], v[100:101], off offset:160
	global_load_dwordx2 v[132:133], v[100:101], off offset:192
	global_load_dwordx2 v[128:129], v[100:101], off offset:224
	global_load_dwordx2 v[106:107], v[144:145], off offset:128
	global_load_dwordx2 v[104:105], v[144:145], off offset:160
	global_load_dwordx2 v[102:103], v[144:145], off offset:192
	s_nop 0
	global_load_dwordx2 v[100:101], v[144:145], off offset:224
	s_cmpk_eq_i32 s16, 0xff80
	s_cbranch_scc1 .LBB0_1259
	v_add_u32_e32 v28, s16, v121
	v_ashrrev_i32_e32 v29, 31, v28
	v_lshlrev_b64 v[4:5], 8, v[28:29]
	v_add_u32_e32 v12, 32, v28
	v_add_u32_e32 v20, 64, v28
	v_add_u32_e32 v28, 0x60, v28
	v_ashrrev_i32_e32 v139, 31, v138
	v_mov_b32_e32 v121, v3
	v_ashrrev_i32_e32 v13, 31, v12
	v_ashrrev_i32_e32 v21, 31, v20
	v_ashrrev_i32_e32 v29, 31, v28
	v_lshlrev_b64 v[36:37], 8, v[138:139]
	v_lshl_add_u64 v[30:31], s[60:61], 0, v[120:121]
	v_lshl_add_u64 v[32:33], s[72:73], 0, v[120:121]
	v_lshlrev_b64 v[12:13], 8, v[12:13]
	v_lshlrev_b64 v[20:21], 8, v[20:21]
	v_lshlrev_b64 v[28:29], 8, v[28:29]
	v_lshl_add_u64 v[36:37], s[36:37], 0, v[36:37]
	v_lshlrev_b32_e32 v2, 1, v2
	v_lshl_add_u64 v[6:7], v[30:31], 0, v[4:5]
	v_lshl_add_u64 v[8:9], v[32:33], 0, v[4:5]
	v_lshl_add_u64 v[14:15], v[30:31], 0, v[12:13]
	v_lshl_add_u64 v[16:17], v[32:33], 0, v[12:13]
	v_lshl_add_u64 v[22:23], v[30:31], 0, v[20:21]
	v_lshl_add_u64 v[24:25], v[32:33], 0, v[20:21]
	v_lshl_add_u64 v[30:31], v[30:31], 0, v[28:29]
	v_lshl_add_u64 v[32:33], v[32:33], 0, v[28:29]
	v_lshl_add_u64 v[48:49], v[36:37], 0, v[2:3]
	global_load_dwordx4 v[4:7], v[6:7], off
	s_nop 0
	global_load_dwordx4 v[8:11], v[8:9], off
	s_nop 0
	global_load_dwordx4 v[12:15], v[14:15], off
	s_nop 0
	global_load_dwordx4 v[16:19], v[16:17], off
	s_nop 0
	global_load_dwordx4 v[20:23], v[22:23], off
	s_nop 0
	global_load_dwordx4 v[24:27], v[24:25], off
	s_nop 0
	global_load_dwordx4 v[28:31], v[30:31], off
	s_nop 0
	global_load_dwordx4 v[32:35], v[32:33], off
	s_nop 0
	global_load_dwordx4 v[36:39], v[48:49], off
	global_load_dwordx4 v[40:43], v[48:49], off offset:64
	global_load_dwordx4 v[44:47], v[48:49], off offset:128
	s_nop 0
	global_load_dwordx4 v[48:51], v[48:49], off offset:192
	s_branch .LBB0_1259
